# one static s_setprio 1 for waves 4-7 at kernel entry; all per-segment s_setprio toggles removed (peeled k-steps, block-diagonal GEMM)
# baseline (speedup 1.0000x reference)
; #define LAS __attribute__((address_space(3)))
; __global__ void __launch_bounds__(NT) fwd_megakernel(Params p) {
;   __shared__ __attribute__((aligned(16))) char lds[LDS_BYTES];
;   cg::grid_group grid = cg::this_grid();
;   __shared__ uint4 xb_words;
;   if (threadIdx.x == 0) xb_words = make_uint4(0u, 0u, 0u, 0u);
;   __syncthreads();
;   const XcdBarrier xb = xcd_barrier_post(p.bar, (volatile LAS unsigned*)&xb_words);
.LBB0_2:
	s_or_b64 exec, exec, s[4:5]
	v_readfirstlane_b32 s100, v216
	s_lshr_b32 s100, s100, 8
	s_cmp_eq_u32 s100, 0
	s_cbranch_scc1 .Lprio_done
	s_setprio 1
.Lprio_done:
	s_load_dword s48, s[0:1], 0x838
	s_load_dwordx2 s[96:97], s[0:1], 0x58
	s_waitcnt lgkmcnt(0)
	s_barrier
	s_getreg_b32 s4, hwreg(HW_REG_XCC_ID, 0, 4)
	s_and_b32 s33, s4, 15
	s_mov_b64 s[4:5], exec
	v_readlane_b32 s6, v253, 0
	v_readlane_b32 s7, v253, 1
	s_and_b64 s[6:7], s[4:5], s[6:7]
	s_mov_b64 exec, s[6:7]
	s_cbranch_execz .LBB0_8
	s_mov_b64 s[8:9], exec
	v_mbcnt_lo_u32_b32 v1, s8, 0
	v_mbcnt_hi_u32_b32 v1, s9, v1
	s_lshl_b32 s12, s33, 6
	v_cmp_eq_u32_e32 vcc, 0, v1
	s_and_saveexec_b64 s[6:7], vcc
	s_cbranch_execz .LBB0_5
	s_lshl_b32 s10, s12, 2
	s_bcnt1_i32_b64 s8, s[8:9]
	v_mov_b32_e32 v1, s10
	v_mov_b32_e32 v2, s8
	global_atomic_add v1, v2, s[96:97] offset:1024

; DI f32x16 mfma(bf16x8 a, bf16x8 b, f32x16 c) { return __builtin_amdgcn_mfma_f32_32x32x16_bf16(a, b, c, 0, 0, 0); }
;     ...
;   for (int kt = 0; kt < nk; ++kt) {
;     char* cur = lds + (kt & 1) * STG; char* nxt = lds + ((kt + 1) & 1) * STG;
;     const bool more = kt + 1 < nk;
;     const bf16_t* An = Ag + (kt + 1) * BK; const bf16_t* Bn = Bg + (kt + 1) * BK;
;     if (!more) epi.pre(row0 + wm * 64, col0 + wn * (32 * NTW), lane, w, lds);
;     bf16x8 fa[2][2], fb[2][NTW];
; #pragma unroll
;     for (int mt = 0; mt < 2; ++mt) { int row = wm * 64 + mt * 32 + l31; fa[0][mt] = *(const bf16x8*)(cur + row * (BK * 2) + ((hh ^ swz<BK>(row)) << 4)); }
; #pragma unroll
;     for (int nt = 0; nt < NTW; ++nt) { int row = wn * (32 * NTW) + nt * 32 + l31; fb[0][nt] = *(const bf16x8*)(cur + ABYTES + row * (BK * 2) + ((hh ^ swz<BK>(row)) << 4)); }
; #pragma unroll
;     for (int kk = 0; kk < NKK; ++kk) {
;       if (kk + 1 < NKK) {
;         const int ch = (kk + 1) * 2 + hh;
; #pragma unroll
;         for (int mt = 0; mt < 2; ++mt) { int row = wm * 64 + mt * 32 + l31; fa[(kk + 1) & 1][mt] = *(const bf16x8*)(cur + row * (BK * 2) + ((ch ^ swz<BK>(row)) << 4)); }
; #pragma unroll
;         for (int nt = 0; nt < NTW; ++nt) { int row = wn * (32 * NTW) + nt * 32 + l31; fb[(kk + 1) & 1][nt] = *(const bf16x8*)(cur + ABYTES + row * (BK * 2) + ((ch ^ swz<BK>(row)) << 4)); }
;       }
;       if (more) {
; #pragma unroll
;         for (int q = 0; q < PPK; ++q) {
;           const int pi = kk * PPK + q;
;           if (pi < NPA) stage_piece<BM, BK>(An, lda, nxt, tid, pi, wv);
;           else if (pi < NP) stage_piece<BN, BK>(Bn, ldb, nxt + ABYTES, tid, pi - NPA, wv);
;         }
;       }
;       __builtin_amdgcn_s_setprio(1);
; #pragma unroll
;       for (int mt = 0; mt < 2; ++mt)
; #pragma unroll
;         for (int nt = 0; nt < NTW; ++nt) acc[mt][nt] = mfma(fa[kk & 1][mt], fb[kk & 1][nt], acc[mt][nt]);
;       __builtin_amdgcn_s_setprio(0);
;       __builtin_amdgcn_sched_barrier(0);
;     }
;     wait_vm0();
;     __syncthreads();
;   DI void xpass(int ps, int grow0, int gcol0, int lane, int w, char* lds) const {
;     char* xs = lds + (ps & 1) * 65536 + __builtin_amdgcn_readfirstlane(w) * 8192;
;     const float* xsrc = Xin + (size_t)(grow0 + (ps >> 1) * 32 + (ps & 1) * 16 + (lane >> 5)) * D_ + gcol0 + (lane & 31) * 4;
; #pragma unroll
;     for (int pc = 0; pc < 8; ++pc)
.Lk173_exit:
	v_mfma_f32_32x32x16_bf16 v[114:129], v[194:197], v[202:205], v[114:129]
	v_mfma_f32_32x32x16_bf16 v[98:113], v[194:197], v[206:209], v[98:113]
	v_mfma_f32_32x32x16_bf16 v[82:97], v[194:197], v[210:213], v[82:97]
	v_mfma_f32_32x32x16_bf16 v[66:81], v[194:197], v[226:229], v[66:81]
	v_mfma_f32_32x32x16_bf16 v[50:65], v[198:201], v[202:205], v[50:65]
	v_mfma_f32_32x32x16_bf16 v[34:49], v[198:201], v[206:209], v[34:49]
	v_mfma_f32_32x32x16_bf16 v[18:33], v[198:201], v[210:213], v[18:33]
	v_mfma_f32_32x32x16_bf16 v[2:17], v[198:201], v[226:229], v[2:17]
	s_waitcnt lgkmcnt(0)
	v_readlane_b32 s3, v253, 9
	v_readlane_b32 s6, v253, 27
	v_readfirstlane_b32 s2, v134
	v_or_b32_e32 v130, s3, v135
	v_add_u32_e32 v130, v130, v169
	v_ashrrev_i32_e32 v131, 31, v130
	v_lshlrev_b64 v[130:131], 12, v[130:131]
	v_add_u32_e32 v132, s6, v164
	v_ashrrev_i32_e32 v133, 31, v132
	v_lshl_add_u64 v[130:131], s[10:11], 0, v[130:131]
	v_lshlrev_b32_e32 v0, 4, v0
	s_lshl_b32 s2, s2, 13
	v_lshl_add_u64 v[130:131], v[132:133], 2, v[130:131]
	v_and_b32_e32 v132, 0x1f0, v0
	v_mov_b32_e32 v133, v1
	v_lshl_add_u64 v[130:131], v[130:131], 0, v[132:133]
	s_mov_b32 m0, s2
	s_mov_b64 s[34:35], 0x2000
	global_load_lds_dwordx4 v[130:131], off
	v_lshl_add_u64 v[132:133], v[130:131], 0, s[34:35]
	s_or_b32 m0, s2, 0x400
	s_mov_b64 s[36:37], 0x4000
	global_load_lds_dwordx4 v[132:133], off
	v_lshl_add_u64 v[132:133], v[130:131], 0, s[36:37]
	s_or_b32 m0, s2, 0x800
	s_mov_b64 s[40:41], 0x6000
	global_load_lds_dwordx4 v[132:133], off
	v_lshl_add_u64 v[132:133], v[130:131], 0, s[40:41]
	s_or_b32 m0, s2, 0xc00
	s_mov_b64 s[44:45], 0x8000
	global_load_lds_dwordx4 v[132:133], off
	v_lshl_add_u64 v[132:133], v[130:131], 0, s[44:45]
	s_or_b32 m0, s2, 0x1000
	s_mov_b64 s[46:47], 0xa000
	global_load_lds_dwordx4 v[132:133], off
	v_lshl_add_u64 v[132:133], v[130:131], 0, s[46:47]
	s_or_b32 m0, s2, 0x1400
	s_mov_b64 s[52:53], 0xc000
	global_load_lds_dwordx4 v[132:133], off
	v_lshl_add_u64 v[132:133], v[130:131], 0, s[52:53]
	s_or_b32 m0, s2, 0x1800
	s_mov_b64 s[54:55], 0xe000
	global_load_lds_dwordx4 v[132:133], off
	v_lshl_add_u64 v[130:131], v[130:131], 0, s[54:55]
	s_or_b32 m0, s2, 0x1c00
	v_add_u32_e32 v0, s30, v136
	global_load_lds_dwordx4 v[130:131], off
	v_add_u32_e32 v134, s30, v144
	v_add_u32_e32 v130, v0, v143
	v_add_u32_e32 v135, v134, v146
	ds_read_b128 v[130:133], v130
	ds_read_b128 v[170:173], v135
	v_add_u32_e32 v135, s30, v145
	v_add_u32_e32 v136, v135, v151
	v_add_u32_e32 v143, s30, v152
	v_add_u32_e32 v144, v143, v156
	ds_read_b128 v[174:177], v136 offset:32768
	ds_read_b128 v[178:181], v144 offset:32768
	v_add_u32_e32 v136, s30, v155
	v_add_u32_e32 v144, v136, v157
	v_add_u32_e32 v164, s30, v158
	v_add_u32_e32 v145, v164, v168
	ds_read_b128 v[182:185], v144 offset:32768
	ds_read_b128 v[186:189], v145 offset:32768
	v_add_u32_e32 v144, v0, v166
	v_add_u32_e32 v145, v134, v167
	ds_read_b128 v[166:169], v144
	ds_read_b128 v[190:193], v145
	v_add_u32_e32 v144, v135, v161
	v_add_u32_e32 v145, v143, v163
	ds_read_b128 v[194:197], v144 offset:32768
	ds_read_b128 v[198:201], v145 offset:32768
	v_add_u32_e32 v144, v136, v159
	v_add_u32_e32 v145, v164, v160
	ds_read_b128 v[156:159], v144 offset:32768
	ds_read_b128 v[202:205], v145 offset:32768
	v_readlane_b32 s7, v253, 28
	s_waitcnt lgkmcnt(0)
	v_mfma_f32_32x32x16_bf16 v[114:129], v[130:133], v[174:177], v[114:129]
	v_mfma_f32_32x32x16_bf16 v[98:113], v[130:133], v[178:181], v[98:113]
	v_mfma_f32_32x32x16_bf16 v[82:97], v[130:133], v[182:185], v[82:97]
	v_mfma_f32_32x32x16_bf16 v[66:81], v[130:133], v[186:189], v[66:81]
	v_mfma_f32_32x32x16_bf16 v[50:65], v[170:173], v[174:177], v[50:65]
	v_mfma_f32_32x32x16_bf16 v[34:49], v[170:173], v[178:181], v[34:49]
	v_mfma_f32_32x32x16_bf16 v[18:33], v[170:173], v[182:185], v[18:33]
	v_mfma_f32_32x32x16_bf16 v[2:17], v[170:173], v[186:189], v[2:17]
	v_add_u32_e32 v130, v0, v153
	v_add_u32_e32 v144, v134, v154
	ds_read_b128 v[130:133], v130
	ds_read_b128 v[152:155], v144
	v_add_u32_e32 v144, v135, v149
	v_add_u32_e32 v145, v143, v150
	ds_read_b128 v[170:173], v144 offset:32768
	ds_read_b128 v[174:177], v145 offset:32768
	v_add_u32_e32 v144, v136, v147
	v_add_u32_e32 v148, v164, v148
	ds_read_b128 v[144:147], v144 offset:32768
	ds_read_b128 v[148:151], v148 offset:32768
	v_mfma_f32_32x32x16_bf16 v[114:129], v[166:169], v[194:197], v[114:129]
	v_mfma_f32_32x32x16_bf16 v[98:113], v[166:169], v[198:201], v[98:113]
	v_mfma_f32_32x32x16_bf16 v[82:97], v[166:169], v[156:159], v[82:97]
	v_mfma_f32_32x32x16_bf16 v[66:81], v[166:169], v[202:205], v[66:81]
	v_mfma_f32_32x32x16_bf16 v[50:65], v[190:193], v[194:197], v[50:65]
	v_mfma_f32_32x32x16_bf16 v[34:49], v[190:193], v[198:201], v[34:49]
	v_mfma_f32_32x32x16_bf16 v[18:33], v[190:193], v[156:159], v[18:33]
	v_mfma_f32_32x32x16_bf16 v[2:17], v[190:193], v[202:205], v[2:17]
	v_add_u32_e32 v0, v0, v141
	v_add_u32_e32 v134, v134, v142
	ds_read_b128 v[156:159], v0
	ds_read_b128 v[166:169], v134
	v_add_u32_e32 v0, v135, v139
	v_add_u32_e32 v134, v143, v140
	ds_read_b128 v[140:143], v0 offset:32768
	ds_read_b128 v[178:181], v134 offset:32768
	v_add_u32_e32 v0, v136, v137
	v_add_u32_e32 v138, v164, v138
	ds_read_b128 v[134:137], v0 offset:32768
	ds_read_b128 v[182:185], v138 offset:32768
	s_waitcnt lgkmcnt(9)
	v_mfma_f32_32x32x16_bf16 v[114:129], v[130:133], v[170:173], v[114:129]
	s_waitcnt lgkmcnt(8)
	v_mfma_f32_32x32x16_bf16 v[98:113], v[130:133], v[174:177], v[98:113]
	s_waitcnt lgkmcnt(7)
	v_mfma_f32_32x32x16_bf16 v[82:97], v[130:133], v[144:147], v[82:97]
	s_waitcnt lgkmcnt(6)
	v_mfma_f32_32x32x16_bf16 v[66:81], v[130:133], v[148:151], v[66:81]
	v_mfma_f32_32x32x16_bf16 v[50:65], v[152:155], v[170:173], v[50:65]
	v_mfma_f32_32x32x16_bf16 v[34:49], v[152:155], v[174:177], v[34:49]
	v_mfma_f32_32x32x16_bf16 v[18:33], v[152:155], v[144:147], v[18:33]
	v_mfma_f32_32x32x16_bf16 v[2:17], v[152:155], v[148:151], v[2:17]
	s_waitcnt lgkmcnt(3)
	v_mfma_f32_32x32x16_bf16 v[114:129], v[156:159], v[140:143], v[114:129]
	s_waitcnt lgkmcnt(2)
	v_mfma_f32_32x32x16_bf16 v[98:113], v[156:159], v[178:181], v[98:113]
	s_waitcnt lgkmcnt(1)
	v_mfma_f32_32x32x16_bf16 v[82:97], v[156:159], v[134:137], v[82:97]
	s_waitcnt lgkmcnt(0)
	v_mfma_f32_32x32x16_bf16 v[66:81], v[156:159], v[182:185], v[66:81]
	v_mfma_f32_32x32x16_bf16 v[50:65], v[166:169], v[140:143], v[50:65]
	v_mfma_f32_32x32x16_bf16 v[34:49], v[166:169], v[178:181], v[34:49]
	v_mfma_f32_32x32x16_bf16 v[18:33], v[166:169], v[134:137], v[18:33]
	v_mfma_f32_32x32x16_bf16 v[2:17], v[166:169], v[182:185], v[2:17]
	v_mov_b32_e32 v164, v216
	s_waitcnt vmcnt(0)
	s_barrier
;   DI void xpass(int ps, int grow0, int gcol0, int lane, int w, char* lds) const {
;     char* xs = lds + (ps & 1) * 65536 + __builtin_amdgcn_readfirstlane(w) * 8192;
;     const float* xsrc = Xin + (size_t)(grow0 + (ps >> 1) * 32 + (ps & 1) * 16 + (lane >> 5)) * D_ + gcol0 + (lane & 31) * 4;
; #pragma unroll
;     for (int pc = 0; pc < 8; ++pc)
;       __builtin_amdgcn_global_load_lds((const unsigned*)(xsrc + (size_t)(2 * pc) * D_), (__attribute__((address_space(3))) unsigned*)(xs + pc * 1024), 16, 0, 0);
;   }
;   DI void operator()(f32x16 (&acc)[2][4], int grow0, int gcol0, int lane, int w, char* lds) {
;     ...
;     for (int ps = 0; ps < 4; ++ps) {
;       const int mt = ps >> 1;
;       if (ps + 1 < 4) {
;         if (ps >= 1) asm volatile("s_waitcnt lgkmcnt(0)" ::: "memory");
;         xpass(ps + 1, grow0, gcol0, lane, w, lds);
;         if (ps >= 1) asm volatile("s_waitcnt vmcnt(8)" ::: "memory");
;       } else asm volatile("s_waitcnt vmcnt(0)" ::: "memory");
;       const char* xs = lds + (ps & 1) * 65536 + w * 8192;
; #pragma unroll
;       for (int qq = 0; qq < 2; ++qq)
; #pragma unroll
;         for (int e = 0; e < 4; ++e) {
;           const int i = 4 * (2 * (ps & 1) + qq) + e;
;           const float* xr = (const float*)(xs + (8 * qq + 4 * hh + e) * 512) + l31;
;           float s1 = 0.f, s2 = 0.f;
; #pragma unroll
;           for (int nt = 0; nt < 4; ++nt) {
;             float v = (acc[mt][nt][i] + bia[nt]) * csc[nt];
;             float z = ALPHA * xr[nt * 32] + hs * v;
;             acc[mt][nt][i] = z; s1 += z; s2 += z * z;
;           }
;           s1 = row16_sum(s1); s2 = row16_sum(s2);
;           if ((lane & 15) == 0) { f32x2 sv = {s1, s2}; *(f32x2*)(redw + (mt * 32 + (i & 3) + 8 * (i >> 2)) * 2) = sv; }
	v_mov_b32_e32 v133, v1
	v_ashrrev_i32_e32 v158, 6, v164
	v_lshrrev_b32_e32 v0, 30, v158
	v_add_u32_e32 v0, v158, v0
	v_ashrrev_i32_e32 v134, 2, v0
	v_mul_i32_i24_e32 v0, 4, v134
	v_sub_u32_e32 v0, v158, v0
	v_lshlrev_b32_e32 v135, 6, v0
	v_add_u32_e32 v163, s3, v135
	v_bfe_u32 v0, v164, 5, 1
	v_or_b32_e32 v159, v163, v0
	v_or_b32_e32 v130, 16, v159
	v_lshlrev_b32_e32 v200, 2, v164
	v_ashrrev_i32_e32 v131, 31, v130
	v_lshl_add_u32 v184, v134, 7, s6
	v_and_b32_e32 v0, 0x7c, v200
	v_lshlrev_b64 v[130:131], 12, v[130:131]
	v_ashrrev_i32_e32 v185, 31, v184
	v_readfirstlane_b32 s2, v158
	v_lshl_add_u64 v[130:131], s[10:11], 0, v[130:131]
	v_lshlrev_b32_e32 v0, 2, v0
	s_lshl_b32 s2, s2, 13
	v_lshl_add_u64 v[130:131], v[184:185], 2, v[130:131]
	v_mov_b32_e32 v132, v0
	s_add_i32 m0, s2, 0x10000
	v_lshl_add_u64 v[130:131], v[130:131], 0, v[132:133]
	global_load_lds_dwordx4 v[130:131], off
	v_lshl_add_u64 v[132:133], v[130:131], 0, s[34:35]
	s_add_i32 m0, s2, 0x10400
	v_and_b32_e32 v210, 0xc0, v135
	global_load_lds_dwordx4 v[132:133], off
	v_lshl_add_u64 v[132:133], v[130:131], 0, s[36:37]
	s_add_i32 m0, s2, 0x10800
	v_mov_b32_e32 v136, v114
	global_load_lds_dwordx4 v[132:133], off
	v_lshl_add_u64 v[132:133], v[130:131], 0, s[40:41]
	s_add_i32 m0, s2, 0x10c00
	v_mov_b32_e32 v137, v82
	global_load_lds_dwordx4 v[132:133], off
	v_lshl_add_u64 v[132:133], v[130:131], 0, s[44:45]
	s_add_i32 m0, s2, 0x11000
	v_mov_b32_e32 v140, v98
	global_load_lds_dwordx4 v[132:133], off
	v_lshl_add_u64 v[132:133], v[130:131], 0, s[46:47]
	s_add_i32 m0, s2, 0x11400
	v_mov_b32_e32 v141, v82
	global_load_lds_dwordx4 v[132:133], off
	v_lshl_add_u64 v[132:133], v[130:131], 0, s[52:53]
	s_add_i32 m0, s2, 0x11800
	v_lshl_add_u64 v[130:131], v[130:131], 0, s[54:55]
	global_load_lds_dwordx4 v[132:133], off
	s_add_i32 m0, s2, 0x11c00
	v_bfe_u32 v132, v164, 4, 1
	global_load_lds_dwordx4 v[130:131], off
	v_and_b32_e32 v130, 31, v164
	v_lshlrev_b32_e32 v131, 1, v134
	v_bfe_u32 v134, v164, 3, 3
	v_and_or_b32 v131, v131, 2, v132
	v_and_b32_e32 v132, 4, v134
	v_lshlrev_b32_e32 v130, 2, v130
	v_lshl_or_b32 v138, v158, 13, v130
	v_lshlrev_b32_e32 v154, 9, v132
	v_or_b32_e32 v133, v210, v132
	v_and_b32_e32 v130, 15, v164
	v_or_b32_e32 v132, v138, v154
	v_lshlrev_b32_e32 v135, 3, v133
	v_lshl_or_b32 v139, v131, 11, v221
	v_cmp_eq_u32_e32 vcc, 0, v130
	s_waitcnt vmcnt(8)
	ds_read2_b32 v[130:131], v132 offset1:32
	ds_read2_b32 v[132:133], v132 offset0:64 offset1:96
	v_pk_add_f32 v[136:137], v[136:137], 0 op_sel_hi:[1,0]
	v_pk_add_f32 v[140:141], v[140:141], 0 op_sel_hi:[1,0]
	s_mov_b32 s2, s67
	s_waitcnt lgkmcnt(0)
	v_mov_b32_e32 v142, v130
	v_mov_b32_e32 v143, v132
	v_mov_b32_e32 v130, v131
	v_mov_b32_e32 v131, v132
	v_pk_fma_f32 v[186:187], v[142:143], s[2:3], v[136:137] op_sel_hi:[1,0,1]
	v_pk_fma_f32 v[188:189], v[130:131], s[2:3], v[140:141] op_sel_hi:[1,0,1]
	v_pk_mul_f32 v[144:145], v[142:143], s[2:3] op_sel_hi:[1,0]
	v_pk_mul_f32 v[142:143], v[186:187], v[186:187]
	v_pk_mul_f32 v[130:131], v[188:189], v[188:189]
	v_pk_mov_b32 v[136:137], v[136:137], v[142:143] op_sel:[1,0]
	v_pk_mov_b32 v[130:131], v[144:145], v[130:131] op_sel:[1,0]
	v_add_f32_e32 v180, 0, v66
	v_pk_add_f32 v[130:131], v[136:137], v[130:131]
	v_pk_add_f32 v[136:137], v[186:187], v[188:189]
	v_pk_mul_f32 v[140:141], v[186:187], v[188:189]
	v_fmac_f32_e32 v180, 0x3fd744fd, v133
	v_mov_b32_e32 v137, v141
	v_pk_add_f32 v[130:131], v[136:137], v[130:131]
	v_mul_f32_e32 v181, v180, v180
	v_pk_add_f32 v[130:131], v[130:131], v[180:181]
	v_add_u32_e32 v181, v139, v135
	s_nop 0
	v_mov_b32_dpp v132, v130 quad_perm:[1,0,3,2] row_mask:0xf bank_mask:0xf bound_ctrl:1
	v_mov_b32_dpp v133, v131 quad_perm:[1,0,3,2] row_mask:0xf bank_mask:0xf bound_ctrl:1
	v_pk_add_f32 v[130:131], v[130:131], v[132:133]
	s_nop 1
	v_mov_b32_dpp v132, v130 quad_perm:[2,3,0,1] row_mask:0xf bank_mask:0xf bound_ctrl:1
	v_mov_b32_dpp v133, v131 quad_perm:[2,3,0,1] row_mask:0xf bank_mask:0xf bound_ctrl:1
	v_pk_add_f32 v[130:131], v[130:131], v[132:133]
	s_nop 1
	v_mov_b32_dpp v132, v130 row_half_mirror row_mask:0xf bank_mask:0xf bound_ctrl:1
	v_mov_b32_dpp v133, v131 row_half_mirror row_mask:0xf bank_mask:0xf bound_ctrl:1
	v_pk_add_f32 v[130:131], v[130:131], v[132:133]
	s_nop 1
	v_mov_b32_dpp v132, v130 row_mirror row_mask:0xf bank_mask:0xf bound_ctrl:1
	v_mov_b32_dpp v133, v131 row_mirror row_mask:0xf bank_mask:0xf bound_ctrl:1
	s_and_saveexec_b64 s[6:7], vcc
	v_pk_add_f32 v[130:131], v[130:131], v[132:133]
	ds_write_b64 v181, v[130:131]
	s_or_b64 exec, exec, s[6:7]
	v_add_u32_e32 v168, v138, v154
	ds_read2_b32 v[130:131], v168 offset0:128 offset1:160
	ds_read2_b32 v[132:133], v168 offset0:192 offset1:224
	v_mov_b32_e32 v82, v115
	v_add_f32_e32 v152, 0, v67
	v_pk_add_f32 v[66:67], v[82:83], 0 op_sel_hi:[1,0]
	v_mov_b32_e32 v82, v99
	v_pk_add_f32 v[82:83], v[82:83], 0 op_sel_hi:[1,0]
	s_waitcnt lgkmcnt(1)
	v_mov_b32_e32 v98, v130
	s_waitcnt lgkmcnt(0)
;   DI void operator()(f32x16 (&acc)[2][4], int grow0, int gcol0, int lane, int w, char* lds) {
;     ...
; #pragma unroll
;       for (int qq = 0; qq < 2; ++qq)
; #pragma unroll
;         for (int e = 0; e < 4; ++e) {
;           const int i = 4 * (2 * (ps & 1) + qq) + e;
;           const float* xr = (const float*)(xs + (8 * qq + 4 * hh + e) * 512) + l31;
;           float s1 = 0.f, s2 = 0.f;
; #pragma unroll
;           for (int nt = 0; nt < 4; ++nt) {
;             float v = (acc[mt][nt][i] + bia[nt]) * csc[nt];
;             float z = ALPHA * xr[nt * 32] + hs * v;
;             acc[mt][nt][i] = z; s1 += z; s2 += z * z;
;           }
;           s1 = row16_sum(s1); s2 = row16_sum(s2);
;           if ((lane & 15) == 0) { f32x2 sv = {s1, s2}; *(f32x2*)(redw + (mt * 32 + (i & 3) + 8 * (i >> 2)) * 2) = sv; }
	v_mov_b32_e32 v99, v132
	s_mov_b32 s2, s67
	v_mov_b32_e32 v130, v131
	v_mov_b32_e32 v131, v132
	v_pk_fma_f32 v[166:167], v[98:99], s[2:3], v[66:67] op_sel_hi:[1,0,1]
	v_pk_fma_f32 v[172:173], v[130:131], s[2:3], v[82:83] op_sel_hi:[1,0,1]
	v_pk_mul_f32 v[114:115], v[98:99], s[2:3] op_sel_hi:[1,0]
	v_pk_mul_f32 v[98:99], v[166:167], v[166:167]
	v_pk_mul_f32 v[82:83], v[172:173], v[172:173]
	v_pk_mov_b32 v[66:67], v[66:67], v[98:99] op_sel:[1,0]
	v_pk_mov_b32 v[82:83], v[114:115], v[82:83] op_sel:[1,0]
	v_pk_mul_f32 v[98:99], v[166:167], v[172:173]
	v_pk_add_f32 v[66:67], v[66:67], v[82:83]
	v_pk_add_f32 v[82:83], v[166:167], v[172:173]
	v_fmac_f32_e32 v152, 0x3fd744fd, v133
	v_mov_b32_e32 v83, v99
	v_pk_add_f32 v[66:67], v[82:83], v[66:67]
	v_mul_f32_e32 v153, v152, v152
	v_pk_add_f32 v[66:67], v[66:67], v[152:153]
	s_nop 1
	v_mov_b32_dpp v82, v66 quad_perm:[1,0,3,2] row_mask:0xf bank_mask:0xf bound_ctrl:1
	v_mov_b32_dpp v83, v67 quad_perm:[1,0,3,2] row_mask:0xf bank_mask:0xf bound_ctrl:1
	v_pk_add_f32 v[66:67], v[66:67], v[82:83]
	s_nop 1
	v_mov_b32_dpp v82, v66 quad_perm:[2,3,0,1] row_mask:0xf bank_mask:0xf bound_ctrl:1
	v_mov_b32_dpp v83, v67 quad_perm:[2,3,0,1] row_mask:0xf bank_mask:0xf bound_ctrl:1
	v_pk_add_f32 v[66:67], v[66:67], v[82:83]
	s_nop 1
	v_mov_b32_dpp v82, v66 row_half_mirror row_mask:0xf bank_mask:0xf bound_ctrl:1
	v_mov_b32_dpp v83, v67 row_half_mirror row_mask:0xf bank_mask:0xf bound_ctrl:1
	v_pk_add_f32 v[66:67], v[66:67], v[82:83]
	s_nop 1
	v_mov_b32_dpp v82, v66 row_mirror row_mask:0xf bank_mask:0xf bound_ctrl:1
	v_mov_b32_dpp v83, v67 row_mirror row_mask:0xf bank_mask:0xf bound_ctrl:1
	s_and_saveexec_b64 s[6:7], vcc
	v_pk_add_f32 v[66:67], v[66:67], v[82:83]
	ds_write_b64 v181, v[66:67] offset:8
	s_or_b64 exec, exec, s[6:7]
	v_add_u32_e32 v153, 0x400, v168
	ds_read2_b32 v[82:83], v153 offset1:32
	ds_read2_b32 v[98:99], v153 offset0:64 offset1:96
	v_mov_b32_e32 v114, v116
	v_mov_b32_e32 v115, v84
	v_mov_b32_e32 v130, v100
	v_mov_b32_e32 v131, v84
	v_pk_add_f32 v[114:115], v[114:115], 0 op_sel_hi:[1,0]
	v_pk_add_f32 v[130:131], v[130:131], 0 op_sel_hi:[1,0]
	s_waitcnt lgkmcnt(1)
	v_mov_b32_e32 v132, v82
	s_waitcnt lgkmcnt(0)
	v_mov_b32_e32 v133, v98
	s_mov_b32 s2, s67
	v_mov_b32_e32 v140, v83
	v_mov_b32_e32 v141, v98
	v_pk_fma_f32 v[82:83], v[132:133], s[2:3], v[114:115] op_sel_hi:[1,0,1]
	v_pk_fma_f32 v[150:151], v[140:141], s[2:3], v[130:131] op_sel_hi:[1,0,1]
	v_pk_mul_f32 v[136:137], v[132:133], s[2:3] op_sel_hi:[1,0]
	v_pk_mul_f32 v[132:133], v[82:83], v[82:83]
	v_pk_mul_f32 v[130:131], v[150:151], v[150:151]
	v_pk_mov_b32 v[114:115], v[114:115], v[132:133] op_sel:[1,0]
	v_pk_mov_b32 v[130:131], v[136:137], v[130:131] op_sel:[1,0]
	v_add_f32_e32 v66, 0, v68
	v_pk_add_f32 v[114:115], v[114:115], v[130:131]
	v_pk_add_f32 v[130:131], v[82:83], v[150:151]
	v_pk_mul_f32 v[132:133], v[82:83], v[150:151]
	v_fmac_f32_e32 v66, 0x3fd744fd, v99
	v_mov_b32_e32 v131, v133
	v_pk_add_f32 v[114:115], v[130:131], v[114:115]
	v_mul_f32_e32 v67, v66, v66
	v_pk_add_f32 v[98:99], v[114:115], v[66:67]
	s_nop 1
	v_mov_b32_dpp v114, v98 quad_perm:[1,0,3,2] row_mask:0xf bank_mask:0xf bound_ctrl:1
	v_mov_b32_dpp v115, v99 quad_perm:[1,0,3,2] row_mask:0xf bank_mask:0xf bound_ctrl:1
	v_pk_add_f32 v[98:99], v[98:99], v[114:115]
	s_nop 1
	v_mov_b32_dpp v114, v98 quad_perm:[2,3,0,1] row_mask:0xf bank_mask:0xf bound_ctrl:1
	v_mov_b32_dpp v115, v99 quad_perm:[2,3,0,1] row_mask:0xf bank_mask:0xf bound_ctrl:1
	v_pk_add_f32 v[98:99], v[98:99], v[114:115]
	s_nop 1
	v_mov_b32_dpp v114, v98 row_half_mirror row_mask:0xf bank_mask:0xf bound_ctrl:1
	v_mov_b32_dpp v115, v99 row_half_mirror row_mask:0xf bank_mask:0xf bound_ctrl:1
	v_pk_add_f32 v[98:99], v[98:99], v[114:115]
	s_nop 1
	v_mov_b32_dpp v114, v98 row_mirror row_mask:0xf bank_mask:0xf bound_ctrl:1
	v_mov_b32_dpp v115, v99 row_mirror row_mask:0xf bank_mask:0xf bound_ctrl:1
	s_and_saveexec_b64 s[6:7], vcc
	v_pk_add_f32 v[98:99], v[98:99], v[114:115]
	ds_write_b64 v181, v[98:99] offset:16
	s_or_b64 exec, exec, s[6:7]
	v_lshlrev_b32_e32 v139, 9, v134
	v_or_b32_e32 v146, 0x600, v139
	v_add_u32_e32 v151, v138, v146
	ds_read2_b32 v[98:99], v151 offset1:32
	ds_read2_b32 v[114:115], v151 offset0:64 offset1:96
	v_mov_b32_e32 v84, v117
	v_pk_add_f32 v[116:117], v[84:85], 0 op_sel_hi:[1,0]
	v_mov_b32_e32 v84, v101
	v_pk_add_f32 v[84:85], v[84:85], 0 op_sel_hi:[1,0]
	s_waitcnt lgkmcnt(1)
	v_mov_b32_e32 v100, v98
	s_waitcnt lgkmcnt(0)
	v_mov_b32_e32 v101, v114
	s_mov_b32 s2, s67
	v_mov_b32_e32 v132, v99
	v_mov_b32_e32 v133, v114
	v_pk_mul_f32 v[130:131], v[100:101], s[2:3] op_sel_hi:[1,0]
	v_pk_fma_f32 v[98:99], v[100:101], s[2:3], v[116:117] op_sel_hi:[1,0,1]
	v_pk_fma_f32 v[100:101], v[132:133], s[2:3], v[84:85] op_sel_hi:[1,0,1]
	v_pk_mul_f32 v[134:135], v[98:99], v[98:99]
	v_pk_mul_f32 v[84:85], v[100:101], v[100:101]
	v_pk_mov_b32 v[116:117], v[116:117], v[134:135] op_sel:[1,0]
	v_pk_mov_b32 v[84:85], v[130:131], v[84:85] op_sel:[1,0]
	v_add_f32_e32 v68, 0, v69
	v_pk_add_f32 v[84:85], v[116:117], v[84:85]
	v_pk_add_f32 v[116:117], v[98:99], v[100:101]
	v_pk_mul_f32 v[130:131], v[98:99], v[100:101]
	v_fmac_f32_e32 v68, 0x3fd744fd, v115
	v_mov_b32_e32 v117, v131
	v_pk_add_f32 v[84:85], v[116:117], v[84:85]
	v_mul_f32_e32 v69, v68, v68
	v_pk_add_f32 v[84:85], v[84:85], v[68:69]
	s_nop 1
	v_mov_b32_dpp v114, v84 quad_perm:[1,0,3,2] row_mask:0xf bank_mask:0xf bound_ctrl:1
	v_mov_b32_dpp v115, v85 quad_perm:[1,0,3,2] row_mask:0xf bank_mask:0xf bound_ctrl:1
	v_pk_add_f32 v[84:85], v[84:85], v[114:115]
	s_nop 1
	v_mov_b32_dpp v114, v84 quad_perm:[2,3,0,1] row_mask:0xf bank_mask:0xf bound_ctrl:1
	v_mov_b32_dpp v115, v85 quad_perm:[2,3,0,1] row_mask:0xf bank_mask:0xf bound_ctrl:1
	v_pk_add_f32 v[84:85], v[84:85], v[114:115]
	s_nop 1
	v_mov_b32_dpp v114, v84 row_half_mirror row_mask:0xf bank_mask:0xf bound_ctrl:1
	v_mov_b32_dpp v115, v85 row_half_mirror row_mask:0xf bank_mask:0xf bound_ctrl:1
	v_pk_add_f32 v[84:85], v[84:85], v[114:115]
	s_nop 1
	v_mov_b32_dpp v114, v84 row_mirror row_mask:0xf bank_mask:0xf bound_ctrl:1
	v_mov_b32_dpp v115, v85 row_mirror row_mask:0xf bank_mask:0xf bound_ctrl:1
	s_and_saveexec_b64 s[6:7], vcc
	v_pk_add_f32 v[84:85], v[84:85], v[114:115]
	ds_write_b64 v181, v[84:85] offset:24
	s_or_b64 exec, exec, s[6:7]
	v_add_u32_e32 v67, 0x1000, v168
	ds_read2_b32 v[114:115], v67 offset1:32
	ds_read2_b32 v[130:131], v67 offset0:64 offset1:96
	v_mov_b32_e32 v116, v118
	v_mov_b32_e32 v117, v86
	v_pk_add_f32 v[132:133], v[116:117], 0 op_sel_hi:[1,0]
	v_mov_b32_e32 v116, v102
	v_pk_add_f32 v[116:117], v[116:117], 0 op_sel_hi:[1,0]
	s_waitcnt lgkmcnt(1)
;   DI void operator()(f32x16 (&acc)[2][4], int grow0, int gcol0, int lane, int w, char* lds) {
;     ...
; #pragma unroll
;       for (int qq = 0; qq < 2; ++qq)
; #pragma unroll
;         for (int e = 0; e < 4; ++e) {
;           const int i = 4 * (2 * (ps & 1) + qq) + e;
;           const float* xr = (const float*)(xs + (8 * qq + 4 * hh + e) * 512) + l31;
;           float s1 = 0.f, s2 = 0.f;
; #pragma unroll
;           for (int nt = 0; nt < 4; ++nt) {
;             float v = (acc[mt][nt][i] + bia[nt]) * csc[nt];
;             float z = ALPHA * xr[nt * 32] + hs * v;
;             acc[mt][nt][i] = z; s1 += z; s2 += z * z;
;           }
;           s1 = row16_sum(s1); s2 = row16_sum(s2);
;           if ((lane & 15) == 0) { f32x2 sv = {s1, s2}; *(f32x2*)(redw + (mt * 32 + (i & 3) + 8 * (i >> 2)) * 2) = sv; }
	v_mov_b32_e32 v134, v114
	s_waitcnt lgkmcnt(0)
	v_mov_b32_e32 v135, v130
	s_mov_b32 s2, s67
	v_mov_b32_e32 v140, v115
	v_mov_b32_e32 v141, v130
	v_pk_fma_f32 v[114:115], v[134:135], s[2:3], v[132:133] op_sel_hi:[1,0,1]
	v_pk_fma_f32 v[116:117], v[140:141], s[2:3], v[116:117] op_sel_hi:[1,0,1]
	v_pk_mul_f32 v[136:137], v[134:135], s[2:3] op_sel_hi:[1,0]
	v_pk_mul_f32 v[134:135], v[114:115], v[114:115]
	v_pk_mul_f32 v[140:141], v[116:117], v[116:117]
	v_pk_mov_b32 v[132:133], v[132:133], v[134:135] op_sel:[1,0]
	v_pk_mov_b32 v[134:135], v[136:137], v[140:141] op_sel:[1,0]
	v_add_f32_e32 v84, 0, v70
	v_pk_add_f32 v[132:133], v[132:133], v[134:135]
	v_pk_add_f32 v[134:135], v[114:115], v[116:117]
	v_pk_mul_f32 v[136:137], v[114:115], v[116:117]
	v_fmac_f32_e32 v84, 0x3fd744fd, v131
	v_mov_b32_e32 v135, v137
	v_pk_add_f32 v[132:133], v[134:135], v[132:133]
	v_mul_f32_e32 v85, v84, v84
	v_pk_add_f32 v[130:131], v[132:133], v[84:85]
	s_nop 1
	v_mov_b32_dpp v132, v130 quad_perm:[1,0,3,2] row_mask:0xf bank_mask:0xf bound_ctrl:1
	v_mov_b32_dpp v133, v131 quad_perm:[1,0,3,2] row_mask:0xf bank_mask:0xf bound_ctrl:1
	v_pk_add_f32 v[130:131], v[130:131], v[132:133]
	s_nop 1
	v_mov_b32_dpp v132, v130 quad_perm:[2,3,0,1] row_mask:0xf bank_mask:0xf bound_ctrl:1
	v_mov_b32_dpp v133, v131 quad_perm:[2,3,0,1] row_mask:0xf bank_mask:0xf bound_ctrl:1
	v_pk_add_f32 v[130:131], v[130:131], v[132:133]
	s_nop 1
	v_mov_b32_dpp v132, v130 row_half_mirror row_mask:0xf bank_mask:0xf bound_ctrl:1
	v_mov_b32_dpp v133, v131 row_half_mirror row_mask:0xf bank_mask:0xf bound_ctrl:1
	v_pk_add_f32 v[130:131], v[130:131], v[132:133]
	s_nop 1
	v_mov_b32_dpp v132, v130 row_mirror row_mask:0xf bank_mask:0xf bound_ctrl:1
	v_mov_b32_dpp v133, v131 row_mirror row_mask:0xf bank_mask:0xf bound_ctrl:1
	s_and_saveexec_b64 s[6:7], vcc
	v_pk_add_f32 v[130:131], v[130:131], v[132:133]
	ds_write_b64 v181, v[130:131] offset:64
	s_or_b64 exec, exec, s[6:7]
	ds_read2_b32 v[130:131], v67 offset0:128 offset1:160
	ds_read2_b32 v[132:133], v67 offset0:192 offset1:224
	v_mov_b32_e32 v86, v119
	v_pk_add_f32 v[134:135], v[86:87], 0 op_sel_hi:[1,0]
	v_mov_b32_e32 v86, v103
	v_pk_add_f32 v[86:87], v[86:87], 0 op_sel_hi:[1,0]
	s_waitcnt lgkmcnt(1)
	v_mov_b32_e32 v102, v130
	s_waitcnt lgkmcnt(0)
	v_mov_b32_e32 v103, v132
	s_mov_b32 s2, s67
	v_mov_b32_e32 v118, v131
	v_mov_b32_e32 v119, v132
	v_pk_mul_f32 v[136:137], v[102:103], s[2:3] op_sel_hi:[1,0]
	v_pk_fma_f32 v[102:103], v[102:103], s[2:3], v[134:135] op_sel_hi:[1,0,1]
	v_pk_fma_f32 v[118:119], v[118:119], s[2:3], v[86:87] op_sel_hi:[1,0,1]
	v_pk_mul_f32 v[130:131], v[102:103], v[102:103]
	v_pk_mul_f32 v[86:87], v[118:119], v[118:119]
	v_pk_mov_b32 v[130:131], v[134:135], v[130:131] op_sel:[1,0]
	v_pk_mov_b32 v[86:87], v[136:137], v[86:87] op_sel:[1,0]
	v_add_f32_e32 v70, 0, v71
	v_pk_add_f32 v[86:87], v[130:131], v[86:87]
	v_pk_add_f32 v[130:131], v[102:103], v[118:119]
	v_pk_mul_f32 v[134:135], v[102:103], v[118:119]
	v_fmac_f32_e32 v70, 0x3fd744fd, v133
	v_mov_b32_e32 v131, v135
	v_pk_add_f32 v[86:87], v[130:131], v[86:87]
	v_mul_f32_e32 v71, v70, v70
	v_pk_add_f32 v[86:87], v[86:87], v[70:71]
	s_nop 1
	v_mov_b32_dpp v130, v86 quad_perm:[1,0,3,2] row_mask:0xf bank_mask:0xf bound_ctrl:1
	v_mov_b32_dpp v131, v87 quad_perm:[1,0,3,2] row_mask:0xf bank_mask:0xf bound_ctrl:1
	v_pk_add_f32 v[86:87], v[86:87], v[130:131]
	s_nop 1
	v_mov_b32_dpp v130, v86 quad_perm:[2,3,0,1] row_mask:0xf bank_mask:0xf bound_ctrl:1
	v_mov_b32_dpp v131, v87 quad_perm:[2,3,0,1] row_mask:0xf bank_mask:0xf bound_ctrl:1
	v_pk_add_f32 v[86:87], v[86:87], v[130:131]
	s_nop 1
	v_mov_b32_dpp v130, v86 row_half_mirror row_mask:0xf bank_mask:0xf bound_ctrl:1
	v_mov_b32_dpp v131, v87 row_half_mirror row_mask:0xf bank_mask:0xf bound_ctrl:1
	v_pk_add_f32 v[86:87], v[86:87], v[130:131]
	s_nop 1
	v_mov_b32_dpp v130, v86 row_mirror row_mask:0xf bank_mask:0xf bound_ctrl:1
	v_mov_b32_dpp v131, v87 row_mirror row_mask:0xf bank_mask:0xf bound_ctrl:1
	s_and_saveexec_b64 s[6:7], vcc
	v_pk_add_f32 v[86:87], v[86:87], v[130:131]
	ds_write_b64 v181, v[86:87] offset:72
	s_or_b64 exec, exec, s[6:7]
	v_add_u32_e32 v69, 0x1400, v168
	ds_read2_b32 v[130:131], v69 offset1:32
	ds_read2_b32 v[134:135], v69 offset0:64 offset1:96
	v_mov_b32_e32 v132, v120
	v_mov_b32_e32 v133, v88
	v_pk_add_f32 v[136:137], v[132:133], 0 op_sel_hi:[1,0]
	v_mov_b32_e32 v132, v104
	v_pk_add_f32 v[132:133], v[132:133], 0 op_sel_hi:[1,0]
	s_waitcnt lgkmcnt(1)
	v_mov_b32_e32 v140, v130
	s_waitcnt lgkmcnt(0)
	v_mov_b32_e32 v141, v134
	s_mov_b32 s2, s67
	v_mov_b32_e32 v144, v131
	v_mov_b32_e32 v145, v134
	v_pk_fma_f32 v[130:131], v[140:141], s[2:3], v[136:137] op_sel_hi:[1,0,1]
	v_pk_fma_f32 v[132:133], v[144:145], s[2:3], v[132:133] op_sel_hi:[1,0,1]
	v_pk_mul_f32 v[142:143], v[140:141], s[2:3] op_sel_hi:[1,0]
	v_pk_mul_f32 v[140:141], v[130:131], v[130:131]
	v_pk_mul_f32 v[144:145], v[132:133], v[132:133]
	v_pk_mov_b32 v[136:137], v[136:137], v[140:141] op_sel:[1,0]
	v_pk_mov_b32 v[140:141], v[142:143], v[144:145] op_sel:[1,0]
	v_add_f32_e32 v86, 0, v72
	v_pk_add_f32 v[136:137], v[136:137], v[140:141]
	v_pk_add_f32 v[140:141], v[130:131], v[132:133]
	v_pk_mul_f32 v[142:143], v[130:131], v[132:133]
	v_fmac_f32_e32 v86, 0x3fd744fd, v135
	v_mov_b32_e32 v141, v143
	v_pk_add_f32 v[136:137], v[140:141], v[136:137]
	v_mul_f32_e32 v87, v86, v86
	v_pk_add_f32 v[134:135], v[136:137], v[86:87]
	s_nop 1
	v_mov_b32_dpp v136, v134 quad_perm:[1,0,3,2] row_mask:0xf bank_mask:0xf bound_ctrl:1
	v_mov_b32_dpp v137, v135 quad_perm:[1,0,3,2] row_mask:0xf bank_mask:0xf bound_ctrl:1
	v_pk_add_f32 v[134:135], v[134:135], v[136:137]
	s_nop 1
	v_mov_b32_dpp v136, v134 quad_perm:[2,3,0,1] row_mask:0xf bank_mask:0xf bound_ctrl:1
	v_mov_b32_dpp v137, v135 quad_perm:[2,3,0,1] row_mask:0xf bank_mask:0xf bound_ctrl:1
	v_pk_add_f32 v[134:135], v[134:135], v[136:137]
	s_nop 1
	v_mov_b32_dpp v136, v134 row_half_mirror row_mask:0xf bank_mask:0xf bound_ctrl:1
	v_mov_b32_dpp v137, v135 row_half_mirror row_mask:0xf bank_mask:0xf bound_ctrl:1
	v_pk_add_f32 v[134:135], v[134:135], v[136:137]
	s_nop 1
	v_mov_b32_dpp v136, v134 row_mirror row_mask:0xf bank_mask:0xf bound_ctrl:1
	v_mov_b32_dpp v137, v135 row_mirror row_mask:0xf bank_mask:0xf bound_ctrl:1
	s_and_saveexec_b64 s[6:7], vcc
	v_pk_add_f32 v[134:135], v[134:135], v[136:137]
	ds_write_b64 v181, v[134:135] offset:80
	s_or_b64 exec, exec, s[6:7]
	v_or_b32_e32 v101, 0x1600, v139
	v_add_u32_e32 v71, v138, v101
	ds_read2_b32 v[134:135], v71 offset1:32
	ds_read2_b32 v[136:137], v71 offset0:64 offset1:96
	v_mov_b32_e32 v88, v121
	v_pk_add_f32 v[120:121], v[88:89], 0 op_sel_hi:[1,0]
	v_mov_b32_e32 v88, v105
	v_pk_add_f32 v[104:105], v[88:89], 0 op_sel_hi:[1,0]
	s_waitcnt lgkmcnt(1)
;   DI void xpass(int ps, int grow0, int gcol0, int lane, int w, char* lds) const {
;     char* xs = lds + (ps & 1) * 65536 + __builtin_amdgcn_readfirstlane(w) * 8192;
;     const float* xsrc = Xin + (size_t)(grow0 + (ps >> 1) * 32 + (ps & 1) * 16 + (lane >> 5)) * D_ + gcol0 + (lane & 31) * 4;
; #pragma unroll
;     for (int pc = 0; pc < 8; ++pc)
;       __builtin_amdgcn_global_load_lds((const unsigned*)(xsrc + (size_t)(2 * pc) * D_), (__attribute__((address_space(3))) unsigned*)(xs + pc * 1024), 16, 0, 0);
;   }
;   DI void operator()(f32x16 (&acc)[2][4], int grow0, int gcol0, int lane, int w, char* lds) {
;     ...
;     for (int ps = 0; ps < 4; ++ps) {
;       const int mt = ps >> 1;
;       if (ps + 1 < 4) {
;         if (ps >= 1) asm volatile("s_waitcnt lgkmcnt(0)" ::: "memory");
;         xpass(ps + 1, grow0, gcol0, lane, w, lds);
;         if (ps >= 1) asm volatile("s_waitcnt vmcnt(8)" ::: "memory");
;       } else asm volatile("s_waitcnt vmcnt(0)" ::: "memory");
;       const char* xs = lds + (ps & 1) * 65536 + w * 8192;
; #pragma unroll
;       for (int qq = 0; qq < 2; ++qq)
; #pragma unroll
;         for (int e = 0; e < 4; ++e) {
;           const int i = 4 * (2 * (ps & 1) + qq) + e;
;           const float* xr = (const float*)(xs + (8 * qq + 4 * hh + e) * 512) + l31;
;           float s1 = 0.f, s2 = 0.f;
; #pragma unroll
;           for (int nt = 0; nt < 4; ++nt) {
;             float v = (acc[mt][nt][i] + bia[nt]) * csc[nt];
;             float z = ALPHA * xr[nt * 32] + hs * v;
;             acc[mt][nt][i] = z; s1 += z; s2 += z * z;
;           }
;           s1 = row16_sum(s1); s2 = row16_sum(s2);
;           if ((lane & 15) == 0) { f32x2 sv = {s1, s2}; *(f32x2*)(redw + (mt * 32 + (i & 3) + 8 * (i >> 2)) * 2) = sv; }
	v_mov_b32_e32 v88, v134
	s_waitcnt lgkmcnt(0)
	v_mov_b32_e32 v89, v136
	s_mov_b32 s2, s67
	v_mov_b32_e32 v134, v135
	v_mov_b32_e32 v135, v136
	v_pk_mul_f32 v[140:141], v[88:89], s[2:3] op_sel_hi:[1,0]
	v_pk_fma_f32 v[88:89], v[88:89], s[2:3], v[120:121] op_sel_hi:[1,0,1]
	v_pk_fma_f32 v[104:105], v[134:135], s[2:3], v[104:105] op_sel_hi:[1,0,1]
	v_pk_mul_f32 v[142:143], v[88:89], v[88:89]
	v_pk_mul_f32 v[134:135], v[104:105], v[104:105]
	v_pk_mov_b32 v[120:121], v[120:121], v[142:143] op_sel:[1,0]
	v_pk_mov_b32 v[134:135], v[140:141], v[134:135] op_sel:[1,0]
	v_add_f32_e32 v72, 0, v73
	v_pk_add_f32 v[120:121], v[120:121], v[134:135]
	v_pk_add_f32 v[134:135], v[88:89], v[104:105]
	v_pk_mul_f32 v[140:141], v[88:89], v[104:105]
	v_fmac_f32_e32 v72, 0x3fd744fd, v137
	v_mov_b32_e32 v135, v141
	v_pk_add_f32 v[120:121], v[134:135], v[120:121]
	v_mul_f32_e32 v73, v72, v72
	v_pk_add_f32 v[120:121], v[120:121], v[72:73]
	s_nop 1
	v_mov_b32_dpp v134, v120 quad_perm:[1,0,3,2] row_mask:0xf bank_mask:0xf bound_ctrl:1
	v_mov_b32_dpp v135, v121 quad_perm:[1,0,3,2] row_mask:0xf bank_mask:0xf bound_ctrl:1
	v_pk_add_f32 v[120:121], v[120:121], v[134:135]
	s_nop 1
	v_mov_b32_dpp v134, v120 quad_perm:[2,3,0,1] row_mask:0xf bank_mask:0xf bound_ctrl:1
	v_mov_b32_dpp v135, v121 quad_perm:[2,3,0,1] row_mask:0xf bank_mask:0xf bound_ctrl:1
	v_pk_add_f32 v[120:121], v[120:121], v[134:135]
	s_nop 1
	v_mov_b32_dpp v134, v120 row_half_mirror row_mask:0xf bank_mask:0xf bound_ctrl:1
	v_mov_b32_dpp v135, v121 row_half_mirror row_mask:0xf bank_mask:0xf bound_ctrl:1
	v_pk_add_f32 v[120:121], v[120:121], v[134:135]
	s_nop 1
	v_mov_b32_dpp v134, v120 row_mirror row_mask:0xf bank_mask:0xf bound_ctrl:1
	v_mov_b32_dpp v135, v121 row_mirror row_mask:0xf bank_mask:0xf bound_ctrl:1
	s_and_saveexec_b64 s[6:7], vcc
	v_pk_add_f32 v[120:121], v[120:121], v[134:135]
	ds_write_b64 v181, v[120:121] offset:88
	s_or_b64 exec, exec, s[6:7]
	v_or_b32_e32 v120, 32, v159
	v_ashrrev_i32_e32 v121, 31, v120
	v_lshlrev_b64 v[120:121], 12, v[120:121]
	v_readfirstlane_b32 s2, v158
	v_lshl_add_u64 v[120:121], s[10:11], 0, v[120:121]
	s_lshl_b32 s2, s2, 13
	v_lshl_add_u64 v[120:121], v[184:185], 2, v[120:121]
	s_waitcnt lgkmcnt(0)
	v_lshl_add_u64 v[120:121], v[120:121], 0, v[0:1]
	s_mov_b32 m0, s2
	s_mov_b64 s[6:7], 0x2000
	global_load_lds_dwordx4 v[120:121], off
	v_lshl_add_u64 v[134:135], v[120:121], 0, s[6:7]
	s_or_b32 m0, s2, 0x400
	s_mov_b64 s[6:7], 0x4000
	global_load_lds_dwordx4 v[134:135], off
	v_lshl_add_u64 v[134:135], v[120:121], 0, s[6:7]
	s_or_b32 m0, s2, 0x800
	s_mov_b64 s[6:7], 0x6000
	global_load_lds_dwordx4 v[134:135], off
	v_lshl_add_u64 v[134:135], v[120:121], 0, s[6:7]
	s_or_b32 m0, s2, 0xc00
	s_mov_b64 s[6:7], 0x8000
	global_load_lds_dwordx4 v[134:135], off
	v_lshl_add_u64 v[134:135], v[120:121], 0, s[6:7]
	s_or_b32 m0, s2, 0x1000
	s_mov_b64 s[6:7], 0xa000
	global_load_lds_dwordx4 v[134:135], off
	v_lshl_add_u64 v[134:135], v[120:121], 0, s[6:7]
	s_or_b32 m0, s2, 0x1400
	s_mov_b64 s[6:7], 0xc000
	global_load_lds_dwordx4 v[134:135], off
	v_lshl_add_u64 v[134:135], v[120:121], 0, s[6:7]
	s_or_b32 m0, s2, 0x1800
	s_mov_b64 s[6:7], 0xe000
	global_load_lds_dwordx4 v[134:135], off
	v_lshl_add_u64 v[120:121], v[120:121], 0, s[6:7]
	s_or_b32 m0, s2, 0x1c00
	v_add_u32_e32 v105, 0x10000, v138
	global_load_lds_dwordx4 v[120:121], off
	s_waitcnt vmcnt(8)
	v_add_u32_e32 v73, v105, v154
	ds_read2_b32 v[134:135], v73 offset1:32
	ds_read2_b32 v[138:139], v73 offset0:64 offset1:96
	v_mov_b32_e32 v136, v122
	v_mov_b32_e32 v137, v90
	v_pk_add_f32 v[140:141], v[136:137], 0 op_sel_hi:[1,0]
	v_mov_b32_e32 v136, v106
	v_pk_add_f32 v[136:137], v[136:137], 0 op_sel_hi:[1,0]
	s_waitcnt lgkmcnt(0)
	v_mov_b32_e32 v142, v134
	v_mov_b32_e32 v143, v138
	s_mov_b32 s2, s67
	v_mov_b32_e32 v148, v135
	v_mov_b32_e32 v149, v138
	v_pk_fma_f32 v[134:135], v[142:143], s[2:3], v[140:141] op_sel_hi:[1,0,1]
	v_pk_fma_f32 v[136:137], v[148:149], s[2:3], v[136:137] op_sel_hi:[1,0,1]
	v_pk_mul_f32 v[144:145], v[142:143], s[2:3] op_sel_hi:[1,0]
	v_pk_mul_f32 v[142:143], v[134:135], v[134:135]
	v_pk_mul_f32 v[148:149], v[136:137], v[136:137]
	v_pk_mov_b32 v[140:141], v[140:141], v[142:143] op_sel:[1,0]
	v_pk_mov_b32 v[142:143], v[144:145], v[148:149] op_sel:[1,0]
	v_add_f32_e32 v120, 0, v74
	v_pk_add_f32 v[140:141], v[140:141], v[142:143]
	v_pk_add_f32 v[142:143], v[134:135], v[136:137]
	v_pk_mul_f32 v[144:145], v[134:135], v[136:137]
	v_fmac_f32_e32 v120, 0x3fd744fd, v139
	v_mov_b32_e32 v143, v145
	v_pk_add_f32 v[140:141], v[142:143], v[140:141]
	v_mul_f32_e32 v121, v120, v120
	v_pk_add_f32 v[138:139], v[140:141], v[120:121]
	s_nop 1
	v_mov_b32_dpp v140, v138 quad_perm:[1,0,3,2] row_mask:0xf bank_mask:0xf bound_ctrl:1
	v_mov_b32_dpp v141, v139 quad_perm:[1,0,3,2] row_mask:0xf bank_mask:0xf bound_ctrl:1
	v_pk_add_f32 v[138:139], v[138:139], v[140:141]
	s_nop 1
	v_mov_b32_dpp v140, v138 quad_perm:[2,3,0,1] row_mask:0xf bank_mask:0xf bound_ctrl:1
	v_mov_b32_dpp v141, v139 quad_perm:[2,3,0,1] row_mask:0xf bank_mask:0xf bound_ctrl:1
	v_pk_add_f32 v[138:139], v[138:139], v[140:141]
	s_nop 1
	v_mov_b32_dpp v140, v138 row_half_mirror row_mask:0xf bank_mask:0xf bound_ctrl:1
	v_mov_b32_dpp v141, v139 row_half_mirror row_mask:0xf bank_mask:0xf bound_ctrl:1
	v_pk_add_f32 v[138:139], v[138:139], v[140:141]
	s_nop 1
	v_mov_b32_dpp v140, v138 row_mirror row_mask:0xf bank_mask:0xf bound_ctrl:1
	v_mov_b32_dpp v141, v139 row_mirror row_mask:0xf bank_mask:0xf bound_ctrl:1
	s_and_saveexec_b64 s[6:7], vcc
	v_pk_add_f32 v[138:139], v[138:139], v[140:141]
	ds_write_b64 v181, v[138:139] offset:128
	s_or_b64 exec, exec, s[6:7]
	v_or_b32_e32 v74, 0x200, v154
	v_add_u32_e32 v85, v105, v74
	ds_read2_b32 v[138:139], v85 offset1:32
	ds_read2_b32 v[140:141], v85 offset0:64 offset1:96
	v_mov_b32_e32 v90, v123
	v_pk_add_f32 v[142:143], v[90:91], 0 op_sel_hi:[1,0]
	v_mov_b32_e32 v90, v107
	v_pk_add_f32 v[90:91], v[90:91], 0 op_sel_hi:[1,0]
	s_waitcnt lgkmcnt(1)
;   DI void operator()(f32x16 (&acc)[2][4], int grow0, int gcol0, int lane, int w, char* lds) {
;     ...
; #pragma unroll
;       for (int qq = 0; qq < 2; ++qq)
; #pragma unroll
;         for (int e = 0; e < 4; ++e) {
;           const int i = 4 * (2 * (ps & 1) + qq) + e;
;           const float* xr = (const float*)(xs + (8 * qq + 4 * hh + e) * 512) + l31;
;           float s1 = 0.f, s2 = 0.f;
; #pragma unroll
;           for (int nt = 0; nt < 4; ++nt) {
;             float v = (acc[mt][nt][i] + bia[nt]) * csc[nt];
;             float z = ALPHA * xr[nt * 32] + hs * v;
;             acc[mt][nt][i] = z; s1 += z; s2 += z * z;
;           }
;           s1 = row16_sum(s1); s2 = row16_sum(s2);
;           if ((lane & 15) == 0) { f32x2 sv = {s1, s2}; *(f32x2*)(redw + (mt * 32 + (i & 3) + 8 * (i >> 2)) * 2) = sv; }
	v_mov_b32_e32 v106, v138
	s_waitcnt lgkmcnt(0)
	v_mov_b32_e32 v107, v140
	s_mov_b32 s2, s67
	v_mov_b32_e32 v122, v139
	v_mov_b32_e32 v123, v140
	v_pk_mul_f32 v[144:145], v[106:107], s[2:3] op_sel_hi:[1,0]
	v_pk_fma_f32 v[106:107], v[106:107], s[2:3], v[142:143] op_sel_hi:[1,0,1]
	v_pk_fma_f32 v[122:123], v[122:123], s[2:3], v[90:91] op_sel_hi:[1,0,1]
	v_pk_mul_f32 v[138:139], v[106:107], v[106:107]
	v_pk_mul_f32 v[90:91], v[122:123], v[122:123]
	v_pk_mov_b32 v[138:139], v[142:143], v[138:139] op_sel:[1,0]
	v_pk_mov_b32 v[90:91], v[144:145], v[90:91] op_sel:[1,0]
	v_add_f32_e32 v74, 0, v75
	v_pk_add_f32 v[90:91], v[138:139], v[90:91]
	v_pk_add_f32 v[138:139], v[106:107], v[122:123]
	v_pk_mul_f32 v[142:143], v[106:107], v[122:123]
	v_fmac_f32_e32 v74, 0x3fd744fd, v141
	v_mov_b32_e32 v139, v143
	v_pk_add_f32 v[90:91], v[138:139], v[90:91]
	v_mul_f32_e32 v75, v74, v74
	v_pk_add_f32 v[90:91], v[90:91], v[74:75]
	s_nop 1
	v_mov_b32_dpp v138, v90 quad_perm:[1,0,3,2] row_mask:0xf bank_mask:0xf bound_ctrl:1
	v_mov_b32_dpp v139, v91 quad_perm:[1,0,3,2] row_mask:0xf bank_mask:0xf bound_ctrl:1
	v_pk_add_f32 v[90:91], v[90:91], v[138:139]
	s_nop 1
	v_mov_b32_dpp v138, v90 quad_perm:[2,3,0,1] row_mask:0xf bank_mask:0xf bound_ctrl:1
	v_mov_b32_dpp v139, v91 quad_perm:[2,3,0,1] row_mask:0xf bank_mask:0xf bound_ctrl:1
	v_pk_add_f32 v[90:91], v[90:91], v[138:139]
	s_nop 1
	v_mov_b32_dpp v138, v90 row_half_mirror row_mask:0xf bank_mask:0xf bound_ctrl:1
	v_mov_b32_dpp v139, v91 row_half_mirror row_mask:0xf bank_mask:0xf bound_ctrl:1
	v_pk_add_f32 v[90:91], v[90:91], v[138:139]
	s_nop 1
	v_mov_b32_dpp v138, v90 row_mirror row_mask:0xf bank_mask:0xf bound_ctrl:1
	v_mov_b32_dpp v139, v91 row_mirror row_mask:0xf bank_mask:0xf bound_ctrl:1
	s_and_saveexec_b64 s[6:7], vcc
	v_pk_add_f32 v[90:91], v[90:91], v[138:139]
	ds_write_b64 v181, v[90:91] offset:136
	s_or_b64 exec, exec, s[6:7]
	v_or_b32_e32 v75, 0x400, v154
	v_add_u32_e32 v75, v105, v75
	ds_read2_b32 v[138:139], v75 offset1:32
	ds_read2_b32 v[142:143], v75 offset0:64 offset1:96
	v_mov_b32_e32 v140, v124
	v_mov_b32_e32 v141, v92
	v_pk_add_f32 v[144:145], v[140:141], 0 op_sel_hi:[1,0]
	v_mov_b32_e32 v140, v108
	v_pk_add_f32 v[140:141], v[140:141], 0 op_sel_hi:[1,0]
	s_waitcnt lgkmcnt(1)
	v_mov_b32_e32 v148, v138
	s_waitcnt lgkmcnt(0)
	v_mov_b32_e32 v149, v142
	s_mov_b32 s2, s67
	v_mov_b32_e32 v160, v139
	v_mov_b32_e32 v161, v142
	v_pk_fma_f32 v[138:139], v[148:149], s[2:3], v[144:145] op_sel_hi:[1,0,1]
	v_pk_fma_f32 v[140:141], v[160:161], s[2:3], v[140:141] op_sel_hi:[1,0,1]
	v_pk_mul_f32 v[156:157], v[148:149], s[2:3] op_sel_hi:[1,0]
	v_pk_mul_f32 v[148:149], v[138:139], v[138:139]
	v_pk_mul_f32 v[160:161], v[140:141], v[140:141]
	v_pk_mov_b32 v[144:145], v[144:145], v[148:149] op_sel:[1,0]
	v_pk_mov_b32 v[148:149], v[156:157], v[160:161] op_sel:[1,0]
	v_add_f32_e32 v90, 0, v76
	v_pk_add_f32 v[144:145], v[144:145], v[148:149]
	v_pk_add_f32 v[148:149], v[138:139], v[140:141]
	v_pk_mul_f32 v[156:157], v[138:139], v[140:141]
	v_fmac_f32_e32 v90, 0x3fd744fd, v143
	v_mov_b32_e32 v149, v157
	v_pk_add_f32 v[144:145], v[148:149], v[144:145]
	v_mul_f32_e32 v91, v90, v90
	v_pk_add_f32 v[142:143], v[144:145], v[90:91]
	s_nop 1
	v_mov_b32_dpp v144, v142 quad_perm:[1,0,3,2] row_mask:0xf bank_mask:0xf bound_ctrl:1
	v_mov_b32_dpp v145, v143 quad_perm:[1,0,3,2] row_mask:0xf bank_mask:0xf bound_ctrl:1
	v_pk_add_f32 v[142:143], v[142:143], v[144:145]
	s_nop 1
	v_mov_b32_dpp v144, v142 quad_perm:[2,3,0,1] row_mask:0xf bank_mask:0xf bound_ctrl:1
	v_mov_b32_dpp v145, v143 quad_perm:[2,3,0,1] row_mask:0xf bank_mask:0xf bound_ctrl:1
	v_pk_add_f32 v[142:143], v[142:143], v[144:145]
	s_nop 1
	v_mov_b32_dpp v144, v142 row_half_mirror row_mask:0xf bank_mask:0xf bound_ctrl:1
	v_mov_b32_dpp v145, v143 row_half_mirror row_mask:0xf bank_mask:0xf bound_ctrl:1
	v_pk_add_f32 v[142:143], v[142:143], v[144:145]
	s_nop 1
	v_mov_b32_dpp v144, v142 row_mirror row_mask:0xf bank_mask:0xf bound_ctrl:1
	v_mov_b32_dpp v145, v143 row_mirror row_mask:0xf bank_mask:0xf bound_ctrl:1
	s_and_saveexec_b64 s[6:7], vcc
	v_pk_add_f32 v[142:143], v[142:143], v[144:145]
	ds_write_b64 v181, v[142:143] offset:144
	s_or_b64 exec, exec, s[6:7]
	v_add_u32_e32 v87, v105, v146
	ds_read2_b32 v[142:143], v87 offset1:32
	ds_read2_b32 v[144:145], v87 offset0:64 offset1:96
	v_mov_b32_e32 v92, v125
	v_pk_add_f32 v[146:147], v[92:93], 0 op_sel_hi:[1,0]
	v_mov_b32_e32 v92, v109
	v_pk_add_f32 v[92:93], v[92:93], 0 op_sel_hi:[1,0]
	s_waitcnt lgkmcnt(1)
	v_mov_b32_e32 v108, v142
	s_waitcnt lgkmcnt(0)
;   DI void operator()(f32x16 (&acc)[2][4], int grow0, int gcol0, int lane, int w, char* lds) {
;     ...
;       for (int qq = 0; qq < 2; ++qq)
; #pragma unroll
;         for (int e = 0; e < 4; ++e) {
;           const int i = 4 * (2 * (ps & 1) + qq) + e;
;           const float* xr = (const float*)(xs + (8 * qq + 4 * hh + e) * 512) + l31;
;           float s1 = 0.f, s2 = 0.f;
; #pragma unroll
;           for (int nt = 0; nt < 4; ++nt) {
;             float v = (acc[mt][nt][i] + bia[nt]) * csc[nt];
;             float z = ALPHA * xr[nt * 32] + hs * v;
;             acc[mt][nt][i] = z; s1 += z; s2 += z * z;
;           }
;           s1 = row16_sum(s1); s2 = row16_sum(s2);
;           if ((lane & 15) == 0) { f32x2 sv = {s1, s2}; *(f32x2*)(redw + (mt * 32 + (i & 3) + 8 * (i >> 2)) * 2) = sv; }
;         }
	v_mov_b32_e32 v109, v144
	s_mov_b32 s2, s67
	v_mov_b32_e32 v124, v143
	v_mov_b32_e32 v125, v144
	v_pk_mul_f32 v[148:149], v[108:109], s[2:3] op_sel_hi:[1,0]
	v_pk_fma_f32 v[108:109], v[108:109], s[2:3], v[146:147] op_sel_hi:[1,0,1]
	v_pk_fma_f32 v[124:125], v[124:125], s[2:3], v[92:93] op_sel_hi:[1,0,1]
	v_pk_mul_f32 v[142:143], v[108:109], v[108:109]
	v_pk_mul_f32 v[92:93], v[124:125], v[124:125]
	v_pk_mov_b32 v[142:143], v[146:147], v[142:143] op_sel:[1,0]
	v_pk_mov_b32 v[92:93], v[148:149], v[92:93] op_sel:[1,0]
	v_add_f32_e32 v76, 0, v77
	v_pk_add_f32 v[92:93], v[142:143], v[92:93]
	v_pk_add_f32 v[142:143], v[108:109], v[124:125]
	v_pk_mul_f32 v[146:147], v[108:109], v[124:125]
	v_fmac_f32_e32 v76, 0x3fd744fd, v145
	v_mov_b32_e32 v143, v147
	v_pk_add_f32 v[92:93], v[142:143], v[92:93]
	v_mul_f32_e32 v77, v76, v76
	v_pk_add_f32 v[92:93], v[92:93], v[76:77]
	s_nop 1
	v_mov_b32_dpp v142, v92 quad_perm:[1,0,3,2] row_mask:0xf bank_mask:0xf bound_ctrl:1
	v_mov_b32_dpp v143, v93 quad_perm:[1,0,3,2] row_mask:0xf bank_mask:0xf bound_ctrl:1
	v_pk_add_f32 v[92:93], v[92:93], v[142:143]
	s_nop 1
	v_mov_b32_dpp v142, v92 quad_perm:[2,3,0,1] row_mask:0xf bank_mask:0xf bound_ctrl:1
	v_mov_b32_dpp v143, v93 quad_perm:[2,3,0,1] row_mask:0xf bank_mask:0xf bound_ctrl:1
	v_pk_add_f32 v[92:93], v[92:93], v[142:143]
	s_nop 1
	v_mov_b32_dpp v142, v92 row_half_mirror row_mask:0xf bank_mask:0xf bound_ctrl:1
	v_mov_b32_dpp v143, v93 row_half_mirror row_mask:0xf bank_mask:0xf bound_ctrl:1
	v_pk_add_f32 v[92:93], v[92:93], v[142:143]
	s_nop 1
	v_mov_b32_dpp v142, v92 row_mirror row_mask:0xf bank_mask:0xf bound_ctrl:1
	v_mov_b32_dpp v143, v93 row_mirror row_mask:0xf bank_mask:0xf bound_ctrl:1
	s_and_saveexec_b64 s[6:7], vcc
	v_pk_add_f32 v[92:93], v[92:93], v[142:143]
	ds_write_b64 v181, v[92:93] offset:152
	s_or_b64 exec, exec, s[6:7]
	v_or_b32_e32 v77, 0x1000, v154
	v_add_u32_e32 v77, v105, v77
	ds_read2_b32 v[142:143], v77 offset1:32
	ds_read2_b32 v[146:147], v77 offset0:64 offset1:96
	v_mov_b32_e32 v144, v126
	v_mov_b32_e32 v145, v94
	v_pk_add_f32 v[148:149], v[144:145], 0 op_sel_hi:[1,0]
	v_mov_b32_e32 v144, v110
	v_pk_add_f32 v[144:145], v[144:145], 0 op_sel_hi:[1,0]
	s_waitcnt lgkmcnt(1)
	v_mov_b32_e32 v156, v142
	s_waitcnt lgkmcnt(0)
	v_mov_b32_e32 v157, v146
	s_mov_b32 s2, s67
	v_mov_b32_e32 v170, v143
	v_mov_b32_e32 v171, v146
	v_pk_fma_f32 v[142:143], v[156:157], s[2:3], v[148:149] op_sel_hi:[1,0,1]
	v_pk_fma_f32 v[144:145], v[170:171], s[2:3], v[144:145] op_sel_hi:[1,0,1]
	v_pk_mul_f32 v[160:161], v[156:157], s[2:3] op_sel_hi:[1,0]
	v_pk_mul_f32 v[156:157], v[142:143], v[142:143]
	v_pk_mul_f32 v[170:171], v[144:145], v[144:145]
	v_pk_mov_b32 v[148:149], v[148:149], v[156:157] op_sel:[1,0]
	v_pk_mov_b32 v[156:157], v[160:161], v[170:171] op_sel:[1,0]
	v_add_f32_e32 v92, 0, v78
	v_pk_add_f32 v[148:149], v[148:149], v[156:157]
	v_pk_add_f32 v[156:157], v[142:143], v[144:145]
	v_pk_mul_f32 v[160:161], v[142:143], v[144:145]
	v_fmac_f32_e32 v92, 0x3fd744fd, v147
	v_mov_b32_e32 v157, v161
	v_pk_add_f32 v[148:149], v[156:157], v[148:149]
	v_mul_f32_e32 v93, v92, v92
	v_pk_add_f32 v[146:147], v[148:149], v[92:93]
	s_nop 1
	v_mov_b32_dpp v148, v146 quad_perm:[1,0,3,2] row_mask:0xf bank_mask:0xf bound_ctrl:1
	v_mov_b32_dpp v149, v147 quad_perm:[1,0,3,2] row_mask:0xf bank_mask:0xf bound_ctrl:1
	v_pk_add_f32 v[146:147], v[146:147], v[148:149]
	s_nop 1
	v_mov_b32_dpp v148, v146 quad_perm:[2,3,0,1] row_mask:0xf bank_mask:0xf bound_ctrl:1
	v_mov_b32_dpp v149, v147 quad_perm:[2,3,0,1] row_mask:0xf bank_mask:0xf bound_ctrl:1
	v_pk_add_f32 v[146:147], v[146:147], v[148:149]
	s_nop 1
	v_mov_b32_dpp v148, v146 row_half_mirror row_mask:0xf bank_mask:0xf bound_ctrl:1
	v_mov_b32_dpp v149, v147 row_half_mirror row_mask:0xf bank_mask:0xf bound_ctrl:1
	v_pk_add_f32 v[146:147], v[146:147], v[148:149]
	s_nop 1
	v_mov_b32_dpp v148, v146 row_mirror row_mask:0xf bank_mask:0xf bound_ctrl:1
	v_mov_b32_dpp v149, v147 row_mirror row_mask:0xf bank_mask:0xf bound_ctrl:1
	s_and_saveexec_b64 s[6:7], vcc
	v_pk_add_f32 v[146:147], v[146:147], v[148:149]
	ds_write_b64 v181, v[146:147] offset:192
	s_or_b64 exec, exec, s[6:7]
	v_or_b32_e32 v78, 0x1200, v154
	v_add_u32_e32 v91, v105, v78
	ds_read2_b32 v[146:147], v91 offset1:32
	ds_read2_b32 v[148:149], v91 offset0:64 offset1:96
	v_mov_b32_e32 v94, v127
	v_pk_add_f32 v[156:157], v[94:95], 0 op_sel_hi:[1,0]
	v_mov_b32_e32 v94, v111
	v_pk_add_f32 v[94:95], v[94:95], 0 op_sel_hi:[1,0]
	s_waitcnt lgkmcnt(1)
	v_mov_b32_e32 v110, v146
	s_waitcnt lgkmcnt(0)
	v_mov_b32_e32 v111, v148
	s_mov_b32 s2, s67
	v_mov_b32_e32 v126, v147
	v_mov_b32_e32 v127, v148
	v_pk_mul_f32 v[160:161], v[110:111], s[2:3] op_sel_hi:[1,0]
	v_pk_fma_f32 v[110:111], v[110:111], s[2:3], v[156:157] op_sel_hi:[1,0,1]
	v_pk_fma_f32 v[126:127], v[126:127], s[2:3], v[94:95] op_sel_hi:[1,0,1]
	v_pk_mul_f32 v[146:147], v[110:111], v[110:111]
	v_pk_mul_f32 v[94:95], v[126:127], v[126:127]
	v_pk_mov_b32 v[146:147], v[156:157], v[146:147] op_sel:[1,0]
	v_pk_mov_b32 v[94:95], v[160:161], v[94:95] op_sel:[1,0]
	v_add_f32_e32 v78, 0, v79
	v_pk_add_f32 v[94:95], v[146:147], v[94:95]
	v_pk_add_f32 v[146:147], v[110:111], v[126:127]
	v_pk_mul_f32 v[156:157], v[110:111], v[126:127]
	v_fmac_f32_e32 v78, 0x3fd744fd, v149
	v_mov_b32_e32 v147, v157
	v_pk_add_f32 v[94:95], v[146:147], v[94:95]
	v_mul_f32_e32 v79, v78, v78
	v_pk_add_f32 v[94:95], v[94:95], v[78:79]
	s_nop 1
	v_mov_b32_dpp v146, v94 quad_perm:[1,0,3,2] row_mask:0xf bank_mask:0xf bound_ctrl:1
	v_mov_b32_dpp v147, v95 quad_perm:[1,0,3,2] row_mask:0xf bank_mask:0xf bound_ctrl:1
	v_pk_add_f32 v[94:95], v[94:95], v[146:147]
	s_nop 1
	v_mov_b32_dpp v146, v94 quad_perm:[2,3,0,1] row_mask:0xf bank_mask:0xf bound_ctrl:1
	v_mov_b32_dpp v147, v95 quad_perm:[2,3,0,1] row_mask:0xf bank_mask:0xf bound_ctrl:1
	v_pk_add_f32 v[94:95], v[94:95], v[146:147]
	s_nop 1
	v_mov_b32_dpp v146, v94 row_half_mirror row_mask:0xf bank_mask:0xf bound_ctrl:1
	v_mov_b32_dpp v147, v95 row_half_mirror row_mask:0xf bank_mask:0xf bound_ctrl:1
	v_pk_add_f32 v[94:95], v[94:95], v[146:147]
	s_nop 1
	v_mov_b32_dpp v146, v94 row_mirror row_mask:0xf bank_mask:0xf bound_ctrl:1
	v_mov_b32_dpp v147, v95 row_mirror row_mask:0xf bank_mask:0xf bound_ctrl:1
	s_and_saveexec_b64 s[6:7], vcc
	v_pk_add_f32 v[94:95], v[94:95], v[146:147]
	ds_write_b64 v181, v[94:95] offset:200
	s_or_b64 exec, exec, s[6:7]
	v_or_b32_e32 v79, 0x1400, v154
	v_add_u32_e32 v79, v105, v79
	ds_read2_b32 v[146:147], v79 offset1:32
	ds_read2_b32 v[154:155], v79 offset0:64 offset1:96
	v_mov_b32_e32 v148, v128
	v_mov_b32_e32 v149, v96
	v_pk_add_f32 v[156:157], v[148:149], 0 op_sel_hi:[1,0]
	v_mov_b32_e32 v148, v112
	v_pk_add_f32 v[148:149], v[148:149], 0 op_sel_hi:[1,0]
	s_waitcnt lgkmcnt(1)
;   DI void xpass(int ps, int grow0, int gcol0, int lane, int w, char* lds) const {
;     char* xs = lds + (ps & 1) * 65536 + __builtin_amdgcn_readfirstlane(w) * 8192;
;     const float* xsrc = Xin + (size_t)(grow0 + (ps >> 1) * 32 + (ps & 1) * 16 + (lane >> 5)) * D_ + gcol0 + (lane & 31) * 4;
; #pragma unroll
;     for (int pc = 0; pc < 8; ++pc)
;       __builtin_amdgcn_global_load_lds((const unsigned*)(xsrc + (size_t)(2 * pc) * D_), (__attribute__((address_space(3))) unsigned*)(xs + pc * 1024), 16, 0, 0);
;   }
;   DI void operator()(f32x16 (&acc)[2][4], int grow0, int gcol0, int lane, int w, char* lds) {
;     ...
;       for (int qq = 0; qq < 2; ++qq)
; #pragma unroll
;         for (int e = 0; e < 4; ++e) {
;           const int i = 4 * (2 * (ps & 1) + qq) + e;
;           const float* xr = (const float*)(xs + (8 * qq + 4 * hh + e) * 512) + l31;
;           float s1 = 0.f, s2 = 0.f;
; #pragma unroll
;           for (int nt = 0; nt < 4; ++nt) {
;             float v = (acc[mt][nt][i] + bia[nt]) * csc[nt];
;             float z = ALPHA * xr[nt * 32] + hs * v;
;             acc[mt][nt][i] = z; s1 += z; s2 += z * z;
;           }
;           s1 = row16_sum(s1); s2 = row16_sum(s2);
;           if ((lane & 15) == 0) { f32x2 sv = {s1, s2}; *(f32x2*)(redw + (mt * 32 + (i & 3) + 8 * (i >> 2)) * 2) = sv; }
;         }
	v_mov_b32_e32 v160, v146
	s_waitcnt lgkmcnt(0)
	v_mov_b32_e32 v161, v154
	s_mov_b32 s2, s67
	v_mov_b32_e32 v174, v147
	v_mov_b32_e32 v175, v154
	v_pk_fma_f32 v[146:147], v[160:161], s[2:3], v[156:157] op_sel_hi:[1,0,1]
	v_pk_fma_f32 v[148:149], v[174:175], s[2:3], v[148:149] op_sel_hi:[1,0,1]
	v_pk_mul_f32 v[170:171], v[160:161], s[2:3] op_sel_hi:[1,0]
	v_pk_mul_f32 v[160:161], v[146:147], v[146:147]
	v_pk_mul_f32 v[174:175], v[148:149], v[148:149]
	v_pk_mov_b32 v[156:157], v[156:157], v[160:161] op_sel:[1,0]
	v_pk_mov_b32 v[160:161], v[170:171], v[174:175] op_sel:[1,0]
	v_add_f32_e32 v94, 0, v80
	v_pk_add_f32 v[156:157], v[156:157], v[160:161]
	v_pk_add_f32 v[160:161], v[146:147], v[148:149]
	v_pk_mul_f32 v[170:171], v[146:147], v[148:149]
	v_fmac_f32_e32 v94, 0x3fd744fd, v155
	v_mov_b32_e32 v161, v171
	v_pk_add_f32 v[156:157], v[160:161], v[156:157]
	v_mul_f32_e32 v95, v94, v94
	v_pk_add_f32 v[154:155], v[156:157], v[94:95]
	s_nop 1
	v_mov_b32_dpp v156, v154 quad_perm:[1,0,3,2] row_mask:0xf bank_mask:0xf bound_ctrl:1
	v_mov_b32_dpp v157, v155 quad_perm:[1,0,3,2] row_mask:0xf bank_mask:0xf bound_ctrl:1
	v_pk_add_f32 v[154:155], v[154:155], v[156:157]
	s_nop 1
	v_mov_b32_dpp v156, v154 quad_perm:[2,3,0,1] row_mask:0xf bank_mask:0xf bound_ctrl:1
	v_mov_b32_dpp v157, v155 quad_perm:[2,3,0,1] row_mask:0xf bank_mask:0xf bound_ctrl:1
	v_pk_add_f32 v[154:155], v[154:155], v[156:157]
	s_nop 1
	v_mov_b32_dpp v156, v154 row_half_mirror row_mask:0xf bank_mask:0xf bound_ctrl:1
	v_mov_b32_dpp v157, v155 row_half_mirror row_mask:0xf bank_mask:0xf bound_ctrl:1
	v_pk_add_f32 v[154:155], v[154:155], v[156:157]
	s_nop 1
	v_mov_b32_dpp v156, v154 row_mirror row_mask:0xf bank_mask:0xf bound_ctrl:1
	v_mov_b32_dpp v157, v155 row_mirror row_mask:0xf bank_mask:0xf bound_ctrl:1
	s_and_saveexec_b64 s[6:7], vcc
	v_pk_add_f32 v[154:155], v[154:155], v[156:157]
	ds_write_b64 v181, v[154:155] offset:208
	s_or_b64 exec, exec, s[6:7]
	v_add_u32_e32 v93, v105, v101
	ds_read2_b32 v[154:155], v93 offset1:32
	ds_read2_b32 v[156:157], v93 offset0:64 offset1:96
	v_mov_b32_e32 v96, v129
	v_pk_add_f32 v[128:129], v[96:97], 0 op_sel_hi:[1,0]
	v_mov_b32_e32 v96, v113
	v_pk_add_f32 v[112:113], v[96:97], 0 op_sel_hi:[1,0]
	s_waitcnt lgkmcnt(1)
	v_mov_b32_e32 v96, v154
	s_waitcnt lgkmcnt(0)
	v_mov_b32_e32 v97, v156
	s_mov_b32 s2, s67
	v_mov_b32_e32 v154, v155
	v_mov_b32_e32 v155, v156
	v_pk_mul_f32 v[160:161], v[96:97], s[2:3] op_sel_hi:[1,0]
	v_pk_fma_f32 v[96:97], v[96:97], s[2:3], v[128:129] op_sel_hi:[1,0,1]
	v_pk_fma_f32 v[112:113], v[154:155], s[2:3], v[112:113] op_sel_hi:[1,0,1]
	v_pk_mul_f32 v[170:171], v[96:97], v[96:97]
	v_pk_mul_f32 v[154:155], v[112:113], v[112:113]
	v_pk_mov_b32 v[128:129], v[128:129], v[170:171] op_sel:[1,0]
	v_pk_mov_b32 v[154:155], v[160:161], v[154:155] op_sel:[1,0]
	v_add_f32_e32 v80, 0, v81
	v_pk_add_f32 v[128:129], v[128:129], v[154:155]
	v_pk_add_f32 v[154:155], v[96:97], v[112:113]
	v_pk_mul_f32 v[160:161], v[96:97], v[112:113]
	v_fmac_f32_e32 v80, 0x3fd744fd, v157
	v_mov_b32_e32 v155, v161
	v_pk_add_f32 v[128:129], v[154:155], v[128:129]
	v_mul_f32_e32 v81, v80, v80
	v_pk_add_f32 v[128:129], v[128:129], v[80:81]
	s_nop 1
	v_mov_b32_dpp v154, v128 quad_perm:[1,0,3,2] row_mask:0xf bank_mask:0xf bound_ctrl:1
	v_mov_b32_dpp v155, v129 quad_perm:[1,0,3,2] row_mask:0xf bank_mask:0xf bound_ctrl:1
	v_pk_add_f32 v[128:129], v[128:129], v[154:155]
	s_nop 1
	v_mov_b32_dpp v154, v128 quad_perm:[2,3,0,1] row_mask:0xf bank_mask:0xf bound_ctrl:1
	v_mov_b32_dpp v155, v129 quad_perm:[2,3,0,1] row_mask:0xf bank_mask:0xf bound_ctrl:1
	v_pk_add_f32 v[128:129], v[128:129], v[154:155]
	s_nop 1
	v_mov_b32_dpp v154, v128 row_half_mirror row_mask:0xf bank_mask:0xf bound_ctrl:1
	v_mov_b32_dpp v155, v129 row_half_mirror row_mask:0xf bank_mask:0xf bound_ctrl:1
	v_pk_add_f32 v[128:129], v[128:129], v[154:155]
	s_nop 1
	v_mov_b32_dpp v154, v128 row_mirror row_mask:0xf bank_mask:0xf bound_ctrl:1
	v_mov_b32_dpp v155, v129 row_mirror row_mask:0xf bank_mask:0xf bound_ctrl:1
	s_and_saveexec_b64 s[6:7], vcc
	v_pk_add_f32 v[128:129], v[128:129], v[154:155]
	ds_write_b64 v181, v[128:129] offset:216
	s_or_b64 exec, exec, s[6:7]
	v_or_b32_e32 v128, 48, v159
	v_ashrrev_i32_e32 v129, 31, v128
	v_lshlrev_b64 v[128:129], 12, v[128:129]
	v_readfirstlane_b32 s2, v158
	v_lshl_add_u64 v[128:129], s[10:11], 0, v[128:129]
	s_lshl_b32 s2, s2, 13
	v_lshl_add_u64 v[128:129], v[184:185], 2, v[128:129]
	s_waitcnt lgkmcnt(0)
	s_add_i32 m0, s2, 0x10000
	v_lshl_add_u64 v[128:129], v[128:129], 0, v[0:1]
	s_mov_b64 s[6:7], 0x2000
	global_load_lds_dwordx4 v[128:129], off
	v_lshl_add_u64 v[154:155], v[128:129], 0, s[6:7]
	s_add_i32 m0, s2, 0x10400
	s_mov_b64 s[6:7], 0x4000
	global_load_lds_dwordx4 v[154:155], off
	v_lshl_add_u64 v[154:155], v[128:129], 0, s[6:7]
	s_add_i32 m0, s2, 0x10800
	s_mov_b64 s[6:7], 0x6000
	global_load_lds_dwordx4 v[154:155], off
	v_lshl_add_u64 v[154:155], v[128:129], 0, s[6:7]
	s_add_i32 m0, s2, 0x10c00
	s_mov_b64 s[6:7], 0x8000
	global_load_lds_dwordx4 v[154:155], off
	v_lshl_add_u64 v[154:155], v[128:129], 0, s[6:7]
	s_add_i32 m0, s2, 0x11000
	s_mov_b64 s[6:7], 0xa000
	global_load_lds_dwordx4 v[154:155], off
	v_lshl_add_u64 v[154:155], v[128:129], 0, s[6:7]
	s_add_i32 m0, s2, 0x11400
	s_mov_b64 s[6:7], 0xc000
	global_load_lds_dwordx4 v[154:155], off
	v_lshl_add_u64 v[154:155], v[128:129], 0, s[6:7]
	s_add_i32 m0, s2, 0x11800
	s_mov_b64 s[6:7], 0xe000
	global_load_lds_dwordx4 v[154:155], off
	v_lshl_add_u64 v[128:129], v[128:129], 0, s[6:7]
	s_add_i32 m0, s2, 0x11c00
	v_mov_b32_e32 v156, v50
	global_load_lds_dwordx4 v[128:129], off
	s_waitcnt vmcnt(8)
;   DI void operator()(f32x16 (&acc)[2][4], int grow0, int gcol0, int lane, int w, char* lds) {
;     ...
;       for (int qq = 0; qq < 2; ++qq)
; #pragma unroll
;         for (int e = 0; e < 4; ++e) {
;           const int i = 4 * (2 * (ps & 1) + qq) + e;
;           const float* xr = (const float*)(xs + (8 * qq + 4 * hh + e) * 512) + l31;
;           float s1 = 0.f, s2 = 0.f;
; #pragma unroll
;           for (int nt = 0; nt < 4; ++nt) {
;             float v = (acc[mt][nt][i] + bia[nt]) * csc[nt];
;             float z = ALPHA * xr[nt * 32] + hs * v;
;             acc[mt][nt][i] = z; s1 += z; s2 += z * z;
;           }
;           s1 = row16_sum(s1); s2 = row16_sum(s2);
;           if ((lane & 15) == 0) { f32x2 sv = {s1, s2}; *(f32x2*)(redw + (mt * 32 + (i & 3) + 8 * (i >> 2)) * 2) = sv; }
;         }
	ds_read2_b32 v[154:155], v168 offset1:32
	ds_read2_b32 v[158:159], v168 offset0:64 offset1:96
	v_mov_b32_e32 v157, v18
	v_pk_add_f32 v[160:161], v[156:157], 0 op_sel_hi:[1,0]
	v_mov_b32_e32 v156, v34
	v_pk_add_f32 v[156:157], v[156:157], 0 op_sel_hi:[1,0]
	s_waitcnt lgkmcnt(0)
	v_mov_b32_e32 v170, v154
	v_mov_b32_e32 v171, v158
	s_mov_b32 s2, s67
	v_mov_b32_e32 v176, v155
	v_mov_b32_e32 v177, v158
	v_pk_fma_f32 v[154:155], v[170:171], s[2:3], v[160:161] op_sel_hi:[1,0,1]
	v_pk_fma_f32 v[156:157], v[176:177], s[2:3], v[156:157] op_sel_hi:[1,0,1]
	v_pk_mul_f32 v[174:175], v[170:171], s[2:3] op_sel_hi:[1,0]
	v_pk_mul_f32 v[170:171], v[154:155], v[154:155]
	v_pk_mul_f32 v[176:177], v[156:157], v[156:157]
	v_pk_mov_b32 v[160:161], v[160:161], v[170:171] op_sel:[1,0]
	v_pk_mov_b32 v[170:171], v[174:175], v[176:177] op_sel:[1,0]
	v_add_f32_e32 v128, 0, v2
	v_pk_add_f32 v[160:161], v[160:161], v[170:171]
	v_pk_add_f32 v[170:171], v[154:155], v[156:157]
	v_pk_mul_f32 v[174:175], v[154:155], v[156:157]
	v_fmac_f32_e32 v128, 0x3fd744fd, v159
	v_mov_b32_e32 v171, v175
	v_pk_add_f32 v[160:161], v[170:171], v[160:161]
	v_mul_f32_e32 v129, v128, v128
	v_pk_add_f32 v[158:159], v[160:161], v[128:129]
	s_nop 1
	v_mov_b32_dpp v160, v158 quad_perm:[1,0,3,2] row_mask:0xf bank_mask:0xf bound_ctrl:1
	v_mov_b32_dpp v161, v159 quad_perm:[1,0,3,2] row_mask:0xf bank_mask:0xf bound_ctrl:1
	v_pk_add_f32 v[158:159], v[158:159], v[160:161]
	s_nop 1
	v_mov_b32_dpp v160, v158 quad_perm:[2,3,0,1] row_mask:0xf bank_mask:0xf bound_ctrl:1
	v_mov_b32_dpp v161, v159 quad_perm:[2,3,0,1] row_mask:0xf bank_mask:0xf bound_ctrl:1
	v_pk_add_f32 v[158:159], v[158:159], v[160:161]
	s_nop 1
	v_mov_b32_dpp v160, v158 row_half_mirror row_mask:0xf bank_mask:0xf bound_ctrl:1
	v_mov_b32_dpp v161, v159 row_half_mirror row_mask:0xf bank_mask:0xf bound_ctrl:1
	v_pk_add_f32 v[158:159], v[158:159], v[160:161]
	s_nop 1
	v_mov_b32_dpp v160, v158 row_mirror row_mask:0xf bank_mask:0xf bound_ctrl:1
	v_mov_b32_dpp v161, v159 row_mirror row_mask:0xf bank_mask:0xf bound_ctrl:1
	s_and_saveexec_b64 s[6:7], vcc
	v_pk_add_f32 v[158:159], v[158:159], v[160:161]
	ds_write_b64 v181, v[158:159] offset:256
	s_or_b64 exec, exec, s[6:7]
	ds_read2_b32 v[158:159], v168 offset0:128 offset1:160
	ds_read2_b32 v[160:161], v168 offset0:192 offset1:224
	v_mov_b32_e32 v18, v51
	v_pk_add_f32 v[168:169], v[18:19], 0 op_sel_hi:[1,0]
	v_mov_b32_e32 v18, v35
	v_pk_add_f32 v[18:19], v[18:19], 0 op_sel_hi:[1,0]
	s_waitcnt lgkmcnt(1)
	v_mov_b32_e32 v34, v158
	s_waitcnt lgkmcnt(0)
	v_mov_b32_e32 v35, v160
	s_mov_b32 s2, s67
	v_mov_b32_e32 v50, v159
	v_mov_b32_e32 v51, v160
	v_pk_mul_f32 v[170:171], v[34:35], s[2:3] op_sel_hi:[1,0]
	v_pk_fma_f32 v[34:35], v[34:35], s[2:3], v[168:169] op_sel_hi:[1,0,1]
	v_pk_fma_f32 v[50:51], v[50:51], s[2:3], v[18:19] op_sel_hi:[1,0,1]
	v_pk_mul_f32 v[158:159], v[34:35], v[34:35]
	v_pk_mul_f32 v[18:19], v[50:51], v[50:51]
	v_pk_mov_b32 v[158:159], v[168:169], v[158:159] op_sel:[1,0]
	v_pk_mov_b32 v[18:19], v[170:171], v[18:19] op_sel:[1,0]
	v_add_f32_e32 v2, 0, v3
	v_pk_add_f32 v[18:19], v[158:159], v[18:19]
	v_pk_add_f32 v[158:159], v[34:35], v[50:51]
	v_pk_mul_f32 v[168:169], v[34:35], v[50:51]
	v_fmac_f32_e32 v2, 0x3fd744fd, v161
	v_mov_b32_e32 v159, v169
	v_pk_add_f32 v[18:19], v[158:159], v[18:19]
	v_mul_f32_e32 v3, v2, v2
	v_pk_add_f32 v[18:19], v[18:19], v[2:3]
	s_nop 1
	v_mov_b32_dpp v158, v18 quad_perm:[1,0,3,2] row_mask:0xf bank_mask:0xf bound_ctrl:1
	v_mov_b32_dpp v159, v19 quad_perm:[1,0,3,2] row_mask:0xf bank_mask:0xf bound_ctrl:1
	v_pk_add_f32 v[18:19], v[18:19], v[158:159]
	s_nop 1
	v_mov_b32_dpp v158, v18 quad_perm:[2,3,0,1] row_mask:0xf bank_mask:0xf bound_ctrl:1
	v_mov_b32_dpp v159, v19 quad_perm:[2,3,0,1] row_mask:0xf bank_mask:0xf bound_ctrl:1
	v_pk_add_f32 v[18:19], v[18:19], v[158:159]
	s_nop 1
	v_mov_b32_dpp v158, v18 row_half_mirror row_mask:0xf bank_mask:0xf bound_ctrl:1
	v_mov_b32_dpp v159, v19 row_half_mirror row_mask:0xf bank_mask:0xf bound_ctrl:1
	v_pk_add_f32 v[18:19], v[18:19], v[158:159]
	s_nop 1
	v_mov_b32_dpp v158, v18 row_mirror row_mask:0xf bank_mask:0xf bound_ctrl:1
	v_mov_b32_dpp v159, v19 row_mirror row_mask:0xf bank_mask:0xf bound_ctrl:1
	s_and_saveexec_b64 s[6:7], vcc
	v_pk_add_f32 v[18:19], v[18:19], v[158:159]
	ds_write_b64 v181, v[18:19] offset:264
	s_or_b64 exec, exec, s[6:7]
	ds_read2_b32 v[158:159], v153 offset1:32
	ds_read2_b32 v[168:169], v153 offset0:64 offset1:96
	v_mov_b32_e32 v160, v52
	v_mov_b32_e32 v161, v20
	v_pk_add_f32 v[170:171], v[160:161], 0 op_sel_hi:[1,0]
	v_mov_b32_e32 v160, v36
	v_pk_add_f32 v[160:161], v[160:161], 0 op_sel_hi:[1,0]
	s_waitcnt lgkmcnt(1)
	v_mov_b32_e32 v174, v158
	s_waitcnt lgkmcnt(0)
;   DI void operator()(f32x16 (&acc)[2][4], int grow0, int gcol0, int lane, int w, char* lds) {
;     ...
;       for (int qq = 0; qq < 2; ++qq)
; #pragma unroll
;         for (int e = 0; e < 4; ++e) {
;           const int i = 4 * (2 * (ps & 1) + qq) + e;
;           const float* xr = (const float*)(xs + (8 * qq + 4 * hh + e) * 512) + l31;
;           float s1 = 0.f, s2 = 0.f;
; #pragma unroll
;           for (int nt = 0; nt < 4; ++nt) {
;             float v = (acc[mt][nt][i] + bia[nt]) * csc[nt];
;             float z = ALPHA * xr[nt * 32] + hs * v;
;             acc[mt][nt][i] = z; s1 += z; s2 += z * z;
;           }
;           s1 = row16_sum(s1); s2 = row16_sum(s2);
;           if ((lane & 15) == 0) { f32x2 sv = {s1, s2}; *(f32x2*)(redw + (mt * 32 + (i & 3) + 8 * (i >> 2)) * 2) = sv; }
;         }
	v_mov_b32_e32 v175, v168
	s_mov_b32 s2, s67
	v_mov_b32_e32 v178, v159
	v_mov_b32_e32 v179, v168
	v_pk_fma_f32 v[158:159], v[174:175], s[2:3], v[170:171] op_sel_hi:[1,0,1]
	v_pk_fma_f32 v[160:161], v[178:179], s[2:3], v[160:161] op_sel_hi:[1,0,1]
	v_pk_mul_f32 v[176:177], v[174:175], s[2:3] op_sel_hi:[1,0]
	v_pk_mul_f32 v[174:175], v[158:159], v[158:159]
	v_pk_mul_f32 v[178:179], v[160:161], v[160:161]
	v_pk_mov_b32 v[170:171], v[170:171], v[174:175] op_sel:[1,0]
	v_pk_mov_b32 v[174:175], v[176:177], v[178:179] op_sel:[1,0]
	v_add_f32_e32 v18, 0, v4
	v_pk_add_f32 v[170:171], v[170:171], v[174:175]
	v_pk_add_f32 v[174:175], v[158:159], v[160:161]
	v_pk_mul_f32 v[176:177], v[158:159], v[160:161]
	v_fmac_f32_e32 v18, 0x3fd744fd, v169
	v_mov_b32_e32 v175, v177
	v_pk_add_f32 v[170:171], v[174:175], v[170:171]
	v_mul_f32_e32 v19, v18, v18
	v_pk_add_f32 v[168:169], v[170:171], v[18:19]
	s_nop 1
	v_mov_b32_dpp v170, v168 quad_perm:[1,0,3,2] row_mask:0xf bank_mask:0xf bound_ctrl:1
	v_mov_b32_dpp v171, v169 quad_perm:[1,0,3,2] row_mask:0xf bank_mask:0xf bound_ctrl:1
	v_pk_add_f32 v[168:169], v[168:169], v[170:171]
	s_nop 1
	v_mov_b32_dpp v170, v168 quad_perm:[2,3,0,1] row_mask:0xf bank_mask:0xf bound_ctrl:1
	v_mov_b32_dpp v171, v169 quad_perm:[2,3,0,1] row_mask:0xf bank_mask:0xf bound_ctrl:1
	v_pk_add_f32 v[168:169], v[168:169], v[170:171]
	s_nop 1
	v_mov_b32_dpp v170, v168 row_half_mirror row_mask:0xf bank_mask:0xf bound_ctrl:1
	v_mov_b32_dpp v171, v169 row_half_mirror row_mask:0xf bank_mask:0xf bound_ctrl:1
	v_pk_add_f32 v[168:169], v[168:169], v[170:171]
	s_nop 1
	v_mov_b32_dpp v170, v168 row_mirror row_mask:0xf bank_mask:0xf bound_ctrl:1
	v_mov_b32_dpp v171, v169 row_mirror row_mask:0xf bank_mask:0xf bound_ctrl:1
	s_and_saveexec_b64 s[6:7], vcc
	v_pk_add_f32 v[168:169], v[168:169], v[170:171]
	ds_write_b64 v181, v[168:169] offset:272
	s_or_b64 exec, exec, s[6:7]
	ds_read2_b32 v[168:169], v151 offset1:32
	ds_read2_b32 v[170:171], v151 offset0:64 offset1:96
	v_mov_b32_e32 v20, v53
	v_pk_add_f32 v[174:175], v[20:21], 0 op_sel_hi:[1,0]
	v_mov_b32_e32 v20, v37
	v_pk_add_f32 v[20:21], v[20:21], 0 op_sel_hi:[1,0]
	s_waitcnt lgkmcnt(1)
	v_mov_b32_e32 v36, v168
	s_waitcnt lgkmcnt(0)
	v_mov_b32_e32 v37, v170
	s_mov_b32 s2, s67
	v_mov_b32_e32 v52, v169
	v_mov_b32_e32 v53, v170
	v_pk_mul_f32 v[176:177], v[36:37], s[2:3] op_sel_hi:[1,0]
	v_pk_fma_f32 v[36:37], v[36:37], s[2:3], v[174:175] op_sel_hi:[1,0,1]
	v_pk_fma_f32 v[52:53], v[52:53], s[2:3], v[20:21] op_sel_hi:[1,0,1]
	v_pk_mul_f32 v[168:169], v[36:37], v[36:37]
	v_pk_mul_f32 v[20:21], v[52:53], v[52:53]
	v_pk_mov_b32 v[168:169], v[174:175], v[168:169] op_sel:[1,0]
	v_pk_mov_b32 v[20:21], v[176:177], v[20:21] op_sel:[1,0]
	v_add_f32_e32 v4, 0, v5
	v_pk_add_f32 v[20:21], v[168:169], v[20:21]
	v_pk_add_f32 v[168:169], v[36:37], v[52:53]
	v_pk_mul_f32 v[174:175], v[36:37], v[52:53]
	v_fmac_f32_e32 v4, 0x3fd744fd, v171
	v_mov_b32_e32 v169, v175
	v_pk_add_f32 v[20:21], v[168:169], v[20:21]
	v_mul_f32_e32 v5, v4, v4
	v_pk_add_f32 v[20:21], v[20:21], v[4:5]
	s_nop 1
	v_mov_b32_dpp v168, v20 quad_perm:[1,0,3,2] row_mask:0xf bank_mask:0xf bound_ctrl:1
	v_mov_b32_dpp v169, v21 quad_perm:[1,0,3,2] row_mask:0xf bank_mask:0xf bound_ctrl:1
	v_pk_add_f32 v[20:21], v[20:21], v[168:169]
	s_nop 1
	v_mov_b32_dpp v168, v20 quad_perm:[2,3,0,1] row_mask:0xf bank_mask:0xf bound_ctrl:1
	v_mov_b32_dpp v169, v21 quad_perm:[2,3,0,1] row_mask:0xf bank_mask:0xf bound_ctrl:1
	v_pk_add_f32 v[20:21], v[20:21], v[168:169]
	s_nop 1
	v_mov_b32_dpp v168, v20 row_half_mirror row_mask:0xf bank_mask:0xf bound_ctrl:1
	v_mov_b32_dpp v169, v21 row_half_mirror row_mask:0xf bank_mask:0xf bound_ctrl:1
	v_pk_add_f32 v[20:21], v[20:21], v[168:169]
	s_nop 1
	v_mov_b32_dpp v168, v20 row_mirror row_mask:0xf bank_mask:0xf bound_ctrl:1
	v_mov_b32_dpp v169, v21 row_mirror row_mask:0xf bank_mask:0xf bound_ctrl:1
	s_and_saveexec_b64 s[6:7], vcc
	v_pk_add_f32 v[20:21], v[20:21], v[168:169]
	ds_write_b64 v181, v[20:21] offset:280
	s_or_b64 exec, exec, s[6:7]
	ds_read2_b32 v[168:169], v67 offset1:32
	ds_read2_b32 v[174:175], v67 offset0:64 offset1:96
	v_mov_b32_e32 v170, v54
	v_mov_b32_e32 v171, v22
	v_pk_add_f32 v[176:177], v[170:171], 0 op_sel_hi:[1,0]
	v_mov_b32_e32 v170, v38
	v_pk_add_f32 v[170:171], v[170:171], 0 op_sel_hi:[1,0]
	s_waitcnt lgkmcnt(1)
	v_mov_b32_e32 v178, v168
	s_waitcnt lgkmcnt(0)
	v_mov_b32_e32 v179, v174
	s_mov_b32 s2, s67
	v_mov_b32_e32 v190, v169
	v_mov_b32_e32 v191, v174
	v_pk_fma_f32 v[168:169], v[178:179], s[2:3], v[176:177] op_sel_hi:[1,0,1]
	v_pk_fma_f32 v[170:171], v[190:191], s[2:3], v[170:171] op_sel_hi:[1,0,1]
	v_pk_mul_f32 v[182:183], v[178:179], s[2:3] op_sel_hi:[1,0]
	v_pk_mul_f32 v[178:179], v[168:169], v[168:169]
	v_pk_mul_f32 v[190:191], v[170:171], v[170:171]
	v_pk_mov_b32 v[176:177], v[176:177], v[178:179] op_sel:[1,0]
	v_pk_mov_b32 v[178:179], v[182:183], v[190:191] op_sel:[1,0]
	v_add_f32_e32 v20, 0, v6
	v_pk_add_f32 v[176:177], v[176:177], v[178:179]
	v_pk_add_f32 v[178:179], v[168:169], v[170:171]
	v_pk_mul_f32 v[182:183], v[168:169], v[170:171]
	v_fmac_f32_e32 v20, 0x3fd744fd, v175
	v_mov_b32_e32 v179, v183
	v_pk_add_f32 v[176:177], v[178:179], v[176:177]
	v_mul_f32_e32 v21, v20, v20
	v_pk_add_f32 v[174:175], v[176:177], v[20:21]
	s_nop 1
	v_mov_b32_dpp v176, v174 quad_perm:[1,0,3,2] row_mask:0xf bank_mask:0xf bound_ctrl:1
	v_mov_b32_dpp v177, v175 quad_perm:[1,0,3,2] row_mask:0xf bank_mask:0xf bound_ctrl:1
	v_pk_add_f32 v[174:175], v[174:175], v[176:177]
	s_nop 1
	v_mov_b32_dpp v176, v174 quad_perm:[2,3,0,1] row_mask:0xf bank_mask:0xf bound_ctrl:1
	v_mov_b32_dpp v177, v175 quad_perm:[2,3,0,1] row_mask:0xf bank_mask:0xf bound_ctrl:1
	v_pk_add_f32 v[174:175], v[174:175], v[176:177]
	s_nop 1
	v_mov_b32_dpp v176, v174 row_half_mirror row_mask:0xf bank_mask:0xf bound_ctrl:1
	v_mov_b32_dpp v177, v175 row_half_mirror row_mask:0xf bank_mask:0xf bound_ctrl:1
	v_pk_add_f32 v[174:175], v[174:175], v[176:177]
	s_nop 1
	v_mov_b32_dpp v176, v174 row_mirror row_mask:0xf bank_mask:0xf bound_ctrl:1
	v_mov_b32_dpp v177, v175 row_mirror row_mask:0xf bank_mask:0xf bound_ctrl:1
	s_and_saveexec_b64 s[6:7], vcc
	v_pk_add_f32 v[174:175], v[174:175], v[176:177]
	ds_write_b64 v181, v[174:175] offset:320
	s_or_b64 exec, exec, s[6:7]
	ds_read2_b32 v[174:175], v67 offset0:128 offset1:160
	ds_read2_b32 v[176:177], v67 offset0:192 offset1:224
	v_mov_b32_e32 v22, v55
	v_pk_add_f32 v[178:179], v[22:23], 0 op_sel_hi:[1,0]
	v_mov_b32_e32 v22, v39
	v_pk_add_f32 v[22:23], v[22:23], 0 op_sel_hi:[1,0]
	s_waitcnt lgkmcnt(1)
;   DI void operator()(f32x16 (&acc)[2][4], int grow0, int gcol0, int lane, int w, char* lds) {
;     ...
;       } else asm volatile("s_waitcnt vmcnt(0)" ::: "memory");
;     ...
;       for (int qq = 0; qq < 2; ++qq)
; #pragma unroll
;         for (int e = 0; e < 4; ++e) {
;           const int i = 4 * (2 * (ps & 1) + qq) + e;
;           const float* xr = (const float*)(xs + (8 * qq + 4 * hh + e) * 512) + l31;
;           float s1 = 0.f, s2 = 0.f;
; #pragma unroll
;           for (int nt = 0; nt < 4; ++nt) {
;             float v = (acc[mt][nt][i] + bia[nt]) * csc[nt];
;             float z = ALPHA * xr[nt * 32] + hs * v;
;             acc[mt][nt][i] = z; s1 += z; s2 += z * z;
;           }
;           s1 = row16_sum(s1); s2 = row16_sum(s2);
;           if ((lane & 15) == 0) { f32x2 sv = {s1, s2}; *(f32x2*)(redw + (mt * 32 + (i & 3) + 8 * (i >> 2)) * 2) = sv; }
;         }
	v_mov_b32_e32 v38, v174
	s_waitcnt lgkmcnt(0)
	v_mov_b32_e32 v39, v176
	s_mov_b32 s2, s67
	v_mov_b32_e32 v54, v175
	v_mov_b32_e32 v55, v176
	v_pk_mul_f32 v[182:183], v[38:39], s[2:3] op_sel_hi:[1,0]
	v_pk_fma_f32 v[38:39], v[38:39], s[2:3], v[178:179] op_sel_hi:[1,0,1]
	v_pk_fma_f32 v[54:55], v[54:55], s[2:3], v[22:23] op_sel_hi:[1,0,1]
	v_pk_mul_f32 v[174:175], v[38:39], v[38:39]
	v_pk_mul_f32 v[22:23], v[54:55], v[54:55]
	v_pk_mov_b32 v[174:175], v[178:179], v[174:175] op_sel:[1,0]
	v_pk_mov_b32 v[22:23], v[182:183], v[22:23] op_sel:[1,0]
	v_add_f32_e32 v6, 0, v7
	v_pk_add_f32 v[22:23], v[174:175], v[22:23]
	v_pk_add_f32 v[174:175], v[38:39], v[54:55]
	v_pk_mul_f32 v[178:179], v[38:39], v[54:55]
	v_fmac_f32_e32 v6, 0x3fd744fd, v177
	v_mov_b32_e32 v175, v179
	v_pk_add_f32 v[22:23], v[174:175], v[22:23]
	v_mul_f32_e32 v7, v6, v6
	v_pk_add_f32 v[22:23], v[22:23], v[6:7]
	s_nop 1
	v_mov_b32_dpp v174, v22 quad_perm:[1,0,3,2] row_mask:0xf bank_mask:0xf bound_ctrl:1
	v_mov_b32_dpp v175, v23 quad_perm:[1,0,3,2] row_mask:0xf bank_mask:0xf bound_ctrl:1
	v_pk_add_f32 v[22:23], v[22:23], v[174:175]
	s_nop 1
	v_mov_b32_dpp v174, v22 quad_perm:[2,3,0,1] row_mask:0xf bank_mask:0xf bound_ctrl:1
	v_mov_b32_dpp v175, v23 quad_perm:[2,3,0,1] row_mask:0xf bank_mask:0xf bound_ctrl:1
	v_pk_add_f32 v[22:23], v[22:23], v[174:175]
	s_nop 1
	v_mov_b32_dpp v174, v22 row_half_mirror row_mask:0xf bank_mask:0xf bound_ctrl:1
	v_mov_b32_dpp v175, v23 row_half_mirror row_mask:0xf bank_mask:0xf bound_ctrl:1
	v_pk_add_f32 v[22:23], v[22:23], v[174:175]
	s_nop 1
	v_mov_b32_dpp v174, v22 row_mirror row_mask:0xf bank_mask:0xf bound_ctrl:1
	v_mov_b32_dpp v175, v23 row_mirror row_mask:0xf bank_mask:0xf bound_ctrl:1
	s_and_saveexec_b64 s[6:7], vcc
	v_pk_add_f32 v[22:23], v[22:23], v[174:175]
	ds_write_b64 v181, v[22:23] offset:328
	s_or_b64 exec, exec, s[6:7]
	ds_read2_b32 v[174:175], v69 offset1:32
	ds_read2_b32 v[178:179], v69 offset0:64 offset1:96
	v_mov_b32_e32 v176, v56
	v_mov_b32_e32 v177, v24
	v_pk_add_f32 v[182:183], v[176:177], 0 op_sel_hi:[1,0]
	v_mov_b32_e32 v176, v40
	v_pk_add_f32 v[176:177], v[176:177], 0 op_sel_hi:[1,0]
	s_waitcnt lgkmcnt(1)
	v_mov_b32_e32 v190, v174
	s_waitcnt lgkmcnt(0)
	v_mov_b32_e32 v191, v178
	s_mov_b32 s2, s67
	v_mov_b32_e32 v194, v175
	v_mov_b32_e32 v195, v178
	v_pk_fma_f32 v[174:175], v[190:191], s[2:3], v[182:183] op_sel_hi:[1,0,1]
	v_pk_fma_f32 v[176:177], v[194:195], s[2:3], v[176:177] op_sel_hi:[1,0,1]
	v_pk_mul_f32 v[192:193], v[190:191], s[2:3] op_sel_hi:[1,0]
	v_pk_mul_f32 v[190:191], v[174:175], v[174:175]
	v_pk_mul_f32 v[194:195], v[176:177], v[176:177]
	v_pk_mov_b32 v[182:183], v[182:183], v[190:191] op_sel:[1,0]
	v_pk_mov_b32 v[190:191], v[192:193], v[194:195] op_sel:[1,0]
	v_add_f32_e32 v22, 0, v8
	v_pk_add_f32 v[182:183], v[182:183], v[190:191]
	v_pk_add_f32 v[190:191], v[174:175], v[176:177]
	v_pk_mul_f32 v[192:193], v[174:175], v[176:177]
	v_fmac_f32_e32 v22, 0x3fd744fd, v179
	v_mov_b32_e32 v191, v193
	v_pk_add_f32 v[182:183], v[190:191], v[182:183]
	v_mul_f32_e32 v23, v22, v22
	v_pk_add_f32 v[178:179], v[182:183], v[22:23]
	s_nop 1
	v_mov_b32_dpp v182, v178 quad_perm:[1,0,3,2] row_mask:0xf bank_mask:0xf bound_ctrl:1
	v_mov_b32_dpp v183, v179 quad_perm:[1,0,3,2] row_mask:0xf bank_mask:0xf bound_ctrl:1
	v_pk_add_f32 v[178:179], v[178:179], v[182:183]
	s_nop 1
	v_mov_b32_dpp v182, v178 quad_perm:[2,3,0,1] row_mask:0xf bank_mask:0xf bound_ctrl:1
	v_mov_b32_dpp v183, v179 quad_perm:[2,3,0,1] row_mask:0xf bank_mask:0xf bound_ctrl:1
	v_pk_add_f32 v[178:179], v[178:179], v[182:183]
	s_nop 1
	v_mov_b32_dpp v182, v178 row_half_mirror row_mask:0xf bank_mask:0xf bound_ctrl:1
	v_mov_b32_dpp v183, v179 row_half_mirror row_mask:0xf bank_mask:0xf bound_ctrl:1
	v_pk_add_f32 v[178:179], v[178:179], v[182:183]
	s_nop 1
	v_mov_b32_dpp v182, v178 row_mirror row_mask:0xf bank_mask:0xf bound_ctrl:1
	v_mov_b32_dpp v183, v179 row_mirror row_mask:0xf bank_mask:0xf bound_ctrl:1
	s_and_saveexec_b64 s[6:7], vcc
	v_pk_add_f32 v[178:179], v[178:179], v[182:183]
	ds_write_b64 v181, v[178:179] offset:336
	s_or_b64 exec, exec, s[6:7]
	ds_read2_b32 v[178:179], v71 offset1:32
	ds_read2_b32 v[182:183], v71 offset0:64 offset1:96
	v_mov_b32_e32 v24, v57
	v_pk_add_f32 v[190:191], v[24:25], 0 op_sel_hi:[1,0]
	v_mov_b32_e32 v24, v41
	v_pk_add_f32 v[24:25], v[24:25], 0 op_sel_hi:[1,0]
	s_waitcnt lgkmcnt(1)
	v_mov_b32_e32 v40, v178
	s_waitcnt lgkmcnt(0)
	v_mov_b32_e32 v41, v182
	s_mov_b32 s2, s67
	v_mov_b32_e32 v56, v179
	v_mov_b32_e32 v57, v182
	v_pk_mul_f32 v[192:193], v[40:41], s[2:3] op_sel_hi:[1,0]
	v_pk_fma_f32 v[40:41], v[40:41], s[2:3], v[190:191] op_sel_hi:[1,0,1]
	v_pk_fma_f32 v[56:57], v[56:57], s[2:3], v[24:25] op_sel_hi:[1,0,1]
	v_pk_mul_f32 v[178:179], v[40:41], v[40:41]
	v_pk_mul_f32 v[24:25], v[56:57], v[56:57]
	v_pk_mov_b32 v[178:179], v[190:191], v[178:179] op_sel:[1,0]
	v_pk_mov_b32 v[24:25], v[192:193], v[24:25] op_sel:[1,0]
	v_add_f32_e32 v8, 0, v9
	v_pk_add_f32 v[24:25], v[178:179], v[24:25]
	v_pk_add_f32 v[178:179], v[40:41], v[56:57]
	v_pk_mul_f32 v[190:191], v[40:41], v[56:57]
	v_fmac_f32_e32 v8, 0x3fd744fd, v183
	v_mov_b32_e32 v179, v191
	v_pk_add_f32 v[24:25], v[178:179], v[24:25]
	v_mul_f32_e32 v9, v8, v8
	v_pk_add_f32 v[24:25], v[24:25], v[8:9]
	s_nop 1
	v_mov_b32_dpp v178, v24 quad_perm:[1,0,3,2] row_mask:0xf bank_mask:0xf bound_ctrl:1
	v_mov_b32_dpp v179, v25 quad_perm:[1,0,3,2] row_mask:0xf bank_mask:0xf bound_ctrl:1
	v_pk_add_f32 v[24:25], v[24:25], v[178:179]
	s_nop 1
	v_mov_b32_dpp v178, v24 quad_perm:[2,3,0,1] row_mask:0xf bank_mask:0xf bound_ctrl:1
	v_mov_b32_dpp v179, v25 quad_perm:[2,3,0,1] row_mask:0xf bank_mask:0xf bound_ctrl:1
	v_pk_add_f32 v[24:25], v[24:25], v[178:179]
	s_nop 1
	v_mov_b32_dpp v178, v24 row_half_mirror row_mask:0xf bank_mask:0xf bound_ctrl:1
	v_mov_b32_dpp v179, v25 row_half_mirror row_mask:0xf bank_mask:0xf bound_ctrl:1
	v_pk_add_f32 v[24:25], v[24:25], v[178:179]
	s_nop 1
	v_mov_b32_dpp v178, v24 row_mirror row_mask:0xf bank_mask:0xf bound_ctrl:1
	v_mov_b32_dpp v179, v25 row_mirror row_mask:0xf bank_mask:0xf bound_ctrl:1
	s_and_saveexec_b64 s[6:7], vcc
	v_pk_add_f32 v[24:25], v[24:25], v[178:179]
	ds_write_b64 v181, v[24:25] offset:344
	s_or_b64 exec, exec, s[6:7]
	s_waitcnt vmcnt(0)
;   DI void operator()(f32x16 (&acc)[2][4], int grow0, int gcol0, int lane, int w, char* lds) {
;     ...
;       for (int qq = 0; qq < 2; ++qq)
; #pragma unroll
;         for (int e = 0; e < 4; ++e) {
;           const int i = 4 * (2 * (ps & 1) + qq) + e;
;           const float* xr = (const float*)(xs + (8 * qq + 4 * hh + e) * 512) + l31;
;           float s1 = 0.f, s2 = 0.f;
; #pragma unroll
;           for (int nt = 0; nt < 4; ++nt) {
;             float v = (acc[mt][nt][i] + bia[nt]) * csc[nt];
;             float z = ALPHA * xr[nt * 32] + hs * v;
;             acc[mt][nt][i] = z; s1 += z; s2 += z * z;
;           }
;           s1 = row16_sum(s1); s2 = row16_sum(s2);
;           if ((lane & 15) == 0) { f32x2 sv = {s1, s2}; *(f32x2*)(redw + (mt * 32 + (i & 3) + 8 * (i >> 2)) * 2) = sv; }
;         }
	ds_read2_b32 v[182:183], v73 offset1:32
	ds_read2_b32 v[192:193], v73 offset0:64 offset1:96
	v_add_f32_e32 v179, 0, v42
	v_mov_b32_e32 v190, v58
	v_mov_b32_e32 v191, v26
	s_waitcnt lgkmcnt(1)
	v_fmac_f32_e32 v179, 0x3fd744fd, v183
	v_pk_add_f32 v[194:195], v[190:191], 0 op_sel_hi:[1,0]
	s_waitcnt lgkmcnt(0)
	v_mov_b32_e32 v183, v192
	s_mov_b32 s2, s67
	v_pk_fma_f32 v[190:191], v[182:183], s[2:3], v[194:195] op_sel_hi:[1,0,1]
	v_mov_b32_e32 v178, v192
	v_pk_mul_f32 v[182:183], v[190:191], v[190:191]
	v_mov_b32_e32 v196, v165
	v_mov_b32_e32 v197, v179
	v_pk_mov_b32 v[182:183], v[194:195], v[182:183] op_sel:[1,0]
	v_add_f32_e32 v24, 0, v10
	v_pk_fma_f32 v[182:183], v[178:179], v[196:197], v[182:183]
	v_fmac_f32_e32 v24, 0x3fd744fd, v193
	v_pk_mov_b32 v[194:195], v[178:179], v[182:183] op_sel:[1,0]
	v_mul_f32_e32 v25, v24, v24
	v_pk_add_f32 v[196:197], v[190:191], v[194:195]
	v_pk_mul_f32 v[194:195], v[190:191], v[194:195]
	s_nop 0
	v_mov_b32_e32 v197, v195
	v_pk_add_f32 v[194:195], v[182:183], v[196:197]
	s_nop 0
	v_pk_add_f32 v[192:193], v[194:195], v[24:25]
	s_nop 1
	v_mov_b32_dpp v194, v192 quad_perm:[1,0,3,2] row_mask:0xf bank_mask:0xf bound_ctrl:1
	v_mov_b32_dpp v195, v193 quad_perm:[1,0,3,2] row_mask:0xf bank_mask:0xf bound_ctrl:1
	v_pk_add_f32 v[192:193], v[192:193], v[194:195]
	s_nop 1
	v_mov_b32_dpp v194, v192 quad_perm:[2,3,0,1] row_mask:0xf bank_mask:0xf bound_ctrl:1
	v_mov_b32_dpp v195, v193 quad_perm:[2,3,0,1] row_mask:0xf bank_mask:0xf bound_ctrl:1
	v_pk_add_f32 v[192:193], v[192:193], v[194:195]
	s_nop 1
	v_mov_b32_dpp v194, v192 row_half_mirror row_mask:0xf bank_mask:0xf bound_ctrl:1
	v_mov_b32_dpp v195, v193 row_half_mirror row_mask:0xf bank_mask:0xf bound_ctrl:1
	v_pk_add_f32 v[192:193], v[192:193], v[194:195]
	s_nop 1
	v_mov_b32_dpp v194, v192 row_mirror row_mask:0xf bank_mask:0xf bound_ctrl:1
	v_mov_b32_dpp v195, v193 row_mirror row_mask:0xf bank_mask:0xf bound_ctrl:1
	s_and_saveexec_b64 s[6:7], vcc
	v_pk_add_f32 v[192:193], v[192:193], v[194:195]
	ds_write_b64 v181, v[192:193] offset:384
	s_or_b64 exec, exec, s[6:7]
	ds_read2_b32 v[192:193], v85 offset1:32
	ds_read2_b32 v[194:195], v85 offset0:64 offset1:96
	v_mov_b32_e32 v26, v59
	v_pk_add_f32 v[196:197], v[26:27], 0 op_sel_hi:[1,0]
	v_mov_b32_e32 v26, v43
	v_pk_add_f32 v[26:27], v[26:27], 0 op_sel_hi:[1,0]
	s_waitcnt lgkmcnt(1)
	v_mov_b32_e32 v42, v192
	s_waitcnt lgkmcnt(0)
	v_mov_b32_e32 v43, v194
	s_mov_b32 s2, s67
	v_mov_b32_e32 v58, v193
	v_mov_b32_e32 v59, v194
	v_pk_mul_f32 v[198:199], v[42:43], s[2:3] op_sel_hi:[1,0]
	v_pk_fma_f32 v[42:43], v[42:43], s[2:3], v[196:197] op_sel_hi:[1,0,1]
	v_pk_fma_f32 v[58:59], v[58:59], s[2:3], v[26:27] op_sel_hi:[1,0,1]
	v_pk_mul_f32 v[192:193], v[42:43], v[42:43]
	v_pk_mul_f32 v[26:27], v[58:59], v[58:59]
	v_pk_mov_b32 v[192:193], v[196:197], v[192:193] op_sel:[1,0]
	v_pk_mov_b32 v[26:27], v[198:199], v[26:27] op_sel:[1,0]
	v_add_f32_e32 v10, 0, v11
	v_pk_add_f32 v[26:27], v[192:193], v[26:27]
	v_pk_add_f32 v[192:193], v[42:43], v[58:59]
	v_pk_mul_f32 v[196:197], v[42:43], v[58:59]
	v_fmac_f32_e32 v10, 0x3fd744fd, v195
	v_mov_b32_e32 v193, v197
	v_pk_add_f32 v[26:27], v[192:193], v[26:27]
	v_mul_f32_e32 v11, v10, v10
	v_pk_add_f32 v[26:27], v[26:27], v[10:11]
	s_nop 1
	v_mov_b32_dpp v192, v26 quad_perm:[1,0,3,2] row_mask:0xf bank_mask:0xf bound_ctrl:1
	v_mov_b32_dpp v193, v27 quad_perm:[1,0,3,2] row_mask:0xf bank_mask:0xf bound_ctrl:1
	v_pk_add_f32 v[26:27], v[26:27], v[192:193]
	s_nop 1
	v_mov_b32_dpp v192, v26 quad_perm:[2,3,0,1] row_mask:0xf bank_mask:0xf bound_ctrl:1
	v_mov_b32_dpp v193, v27 quad_perm:[2,3,0,1] row_mask:0xf bank_mask:0xf bound_ctrl:1
	v_pk_add_f32 v[26:27], v[26:27], v[192:193]
	s_nop 1
	v_mov_b32_dpp v192, v26 row_half_mirror row_mask:0xf bank_mask:0xf bound_ctrl:1
	v_mov_b32_dpp v193, v27 row_half_mirror row_mask:0xf bank_mask:0xf bound_ctrl:1
	v_pk_add_f32 v[26:27], v[26:27], v[192:193]
	s_nop 1
	v_mov_b32_dpp v192, v26 row_mirror row_mask:0xf bank_mask:0xf bound_ctrl:1
	v_mov_b32_dpp v193, v27 row_mirror row_mask:0xf bank_mask:0xf bound_ctrl:1
	s_and_saveexec_b64 s[6:7], vcc
	v_pk_add_f32 v[26:27], v[26:27], v[192:193]
	ds_write_b64 v181, v[26:27] offset:392
	s_or_b64 exec, exec, s[6:7]
	ds_read2_b32 v[192:193], v75 offset1:32
	ds_read2_b32 v[196:197], v75 offset0:64 offset1:96
	v_mov_b32_e32 v194, v60
	v_mov_b32_e32 v195, v28
	v_pk_add_f32 v[198:199], v[194:195], 0 op_sel_hi:[1,0]
	v_mov_b32_e32 v194, v44
	v_pk_add_f32 v[194:195], v[194:195], 0 op_sel_hi:[1,0]
	s_waitcnt lgkmcnt(1)
	v_mov_b32_e32 v202, v192
	s_waitcnt lgkmcnt(0)
	v_mov_b32_e32 v203, v196
	s_mov_b32 s2, s67
	v_mov_b32_e32 v206, v193
	v_mov_b32_e32 v207, v196
	v_pk_fma_f32 v[192:193], v[202:203], s[2:3], v[198:199] op_sel_hi:[1,0,1]
	v_pk_fma_f32 v[194:195], v[206:207], s[2:3], v[194:195] op_sel_hi:[1,0,1]
	v_pk_mul_f32 v[204:205], v[202:203], s[2:3] op_sel_hi:[1,0]
	v_pk_mul_f32 v[202:203], v[192:193], v[192:193]
	v_pk_mul_f32 v[206:207], v[194:195], v[194:195]
	v_pk_mov_b32 v[198:199], v[198:199], v[202:203] op_sel:[1,0]
	v_pk_mov_b32 v[202:203], v[204:205], v[206:207] op_sel:[1,0]
	v_add_f32_e32 v26, 0, v12
	v_pk_add_f32 v[198:199], v[198:199], v[202:203]
	v_pk_add_f32 v[202:203], v[192:193], v[194:195]
	v_pk_mul_f32 v[204:205], v[192:193], v[194:195]
	v_fmac_f32_e32 v26, 0x3fd744fd, v197
	v_mov_b32_e32 v203, v205
	v_pk_add_f32 v[198:199], v[202:203], v[198:199]
	v_mul_f32_e32 v27, v26, v26
	v_pk_add_f32 v[196:197], v[198:199], v[26:27]
	s_nop 1
	v_mov_b32_dpp v198, v196 quad_perm:[1,0,3,2] row_mask:0xf bank_mask:0xf bound_ctrl:1
	v_mov_b32_dpp v199, v197 quad_perm:[1,0,3,2] row_mask:0xf bank_mask:0xf bound_ctrl:1
	v_pk_add_f32 v[196:197], v[196:197], v[198:199]
	s_nop 1
	v_mov_b32_dpp v198, v196 quad_perm:[2,3,0,1] row_mask:0xf bank_mask:0xf bound_ctrl:1
	v_mov_b32_dpp v199, v197 quad_perm:[2,3,0,1] row_mask:0xf bank_mask:0xf bound_ctrl:1
	v_pk_add_f32 v[196:197], v[196:197], v[198:199]
	s_nop 1
	v_mov_b32_dpp v198, v196 row_half_mirror row_mask:0xf bank_mask:0xf bound_ctrl:1
	v_mov_b32_dpp v199, v197 row_half_mirror row_mask:0xf bank_mask:0xf bound_ctrl:1
	v_pk_add_f32 v[196:197], v[196:197], v[198:199]
	s_nop 1
	v_mov_b32_dpp v198, v196 row_mirror row_mask:0xf bank_mask:0xf bound_ctrl:1
	v_mov_b32_dpp v199, v197 row_mirror row_mask:0xf bank_mask:0xf bound_ctrl:1
	s_and_saveexec_b64 s[6:7], vcc
	v_pk_add_f32 v[196:197], v[196:197], v[198:199]
	ds_write_b64 v181, v[196:197] offset:400
	s_or_b64 exec, exec, s[6:7]
	ds_read2_b32 v[196:197], v87 offset1:32
	ds_read2_b32 v[198:199], v87 offset0:64 offset1:96
	v_mov_b32_e32 v28, v61
	v_pk_add_f32 v[202:203], v[28:29], 0 op_sel_hi:[1,0]
	v_mov_b32_e32 v28, v45
	v_pk_add_f32 v[28:29], v[28:29], 0 op_sel_hi:[1,0]
	s_waitcnt lgkmcnt(1)
;   DI void operator()(f32x16 (&acc)[2][4], int grow0, int gcol0, int lane, int w, char* lds) {
;     ...
;       for (int qq = 0; qq < 2; ++qq)
; #pragma unroll
;         for (int e = 0; e < 4; ++e) {
;           const int i = 4 * (2 * (ps & 1) + qq) + e;
;           const float* xr = (const float*)(xs + (8 * qq + 4 * hh + e) * 512) + l31;
;           float s1 = 0.f, s2 = 0.f;
; #pragma unroll
;           for (int nt = 0; nt < 4; ++nt) {
;             float v = (acc[mt][nt][i] + bia[nt]) * csc[nt];
;             float z = ALPHA * xr[nt * 32] + hs * v;
;             acc[mt][nt][i] = z; s1 += z; s2 += z * z;
;           }
;           s1 = row16_sum(s1); s2 = row16_sum(s2);
;           if ((lane & 15) == 0) { f32x2 sv = {s1, s2}; *(f32x2*)(redw + (mt * 32 + (i & 3) + 8 * (i >> 2)) * 2) = sv; }
;         }
	v_mov_b32_e32 v44, v196
	s_waitcnt lgkmcnt(0)
	v_mov_b32_e32 v45, v198
	s_mov_b32 s2, s67
	v_mov_b32_e32 v60, v197
	v_mov_b32_e32 v61, v198
	v_pk_mul_f32 v[204:205], v[44:45], s[2:3] op_sel_hi:[1,0]
	v_pk_fma_f32 v[44:45], v[44:45], s[2:3], v[202:203] op_sel_hi:[1,0,1]
	v_pk_fma_f32 v[60:61], v[60:61], s[2:3], v[28:29] op_sel_hi:[1,0,1]
	v_pk_mul_f32 v[196:197], v[44:45], v[44:45]
	v_pk_mul_f32 v[28:29], v[60:61], v[60:61]
	v_pk_mov_b32 v[196:197], v[202:203], v[196:197] op_sel:[1,0]
	v_pk_mov_b32 v[28:29], v[204:205], v[28:29] op_sel:[1,0]
	v_add_f32_e32 v12, 0, v13
	v_pk_add_f32 v[28:29], v[196:197], v[28:29]
	v_pk_add_f32 v[196:197], v[44:45], v[60:61]
	v_pk_mul_f32 v[202:203], v[44:45], v[60:61]
	v_fmac_f32_e32 v12, 0x3fd744fd, v199
	v_mov_b32_e32 v197, v203
	v_pk_add_f32 v[28:29], v[196:197], v[28:29]
	v_mul_f32_e32 v13, v12, v12
	v_pk_add_f32 v[28:29], v[28:29], v[12:13]
	s_nop 1
	v_mov_b32_dpp v196, v28 quad_perm:[1,0,3,2] row_mask:0xf bank_mask:0xf bound_ctrl:1
	v_mov_b32_dpp v197, v29 quad_perm:[1,0,3,2] row_mask:0xf bank_mask:0xf bound_ctrl:1
	v_pk_add_f32 v[28:29], v[28:29], v[196:197]
	s_nop 1
	v_mov_b32_dpp v196, v28 quad_perm:[2,3,0,1] row_mask:0xf bank_mask:0xf bound_ctrl:1
	v_mov_b32_dpp v197, v29 quad_perm:[2,3,0,1] row_mask:0xf bank_mask:0xf bound_ctrl:1
	v_pk_add_f32 v[28:29], v[28:29], v[196:197]
	s_nop 1
	v_mov_b32_dpp v196, v28 row_half_mirror row_mask:0xf bank_mask:0xf bound_ctrl:1
	v_mov_b32_dpp v197, v29 row_half_mirror row_mask:0xf bank_mask:0xf bound_ctrl:1
	v_pk_add_f32 v[28:29], v[28:29], v[196:197]
	s_nop 1
	v_mov_b32_dpp v196, v28 row_mirror row_mask:0xf bank_mask:0xf bound_ctrl:1
	v_mov_b32_dpp v197, v29 row_mirror row_mask:0xf bank_mask:0xf bound_ctrl:1
	s_and_saveexec_b64 s[6:7], vcc
	v_pk_add_f32 v[28:29], v[28:29], v[196:197]
	ds_write_b64 v181, v[28:29] offset:408
	s_or_b64 exec, exec, s[6:7]
	ds_read2_b32 v[196:197], v77 offset1:32
	ds_read2_b32 v[202:203], v77 offset0:64 offset1:96
	v_mov_b32_e32 v198, v62
	v_mov_b32_e32 v199, v30
	v_pk_add_f32 v[204:205], v[198:199], 0 op_sel_hi:[1,0]
	v_mov_b32_e32 v198, v46
	v_pk_add_f32 v[198:199], v[198:199], 0 op_sel_hi:[1,0]
	s_waitcnt lgkmcnt(1)
	v_mov_b32_e32 v206, v196
	s_waitcnt lgkmcnt(0)
	v_mov_b32_e32 v207, v202
	s_mov_b32 s2, s67
	v_mov_b32_e32 v212, v197
	v_mov_b32_e32 v213, v202
	v_pk_fma_f32 v[196:197], v[206:207], s[2:3], v[204:205] op_sel_hi:[1,0,1]
	v_pk_fma_f32 v[198:199], v[212:213], s[2:3], v[198:199] op_sel_hi:[1,0,1]
	v_pk_mul_f32 v[208:209], v[206:207], s[2:3] op_sel_hi:[1,0]
	v_pk_mul_f32 v[206:207], v[196:197], v[196:197]
	v_pk_mul_f32 v[212:213], v[198:199], v[198:199]
	v_pk_mov_b32 v[204:205], v[204:205], v[206:207] op_sel:[1,0]
	v_pk_mov_b32 v[206:207], v[208:209], v[212:213] op_sel:[1,0]
	v_add_f32_e32 v28, 0, v14
	v_pk_add_f32 v[204:205], v[204:205], v[206:207]
	v_pk_add_f32 v[206:207], v[196:197], v[198:199]
	v_pk_mul_f32 v[208:209], v[196:197], v[198:199]
	v_fmac_f32_e32 v28, 0x3fd744fd, v203
	v_mov_b32_e32 v207, v209
	v_pk_add_f32 v[204:205], v[206:207], v[204:205]
	v_mul_f32_e32 v29, v28, v28
	v_pk_add_f32 v[202:203], v[204:205], v[28:29]
	s_nop 1
	v_mov_b32_dpp v204, v202 quad_perm:[1,0,3,2] row_mask:0xf bank_mask:0xf bound_ctrl:1
	v_mov_b32_dpp v205, v203 quad_perm:[1,0,3,2] row_mask:0xf bank_mask:0xf bound_ctrl:1
	v_pk_add_f32 v[202:203], v[202:203], v[204:205]
	s_nop 1
	v_mov_b32_dpp v204, v202 quad_perm:[2,3,0,1] row_mask:0xf bank_mask:0xf bound_ctrl:1
	v_mov_b32_dpp v205, v203 quad_perm:[2,3,0,1] row_mask:0xf bank_mask:0xf bound_ctrl:1
	v_pk_add_f32 v[202:203], v[202:203], v[204:205]
	s_nop 1
	v_mov_b32_dpp v204, v202 row_half_mirror row_mask:0xf bank_mask:0xf bound_ctrl:1
	v_mov_b32_dpp v205, v203 row_half_mirror row_mask:0xf bank_mask:0xf bound_ctrl:1
	v_pk_add_f32 v[202:203], v[202:203], v[204:205]
	s_nop 1
	v_mov_b32_dpp v204, v202 row_mirror row_mask:0xf bank_mask:0xf bound_ctrl:1
	v_mov_b32_dpp v205, v203 row_mirror row_mask:0xf bank_mask:0xf bound_ctrl:1
	s_and_saveexec_b64 s[6:7], vcc
	v_pk_add_f32 v[202:203], v[202:203], v[204:205]
	ds_write_b64 v181, v[202:203] offset:448
	s_or_b64 exec, exec, s[6:7]
	ds_read2_b32 v[202:203], v91 offset1:32
	ds_read2_b32 v[204:205], v91 offset0:64 offset1:96
	v_mov_b32_e32 v30, v63
	v_pk_add_f32 v[206:207], v[30:31], 0 op_sel_hi:[1,0]
	v_mov_b32_e32 v30, v47
	v_pk_add_f32 v[30:31], v[30:31], 0 op_sel_hi:[1,0]
	s_waitcnt lgkmcnt(1)
	v_mov_b32_e32 v46, v202
	s_waitcnt lgkmcnt(0)
	v_mov_b32_e32 v47, v204
	s_mov_b32 s2, s67
	v_mov_b32_e32 v62, v203
	v_mov_b32_e32 v63, v204
	v_pk_mul_f32 v[208:209], v[46:47], s[2:3] op_sel_hi:[1,0]
	v_pk_fma_f32 v[46:47], v[46:47], s[2:3], v[206:207] op_sel_hi:[1,0,1]
	v_pk_fma_f32 v[62:63], v[62:63], s[2:3], v[30:31] op_sel_hi:[1,0,1]
	v_pk_mul_f32 v[202:203], v[46:47], v[46:47]
	v_pk_mul_f32 v[30:31], v[62:63], v[62:63]
	v_pk_mov_b32 v[202:203], v[206:207], v[202:203] op_sel:[1,0]
	v_pk_mov_b32 v[30:31], v[208:209], v[30:31] op_sel:[1,0]
	v_add_f32_e32 v14, 0, v15
	v_pk_add_f32 v[30:31], v[202:203], v[30:31]
	v_pk_add_f32 v[202:203], v[46:47], v[62:63]
	v_pk_mul_f32 v[206:207], v[46:47], v[62:63]
	v_fmac_f32_e32 v14, 0x3fd744fd, v205
	v_mov_b32_e32 v203, v207
	v_pk_add_f32 v[30:31], v[202:203], v[30:31]
	v_mul_f32_e32 v15, v14, v14
	v_pk_add_f32 v[30:31], v[30:31], v[14:15]
	s_nop 1
	v_mov_b32_dpp v202, v30 quad_perm:[1,0,3,2] row_mask:0xf bank_mask:0xf bound_ctrl:1
	v_mov_b32_dpp v203, v31 quad_perm:[1,0,3,2] row_mask:0xf bank_mask:0xf bound_ctrl:1
	v_pk_add_f32 v[30:31], v[30:31], v[202:203]
	s_nop 1
	v_mov_b32_dpp v202, v30 quad_perm:[2,3,0,1] row_mask:0xf bank_mask:0xf bound_ctrl:1
	v_mov_b32_dpp v203, v31 quad_perm:[2,3,0,1] row_mask:0xf bank_mask:0xf bound_ctrl:1
	v_pk_add_f32 v[30:31], v[30:31], v[202:203]
	s_nop 1
	v_mov_b32_dpp v202, v30 row_half_mirror row_mask:0xf bank_mask:0xf bound_ctrl:1
	v_mov_b32_dpp v203, v31 row_half_mirror row_mask:0xf bank_mask:0xf bound_ctrl:1
	v_pk_add_f32 v[30:31], v[30:31], v[202:203]
	s_nop 1
	v_mov_b32_dpp v202, v30 row_mirror row_mask:0xf bank_mask:0xf bound_ctrl:1
	v_mov_b32_dpp v203, v31 row_mirror row_mask:0xf bank_mask:0xf bound_ctrl:1
	s_and_saveexec_b64 s[6:7], vcc
	v_pk_add_f32 v[30:31], v[30:31], v[202:203]
	ds_write_b64 v181, v[30:31] offset:456
	s_or_b64 exec, exec, s[6:7]
	ds_read2_b32 v[202:203], v79 offset1:32
	ds_read2_b32 v[206:207], v79 offset0:64 offset1:96
	v_mov_b32_e32 v204, v64
	v_mov_b32_e32 v205, v32
	v_pk_add_f32 v[208:209], v[204:205], 0 op_sel_hi:[1,0]
	v_mov_b32_e32 v204, v48
	v_pk_add_f32 v[204:205], v[204:205], 0 op_sel_hi:[1,0]
	s_waitcnt lgkmcnt(1)
; DI void ag_st64(u64_t* p, u64_t v) { __hip_atomic_store(p, v, __ATOMIC_RELAXED, __HIP_MEMORY_SCOPE_AGENT); }
;   DI void operator()(f32x16 (&acc)[2][4], int grow0, int gcol0, int lane, int w, char* lds) {
;     ...
;       for (int qq = 0; qq < 2; ++qq)
; #pragma unroll
;         for (int e = 0; e < 4; ++e) {
;           const int i = 4 * (2 * (ps & 1) + qq) + e;
;           const float* xr = (const float*)(xs + (8 * qq + 4 * hh + e) * 512) + l31;
;           float s1 = 0.f, s2 = 0.f;
; #pragma unroll
;           for (int nt = 0; nt < 4; ++nt) {
;             float v = (acc[mt][nt][i] + bia[nt]) * csc[nt];
;             float z = ALPHA * xr[nt * 32] + hs * v;
;             acc[mt][nt][i] = z; s1 += z; s2 += z * z;
;           }
;           s1 = row16_sum(s1); s2 = row16_sum(s2);
;           if ((lane & 15) == 0) { f32x2 sv = {s1, s2}; *(f32x2*)(redw + (mt * 32 + (i & 3) + 8 * (i >> 2)) * 2) = sv; }
;         }
;     }
;     __syncthreads();
;     u64_t* myslots = xstat + ((size_t)pm * 256) * 4;
;     if (tid < 256) {
;       float s1 = (red[tid * 2] + red[(256 + tid) * 2]) + (red[(512 + tid) * 2] + red[(768 + tid) * 2]);
;       float s2 = (red[tid * 2 + 1] + red[(256 + tid) * 2 + 1]) + (red[(512 + tid) * 2 + 1] + red[(768 + tid) * 2 + 1]);
;       ag_st64(myslots + tid * 4 + pn, ((u64_t)__float_as_uint(s2) << 32) | (u64_t)__float_as_uint(s1));
	v_mov_b32_e32 v212, v202
	s_waitcnt lgkmcnt(0)
	v_mov_b32_e32 v213, v206
	s_mov_b32 s2, s67
	v_mov_b32_e32 v226, v203
	v_mov_b32_e32 v227, v206
	v_pk_fma_f32 v[202:203], v[212:213], s[2:3], v[208:209] op_sel_hi:[1,0,1]
	v_pk_fma_f32 v[204:205], v[226:227], s[2:3], v[204:205] op_sel_hi:[1,0,1]
	v_pk_mul_f32 v[214:215], v[212:213], s[2:3] op_sel_hi:[1,0]
	v_pk_mul_f32 v[212:213], v[202:203], v[202:203]
	v_pk_mul_f32 v[226:227], v[204:205], v[204:205]
	v_pk_mov_b32 v[208:209], v[208:209], v[212:213] op_sel:[1,0]
	v_pk_mov_b32 v[212:213], v[214:215], v[226:227] op_sel:[1,0]
	v_add_f32_e32 v30, 0, v16
	v_pk_add_f32 v[208:209], v[208:209], v[212:213]
	v_pk_add_f32 v[212:213], v[202:203], v[204:205]
	v_pk_mul_f32 v[214:215], v[202:203], v[204:205]
	v_fmac_f32_e32 v30, 0x3fd744fd, v207
	v_mov_b32_e32 v213, v215
	v_pk_add_f32 v[208:209], v[212:213], v[208:209]
	v_mul_f32_e32 v31, v30, v30
	v_pk_add_f32 v[206:207], v[208:209], v[30:31]
	s_nop 1
	v_mov_b32_dpp v208, v206 quad_perm:[1,0,3,2] row_mask:0xf bank_mask:0xf bound_ctrl:1
	v_mov_b32_dpp v209, v207 quad_perm:[1,0,3,2] row_mask:0xf bank_mask:0xf bound_ctrl:1
	v_pk_add_f32 v[206:207], v[206:207], v[208:209]
	s_nop 1
	v_mov_b32_dpp v208, v206 quad_perm:[2,3,0,1] row_mask:0xf bank_mask:0xf bound_ctrl:1
	v_mov_b32_dpp v209, v207 quad_perm:[2,3,0,1] row_mask:0xf bank_mask:0xf bound_ctrl:1
	v_pk_add_f32 v[206:207], v[206:207], v[208:209]
	s_nop 1
	v_mov_b32_dpp v208, v206 row_half_mirror row_mask:0xf bank_mask:0xf bound_ctrl:1
	v_mov_b32_dpp v209, v207 row_half_mirror row_mask:0xf bank_mask:0xf bound_ctrl:1
	v_pk_add_f32 v[206:207], v[206:207], v[208:209]
	s_nop 1
	v_mov_b32_dpp v208, v206 row_mirror row_mask:0xf bank_mask:0xf bound_ctrl:1
	v_mov_b32_dpp v209, v207 row_mirror row_mask:0xf bank_mask:0xf bound_ctrl:1
	s_and_saveexec_b64 s[6:7], vcc
	v_pk_add_f32 v[206:207], v[206:207], v[208:209]
	ds_write_b64 v181, v[206:207] offset:464
	s_or_b64 exec, exec, s[6:7]
	ds_read2_b32 v[206:207], v93 offset1:32
	ds_read2_b32 v[208:209], v93 offset0:64 offset1:96
	v_mov_b32_e32 v32, v65
	v_pk_add_f32 v[64:65], v[32:33], 0 op_sel_hi:[1,0]
	v_mov_b32_e32 v32, v49
	v_pk_add_f32 v[48:49], v[32:33], 0 op_sel_hi:[1,0]
	s_waitcnt lgkmcnt(1)
	v_mov_b32_e32 v32, v206
	s_waitcnt lgkmcnt(0)
	v_mov_b32_e32 v33, v208
	s_mov_b32 s2, s67
	v_mov_b32_e32 v206, v207
	v_mov_b32_e32 v207, v208
	v_pk_mul_f32 v[212:213], v[32:33], s[2:3] op_sel_hi:[1,0]
	v_pk_fma_f32 v[32:33], v[32:33], s[2:3], v[64:65] op_sel_hi:[1,0,1]
	v_pk_fma_f32 v[48:49], v[206:207], s[2:3], v[48:49] op_sel_hi:[1,0,1]
	v_pk_mul_f32 v[214:215], v[32:33], v[32:33]
	v_pk_mul_f32 v[206:207], v[48:49], v[48:49]
	v_pk_mov_b32 v[64:65], v[64:65], v[214:215] op_sel:[1,0]
	v_pk_mov_b32 v[206:207], v[212:213], v[206:207] op_sel:[1,0]
	v_add_f32_e32 v16, 0, v17
	v_pk_add_f32 v[64:65], v[64:65], v[206:207]
	v_pk_add_f32 v[206:207], v[32:33], v[48:49]
	v_pk_mul_f32 v[212:213], v[32:33], v[48:49]
	v_fmac_f32_e32 v16, 0x3fd744fd, v209
	v_mov_b32_e32 v207, v213
	v_pk_add_f32 v[64:65], v[206:207], v[64:65]
	v_mul_f32_e32 v17, v16, v16
	v_pk_add_f32 v[64:65], v[64:65], v[16:17]
	s_nop 1
	v_mov_b32_dpp v206, v64 quad_perm:[1,0,3,2] row_mask:0xf bank_mask:0xf bound_ctrl:1
	v_mov_b32_dpp v207, v65 quad_perm:[1,0,3,2] row_mask:0xf bank_mask:0xf bound_ctrl:1
	v_pk_add_f32 v[64:65], v[64:65], v[206:207]
	s_nop 1
	v_mov_b32_dpp v206, v64 quad_perm:[2,3,0,1] row_mask:0xf bank_mask:0xf bound_ctrl:1
	v_mov_b32_dpp v207, v65 quad_perm:[2,3,0,1] row_mask:0xf bank_mask:0xf bound_ctrl:1
	v_pk_add_f32 v[64:65], v[64:65], v[206:207]
	s_nop 1
	v_mov_b32_dpp v206, v64 row_half_mirror row_mask:0xf bank_mask:0xf bound_ctrl:1
	v_mov_b32_dpp v207, v65 row_half_mirror row_mask:0xf bank_mask:0xf bound_ctrl:1
	v_pk_add_f32 v[64:65], v[64:65], v[206:207]
	s_nop 1
	v_mov_b32_dpp v206, v64 row_mirror row_mask:0xf bank_mask:0xf bound_ctrl:1
	v_mov_b32_dpp v207, v65 row_mirror row_mask:0xf bank_mask:0xf bound_ctrl:1
	s_and_saveexec_b64 s[6:7], vcc
	v_pk_add_f32 v[64:65], v[64:65], v[206:207]
	ds_write_b64 v181, v[64:65] offset:472
	s_or_b64 exec, exec, s[6:7]
	v_ashrrev_i32_e32 v206, 8, v163
	v_ashrrev_i32_e32 v207, 31, v206
	v_lshlrev_b64 v[64:65], 13, v[206:207]
	v_lshl_add_u64 v[64:65], s[8:9], 0, v[64:65]
	v_cmp_gt_i32_e64 s[40:41], s60, v164
	v_ashrrev_i32_e32 v201, 31, v200
	s_waitcnt lgkmcnt(0)
	s_barrier
	s_and_saveexec_b64 s[6:7], s[40:41]
	s_cbranch_execz .LBB0_240
	v_lshl_add_u32 v0, v164, 3, v221
	ds_read2st64_b64 v[212:215], v0 offset1:4
	ds_read2st64_b64 v[226:229], v0 offset0:8 offset1:12
	v_ashrrev_i32_e32 v208, 8, v184
	v_ashrrev_i32_e32 v209, 31, v208
	s_waitcnt lgkmcnt(1)
	v_mov_b32_e32 v230, v212
	s_waitcnt lgkmcnt(0)
	v_mov_b32_e32 v231, v226
	v_mov_b32_e32 v232, v214
	v_mov_b32_e32 v233, v228
	v_mov_b32_e32 v226, v213
	v_mov_b32_e32 v228, v215
	v_pk_add_f32 v[230:231], v[230:231], v[232:233]
	v_pk_add_f32 v[212:213], v[226:227], v[228:229]
	v_pk_add_f32 v[230:231], v[230:231], v[230:231] op_sel:[0,1] op_sel_hi:[1,0]
	v_pk_add_f32 v[212:213], v[212:213], v[212:213] op_sel:[0,1] op_sel_hi:[1,0]
	v_lshl_add_u64 v[214:215], v[200:201], 3, v[64:65]
	v_lshl_add_u64 v[208:209], v[208:209], 3, v[214:215]
	v_mov_b32_e32 v231, v212
	global_store_dwordx2 v[208:209], v[230:231], off sc1

; DI f32x16 mfma(bf16x8 a, bf16x8 b, f32x16 c) { return __builtin_amdgcn_mfma_f32_32x32x16_bf16(a, b, c, 0, 0, 0); }
; DI int launder(int x) { asm volatile("" : "+v"(x)); return x; }
; template <int BK> DI int swz(int row) { constexpr int CPR = BK / 8; return (row / (16 / CPR)) % CPR; }
; DI void wait_vm0() { asm volatile("s_waitcnt vmcnt(0)" ::: "memory"); }
;   DI void pre(int grow0, int gcol0, int lane, int w, char* lds) { xpass(0, grow0, gcol0, lane, w, lds); }
;     ...
;     for (int kk = 0; kk < NKK; ++kk) {
;       if (kk + 1 < NKK) {
;         const int ch = (kk + 1) * 2 + hh;
; #pragma unroll
;         for (int mt = 0; mt < 2; ++mt) { int row = wm * 64 + mt * 32 + l31; fa[(kk + 1) & 1][mt] = *(const bf16x8*)(cur + row * (BK * 2) + ((ch ^ swz<BK>(row)) << 4)); }
; #pragma unroll
;         for (int nt = 0; nt < NTW; ++nt) { int row = wn * (32 * NTW) + nt * 32 + l31; fb[(kk + 1) & 1][nt] = *(const bf16x8*)(cur + ABYTES + row * (BK * 2) + ((ch ^ swz<BK>(row)) << 4)); }
;       }
;       if (more) {
; #pragma unroll
;         for (int q = 0; q < PPK; ++q) {
;           const int pi = kk * PPK + q;
;           if (pi < NPA) stage_piece<BM, BK>(An, lda, nxt, tid, pi, wv);
;           else if (pi < NP) stage_piece<BN, BK>(Bn, ldb, nxt + ABYTES, tid, pi - NPA, wv);
;         }
;       }
;       __builtin_amdgcn_s_setprio(1);
; #pragma unroll
;       for (int mt = 0; mt < 2; ++mt)
; #pragma unroll
;         for (int nt = 0; nt < NTW; ++nt) acc[mt][nt] = mfma(fa[kk & 1][mt], fb[kk & 1][nt], acc[mt][nt]);
;       __builtin_amdgcn_s_setprio(0);
;       __builtin_amdgcn_sched_barrier(0);
;     }
;     wait_vm0();
;     __syncthreads();
;   }
;   if (has_next) { const int tid3 = launder(threadIdx.x); stage_tile<BM, BK>(A + (size_t)row0n * lda, lda, lds, tid3); stage_tile<BN, BK>(Bt + (size_t)col0n * ldb, ldb, lds + ABYTES, tid3); }
; template <class Epi>
; DI void gemm_phase256(const bf16_t* A, int lda, const bf16_t* Bt, int K, int nN, char* lds, Epi& epi, int vb) {
;     ...
;   for (int t = vb; t < ntiles; t += gridDim.x) {
;     const int x = t & 7, L = t >> 3; const int pm = 8 * x + (L & 7), pn = L >> 3;
;     const int t2 = t + gridDim.x; const bool hn = t2 < ntiles;
;     const int x2 = t2 & 7, L2 = t2 >> 3; const int pm2 = 8 * x2 + (L2 & 7), pn2 = L2 >> 3;
;     gemm_tile<4, 64>(A, lda, Bt, K, K, pm * 256, pn * 256, lds, epi, pre, hn, pm2 * 256, pn2 * 256);
;     pre = hn;
.Lk284_exit:
	v_mfma_f32_32x32x16_bf16 v[114:129], v[190:193], v[198:201], v[114:129]
	v_mfma_f32_32x32x16_bf16 v[98:113], v[190:193], v[202:205], v[98:113]
	v_mfma_f32_32x32x16_bf16 v[82:97], v[190:193], v[206:209], v[82:97]
	v_mfma_f32_32x32x16_bf16 v[66:81], v[190:193], v[210:213], v[66:81]
	v_mfma_f32_32x32x16_bf16 v[50:65], v[194:197], v[198:201], v[50:65]
	v_mfma_f32_32x32x16_bf16 v[34:49], v[194:197], v[202:205], v[34:49]
	v_mfma_f32_32x32x16_bf16 v[18:33], v[194:197], v[206:209], v[18:33]
	v_mfma_f32_32x32x16_bf16 v[2:17], v[194:197], v[210:213], v[2:17]
	s_waitcnt lgkmcnt(0)
	v_add_u32_e32 v0, 0x10000, v140
	v_add_u32_e32 v198, 0x10000, v142
	v_add_u32_e32 v130, v0, v141
	v_add_u32_e32 v140, v198, v144
	v_add_u32_e32 v199, 0x18000, v143
	v_add_u32_e32 v200, 0x18000, v152
	ds_read_b128 v[130:133], v130
	ds_read_b128 v[166:169], v140
	v_add_u32_e32 v140, v199, v151
	v_add_u32_e32 v144, v200, v154
	v_add_u32_e32 v201, 0x18000, v153
	ds_read_b128 v[140:143], v140
	ds_read_b128 v[170:173], v144
	v_add_u32_e32 v144, v201, v155
	v_add_u32_e32 v202, 0x18000, v156
	v_add_u32_e32 v151, v202, v164
	ds_read_b128 v[152:155], v144
	ds_read_b128 v[174:177], v151
	v_add_u32_e32 v144, v0, v161
	v_add_u32_e32 v151, v198, v163
	ds_read_b128 v[178:181], v144
	ds_read_b128 v[182:185], v151
	v_add_u32_e32 v144, v199, v159
	v_add_u32_e32 v151, v200, v160
	ds_read_b128 v[186:189], v144
	ds_read_b128 v[190:193], v151
	v_add_u32_e32 v144, v201, v157
	v_add_u32_e32 v151, v202, v158
	ds_read_b128 v[156:159], v144
	ds_read_b128 v[194:197], v151
	s_add_i32 s44, s44, s94
	s_cmpk_gt_i32 s44, 0xff
	s_cselect_b64 s[30:31], -1, 0
	s_cmpk_lt_i32 s44, 0x100
	s_waitcnt lgkmcnt(9)
	v_mfma_f32_32x32x16_bf16 v[114:129], v[130:133], v[140:143], v[114:129]
	s_waitcnt lgkmcnt(8)
	v_mfma_f32_32x32x16_bf16 v[98:113], v[130:133], v[170:173], v[98:113]
	s_waitcnt lgkmcnt(7)
	v_mfma_f32_32x32x16_bf16 v[82:97], v[130:133], v[152:155], v[82:97]
	s_waitcnt lgkmcnt(6)
	v_mfma_f32_32x32x16_bf16 v[66:81], v[130:133], v[174:177], v[66:81]
	v_mfma_f32_32x32x16_bf16 v[50:65], v[166:169], v[140:143], v[50:65]
	v_mfma_f32_32x32x16_bf16 v[34:49], v[166:169], v[170:173], v[34:49]
	v_mfma_f32_32x32x16_bf16 v[18:33], v[166:169], v[152:155], v[18:33]
	v_mfma_f32_32x32x16_bf16 v[2:17], v[166:169], v[174:177], v[2:17]
	v_add_u32_e32 v130, v0, v149
	v_add_u32_e32 v140, v198, v150
	v_add_u32_e32 v144, v199, v147
	ds_read_b128 v[130:133], v130
	ds_read_b128 v[140:143], v140
	v_add_u32_e32 v147, v200, v148
	ds_read_b128 v[148:151], v144
	ds_read_b128 v[152:155], v147
	v_add_u32_e32 v144, v201, v145
	v_add_u32_e32 v160, v202, v146
	ds_read_b128 v[144:147], v144
	ds_read_b128 v[166:169], v160
	s_waitcnt lgkmcnt(9)
	v_mfma_f32_32x32x16_bf16 v[114:129], v[178:181], v[186:189], v[114:129]
	s_waitcnt lgkmcnt(8)
	v_mfma_f32_32x32x16_bf16 v[98:113], v[178:181], v[190:193], v[98:113]
	s_waitcnt lgkmcnt(7)
	v_mfma_f32_32x32x16_bf16 v[82:97], v[178:181], v[156:159], v[82:97]
	s_waitcnt lgkmcnt(6)
	v_mfma_f32_32x32x16_bf16 v[66:81], v[178:181], v[194:197], v[66:81]
	v_mfma_f32_32x32x16_bf16 v[50:65], v[182:185], v[186:189], v[50:65]
	v_mfma_f32_32x32x16_bf16 v[34:49], v[182:185], v[190:193], v[34:49]
	v_mfma_f32_32x32x16_bf16 v[18:33], v[182:185], v[156:159], v[18:33]
	v_mfma_f32_32x32x16_bf16 v[2:17], v[182:185], v[194:197], v[2:17]
	v_add_u32_e32 v0, v0, v138
	v_add_u32_e32 v138, v198, v139
	ds_read_b128 v[156:159], v0
	ds_read_b128 v[170:173], v138
	v_add_u32_e32 v0, v199, v136
	v_add_u32_e32 v160, v200, v137
	ds_read_b128 v[136:139], v0
	ds_read_b128 v[174:177], v160
	v_add_u32_e32 v0, v201, v134
	v_add_u32_e32 v134, v202, v135
	ds_read_b128 v[178:181], v0
	ds_read_b128 v[182:185], v134
	s_waitcnt lgkmcnt(9)
	v_mfma_f32_32x32x16_bf16 v[114:129], v[130:133], v[148:151], v[114:129]
	s_waitcnt lgkmcnt(8)
	v_mfma_f32_32x32x16_bf16 v[98:113], v[130:133], v[152:155], v[98:113]
	s_waitcnt lgkmcnt(7)
	v_mfma_f32_32x32x16_bf16 v[82:97], v[130:133], v[144:147], v[82:97]
	s_waitcnt lgkmcnt(6)
	v_mfma_f32_32x32x16_bf16 v[66:81], v[130:133], v[166:169], v[66:81]
	v_mfma_f32_32x32x16_bf16 v[50:65], v[140:143], v[148:151], v[50:65]
	v_mfma_f32_32x32x16_bf16 v[34:49], v[140:143], v[152:155], v[34:49]
	v_mfma_f32_32x32x16_bf16 v[18:33], v[140:143], v[144:147], v[18:33]
	v_mfma_f32_32x32x16_bf16 v[2:17], v[140:143], v[166:169], v[2:17]
	s_waitcnt lgkmcnt(3)
	v_mfma_f32_32x32x16_bf16 v[114:129], v[156:159], v[136:139], v[114:129]
	s_waitcnt lgkmcnt(2)
	v_mfma_f32_32x32x16_bf16 v[98:113], v[156:159], v[174:177], v[98:113]
	s_waitcnt lgkmcnt(1)
	v_mfma_f32_32x32x16_bf16 v[82:97], v[156:159], v[178:181], v[82:97]
	s_waitcnt lgkmcnt(0)
	v_mfma_f32_32x32x16_bf16 v[66:81], v[156:159], v[182:185], v[66:81]
	v_mfma_f32_32x32x16_bf16 v[50:65], v[170:173], v[136:139], v[50:65]
	v_mfma_f32_32x32x16_bf16 v[34:49], v[170:173], v[174:177], v[34:49]
	v_mfma_f32_32x32x16_bf16 v[18:33], v[170:173], v[178:181], v[18:33]
	v_mfma_f32_32x32x16_bf16 v[2:17], v[170:173], v[182:185], v[2:17]
	s_waitcnt vmcnt(0)
	s_barrier
	s_cbranch_scc0 .LBB0_280
	v_mov_b32_e32 v132, v216
	s_lshl_b32 s3, s44, 3
	v_ashrrev_i32_e32 v0, 31, v132
	v_lshrrev_b32_e32 v130, 29, v0
	v_lshrrev_b32_e32 v0, 28, v0
	v_add_u32_e32 v0, v132, v0
	v_ashrrev_i32_e32 v0, 4, v0
	s_and_b32 s3, s3, 56
	s_bfe_u32 s7, s44, 0x30003
	v_lshrrev_b32_e32 v133, 29, v0
	s_or_b32 s3, s3, s7
	s_lshl_b32 s7, s44, 2
	v_add_u32_e32 v130, v132, v130
	v_add_u32_e32 v133, v0, v133
	s_and_b32 s34, s7, 0xffffff00
	s_lshl_b32 s3, s3, 19
	v_and_b32_e32 v131, 0xffffff8, v130
	v_and_b32_e32 v133, 0xffffff8, v133
	s_add_u32 s46, s12, s3
	v_sub_u32_e32 v131, v132, v131
	v_sub_u32_e32 v0, v0, v133
	v_lshlrev_b32_e32 v130, 8, v130
	v_readfirstlane_b32 s3, v132
	s_addc_u32 s47, s13, 0
	v_xor_b32_e32 v0, v0, v131
	v_and_b32_e32 v130, 0xfffff800, v130
	s_lshl_b32 s3, s3, 4
	v_lshl_add_u32 v0, v0, 4, v130
	s_and_b32 s3, s3, 0xfffffc00
	v_lshl_add_u64 v[130:131], s[46:47], 0, v[0:1]
	s_mov_b32 m0, s3
	v_lshl_add_u64 v[132:133], v[130:131], 0, s[58:59]
	global_load_lds_dwordx4 v0, s[46:47]
	s_add_i32 m0, s3, 0x2000
	s_ashr_i32 s35, s34, 31
	global_load_lds_dwordx4 v[132:133], off
	v_lshl_add_u64 v[132:133], v[130:131], 0, s[48:49]
	s_add_i32 m0, s3, 0x4000
	s_lshl_b64 s[34:35], s[34:35], 11
	global_load_lds_dwordx4 v[132:133], off
	s_add_i32 m0, s3, 0x6000
	s_add_u32 s34, s40, s34
	v_lshl_add_u64 v[130:131], v[130:131], 0, s[50:51]
	s_addc_u32 s35, s41, s35
	global_load_lds_dwordx4 v[130:131], off
	v_lshl_add_u64 v[130:131], s[34:35], 0, v[0:1]
	s_add_i32 m0, s3, 0x8000
	v_lshl_add_u64 v[132:133], v[130:131], 0, s[58:59]
	global_load_lds_dwordx4 v0, s[34:35]
	s_add_i32 m0, s3, 0xa000
	s_nop 0
	global_load_lds_dwordx4 v[132:133], off
	v_lshl_add_u64 v[132:133], v[130:131], 0, s[48:49]
	s_add_i32 m0, s3, 0xc000
	v_lshl_add_u64 v[130:131], v[130:131], 0, s[50:51]
	global_load_lds_dwordx4 v[132:133], off
	s_add_i32 m0, s3, 0xe000
	s_nop 0
	global_load_lds_dwordx4 v[130:131], off
	s_branch .LBB0_280

; DI void wait_vm0() { asm volatile("s_waitcnt vmcnt(0)" ::: "memory"); }
;     ...
;     if (!more) epi.pre(row0 + wm * 64, col0 + wn * (32 * NTW), lane, w, lds);
;     bf16x8 fa[2][2], fb[2][NTW];
; #pragma unroll
;     for (int mt = 0; mt < 2; ++mt) { int row = wm * 64 + mt * 32 + l31; fa[0][mt] = *(const bf16x8*)(cur + row * (BK * 2) + ((hh ^ swz<BK>(row)) << 4)); }
; #pragma unroll
;     for (int nt = 0; nt < NTW; ++nt) { int row = wn * (32 * NTW) + nt * 32 + l31; fb[0][nt] = *(const bf16x8*)(cur + ABYTES + row * (BK * 2) + ((hh ^ swz<BK>(row)) << 4)); }
; #pragma unroll
;     for (int kk = 0; kk < NKK; ++kk) {
;       if (kk + 1 < NKK) {
;         const int ch = (kk + 1) * 2 + hh;
; #pragma unroll
;         for (int mt = 0; mt < 2; ++mt) { int row = wm * 64 + mt * 32 + l31; fa[(kk + 1) & 1][mt] = *(const bf16x8*)(cur + row * (BK * 2) + ((ch ^ swz<BK>(row)) << 4)); }
; #pragma unroll
;         for (int nt = 0; nt < NTW; ++nt) { int row = wn * (32 * NTW) + nt * 32 + l31; fb[(kk + 1) & 1][nt] = *(const bf16x8*)(cur + ABYTES + row * (BK * 2) + ((ch ^ swz<BK>(row)) << 4)); }
;       }
;       if (more) {
; #pragma unroll
;         for (int q = 0; q < PPK; ++q) {
;           const int pi = kk * PPK + q;
;           if (pi < NPA) stage_piece<BM, BK>(An, lda, nxt, tid, pi, wv);
;           else if (pi < NP) stage_piece<BN, BK>(Bn, ldb, nxt + ABYTES, tid, pi - NPA, wv);
;         }
;       }
;       __builtin_amdgcn_s_setprio(1);
; #pragma unroll
;       for (int mt = 0; mt < 2; ++mt)
; #pragma unroll
;         for (int nt = 0; nt < NTW; ++nt) acc[mt][nt] = mfma(fa[kk & 1][mt], fb[kk & 1][nt], acc[mt][nt]);
;       __builtin_amdgcn_s_setprio(0);
;       __builtin_amdgcn_sched_barrier(0);
;     }
;     wait_vm0();
;     __syncthreads();
;   DI void xpass(int ps, int grow0, int gcol0, int lane, int w, char* lds) const {
;     char* xs = lds + (ps & 1) * 65536 + __builtin_amdgcn_readfirstlane(w) * 8192;
;     const float* xsrc = Xin + (size_t)(grow0 + (ps >> 1) * 32 + (ps & 1) * 16 + (lane >> 5)) * D_ + gcol0 + (lane & 31) * 4;
; #pragma unroll
;     for (int pc = 0; pc < 8; ++pc)
;       __builtin_amdgcn_global_load_lds((const unsigned*)(xsrc + (size_t)(2 * pc) * D_), (__attribute__((address_space(3))) unsigned*)(xs + pc * 1024), 16, 0, 0);
;   }
;   DI void pre(int grow0, int gcol0, int lane, int w, char* lds) { xpass(0, grow0, gcol0, lane, w, lds); }
.Lk292_exit:
	v_mfma_f32_32x32x16_bf16 v[114:129], v[194:197], v[202:205], v[114:129]
	v_mfma_f32_32x32x16_bf16 v[98:113], v[194:197], v[206:209], v[98:113]
	v_mfma_f32_32x32x16_bf16 v[82:97], v[194:197], v[210:213], v[82:97]
	v_mfma_f32_32x32x16_bf16 v[66:81], v[194:197], v[226:229], v[66:81]
	v_mfma_f32_32x32x16_bf16 v[50:65], v[198:201], v[202:205], v[50:65]
	v_mfma_f32_32x32x16_bf16 v[34:49], v[198:201], v[206:209], v[34:49]
	v_mfma_f32_32x32x16_bf16 v[18:33], v[198:201], v[210:213], v[18:33]
	v_mfma_f32_32x32x16_bf16 v[2:17], v[198:201], v[226:229], v[2:17]
	s_waitcnt lgkmcnt(0)
	v_readlane_b32 s3, v253, 9
	v_readlane_b32 s6, v253, 27
	v_readlane_b32 s54, v255, 29
	v_or_b32_e32 v130, s3, v135
	v_add_u32_e32 v130, v130, v169
	v_ashrrev_i32_e32 v131, 31, v130
	v_lshlrev_b64 v[130:131], 12, v[130:131]
	v_add_u32_e32 v132, s6, v168
	v_readlane_b32 s55, v255, 30
	v_ashrrev_i32_e32 v133, 31, v132
	v_readfirstlane_b32 s2, v134
	v_lshl_add_u64 v[130:131], s[54:55], 0, v[130:131]
	v_lshlrev_b32_e32 v0, 4, v0
	s_lshl_b32 s2, s2, 13
	v_lshl_add_u64 v[130:131], v[132:133], 2, v[130:131]
	v_and_b32_e32 v0, 0x1f0, v0
	v_lshl_add_u64 v[130:131], v[130:131], 0, v[0:1]
	s_mov_b32 m0, s2
	s_mov_b64 s[34:35], 0x2000
	global_load_lds_dwordx4 v[130:131], off
	v_lshl_add_u64 v[132:133], v[130:131], 0, s[34:35]
	s_or_b32 m0, s2, 0x400
	s_mov_b64 s[36:37], 0x4000
	global_load_lds_dwordx4 v[132:133], off
	v_lshl_add_u64 v[132:133], v[130:131], 0, s[36:37]
	s_or_b32 m0, s2, 0x800
	s_mov_b64 s[40:41], 0x6000
	global_load_lds_dwordx4 v[132:133], off
	v_lshl_add_u64 v[132:133], v[130:131], 0, s[40:41]
	s_or_b32 m0, s2, 0xc00
	s_mov_b64 s[42:43], 0x8000
	global_load_lds_dwordx4 v[132:133], off
	v_lshl_add_u64 v[132:133], v[130:131], 0, s[42:43]
	s_or_b32 m0, s2, 0x1000
	s_mov_b64 s[44:45], 0xa000
	global_load_lds_dwordx4 v[132:133], off
	v_lshl_add_u64 v[132:133], v[130:131], 0, s[44:45]
	s_or_b32 m0, s2, 0x1400
	s_mov_b64 s[46:47], 0xc000
	global_load_lds_dwordx4 v[132:133], off
	v_lshl_add_u64 v[132:133], v[130:131], 0, s[46:47]
	s_or_b32 m0, s2, 0x1800
	s_mov_b64 s[52:53], 0xe000
	global_load_lds_dwordx4 v[132:133], off
	v_lshl_add_u64 v[130:131], v[130:131], 0, s[52:53]
	s_or_b32 m0, s2, 0x1c00
	v_add_u32_e32 v0, s30, v136
	global_load_lds_dwordx4 v[130:131], off
	v_add_u32_e32 v134, s30, v144
	v_add_u32_e32 v130, v0, v143
	v_add_u32_e32 v135, v134, v146
	ds_read_b128 v[130:133], v130
	ds_read_b128 v[168:171], v135
	v_add_u32_e32 v135, s30, v145
	v_add_u32_e32 v136, v135, v151
	v_add_u32_e32 v143, s30, v152
	v_add_u32_e32 v144, v143, v156
	ds_read_b128 v[172:175], v136 offset:32768
	ds_read_b128 v[176:179], v144 offset:32768
	v_add_u32_e32 v136, s30, v155
	v_add_u32_e32 v144, v136, v157
	v_add_u32_e32 v208, s30, v158
	v_add_u32_e32 v145, v208, v167
	ds_read_b128 v[180:183], v144 offset:32768
	ds_read_b128 v[184:187], v145 offset:32768
	v_add_u32_e32 v144, v0, v164
	v_add_u32_e32 v145, v134, v166
	ds_read_b128 v[188:191], v144
	ds_read_b128 v[192:195], v145
	v_add_u32_e32 v144, v135, v161
	v_add_u32_e32 v145, v143, v163
	ds_read_b128 v[196:199], v144 offset:32768
	ds_read_b128 v[200:203], v145 offset:32768
	v_add_u32_e32 v144, v136, v159
	v_add_u32_e32 v145, v208, v160
	ds_read_b128 v[156:159], v144 offset:32768
	ds_read_b128 v[204:207], v145 offset:32768
	v_readlane_b32 s7, v253, 28
	s_waitcnt lgkmcnt(0)
	v_mfma_f32_32x32x16_bf16 v[114:129], v[130:133], v[172:175], v[114:129]
	v_mfma_f32_32x32x16_bf16 v[98:113], v[130:133], v[176:179], v[98:113]
	v_mfma_f32_32x32x16_bf16 v[82:97], v[130:133], v[180:183], v[82:97]
	v_mfma_f32_32x32x16_bf16 v[66:81], v[130:133], v[184:187], v[66:81]
	v_mfma_f32_32x32x16_bf16 v[50:65], v[168:171], v[172:175], v[50:65]
	v_mfma_f32_32x32x16_bf16 v[34:49], v[168:171], v[176:179], v[34:49]
	v_mfma_f32_32x32x16_bf16 v[18:33], v[168:171], v[180:183], v[18:33]
	v_mfma_f32_32x32x16_bf16 v[2:17], v[168:171], v[184:187], v[2:17]
	v_add_u32_e32 v130, v0, v153
	v_add_u32_e32 v144, v134, v154
	ds_read_b128 v[130:133], v130
	ds_read_b128 v[152:155], v144
	v_add_u32_e32 v144, v135, v149
	v_add_u32_e32 v145, v143, v150
	ds_read_b128 v[166:169], v144 offset:32768
	ds_read_b128 v[170:173], v145 offset:32768
	v_add_u32_e32 v144, v136, v147
	v_add_u32_e32 v148, v208, v148
	ds_read_b128 v[144:147], v144 offset:32768
	ds_read_b128 v[148:151], v148 offset:32768
	v_mfma_f32_32x32x16_bf16 v[114:129], v[188:191], v[196:199], v[114:129]
	v_mfma_f32_32x32x16_bf16 v[98:113], v[188:191], v[200:203], v[98:113]
	v_mfma_f32_32x32x16_bf16 v[82:97], v[188:191], v[156:159], v[82:97]
	v_mfma_f32_32x32x16_bf16 v[66:81], v[188:191], v[204:207], v[66:81]
	v_mfma_f32_32x32x16_bf16 v[50:65], v[192:195], v[196:199], v[50:65]
	v_mfma_f32_32x32x16_bf16 v[34:49], v[192:195], v[200:203], v[34:49]
	v_mfma_f32_32x32x16_bf16 v[18:33], v[192:195], v[156:159], v[18:33]
	v_mfma_f32_32x32x16_bf16 v[2:17], v[192:195], v[204:207], v[2:17]
	v_add_u32_e32 v0, v0, v141
	v_add_u32_e32 v134, v134, v142
	ds_read_b128 v[156:159], v0
	ds_read_b128 v[174:177], v134
	v_add_u32_e32 v0, v135, v139
	v_add_u32_e32 v134, v143, v140
	ds_read_b128 v[140:143], v0 offset:32768
	ds_read_b128 v[178:181], v134 offset:32768
	v_add_u32_e32 v0, v136, v137
	v_add_u32_e32 v138, v208, v138
	ds_read_b128 v[134:137], v0 offset:32768
	ds_read_b128 v[182:185], v138 offset:32768
	s_waitcnt lgkmcnt(9)
	v_mfma_f32_32x32x16_bf16 v[114:129], v[130:133], v[166:169], v[114:129]
	s_waitcnt lgkmcnt(8)
	v_mfma_f32_32x32x16_bf16 v[98:113], v[130:133], v[170:173], v[98:113]
	s_waitcnt lgkmcnt(7)
	v_mfma_f32_32x32x16_bf16 v[82:97], v[130:133], v[144:147], v[82:97]
	s_waitcnt lgkmcnt(6)
	v_mfma_f32_32x32x16_bf16 v[66:81], v[130:133], v[148:151], v[66:81]
	v_mfma_f32_32x32x16_bf16 v[50:65], v[152:155], v[166:169], v[50:65]
	v_mfma_f32_32x32x16_bf16 v[34:49], v[152:155], v[170:173], v[34:49]
	v_mfma_f32_32x32x16_bf16 v[18:33], v[152:155], v[144:147], v[18:33]
	v_mfma_f32_32x32x16_bf16 v[2:17], v[152:155], v[148:151], v[2:17]
	s_waitcnt lgkmcnt(3)
	v_mfma_f32_32x32x16_bf16 v[114:129], v[156:159], v[140:143], v[114:129]
	s_waitcnt lgkmcnt(2)
	v_mfma_f32_32x32x16_bf16 v[98:113], v[156:159], v[178:181], v[98:113]
	s_waitcnt lgkmcnt(1)
	v_mfma_f32_32x32x16_bf16 v[82:97], v[156:159], v[134:137], v[82:97]
	s_waitcnt lgkmcnt(0)
	v_mfma_f32_32x32x16_bf16 v[66:81], v[156:159], v[182:185], v[66:81]
	v_mfma_f32_32x32x16_bf16 v[50:65], v[174:177], v[140:143], v[50:65]
	v_mfma_f32_32x32x16_bf16 v[34:49], v[174:177], v[178:181], v[34:49]
	v_mfma_f32_32x32x16_bf16 v[18:33], v[174:177], v[134:137], v[18:33]
	v_mfma_f32_32x32x16_bf16 v[2:17], v[174:177], v[182:185], v[2:17]
	v_mov_b32_e32 v210, v216
	s_waitcnt vmcnt(0)
	s_barrier
;   DI void xpass(int ps, int grow0, int gcol0, int lane, int w, char* lds) const {
;     char* xs = lds + (ps & 1) * 65536 + __builtin_amdgcn_readfirstlane(w) * 8192;
;     const float* xsrc = Xin + (size_t)(grow0 + (ps >> 1) * 32 + (ps & 1) * 16 + (lane >> 5)) * D_ + gcol0 + (lane & 31) * 4;
; #pragma unroll
;     for (int pc = 0; pc < 8; ++pc)
;       __builtin_amdgcn_global_load_lds((const unsigned*)(xsrc + (size_t)(2 * pc) * D_), (__attribute__((address_space(3))) unsigned*)(xs + pc * 1024), 16, 0, 0);
;   }
;   DI void operator()(f32x16 (&acc)[2][4], int grow0, int gcol0, int lane, int w, char* lds) {
;     float* red = (float*)(lds + 131072); float* stat = (float*)lds;
;     const int l31 = lane & 31, hh = lane >> 5, tid = w * 64 + lane;
;     const int pm = grow0 >> 8, pn = gcol0 >> 8, wn = (gcol0 >> 7) & 1, lrow0 = grow0 & 255;
;     float bia[4], csc[4];
; #pragma unroll
;     for (int nt = 0; nt < 4; ++nt) { int c = gcol0 + nt * 32 + l31; bia[nt] = bias ? bias[c] : 0.f; csc[nt] = cscale ? cscale[c] : 1.f; }
;     float* redw = red + ((wn * 2 + ((lane >> 4) & 1)) * 256 + lrow0 + 4 * hh) * 2;
; #pragma unroll
;     for (int ps = 0; ps < 4; ++ps) {
;       const int mt = ps >> 1;
;       if (ps + 1 < 4) {
;         if (ps >= 1) asm volatile("s_waitcnt lgkmcnt(0)" ::: "memory");
;         xpass(ps + 1, grow0, gcol0, lane, w, lds);
;         if (ps >= 1) asm volatile("s_waitcnt vmcnt(8)" ::: "memory");
;       } else asm volatile("s_waitcnt vmcnt(0)" ::: "memory");
;       const char* xs = lds + (ps & 1) * 65536 + w * 8192;
; #pragma unroll
;       for (int qq = 0; qq < 2; ++qq)
; #pragma unroll
;         for (int e = 0; e < 4; ++e) {
;           const int i = 4 * (2 * (ps & 1) + qq) + e;
;           const float* xr = (const float*)(xs + (8 * qq + 4 * hh + e) * 512) + l31;
;           float s1 = 0.f, s2 = 0.f;
; #pragma unroll
;           for (int nt = 0; nt < 4; ++nt) {
;             float v = (acc[mt][nt][i] + bia[nt]) * csc[nt];
;             float z = ALPHA * xr[nt * 32] + hs * v;
;             acc[mt][nt][i] = z; s1 += z; s2 += z * z;
;           }
;           s1 = row16_sum(s1); s2 = row16_sum(s2);
;           if ((lane & 15) == 0) { f32x2 sv = {s1, s2}; *(f32x2*)(redw + (mt * 32 + (i & 3) + 8 * (i >> 2)) * 2) = sv; }
;         }
	v_add_f32_e32 v114, 0, v114
	v_ashrrev_i32_e32 v169, 6, v210
	v_lshrrev_b32_e32 v0, 30, v169
	v_add_u32_e32 v0, v169, v0
	v_ashrrev_i32_e32 v134, 2, v0
	v_mul_i32_i24_e32 v0, 4, v134
	v_sub_u32_e32 v0, v169, v0
	v_lshlrev_b32_e32 v135, 6, v0
	v_add_u32_e32 v164, s3, v135
	v_bfe_u32 v0, v210, 5, 1
	v_or_b32_e32 v176, v164, v0
	v_or_b32_e32 v130, 16, v176
	v_ashrrev_i32_e32 v131, 31, v130
	v_lshl_add_u32 v154, v134, 7, s6
	v_lshlrev_b32_e32 v168, 2, v210
	v_lshlrev_b64 v[130:131], 12, v[130:131]
	v_ashrrev_i32_e32 v155, 31, v154
	v_and_b32_e32 v0, 0x7c, v168
	v_readfirstlane_b32 s2, v169
	v_lshl_add_u64 v[130:131], s[54:55], 0, v[130:131]
	s_lshl_b32 s2, s2, 13
	v_lshl_add_u64 v[130:131], v[154:155], 2, v[130:131]
	v_lshlrev_b32_e32 v0, 2, v0
	s_add_i32 m0, s2, 0x10000
	v_lshl_add_u64 v[130:131], v[130:131], 0, v[0:1]
	global_load_lds_dwordx4 v[130:131], off
	v_lshl_add_u64 v[132:133], v[130:131], 0, s[34:35]
	s_add_i32 m0, s2, 0x10400
	v_and_b32_e32 v211, 0xc0, v135
	global_load_lds_dwordx4 v[132:133], off
	v_lshl_add_u64 v[132:133], v[130:131], 0, s[36:37]
	s_add_i32 m0, s2, 0x10800
	v_mov_b32_e32 v144, v98
	global_load_lds_dwordx4 v[132:133], off
	v_lshl_add_u64 v[132:133], v[130:131], 0, s[40:41]
	s_add_i32 m0, s2, 0x10c00
	v_mov_b32_e32 v145, v82
	global_load_lds_dwordx4 v[132:133], off
	v_lshl_add_u64 v[132:133], v[130:131], 0, s[42:43]
	s_add_i32 m0, s2, 0x11000
	v_mul_f32_e32 v141, 0.5, v114
	global_load_lds_dwordx4 v[132:133], off
	v_lshl_add_u64 v[132:133], v[130:131], 0, s[44:45]
	s_add_i32 m0, s2, 0x11400
	v_pk_add_f32 v[144:145], v[144:145], 0 op_sel_hi:[1,0]
	global_load_lds_dwordx4 v[132:133], off
	v_lshl_add_u64 v[132:133], v[130:131], 0, s[46:47]
	s_add_i32 m0, s2, 0x11800
	v_lshl_add_u64 v[130:131], v[130:131], 0, s[52:53]
	global_load_lds_dwordx4 v[132:133], off
	s_add_i32 m0, s2, 0x11c00
	v_bfe_u32 v132, v210, 4, 1
	global_load_lds_dwordx4 v[130:131], off
	v_and_b32_e32 v130, 31, v210
	v_lshlrev_b32_e32 v131, 1, v134
	v_bfe_u32 v134, v210, 3, 3
	v_and_or_b32 v131, v131, 2, v132
	v_and_b32_e32 v132, 4, v134
	v_lshlrev_b32_e32 v130, 2, v130
	v_or_b32_e32 v133, v211, v132
	v_lshl_or_b32 v138, v169, 13, v130
	v_lshlrev_b32_e32 v172, 9, v132
	v_lshlrev_b32_e32 v135, 3, v133
	v_or_b32_e32 v132, v138, v172
	v_and_b32_e32 v133, 15, v210
	v_lshl_or_b32 v139, v131, 11, v221
	s_waitcnt vmcnt(8)
	ds_read2_b32 v[130:131], v132 offset1:32
	v_cmp_eq_u32_e32 vcc, 0, v133
	ds_read2_b32 v[132:133], v132 offset0:64 offset1:96
	v_mov_b32_e32 v140, v82
	v_mov_b32_e32 v136, v1
	s_waitcnt lgkmcnt(0)
	v_mul_f32_e32 v137, 0x3fd744fd, v130
	v_mov_b32_e32 v130, v131
	v_mov_b32_e32 v131, v132
	s_mov_b32 s2, s67
	v_pk_add_f32 v[160:161], v[140:141], v[136:137]
	v_pk_mul_f32 v[130:131], v[130:131], s[2:3] op_sel_hi:[1,0]
	v_pk_mul_f32 v[136:137], v[144:145], 0.5 op_sel_hi:[1,0]
	v_pk_fma_f32 v[158:159], v[144:145], 0.5, v[130:131] op_sel_hi:[1,0,1]
	v_mov_b32_e32 v136, v161
	v_mov_b32_e32 v144, v1
	v_mov_b32_e32 v145, v131
	v_add_f32_e32 v142, 0, v66
	v_mov_b32_e32 v143, v133
	v_pk_mul_f32 v[140:141], v[158:159], v[158:159]
	v_pk_add_f32 v[136:137], v[136:137], v[144:145]
	v_mul_f32_e32 v66, 0x3fd744fd, v133
	v_mov_b32_e32 v163, v161
	v_pk_mov_b32 v[130:131], v[130:131], v[140:141] op_sel:[1,0]
	v_pk_add_f32 v[140:141], v[158:159], v[136:137]
	v_pk_mul_f32 v[136:137], v[158:159], v[136:137]
	v_pk_fma_f32 v[166:167], v[142:143], s[66:67], v[66:67] op_sel_hi:[1,1,0]
	v_pk_fma_f32 v[130:131], v[160:161], v[162:163], v[130:131]
	v_mov_b32_e32 v141, v137
	v_pk_mul_f32 v[132:133], v[166:167], v[166:167]
	v_pk_add_f32 v[130:131], v[140:141], v[130:131]
	v_mov_b32_e32 v167, v132
	v_pk_add_f32 v[130:131], v[130:131], v[166:167]
	v_add_u32_e32 v160, v139, v135
	s_nop 0
	v_mov_b32_dpp v132, v130 quad_perm:[1,0,3,2] row_mask:0xf bank_mask:0xf bound_ctrl:1
	v_mov_b32_dpp v133, v131 quad_perm:[1,0,3,2] row_mask:0xf bank_mask:0xf bound_ctrl:1
	v_pk_add_f32 v[130:131], v[130:131], v[132:133]
	s_nop 1
	v_mov_b32_dpp v132, v130 quad_perm:[2,3,0,1] row_mask:0xf bank_mask:0xf bound_ctrl:1
	v_mov_b32_dpp v133, v131 quad_perm:[2,3,0,1] row_mask:0xf bank_mask:0xf bound_ctrl:1
	v_pk_add_f32 v[130:131], v[130:131], v[132:133]
	s_nop 1
	v_mov_b32_dpp v132, v130 row_half_mirror row_mask:0xf bank_mask:0xf bound_ctrl:1
	v_mov_b32_dpp v133, v131 row_half_mirror row_mask:0xf bank_mask:0xf bound_ctrl:1
	v_pk_add_f32 v[130:131], v[130:131], v[132:133]
	s_nop 1
	v_mov_b32_dpp v132, v130 row_mirror row_mask:0xf bank_mask:0xf bound_ctrl:1
	v_mov_b32_dpp v133, v131 row_mirror row_mask:0xf bank_mask:0xf bound_ctrl:1
	s_and_saveexec_b64 s[6:7], vcc
	v_pk_add_f32 v[130:131], v[130:131], v[132:133]
	ds_write_b64 v160, v[130:131]
	s_or_b64 exec, exec, s[6:7]
	v_add_u32_e32 v167, v138, v172
	ds_read2_b32 v[130:131], v167 offset0:128 offset1:160
	ds_read2_b32 v[132:133], v167 offset0:192 offset1:224
	v_add_f32_e32 v82, 0, v115
	v_mul_f32_e32 v115, 0.5, v82
	v_mov_b32_e32 v82, v99
	s_waitcnt lgkmcnt(1)
	v_mul_f32_e32 v137, 0x3fd744fd, v130
	v_pk_add_f32 v[98:99], v[82:83], 0 op_sel_hi:[1,0]
	v_mov_b32_e32 v114, v83
	v_mov_b32_e32 v136, v1
	v_mov_b32_e32 v82, v131
	s_waitcnt lgkmcnt(0)
;   DI void operator()(f32x16 (&acc)[2][4], int grow0, int gcol0, int lane, int w, char* lds) {
;     ...
;       for (int qq = 0; qq < 2; ++qq)
; #pragma unroll
;         for (int e = 0; e < 4; ++e) {
;           const int i = 4 * (2 * (ps & 1) + qq) + e;
;           const float* xr = (const float*)(xs + (8 * qq + 4 * hh + e) * 512) + l31;
;           float s1 = 0.f, s2 = 0.f;
; #pragma unroll
;           for (int nt = 0; nt < 4; ++nt) {
;             float v = (acc[mt][nt][i] + bia[nt]) * csc[nt];
;             float z = ALPHA * xr[nt * 32] + hs * v;
;             acc[mt][nt][i] = z; s1 += z; s2 += z * z;
;           }
;           s1 = row16_sum(s1); s2 = row16_sum(s2);
;           if ((lane & 15) == 0) { f32x2 sv = {s1, s2}; *(f32x2*)(redw + (mt * 32 + (i & 3) + 8 * (i >> 2)) * 2) = sv; }
;         }
	v_mov_b32_e32 v83, v132
	s_mov_b32 s2, s67
	v_pk_add_f32 v[170:171], v[114:115], v[136:137]
	v_pk_mul_f32 v[82:83], v[82:83], s[2:3] op_sel_hi:[1,0]
	v_pk_mul_f32 v[114:115], v[98:99], 0.5 op_sel_hi:[1,0]
	v_pk_fma_f32 v[148:149], v[98:99], 0.5, v[82:83] op_sel_hi:[1,0,1]
	v_mov_b32_e32 v114, v171
	v_mov_b32_e32 v130, v1
	v_mov_b32_e32 v131, v83
	v_pk_mul_f32 v[98:99], v[148:149], v[148:149]
	v_pk_add_f32 v[114:115], v[114:115], v[130:131]
	v_mov_b32_e32 v163, v171
	v_pk_mov_b32 v[82:83], v[82:83], v[98:99] op_sel:[1,0]
	v_pk_add_f32 v[98:99], v[148:149], v[114:115]
	v_pk_mul_f32 v[114:115], v[148:149], v[114:115]
	v_pk_fma_f32 v[82:83], v[170:171], v[162:163], v[82:83]
	v_mov_b32_e32 v99, v115
	v_add_f32_e32 v66, 0, v67
	v_mov_b32_e32 v67, v133
	v_pk_add_f32 v[82:83], v[98:99], v[82:83]
	v_mul_f32_e32 v98, 0x3fd744fd, v133
	v_pk_fma_f32 v[142:143], v[66:67], s[66:67], v[98:99] op_sel_hi:[1,1,0]
	s_nop 0
	v_pk_mul_f32 v[66:67], v[142:143], v[142:143]
	s_nop 0
	v_mov_b32_e32 v143, v66
	v_pk_add_f32 v[66:67], v[82:83], v[142:143]
	s_nop 1
	v_mov_b32_dpp v82, v66 quad_perm:[1,0,3,2] row_mask:0xf bank_mask:0xf bound_ctrl:1
	v_mov_b32_dpp v83, v67 quad_perm:[1,0,3,2] row_mask:0xf bank_mask:0xf bound_ctrl:1
	v_pk_add_f32 v[66:67], v[66:67], v[82:83]
	s_nop 1
	v_mov_b32_dpp v82, v66 quad_perm:[2,3,0,1] row_mask:0xf bank_mask:0xf bound_ctrl:1
	v_mov_b32_dpp v83, v67 quad_perm:[2,3,0,1] row_mask:0xf bank_mask:0xf bound_ctrl:1
	v_pk_add_f32 v[66:67], v[66:67], v[82:83]
	s_nop 1
	v_mov_b32_dpp v82, v66 row_half_mirror row_mask:0xf bank_mask:0xf bound_ctrl:1
	v_mov_b32_dpp v83, v67 row_half_mirror row_mask:0xf bank_mask:0xf bound_ctrl:1
	v_pk_add_f32 v[66:67], v[66:67], v[82:83]
	s_nop 1
	v_mov_b32_dpp v82, v66 row_mirror row_mask:0xf bank_mask:0xf bound_ctrl:1
	v_mov_b32_dpp v83, v67 row_mirror row_mask:0xf bank_mask:0xf bound_ctrl:1
	s_and_saveexec_b64 s[6:7], vcc
	v_pk_add_f32 v[66:67], v[66:67], v[82:83]
	ds_write_b64 v160, v[66:67] offset:8
	s_or_b64 exec, exec, s[6:7]
	v_add_u32_e32 v143, 0x400, v167
	ds_read2_b32 v[66:67], v143 offset1:32
	ds_read2_b32 v[82:83], v143 offset0:64 offset1:96
	v_add_f32_e32 v99, 0, v116
	v_mov_b32_e32 v132, v100
	v_mov_b32_e32 v133, v84
	v_mul_f32_e32 v115, 0.5, v99
	s_waitcnt lgkmcnt(1)
	v_mul_f32_e32 v131, 0x3fd744fd, v66
	v_pk_add_f32 v[132:133], v[132:133], 0 op_sel_hi:[1,0]
	v_mov_b32_e32 v114, v84
	v_mov_b32_e32 v130, v1
	v_mov_b32_e32 v66, v67
	s_waitcnt lgkmcnt(0)
	v_mov_b32_e32 v67, v82
	s_mov_b32 s2, s67
	v_pk_add_f32 v[144:145], v[114:115], v[130:131]
	v_pk_mul_f32 v[114:115], v[66:67], s[2:3] op_sel_hi:[1,0]
	v_pk_mul_f32 v[130:131], v[132:133], 0.5 op_sel_hi:[1,0]
	v_pk_fma_f32 v[66:67], v[132:133], 0.5, v[114:115] op_sel_hi:[1,0,1]
	v_mov_b32_e32 v130, v145
	v_mov_b32_e32 v136, v1
	v_mov_b32_e32 v137, v115
	v_add_f32_e32 v98, 0, v68
	v_mov_b32_e32 v99, v83
	v_pk_mul_f32 v[132:133], v[66:67], v[66:67]
	v_pk_add_f32 v[130:131], v[130:131], v[136:137]
	v_mul_f32_e32 v68, 0x3fd744fd, v83
	v_mov_b32_e32 v163, v145
	v_pk_mov_b32 v[114:115], v[114:115], v[132:133] op_sel:[1,0]
	v_pk_add_f32 v[132:133], v[66:67], v[130:131]
	v_pk_mul_f32 v[130:131], v[66:67], v[130:131]
	v_pk_fma_f32 v[82:83], v[98:99], s[66:67], v[68:69] op_sel_hi:[1,1,0]
	v_pk_fma_f32 v[114:115], v[144:145], v[162:163], v[114:115]
	v_mov_b32_e32 v133, v131
	v_pk_mul_f32 v[98:99], v[82:83], v[82:83]
	v_pk_add_f32 v[114:115], v[132:133], v[114:115]
	v_mov_b32_e32 v83, v98
	v_pk_add_f32 v[98:99], v[114:115], v[82:83]
	s_nop 1
	v_mov_b32_dpp v114, v98 quad_perm:[1,0,3,2] row_mask:0xf bank_mask:0xf bound_ctrl:1
	v_mov_b32_dpp v115, v99 quad_perm:[1,0,3,2] row_mask:0xf bank_mask:0xf bound_ctrl:1
	v_pk_add_f32 v[98:99], v[98:99], v[114:115]
	s_nop 1
	v_mov_b32_dpp v114, v98 quad_perm:[2,3,0,1] row_mask:0xf bank_mask:0xf bound_ctrl:1
	v_mov_b32_dpp v115, v99 quad_perm:[2,3,0,1] row_mask:0xf bank_mask:0xf bound_ctrl:1
	v_pk_add_f32 v[98:99], v[98:99], v[114:115]
	s_nop 1
	v_mov_b32_dpp v114, v98 row_half_mirror row_mask:0xf bank_mask:0xf bound_ctrl:1
	v_mov_b32_dpp v115, v99 row_half_mirror row_mask:0xf bank_mask:0xf bound_ctrl:1
	v_pk_add_f32 v[98:99], v[98:99], v[114:115]
	s_nop 1
	v_mov_b32_dpp v114, v98 row_mirror row_mask:0xf bank_mask:0xf bound_ctrl:1
	v_mov_b32_dpp v115, v99 row_mirror row_mask:0xf bank_mask:0xf bound_ctrl:1
	s_and_saveexec_b64 s[6:7], vcc
	v_pk_add_f32 v[98:99], v[98:99], v[114:115]
	ds_write_b64 v160, v[98:99] offset:16
	s_or_b64 exec, exec, s[6:7]
	v_lshlrev_b32_e32 v139, 9, v134
	v_or_b32_e32 v152, 0x600, v139
	v_add_u32_e32 v144, v138, v152
	ds_read2_b32 v[114:115], v144 offset1:32
	ds_read2_b32 v[130:131], v144 offset0:64 offset1:96
	v_add_f32_e32 v68, 0, v117
	v_add_f32_e32 v116, 0, v69
	v_mul_f32_e32 v69, 0.5, v68
	s_waitcnt lgkmcnt(1)
	v_mul_f32_e32 v99, 0x3fd744fd, v114
	v_mov_b32_e32 v84, v101
	v_mov_b32_e32 v68, v85
	v_mov_b32_e32 v98, v1
	v_pk_add_f32 v[100:101], v[84:85], 0 op_sel_hi:[1,0]
	v_pk_add_f32 v[98:99], v[68:69], v[98:99]
	v_mov_b32_e32 v68, v115
	s_waitcnt lgkmcnt(0)
;   DI void operator()(f32x16 (&acc)[2][4], int grow0, int gcol0, int lane, int w, char* lds) {
;     ...
;       for (int qq = 0; qq < 2; ++qq)
; #pragma unroll
;         for (int e = 0; e < 4; ++e) {
;           const int i = 4 * (2 * (ps & 1) + qq) + e;
;           const float* xr = (const float*)(xs + (8 * qq + 4 * hh + e) * 512) + l31;
;           float s1 = 0.f, s2 = 0.f;
; #pragma unroll
;           for (int nt = 0; nt < 4; ++nt) {
;             float v = (acc[mt][nt][i] + bia[nt]) * csc[nt];
;             float z = ALPHA * xr[nt * 32] + hs * v;
;             acc[mt][nt][i] = z; s1 += z; s2 += z * z;
;           }
;           s1 = row16_sum(s1); s2 = row16_sum(s2);
;           if ((lane & 15) == 0) { f32x2 sv = {s1, s2}; *(f32x2*)(redw + (mt * 32 + (i & 3) + 8 * (i >> 2)) * 2) = sv; }
;         }
	v_mov_b32_e32 v69, v130
	s_mov_b32 s2, s67
	v_pk_mul_f32 v[84:85], v[68:69], s[2:3] op_sel_hi:[1,0]
	v_pk_mul_f32 v[114:115], v[100:101], 0.5 op_sel_hi:[1,0]
	v_pk_fma_f32 v[68:69], v[100:101], 0.5, v[84:85] op_sel_hi:[1,0,1]
	v_mov_b32_e32 v114, v99
	v_mov_b32_e32 v132, v1
	v_mov_b32_e32 v133, v85
	v_pk_mul_f32 v[100:101], v[68:69], v[68:69]
	v_pk_add_f32 v[114:115], v[114:115], v[132:133]
	v_mov_b32_e32 v163, v99
	v_pk_mov_b32 v[84:85], v[84:85], v[100:101] op_sel:[1,0]
	v_pk_add_f32 v[100:101], v[68:69], v[114:115]
	v_pk_mul_f32 v[114:115], v[68:69], v[114:115]
	v_pk_fma_f32 v[84:85], v[98:99], v[162:163], v[84:85]
	v_mov_b32_e32 v101, v115
	v_mov_b32_e32 v117, v131
	v_pk_add_f32 v[100:101], v[100:101], v[84:85]
	v_mul_f32_e32 v84, 0x3fd744fd, v131
	v_pk_fma_f32 v[84:85], v[116:117], s[66:67], v[84:85] op_sel_hi:[1,1,0]
	s_nop 0
	v_pk_mul_f32 v[114:115], v[84:85], v[84:85]
	s_nop 0
	v_mov_b32_e32 v85, v114
	v_pk_add_f32 v[100:101], v[100:101], v[84:85]
	s_nop 1
	v_mov_b32_dpp v114, v100 quad_perm:[1,0,3,2] row_mask:0xf bank_mask:0xf bound_ctrl:1
	v_mov_b32_dpp v115, v101 quad_perm:[1,0,3,2] row_mask:0xf bank_mask:0xf bound_ctrl:1
	v_pk_add_f32 v[100:101], v[100:101], v[114:115]
	s_nop 1
	v_mov_b32_dpp v114, v100 quad_perm:[2,3,0,1] row_mask:0xf bank_mask:0xf bound_ctrl:1
	v_mov_b32_dpp v115, v101 quad_perm:[2,3,0,1] row_mask:0xf bank_mask:0xf bound_ctrl:1
	v_pk_add_f32 v[100:101], v[100:101], v[114:115]
	s_nop 1
	v_mov_b32_dpp v114, v100 row_half_mirror row_mask:0xf bank_mask:0xf bound_ctrl:1
	v_mov_b32_dpp v115, v101 row_half_mirror row_mask:0xf bank_mask:0xf bound_ctrl:1
	v_pk_add_f32 v[100:101], v[100:101], v[114:115]
	s_nop 1
	v_mov_b32_dpp v114, v100 row_mirror row_mask:0xf bank_mask:0xf bound_ctrl:1
	v_mov_b32_dpp v115, v101 row_mirror row_mask:0xf bank_mask:0xf bound_ctrl:1
	s_and_saveexec_b64 s[6:7], vcc
	v_pk_add_f32 v[100:101], v[100:101], v[114:115]
	ds_write_b64 v160, v[100:101] offset:24
	s_or_b64 exec, exec, s[6:7]
	v_add_u32_e32 v83, 0x1000, v167
	ds_read2_b32 v[100:101], v83 offset1:32
	ds_read2_b32 v[114:115], v83 offset0:64 offset1:96
	v_add_f32_e32 v85, 0, v118
	v_mov_b32_e32 v134, v102
	v_mov_b32_e32 v135, v86
	v_mul_f32_e32 v117, 0.5, v85
	s_waitcnt lgkmcnt(1)
	v_mul_f32_e32 v133, 0x3fd744fd, v100
	v_pk_add_f32 v[134:135], v[134:135], 0 op_sel_hi:[1,0]
	v_mov_b32_e32 v116, v86
	v_mov_b32_e32 v132, v1
	v_mov_b32_e32 v100, v101
	s_waitcnt lgkmcnt(0)
	v_mov_b32_e32 v101, v114
	s_mov_b32 s2, s67
	v_pk_add_f32 v[116:117], v[116:117], v[132:133]
	v_pk_mul_f32 v[132:133], v[100:101], s[2:3] op_sel_hi:[1,0]
	v_pk_mul_f32 v[136:137], v[134:135], 0.5 op_sel_hi:[1,0]
	v_pk_fma_f32 v[100:101], v[134:135], 0.5, v[132:133] op_sel_hi:[1,0,1]
	v_mov_b32_e32 v136, v117
	v_mov_b32_e32 v140, v1
	v_mov_b32_e32 v141, v133
	v_add_f32_e32 v130, 0, v70
	v_mov_b32_e32 v131, v115
	v_pk_mul_f32 v[134:135], v[100:101], v[100:101]
	v_pk_add_f32 v[136:137], v[136:137], v[140:141]
	v_mul_f32_e32 v70, 0x3fd744fd, v115
	v_mov_b32_e32 v163, v117
	v_pk_mov_b32 v[132:133], v[132:133], v[134:135] op_sel:[1,0]
	v_pk_add_f32 v[134:135], v[100:101], v[136:137]
	v_pk_mul_f32 v[136:137], v[100:101], v[136:137]
	v_pk_fma_f32 v[114:115], v[130:131], s[66:67], v[70:71] op_sel_hi:[1,1,0]
	v_pk_fma_f32 v[132:133], v[116:117], v[162:163], v[132:133]
	v_mov_b32_e32 v135, v137
	v_pk_mul_f32 v[130:131], v[114:115], v[114:115]
	v_pk_add_f32 v[132:133], v[134:135], v[132:133]
	v_mov_b32_e32 v115, v130
	v_pk_add_f32 v[130:131], v[132:133], v[114:115]
	s_nop 1
	v_mov_b32_dpp v132, v130 quad_perm:[1,0,3,2] row_mask:0xf bank_mask:0xf bound_ctrl:1
	v_mov_b32_dpp v133, v131 quad_perm:[1,0,3,2] row_mask:0xf bank_mask:0xf bound_ctrl:1
	v_pk_add_f32 v[130:131], v[130:131], v[132:133]
	s_nop 1
	v_mov_b32_dpp v132, v130 quad_perm:[2,3,0,1] row_mask:0xf bank_mask:0xf bound_ctrl:1
	v_mov_b32_dpp v133, v131 quad_perm:[2,3,0,1] row_mask:0xf bank_mask:0xf bound_ctrl:1
	v_pk_add_f32 v[130:131], v[130:131], v[132:133]
	s_nop 1
	v_mov_b32_dpp v132, v130 row_half_mirror row_mask:0xf bank_mask:0xf bound_ctrl:1
	v_mov_b32_dpp v133, v131 row_half_mirror row_mask:0xf bank_mask:0xf bound_ctrl:1
	v_pk_add_f32 v[130:131], v[130:131], v[132:133]
	s_nop 1
	v_mov_b32_dpp v132, v130 row_mirror row_mask:0xf bank_mask:0xf bound_ctrl:1
	v_mov_b32_dpp v133, v131 row_mirror row_mask:0xf bank_mask:0xf bound_ctrl:1
	s_and_saveexec_b64 s[6:7], vcc
	v_pk_add_f32 v[130:131], v[130:131], v[132:133]
	ds_write_b64 v160, v[130:131] offset:64
	s_or_b64 exec, exec, s[6:7]
	ds_read2_b32 v[130:131], v83 offset0:128 offset1:160
	ds_read2_b32 v[132:133], v83 offset0:192 offset1:224
	v_add_f32_e32 v70, 0, v119
	v_add_f32_e32 v118, 0, v71
	v_mul_f32_e32 v71, 0.5, v70
	s_waitcnt lgkmcnt(1)
	v_mul_f32_e32 v135, 0x3fd744fd, v130
	v_mov_b32_e32 v86, v103
	v_mov_b32_e32 v70, v87
	v_mov_b32_e32 v134, v1
	v_pk_add_f32 v[136:137], v[86:87], 0 op_sel_hi:[1,0]
	v_pk_add_f32 v[102:103], v[70:71], v[134:135]
	v_mov_b32_e32 v70, v131
	s_waitcnt lgkmcnt(0)
;   DI void operator()(f32x16 (&acc)[2][4], int grow0, int gcol0, int lane, int w, char* lds) {
;     ...
;       for (int qq = 0; qq < 2; ++qq)
; #pragma unroll
;         for (int e = 0; e < 4; ++e) {
;           const int i = 4 * (2 * (ps & 1) + qq) + e;
;           const float* xr = (const float*)(xs + (8 * qq + 4 * hh + e) * 512) + l31;
;           float s1 = 0.f, s2 = 0.f;
; #pragma unroll
;           for (int nt = 0; nt < 4; ++nt) {
;             float v = (acc[mt][nt][i] + bia[nt]) * csc[nt];
;             float z = ALPHA * xr[nt * 32] + hs * v;
;             acc[mt][nt][i] = z; s1 += z; s2 += z * z;
;           }
;           s1 = row16_sum(s1); s2 = row16_sum(s2);
;           if ((lane & 15) == 0) { f32x2 sv = {s1, s2}; *(f32x2*)(redw + (mt * 32 + (i & 3) + 8 * (i >> 2)) * 2) = sv; }
;         }
	v_mov_b32_e32 v71, v132
	s_mov_b32 s2, s67
	v_pk_mul_f32 v[86:87], v[70:71], s[2:3] op_sel_hi:[1,0]
	v_pk_mul_f32 v[130:131], v[136:137], 0.5 op_sel_hi:[1,0]
	v_pk_fma_f32 v[70:71], v[136:137], 0.5, v[86:87] op_sel_hi:[1,0,1]
	v_mov_b32_e32 v130, v103
	v_mov_b32_e32 v136, v1
	v_mov_b32_e32 v137, v87
	v_pk_mul_f32 v[134:135], v[70:71], v[70:71]
	v_pk_add_f32 v[130:131], v[130:131], v[136:137]
	v_mov_b32_e32 v163, v103
	v_pk_mov_b32 v[86:87], v[86:87], v[134:135] op_sel:[1,0]
	v_pk_add_f32 v[134:135], v[70:71], v[130:131]
	v_pk_mul_f32 v[130:131], v[70:71], v[130:131]
	v_pk_fma_f32 v[86:87], v[102:103], v[162:163], v[86:87]
	v_mov_b32_e32 v135, v131
	v_mov_b32_e32 v119, v133
	v_pk_add_f32 v[130:131], v[134:135], v[86:87]
	v_mul_f32_e32 v86, 0x3fd744fd, v133
	v_pk_fma_f32 v[86:87], v[118:119], s[66:67], v[86:87] op_sel_hi:[1,1,0]
	s_nop 0
	v_pk_mul_f32 v[118:119], v[86:87], v[86:87]
	s_nop 0
	v_mov_b32_e32 v87, v118
	v_pk_add_f32 v[118:119], v[130:131], v[86:87]
	s_nop 1
	v_mov_b32_dpp v130, v118 quad_perm:[1,0,3,2] row_mask:0xf bank_mask:0xf bound_ctrl:1
	v_mov_b32_dpp v131, v119 quad_perm:[1,0,3,2] row_mask:0xf bank_mask:0xf bound_ctrl:1
	v_pk_add_f32 v[118:119], v[118:119], v[130:131]
	s_nop 1
	v_mov_b32_dpp v130, v118 quad_perm:[2,3,0,1] row_mask:0xf bank_mask:0xf bound_ctrl:1
	v_mov_b32_dpp v131, v119 quad_perm:[2,3,0,1] row_mask:0xf bank_mask:0xf bound_ctrl:1
	v_pk_add_f32 v[118:119], v[118:119], v[130:131]
	s_nop 1
	v_mov_b32_dpp v130, v118 row_half_mirror row_mask:0xf bank_mask:0xf bound_ctrl:1
	v_mov_b32_dpp v131, v119 row_half_mirror row_mask:0xf bank_mask:0xf bound_ctrl:1
	v_pk_add_f32 v[118:119], v[118:119], v[130:131]
	s_nop 1
	v_mov_b32_dpp v130, v118 row_mirror row_mask:0xf bank_mask:0xf bound_ctrl:1
	v_mov_b32_dpp v131, v119 row_mirror row_mask:0xf bank_mask:0xf bound_ctrl:1
	s_and_saveexec_b64 s[6:7], vcc
	v_pk_add_f32 v[118:119], v[118:119], v[130:131]
	ds_write_b64 v160, v[118:119] offset:72
	s_or_b64 exec, exec, s[6:7]
	v_add_u32_e32 v85, 0x1400, v167
	ds_read2_b32 v[118:119], v85 offset1:32
	ds_read2_b32 v[130:131], v85 offset0:64 offset1:96
	v_add_f32_e32 v87, 0, v120
	v_mov_b32_e32 v140, v104
	v_mov_b32_e32 v141, v88
	v_mul_f32_e32 v133, 0.5, v87
	s_waitcnt lgkmcnt(1)
	v_mul_f32_e32 v137, 0x3fd744fd, v118
	v_pk_add_f32 v[140:141], v[140:141], 0 op_sel_hi:[1,0]
	v_mov_b32_e32 v132, v88
	v_mov_b32_e32 v136, v1
	v_mov_b32_e32 v118, v119
	s_waitcnt lgkmcnt(0)
	v_mov_b32_e32 v119, v130
	s_mov_b32 s2, s67
	v_pk_add_f32 v[132:133], v[132:133], v[136:137]
	v_pk_mul_f32 v[136:137], v[118:119], s[2:3] op_sel_hi:[1,0]
	v_pk_mul_f32 v[146:147], v[140:141], 0.5 op_sel_hi:[1,0]
	v_pk_fma_f32 v[118:119], v[140:141], 0.5, v[136:137] op_sel_hi:[1,0,1]
	v_mov_b32_e32 v146, v133
	v_mov_b32_e32 v150, v1
	v_mov_b32_e32 v151, v137
	v_add_f32_e32 v134, 0, v72
	v_mov_b32_e32 v135, v131
	v_pk_mul_f32 v[140:141], v[118:119], v[118:119]
	v_pk_add_f32 v[146:147], v[146:147], v[150:151]
	v_mul_f32_e32 v72, 0x3fd744fd, v131
	v_mov_b32_e32 v163, v133
	v_pk_mov_b32 v[136:137], v[136:137], v[140:141] op_sel:[1,0]
	v_pk_add_f32 v[140:141], v[118:119], v[146:147]
	v_pk_mul_f32 v[146:147], v[118:119], v[146:147]
	v_pk_fma_f32 v[130:131], v[134:135], s[66:67], v[72:73] op_sel_hi:[1,1,0]
	v_pk_fma_f32 v[136:137], v[132:133], v[162:163], v[136:137]
	v_mov_b32_e32 v141, v147
	v_pk_mul_f32 v[134:135], v[130:131], v[130:131]
	v_pk_add_f32 v[136:137], v[140:141], v[136:137]
	v_mov_b32_e32 v131, v134
	v_pk_add_f32 v[134:135], v[136:137], v[130:131]
	s_nop 1
	v_mov_b32_dpp v136, v134 quad_perm:[1,0,3,2] row_mask:0xf bank_mask:0xf bound_ctrl:1
	v_mov_b32_dpp v137, v135 quad_perm:[1,0,3,2] row_mask:0xf bank_mask:0xf bound_ctrl:1
	v_pk_add_f32 v[134:135], v[134:135], v[136:137]
	s_nop 1
	v_mov_b32_dpp v136, v134 quad_perm:[2,3,0,1] row_mask:0xf bank_mask:0xf bound_ctrl:1
	v_mov_b32_dpp v137, v135 quad_perm:[2,3,0,1] row_mask:0xf bank_mask:0xf bound_ctrl:1
	v_pk_add_f32 v[134:135], v[134:135], v[136:137]
	s_nop 1
	v_mov_b32_dpp v136, v134 row_half_mirror row_mask:0xf bank_mask:0xf bound_ctrl:1
	v_mov_b32_dpp v137, v135 row_half_mirror row_mask:0xf bank_mask:0xf bound_ctrl:1
	v_pk_add_f32 v[134:135], v[134:135], v[136:137]
	s_nop 1
	v_mov_b32_dpp v136, v134 row_mirror row_mask:0xf bank_mask:0xf bound_ctrl:1
	v_mov_b32_dpp v137, v135 row_mirror row_mask:0xf bank_mask:0xf bound_ctrl:1
	s_and_saveexec_b64 s[6:7], vcc
	v_pk_add_f32 v[134:135], v[134:135], v[136:137]
	ds_write_b64 v160, v[134:135] offset:80
	s_or_b64 exec, exec, s[6:7]
	v_or_b32_e32 v115, 0x1600, v139
	v_add_u32_e32 v87, v138, v115
	ds_read2_b32 v[134:135], v87 offset1:32
	ds_read2_b32 v[136:137], v87 offset0:64 offset1:96
	v_add_f32_e32 v72, 0, v121
	v_add_f32_e32 v120, 0, v73
	v_mul_f32_e32 v73, 0.5, v72
	s_waitcnt lgkmcnt(1)
	v_mul_f32_e32 v141, 0x3fd744fd, v134
	v_mov_b32_e32 v88, v105
	v_mov_b32_e32 v72, v89
	v_mov_b32_e32 v140, v1
	v_pk_add_f32 v[146:147], v[88:89], 0 op_sel_hi:[1,0]
	v_pk_add_f32 v[104:105], v[72:73], v[140:141]
	v_mov_b32_e32 v72, v135
	s_waitcnt lgkmcnt(0)
;   DI void xpass(int ps, int grow0, int gcol0, int lane, int w, char* lds) const {
;     char* xs = lds + (ps & 1) * 65536 + __builtin_amdgcn_readfirstlane(w) * 8192;
;     const float* xsrc = Xin + (size_t)(grow0 + (ps >> 1) * 32 + (ps & 1) * 16 + (lane >> 5)) * D_ + gcol0 + (lane & 31) * 4;
; #pragma unroll
;     for (int pc = 0; pc < 8; ++pc)
;       __builtin_amdgcn_global_load_lds((const unsigned*)(xsrc + (size_t)(2 * pc) * D_), (__attribute__((address_space(3))) unsigned*)(xs + pc * 1024), 16, 0, 0);
;   }
;   DI void operator()(f32x16 (&acc)[2][4], int grow0, int gcol0, int lane, int w, char* lds) {
;     ...
;       if (ps + 1 < 4) {
;         if (ps >= 1) asm volatile("s_waitcnt lgkmcnt(0)" ::: "memory");
;         xpass(ps + 1, grow0, gcol0, lane, w, lds);
;         if (ps >= 1) asm volatile("s_waitcnt vmcnt(8)" ::: "memory");
;       } else asm volatile("s_waitcnt vmcnt(0)" ::: "memory");
;       const char* xs = lds + (ps & 1) * 65536 + w * 8192;
; #pragma unroll
;       for (int qq = 0; qq < 2; ++qq)
; #pragma unroll
;         for (int e = 0; e < 4; ++e) {
;           const int i = 4 * (2 * (ps & 1) + qq) + e;
;           const float* xr = (const float*)(xs + (8 * qq + 4 * hh + e) * 512) + l31;
;           float s1 = 0.f, s2 = 0.f;
; #pragma unroll
;           for (int nt = 0; nt < 4; ++nt) {
;             float v = (acc[mt][nt][i] + bia[nt]) * csc[nt];
;             float z = ALPHA * xr[nt * 32] + hs * v;
;             acc[mt][nt][i] = z; s1 += z; s2 += z * z;
;           }
;           s1 = row16_sum(s1); s2 = row16_sum(s2);
;           if ((lane & 15) == 0) { f32x2 sv = {s1, s2}; *(f32x2*)(redw + (mt * 32 + (i & 3) + 8 * (i >> 2)) * 2) = sv; }
;         }
	v_mov_b32_e32 v73, v136
	s_mov_b32 s2, s67
	v_pk_mul_f32 v[88:89], v[72:73], s[2:3] op_sel_hi:[1,0]
	v_pk_mul_f32 v[134:135], v[146:147], 0.5 op_sel_hi:[1,0]
	v_pk_fma_f32 v[72:73], v[146:147], 0.5, v[88:89] op_sel_hi:[1,0,1]
	v_mov_b32_e32 v134, v105
	v_mov_b32_e32 v146, v1
	v_mov_b32_e32 v147, v89
	v_pk_mul_f32 v[140:141], v[72:73], v[72:73]
	v_pk_add_f32 v[134:135], v[134:135], v[146:147]
	v_mov_b32_e32 v163, v105
	v_pk_mov_b32 v[88:89], v[88:89], v[140:141] op_sel:[1,0]
	v_pk_add_f32 v[140:141], v[72:73], v[134:135]
	v_pk_mul_f32 v[134:135], v[72:73], v[134:135]
	v_pk_fma_f32 v[88:89], v[104:105], v[162:163], v[88:89]
	v_mov_b32_e32 v141, v135
	v_mov_b32_e32 v121, v137
	v_pk_add_f32 v[134:135], v[140:141], v[88:89]
	v_mul_f32_e32 v88, 0x3fd744fd, v137
	v_pk_fma_f32 v[88:89], v[120:121], s[66:67], v[88:89] op_sel_hi:[1,1,0]
	s_nop 0
	v_pk_mul_f32 v[120:121], v[88:89], v[88:89]
	s_nop 0
	v_mov_b32_e32 v89, v120
	v_pk_add_f32 v[120:121], v[134:135], v[88:89]
	s_nop 1
	v_mov_b32_dpp v134, v120 quad_perm:[1,0,3,2] row_mask:0xf bank_mask:0xf bound_ctrl:1
	v_mov_b32_dpp v135, v121 quad_perm:[1,0,3,2] row_mask:0xf bank_mask:0xf bound_ctrl:1
	v_pk_add_f32 v[120:121], v[120:121], v[134:135]
	s_nop 1
	v_mov_b32_dpp v134, v120 quad_perm:[2,3,0,1] row_mask:0xf bank_mask:0xf bound_ctrl:1
	v_mov_b32_dpp v135, v121 quad_perm:[2,3,0,1] row_mask:0xf bank_mask:0xf bound_ctrl:1
	v_pk_add_f32 v[120:121], v[120:121], v[134:135]
	s_nop 1
	v_mov_b32_dpp v134, v120 row_half_mirror row_mask:0xf bank_mask:0xf bound_ctrl:1
	v_mov_b32_dpp v135, v121 row_half_mirror row_mask:0xf bank_mask:0xf bound_ctrl:1
	v_pk_add_f32 v[120:121], v[120:121], v[134:135]
	s_nop 1
	v_mov_b32_dpp v134, v120 row_mirror row_mask:0xf bank_mask:0xf bound_ctrl:1
	v_mov_b32_dpp v135, v121 row_mirror row_mask:0xf bank_mask:0xf bound_ctrl:1
	s_and_saveexec_b64 s[6:7], vcc
	v_pk_add_f32 v[120:121], v[120:121], v[134:135]
	ds_write_b64 v160, v[120:121] offset:88
	s_or_b64 exec, exec, s[6:7]
	v_or_b32_e32 v120, 32, v176
	v_ashrrev_i32_e32 v121, 31, v120
	v_readlane_b32 s6, v255, 29
	v_lshlrev_b64 v[120:121], 12, v[120:121]
	v_readlane_b32 s7, v255, 30
	v_readfirstlane_b32 s2, v169
	s_lshl_b32 s2, s2, 13
	v_lshl_add_u64 v[120:121], s[6:7], 0, v[120:121]
	v_lshl_add_u64 v[120:121], v[154:155], 2, v[120:121]
	s_waitcnt lgkmcnt(0)
	v_lshl_add_u64 v[120:121], v[120:121], 0, v[0:1]
	s_mov_b32 m0, s2
	s_mov_b64 s[6:7], 0x2000
	global_load_lds_dwordx4 v[120:121], off
	v_lshl_add_u64 v[134:135], v[120:121], 0, s[6:7]
	s_or_b32 m0, s2, 0x400
	s_mov_b64 s[6:7], 0x4000
	global_load_lds_dwordx4 v[134:135], off
	v_lshl_add_u64 v[134:135], v[120:121], 0, s[6:7]
	s_or_b32 m0, s2, 0x800
	s_mov_b64 s[6:7], 0x6000
	global_load_lds_dwordx4 v[134:135], off
	v_lshl_add_u64 v[134:135], v[120:121], 0, s[6:7]
	s_or_b32 m0, s2, 0xc00
	s_mov_b64 s[6:7], 0x8000
	global_load_lds_dwordx4 v[134:135], off
	v_lshl_add_u64 v[134:135], v[120:121], 0, s[6:7]
	s_or_b32 m0, s2, 0x1000
	s_mov_b64 s[6:7], 0xa000
	global_load_lds_dwordx4 v[134:135], off
	v_lshl_add_u64 v[134:135], v[120:121], 0, s[6:7]
	s_or_b32 m0, s2, 0x1400
	s_mov_b64 s[6:7], 0xc000
	global_load_lds_dwordx4 v[134:135], off
	v_lshl_add_u64 v[134:135], v[120:121], 0, s[6:7]
	s_or_b32 m0, s2, 0x1800
	s_mov_b64 s[6:7], 0xe000
	global_load_lds_dwordx4 v[134:135], off
	v_lshl_add_u64 v[120:121], v[120:121], 0, s[6:7]
	s_or_b32 m0, s2, 0x1c00
	v_add_u32_e32 v116, 0x10000, v138
	global_load_lds_dwordx4 v[120:121], off
	s_waitcnt vmcnt(8)
	v_add_u32_e32 v89, v116, v172
	ds_read2_b32 v[120:121], v89 offset1:32
	ds_read2_b32 v[134:135], v89 offset0:64 offset1:96
	v_add_f32_e32 v98, 0, v122
	v_mov_b32_e32 v146, v106
	v_mov_b32_e32 v147, v90
	s_waitcnt lgkmcnt(0)
	v_mul_f32_e32 v137, 0x3fd744fd, v120
	v_mul_f32_e32 v139, 0.5, v98
	v_pk_add_f32 v[146:147], v[146:147], 0 op_sel_hi:[1,0]
	v_mov_b32_e32 v138, v90
	v_mov_b32_e32 v136, v1
	v_mov_b32_e32 v120, v121
	v_mov_b32_e32 v121, v134
	s_mov_b32 s2, s67
	v_pk_add_f32 v[136:137], v[138:139], v[136:137]
	v_pk_mul_f32 v[138:139], v[120:121], s[2:3] op_sel_hi:[1,0]
	v_pk_mul_f32 v[150:151], v[146:147], 0.5 op_sel_hi:[1,0]
	v_pk_fma_f32 v[120:121], v[146:147], 0.5, v[138:139] op_sel_hi:[1,0,1]
	v_mov_b32_e32 v150, v137
	v_mov_b32_e32 v156, v1
	v_mov_b32_e32 v157, v139
	v_add_f32_e32 v140, 0, v74
	v_mov_b32_e32 v141, v135
	v_pk_mul_f32 v[146:147], v[120:121], v[120:121]
	v_pk_add_f32 v[150:151], v[150:151], v[156:157]
	v_mul_f32_e32 v74, 0x3fd744fd, v135
	v_mov_b32_e32 v163, v137
	v_pk_mov_b32 v[138:139], v[138:139], v[146:147] op_sel:[1,0]
	v_pk_add_f32 v[146:147], v[120:121], v[150:151]
	v_pk_mul_f32 v[150:151], v[120:121], v[150:151]
	v_pk_fma_f32 v[134:135], v[140:141], s[66:67], v[74:75] op_sel_hi:[1,1,0]
	v_pk_fma_f32 v[138:139], v[136:137], v[162:163], v[138:139]
	v_mov_b32_e32 v147, v151
	v_pk_mul_f32 v[140:141], v[134:135], v[134:135]
	v_pk_add_f32 v[138:139], v[146:147], v[138:139]
	v_mov_b32_e32 v135, v140
	v_pk_add_f32 v[138:139], v[138:139], v[134:135]
	s_nop 1
	v_mov_b32_dpp v140, v138 quad_perm:[1,0,3,2] row_mask:0xf bank_mask:0xf bound_ctrl:1
	v_mov_b32_dpp v141, v139 quad_perm:[1,0,3,2] row_mask:0xf bank_mask:0xf bound_ctrl:1
	v_pk_add_f32 v[138:139], v[138:139], v[140:141]
	s_nop 1
	v_mov_b32_dpp v140, v138 quad_perm:[2,3,0,1] row_mask:0xf bank_mask:0xf bound_ctrl:1
	v_mov_b32_dpp v141, v139 quad_perm:[2,3,0,1] row_mask:0xf bank_mask:0xf bound_ctrl:1
	v_pk_add_f32 v[138:139], v[138:139], v[140:141]
	s_nop 1
	v_mov_b32_dpp v140, v138 row_half_mirror row_mask:0xf bank_mask:0xf bound_ctrl:1
	v_mov_b32_dpp v141, v139 row_half_mirror row_mask:0xf bank_mask:0xf bound_ctrl:1
	v_pk_add_f32 v[138:139], v[138:139], v[140:141]
	s_nop 1
	v_mov_b32_dpp v140, v138 row_mirror row_mask:0xf bank_mask:0xf bound_ctrl:1
	v_mov_b32_dpp v141, v139 row_mirror row_mask:0xf bank_mask:0xf bound_ctrl:1
	s_and_saveexec_b64 s[6:7], vcc
	v_pk_add_f32 v[138:139], v[138:139], v[140:141]
	ds_write_b64 v160, v[138:139] offset:128
	s_or_b64 exec, exec, s[6:7]
	v_or_b32_e32 v74, 0x200, v172
	v_add_u32_e32 v98, v116, v74
	ds_read2_b32 v[138:139], v98 offset1:32
	ds_read2_b32 v[140:141], v98 offset0:64 offset1:96
	v_add_f32_e32 v74, 0, v123
	v_add_f32_e32 v122, 0, v75
	v_mul_f32_e32 v75, 0.5, v74
	s_waitcnt lgkmcnt(1)
;   DI void operator()(f32x16 (&acc)[2][4], int grow0, int gcol0, int lane, int w, char* lds) {
;     ...
;       for (int qq = 0; qq < 2; ++qq)
; #pragma unroll
;         for (int e = 0; e < 4; ++e) {
;           const int i = 4 * (2 * (ps & 1) + qq) + e;
;           const float* xr = (const float*)(xs + (8 * qq + 4 * hh + e) * 512) + l31;
;           float s1 = 0.f, s2 = 0.f;
; #pragma unroll
;           for (int nt = 0; nt < 4; ++nt) {
;             float v = (acc[mt][nt][i] + bia[nt]) * csc[nt];
;             float z = ALPHA * xr[nt * 32] + hs * v;
;             acc[mt][nt][i] = z; s1 += z; s2 += z * z;
;           }
;           s1 = row16_sum(s1); s2 = row16_sum(s2);
;           if ((lane & 15) == 0) { f32x2 sv = {s1, s2}; *(f32x2*)(redw + (mt * 32 + (i & 3) + 8 * (i >> 2)) * 2) = sv; }
;         }
	v_mul_f32_e32 v147, 0x3fd744fd, v138
	v_mov_b32_e32 v90, v107
	v_mov_b32_e32 v74, v91
	v_mov_b32_e32 v146, v1
	v_pk_add_f32 v[150:151], v[90:91], 0 op_sel_hi:[1,0]
	v_pk_add_f32 v[106:107], v[74:75], v[146:147]
	v_mov_b32_e32 v74, v139
	s_waitcnt lgkmcnt(0)
	v_mov_b32_e32 v75, v140
	s_mov_b32 s2, s67
	v_pk_mul_f32 v[90:91], v[74:75], s[2:3] op_sel_hi:[1,0]
	v_pk_mul_f32 v[138:139], v[150:151], 0.5 op_sel_hi:[1,0]
	v_pk_fma_f32 v[74:75], v[150:151], 0.5, v[90:91] op_sel_hi:[1,0,1]
	v_mov_b32_e32 v138, v107
	v_mov_b32_e32 v150, v1
	v_mov_b32_e32 v151, v91
	v_pk_mul_f32 v[146:147], v[74:75], v[74:75]
	v_pk_add_f32 v[138:139], v[138:139], v[150:151]
	v_mov_b32_e32 v163, v107
	v_pk_mov_b32 v[90:91], v[90:91], v[146:147] op_sel:[1,0]
	v_pk_add_f32 v[146:147], v[74:75], v[138:139]
	v_pk_mul_f32 v[138:139], v[74:75], v[138:139]
	v_pk_fma_f32 v[90:91], v[106:107], v[162:163], v[90:91]
	v_mov_b32_e32 v147, v139
	v_mov_b32_e32 v123, v141
	v_pk_add_f32 v[138:139], v[146:147], v[90:91]
	v_mul_f32_e32 v90, 0x3fd744fd, v141
	v_pk_fma_f32 v[90:91], v[122:123], s[66:67], v[90:91] op_sel_hi:[1,1,0]
	s_nop 0
	v_pk_mul_f32 v[122:123], v[90:91], v[90:91]
	s_nop 0
	v_mov_b32_e32 v91, v122
	v_pk_add_f32 v[122:123], v[138:139], v[90:91]
	s_nop 1
	v_mov_b32_dpp v138, v122 quad_perm:[1,0,3,2] row_mask:0xf bank_mask:0xf bound_ctrl:1
	v_mov_b32_dpp v139, v123 quad_perm:[1,0,3,2] row_mask:0xf bank_mask:0xf bound_ctrl:1
	v_pk_add_f32 v[122:123], v[122:123], v[138:139]
	s_nop 1
	v_mov_b32_dpp v138, v122 quad_perm:[2,3,0,1] row_mask:0xf bank_mask:0xf bound_ctrl:1
	v_mov_b32_dpp v139, v123 quad_perm:[2,3,0,1] row_mask:0xf bank_mask:0xf bound_ctrl:1
	v_pk_add_f32 v[122:123], v[122:123], v[138:139]
	s_nop 1
	v_mov_b32_dpp v138, v122 row_half_mirror row_mask:0xf bank_mask:0xf bound_ctrl:1
	v_mov_b32_dpp v139, v123 row_half_mirror row_mask:0xf bank_mask:0xf bound_ctrl:1
	v_pk_add_f32 v[122:123], v[122:123], v[138:139]
	s_nop 1
	v_mov_b32_dpp v138, v122 row_mirror row_mask:0xf bank_mask:0xf bound_ctrl:1
	v_mov_b32_dpp v139, v123 row_mirror row_mask:0xf bank_mask:0xf bound_ctrl:1
	s_and_saveexec_b64 s[6:7], vcc
	v_pk_add_f32 v[122:123], v[122:123], v[138:139]
	ds_write_b64 v160, v[122:123] offset:136
	s_or_b64 exec, exec, s[6:7]
	v_or_b32_e32 v91, 0x400, v172
	v_add_u32_e32 v102, v116, v91
	ds_read2_b32 v[122:123], v102 offset1:32
	ds_read2_b32 v[138:139], v102 offset0:64 offset1:96
	v_add_f32_e32 v91, 0, v124
	v_mov_b32_e32 v156, v108
	v_mov_b32_e32 v157, v92
	v_mul_f32_e32 v141, 0.5, v91
	s_waitcnt lgkmcnt(1)
	v_mul_f32_e32 v151, 0x3fd744fd, v122
	v_pk_add_f32 v[156:157], v[156:157], 0 op_sel_hi:[1,0]
	v_mov_b32_e32 v140, v92
	v_mov_b32_e32 v150, v1
	v_mov_b32_e32 v122, v123
	s_waitcnt lgkmcnt(0)
	v_mov_b32_e32 v123, v138
	s_mov_b32 s2, s67
	v_pk_add_f32 v[140:141], v[140:141], v[150:151]
	v_pk_mul_f32 v[150:151], v[122:123], s[2:3] op_sel_hi:[1,0]
	v_pk_mul_f32 v[174:175], v[156:157], 0.5 op_sel_hi:[1,0]
	v_pk_fma_f32 v[122:123], v[156:157], 0.5, v[150:151] op_sel_hi:[1,0,1]
	v_mov_b32_e32 v174, v141
	v_mov_b32_e32 v178, v1
	v_mov_b32_e32 v179, v151
	v_add_f32_e32 v146, 0, v76
	v_mov_b32_e32 v147, v139
	v_pk_mul_f32 v[156:157], v[122:123], v[122:123]
	v_pk_add_f32 v[174:175], v[174:175], v[178:179]
	v_mul_f32_e32 v76, 0x3fd744fd, v139
	v_mov_b32_e32 v163, v141
	v_pk_mov_b32 v[150:151], v[150:151], v[156:157] op_sel:[1,0]
	v_pk_add_f32 v[156:157], v[122:123], v[174:175]
	v_pk_mul_f32 v[174:175], v[122:123], v[174:175]
	v_pk_fma_f32 v[138:139], v[146:147], s[66:67], v[76:77] op_sel_hi:[1,1,0]
	v_pk_fma_f32 v[150:151], v[140:141], v[162:163], v[150:151]
	v_mov_b32_e32 v157, v175
	v_pk_mul_f32 v[146:147], v[138:139], v[138:139]
	v_pk_add_f32 v[150:151], v[156:157], v[150:151]
	v_mov_b32_e32 v139, v146
	v_pk_add_f32 v[146:147], v[150:151], v[138:139]
	s_nop 1
	v_mov_b32_dpp v150, v146 quad_perm:[1,0,3,2] row_mask:0xf bank_mask:0xf bound_ctrl:1
	v_mov_b32_dpp v151, v147 quad_perm:[1,0,3,2] row_mask:0xf bank_mask:0xf bound_ctrl:1
	v_pk_add_f32 v[146:147], v[146:147], v[150:151]
	s_nop 1
	v_mov_b32_dpp v150, v146 quad_perm:[2,3,0,1] row_mask:0xf bank_mask:0xf bound_ctrl:1
	v_mov_b32_dpp v151, v147 quad_perm:[2,3,0,1] row_mask:0xf bank_mask:0xf bound_ctrl:1
	v_pk_add_f32 v[146:147], v[146:147], v[150:151]
	s_nop 1
	v_mov_b32_dpp v150, v146 row_half_mirror row_mask:0xf bank_mask:0xf bound_ctrl:1
	v_mov_b32_dpp v151, v147 row_half_mirror row_mask:0xf bank_mask:0xf bound_ctrl:1
	v_pk_add_f32 v[146:147], v[146:147], v[150:151]
	s_nop 1
	v_mov_b32_dpp v150, v146 row_mirror row_mask:0xf bank_mask:0xf bound_ctrl:1
	v_mov_b32_dpp v151, v147 row_mirror row_mask:0xf bank_mask:0xf bound_ctrl:1
	s_and_saveexec_b64 s[6:7], vcc
	v_pk_add_f32 v[146:147], v[146:147], v[150:151]
	ds_write_b64 v160, v[146:147] offset:144
	s_or_b64 exec, exec, s[6:7]
	v_add_u32_e32 v104, v116, v152
	ds_read2_b32 v[146:147], v104 offset1:32
	ds_read2_b32 v[150:151], v104 offset0:64 offset1:96
	v_add_f32_e32 v76, 0, v125
	v_add_f32_e32 v124, 0, v77
	v_mul_f32_e32 v77, 0.5, v76
	s_waitcnt lgkmcnt(1)
	v_mul_f32_e32 v153, 0x3fd744fd, v146
	v_mov_b32_e32 v92, v109
	v_mov_b32_e32 v76, v93
	v_mov_b32_e32 v152, v1
	v_pk_add_f32 v[156:157], v[92:93], 0 op_sel_hi:[1,0]
	v_pk_add_f32 v[108:109], v[76:77], v[152:153]
	v_mov_b32_e32 v76, v147
	s_waitcnt lgkmcnt(0)
;   DI void operator()(f32x16 (&acc)[2][4], int grow0, int gcol0, int lane, int w, char* lds) {
;     ...
;       for (int qq = 0; qq < 2; ++qq)
; #pragma unroll
;         for (int e = 0; e < 4; ++e) {
;           const int i = 4 * (2 * (ps & 1) + qq) + e;
;           const float* xr = (const float*)(xs + (8 * qq + 4 * hh + e) * 512) + l31;
;           float s1 = 0.f, s2 = 0.f;
; #pragma unroll
;           for (int nt = 0; nt < 4; ++nt) {
;             float v = (acc[mt][nt][i] + bia[nt]) * csc[nt];
;             float z = ALPHA * xr[nt * 32] + hs * v;
;             acc[mt][nt][i] = z; s1 += z; s2 += z * z;
;           }
;           s1 = row16_sum(s1); s2 = row16_sum(s2);
;           if ((lane & 15) == 0) { f32x2 sv = {s1, s2}; *(f32x2*)(redw + (mt * 32 + (i & 3) + 8 * (i >> 2)) * 2) = sv; }
;         }
	v_mov_b32_e32 v77, v150
	s_mov_b32 s2, s67
	v_pk_mul_f32 v[92:93], v[76:77], s[2:3] op_sel_hi:[1,0]
	v_pk_mul_f32 v[146:147], v[156:157], 0.5 op_sel_hi:[1,0]
	v_pk_fma_f32 v[76:77], v[156:157], 0.5, v[92:93] op_sel_hi:[1,0,1]
	v_mov_b32_e32 v146, v109
	v_mov_b32_e32 v156, v1
	v_mov_b32_e32 v157, v93
	v_pk_mul_f32 v[152:153], v[76:77], v[76:77]
	v_pk_add_f32 v[146:147], v[146:147], v[156:157]
	v_mov_b32_e32 v163, v109
	v_pk_mov_b32 v[92:93], v[92:93], v[152:153] op_sel:[1,0]
	v_pk_add_f32 v[152:153], v[76:77], v[146:147]
	v_pk_mul_f32 v[146:147], v[76:77], v[146:147]
	v_pk_fma_f32 v[92:93], v[108:109], v[162:163], v[92:93]
	v_mov_b32_e32 v153, v147
	v_mov_b32_e32 v125, v151
	v_pk_add_f32 v[146:147], v[152:153], v[92:93]
	v_mul_f32_e32 v92, 0x3fd744fd, v151
	v_pk_fma_f32 v[92:93], v[124:125], s[66:67], v[92:93] op_sel_hi:[1,1,0]
	s_nop 0
	v_pk_mul_f32 v[124:125], v[92:93], v[92:93]
	s_nop 0
	v_mov_b32_e32 v93, v124
	v_pk_add_f32 v[124:125], v[146:147], v[92:93]
	s_nop 1
	v_mov_b32_dpp v146, v124 quad_perm:[1,0,3,2] row_mask:0xf bank_mask:0xf bound_ctrl:1
	v_mov_b32_dpp v147, v125 quad_perm:[1,0,3,2] row_mask:0xf bank_mask:0xf bound_ctrl:1
	v_pk_add_f32 v[124:125], v[124:125], v[146:147]
	s_nop 1
	v_mov_b32_dpp v146, v124 quad_perm:[2,3,0,1] row_mask:0xf bank_mask:0xf bound_ctrl:1
	v_mov_b32_dpp v147, v125 quad_perm:[2,3,0,1] row_mask:0xf bank_mask:0xf bound_ctrl:1
	v_pk_add_f32 v[124:125], v[124:125], v[146:147]
	s_nop 1
	v_mov_b32_dpp v146, v124 row_half_mirror row_mask:0xf bank_mask:0xf bound_ctrl:1
	v_mov_b32_dpp v147, v125 row_half_mirror row_mask:0xf bank_mask:0xf bound_ctrl:1
	v_pk_add_f32 v[124:125], v[124:125], v[146:147]
	s_nop 1
	v_mov_b32_dpp v146, v124 row_mirror row_mask:0xf bank_mask:0xf bound_ctrl:1
	v_mov_b32_dpp v147, v125 row_mirror row_mask:0xf bank_mask:0xf bound_ctrl:1
	s_and_saveexec_b64 s[6:7], vcc
	v_pk_add_f32 v[124:125], v[124:125], v[146:147]
	ds_write_b64 v160, v[124:125] offset:152
	s_or_b64 exec, exec, s[6:7]
	v_or_b32_e32 v91, 0x1000, v172
	v_add_u32_e32 v93, v116, v91
	ds_read2_b32 v[124:125], v93 offset1:32
	ds_read2_b32 v[146:147], v93 offset0:64 offset1:96
	v_add_f32_e32 v91, 0, v126
	v_mov_b32_e32 v174, v110
	v_mov_b32_e32 v175, v94
	v_mul_f32_e32 v151, 0.5, v91
	s_waitcnt lgkmcnt(1)
	v_mul_f32_e32 v157, 0x3fd744fd, v124
	v_pk_add_f32 v[174:175], v[174:175], 0 op_sel_hi:[1,0]
	v_mov_b32_e32 v150, v94
	v_mov_b32_e32 v156, v1
	v_mov_b32_e32 v124, v125
	s_waitcnt lgkmcnt(0)
	v_mov_b32_e32 v125, v146
	s_mov_b32 s2, s67
	v_pk_add_f32 v[150:151], v[150:151], v[156:157]
	v_pk_mul_f32 v[156:157], v[124:125], s[2:3] op_sel_hi:[1,0]
	v_pk_mul_f32 v[178:179], v[174:175], 0.5 op_sel_hi:[1,0]
	v_pk_fma_f32 v[124:125], v[174:175], 0.5, v[156:157] op_sel_hi:[1,0,1]
	v_mov_b32_e32 v178, v151
	v_mov_b32_e32 v180, v1
	v_mov_b32_e32 v181, v157
	v_add_f32_e32 v152, 0, v78
	v_mov_b32_e32 v153, v147
	v_pk_mul_f32 v[174:175], v[124:125], v[124:125]
	v_pk_add_f32 v[178:179], v[178:179], v[180:181]
	v_mul_f32_e32 v78, 0x3fd744fd, v147
	v_mov_b32_e32 v163, v151
	v_pk_mov_b32 v[156:157], v[156:157], v[174:175] op_sel:[1,0]
	v_pk_add_f32 v[174:175], v[124:125], v[178:179]
	v_pk_mul_f32 v[178:179], v[124:125], v[178:179]
	v_pk_fma_f32 v[146:147], v[152:153], s[66:67], v[78:79] op_sel_hi:[1,1,0]
	v_pk_fma_f32 v[156:157], v[150:151], v[162:163], v[156:157]
	v_mov_b32_e32 v175, v179
	v_pk_mul_f32 v[152:153], v[146:147], v[146:147]
	v_pk_add_f32 v[156:157], v[174:175], v[156:157]
	v_mov_b32_e32 v147, v152
	v_pk_add_f32 v[152:153], v[156:157], v[146:147]
	s_nop 1
	v_mov_b32_dpp v156, v152 quad_perm:[1,0,3,2] row_mask:0xf bank_mask:0xf bound_ctrl:1
	v_mov_b32_dpp v157, v153 quad_perm:[1,0,3,2] row_mask:0xf bank_mask:0xf bound_ctrl:1
	v_pk_add_f32 v[152:153], v[152:153], v[156:157]
	s_nop 1
	v_mov_b32_dpp v156, v152 quad_perm:[2,3,0,1] row_mask:0xf bank_mask:0xf bound_ctrl:1
	v_mov_b32_dpp v157, v153 quad_perm:[2,3,0,1] row_mask:0xf bank_mask:0xf bound_ctrl:1
	v_pk_add_f32 v[152:153], v[152:153], v[156:157]
	s_nop 1
	v_mov_b32_dpp v156, v152 row_half_mirror row_mask:0xf bank_mask:0xf bound_ctrl:1
	v_mov_b32_dpp v157, v153 row_half_mirror row_mask:0xf bank_mask:0xf bound_ctrl:1
	v_pk_add_f32 v[152:153], v[152:153], v[156:157]
	s_nop 1
	v_mov_b32_dpp v156, v152 row_mirror row_mask:0xf bank_mask:0xf bound_ctrl:1
	v_mov_b32_dpp v157, v153 row_mirror row_mask:0xf bank_mask:0xf bound_ctrl:1
	s_and_saveexec_b64 s[6:7], vcc
	v_pk_add_f32 v[152:153], v[152:153], v[156:157]
	ds_write_b64 v160, v[152:153] offset:192
	s_or_b64 exec, exec, s[6:7]
	v_or_b32_e32 v78, 0x1200, v172
	v_add_u32_e32 v106, v116, v78
	ds_read2_b32 v[152:153], v106 offset1:32
	ds_read2_b32 v[156:157], v106 offset0:64 offset1:96
	v_add_f32_e32 v78, 0, v127
	v_add_f32_e32 v126, 0, v79
	v_mul_f32_e32 v79, 0.5, v78
	s_waitcnt lgkmcnt(1)
	v_mul_f32_e32 v175, 0x3fd744fd, v152
	v_mov_b32_e32 v94, v111
	v_mov_b32_e32 v78, v95
	v_mov_b32_e32 v174, v1
	v_pk_add_f32 v[178:179], v[94:95], 0 op_sel_hi:[1,0]
	v_pk_add_f32 v[110:111], v[78:79], v[174:175]
	v_mov_b32_e32 v78, v153
	s_waitcnt lgkmcnt(0)
;   DI void operator()(f32x16 (&acc)[2][4], int grow0, int gcol0, int lane, int w, char* lds) {
;     ...
;       for (int qq = 0; qq < 2; ++qq)
; #pragma unroll
;         for (int e = 0; e < 4; ++e) {
;           const int i = 4 * (2 * (ps & 1) + qq) + e;
;           const float* xr = (const float*)(xs + (8 * qq + 4 * hh + e) * 512) + l31;
;           float s1 = 0.f, s2 = 0.f;
; #pragma unroll
;           for (int nt = 0; nt < 4; ++nt) {
;             float v = (acc[mt][nt][i] + bia[nt]) * csc[nt];
;             float z = ALPHA * xr[nt * 32] + hs * v;
;             acc[mt][nt][i] = z; s1 += z; s2 += z * z;
;           }
;           s1 = row16_sum(s1); s2 = row16_sum(s2);
;           if ((lane & 15) == 0) { f32x2 sv = {s1, s2}; *(f32x2*)(redw + (mt * 32 + (i & 3) + 8 * (i >> 2)) * 2) = sv; }
;         }
	v_mov_b32_e32 v79, v156
	s_mov_b32 s2, s67
	v_pk_mul_f32 v[94:95], v[78:79], s[2:3] op_sel_hi:[1,0]
	v_pk_mul_f32 v[152:153], v[178:179], 0.5 op_sel_hi:[1,0]
	v_pk_fma_f32 v[78:79], v[178:179], 0.5, v[94:95] op_sel_hi:[1,0,1]
	v_mov_b32_e32 v152, v111
	v_mov_b32_e32 v178, v1
	v_mov_b32_e32 v179, v95
	v_pk_mul_f32 v[174:175], v[78:79], v[78:79]
	v_pk_add_f32 v[152:153], v[152:153], v[178:179]
	v_mov_b32_e32 v163, v111
	v_pk_mov_b32 v[94:95], v[94:95], v[174:175] op_sel:[1,0]
	v_pk_add_f32 v[174:175], v[78:79], v[152:153]
	v_pk_mul_f32 v[152:153], v[78:79], v[152:153]
	v_pk_fma_f32 v[94:95], v[110:111], v[162:163], v[94:95]
	v_mov_b32_e32 v175, v153
	v_mov_b32_e32 v127, v157
	v_pk_add_f32 v[152:153], v[174:175], v[94:95]
	v_mul_f32_e32 v94, 0x3fd744fd, v157
	v_pk_fma_f32 v[94:95], v[126:127], s[66:67], v[94:95] op_sel_hi:[1,1,0]
	s_nop 0
	v_pk_mul_f32 v[126:127], v[94:95], v[94:95]
	s_nop 0
	v_mov_b32_e32 v95, v126
	v_pk_add_f32 v[126:127], v[152:153], v[94:95]
	s_nop 1
	v_mov_b32_dpp v152, v126 quad_perm:[1,0,3,2] row_mask:0xf bank_mask:0xf bound_ctrl:1
	v_mov_b32_dpp v153, v127 quad_perm:[1,0,3,2] row_mask:0xf bank_mask:0xf bound_ctrl:1
	v_pk_add_f32 v[126:127], v[126:127], v[152:153]
	s_nop 1
	v_mov_b32_dpp v152, v126 quad_perm:[2,3,0,1] row_mask:0xf bank_mask:0xf bound_ctrl:1
	v_mov_b32_dpp v153, v127 quad_perm:[2,3,0,1] row_mask:0xf bank_mask:0xf bound_ctrl:1
	v_pk_add_f32 v[126:127], v[126:127], v[152:153]
	s_nop 1
	v_mov_b32_dpp v152, v126 row_half_mirror row_mask:0xf bank_mask:0xf bound_ctrl:1
	v_mov_b32_dpp v153, v127 row_half_mirror row_mask:0xf bank_mask:0xf bound_ctrl:1
	v_pk_add_f32 v[126:127], v[126:127], v[152:153]
	s_nop 1
	v_mov_b32_dpp v152, v126 row_mirror row_mask:0xf bank_mask:0xf bound_ctrl:1
	v_mov_b32_dpp v153, v127 row_mirror row_mask:0xf bank_mask:0xf bound_ctrl:1
	s_and_saveexec_b64 s[6:7], vcc
	v_pk_add_f32 v[126:127], v[126:127], v[152:153]
	ds_write_b64 v160, v[126:127] offset:200
	s_or_b64 exec, exec, s[6:7]
	v_or_b32_e32 v91, 0x1400, v172
	v_add_u32_e32 v95, v116, v91
	ds_read2_b32 v[126:127], v95 offset1:32
	ds_read2_b32 v[152:153], v95 offset0:64 offset1:96
	v_add_f32_e32 v91, 0, v128
	v_mov_b32_e32 v178, v112
	v_mov_b32_e32 v179, v96
	v_mul_f32_e32 v157, 0.5, v91
	s_waitcnt lgkmcnt(1)
	v_mul_f32_e32 v175, 0x3fd744fd, v126
	v_pk_add_f32 v[178:179], v[178:179], 0 op_sel_hi:[1,0]
	v_mov_b32_e32 v156, v96
	v_mov_b32_e32 v174, v1
	v_mov_b32_e32 v126, v127
	s_waitcnt lgkmcnt(0)
	v_mov_b32_e32 v127, v152
	s_mov_b32 s2, s67
	v_pk_add_f32 v[156:157], v[156:157], v[174:175]
	v_pk_mul_f32 v[174:175], v[126:127], s[2:3] op_sel_hi:[1,0]
	v_pk_mul_f32 v[180:181], v[178:179], 0.5 op_sel_hi:[1,0]
	v_pk_fma_f32 v[126:127], v[178:179], 0.5, v[174:175] op_sel_hi:[1,0,1]
	v_mov_b32_e32 v180, v157
	v_mov_b32_e32 v182, v1
	v_mov_b32_e32 v183, v175
	v_add_f32_e32 v172, 0, v80
	v_mov_b32_e32 v173, v153
	v_pk_mul_f32 v[178:179], v[126:127], v[126:127]
	v_pk_add_f32 v[180:181], v[180:181], v[182:183]
	v_mul_f32_e32 v80, 0x3fd744fd, v153
	v_mov_b32_e32 v163, v157
	v_pk_mov_b32 v[174:175], v[174:175], v[178:179] op_sel:[1,0]
	v_pk_add_f32 v[178:179], v[126:127], v[180:181]
	v_pk_mul_f32 v[180:181], v[126:127], v[180:181]
	v_pk_fma_f32 v[152:153], v[172:173], s[66:67], v[80:81] op_sel_hi:[1,1,0]
	v_pk_fma_f32 v[174:175], v[156:157], v[162:163], v[174:175]
	v_mov_b32_e32 v179, v181
	v_pk_mul_f32 v[172:173], v[152:153], v[152:153]
	v_pk_add_f32 v[174:175], v[178:179], v[174:175]
	v_mov_b32_e32 v153, v172
	v_pk_add_f32 v[172:173], v[174:175], v[152:153]
	s_nop 1
	v_mov_b32_dpp v174, v172 quad_perm:[1,0,3,2] row_mask:0xf bank_mask:0xf bound_ctrl:1
	v_mov_b32_dpp v175, v173 quad_perm:[1,0,3,2] row_mask:0xf bank_mask:0xf bound_ctrl:1
	v_pk_add_f32 v[172:173], v[172:173], v[174:175]
	s_nop 1
	v_mov_b32_dpp v174, v172 quad_perm:[2,3,0,1] row_mask:0xf bank_mask:0xf bound_ctrl:1
	v_mov_b32_dpp v175, v173 quad_perm:[2,3,0,1] row_mask:0xf bank_mask:0xf bound_ctrl:1
	v_pk_add_f32 v[172:173], v[172:173], v[174:175]
	s_nop 1
	v_mov_b32_dpp v174, v172 row_half_mirror row_mask:0xf bank_mask:0xf bound_ctrl:1
	v_mov_b32_dpp v175, v173 row_half_mirror row_mask:0xf bank_mask:0xf bound_ctrl:1
	v_pk_add_f32 v[172:173], v[172:173], v[174:175]
	s_nop 1
	v_mov_b32_dpp v174, v172 row_mirror row_mask:0xf bank_mask:0xf bound_ctrl:1
	v_mov_b32_dpp v175, v173 row_mirror row_mask:0xf bank_mask:0xf bound_ctrl:1
	s_and_saveexec_b64 s[6:7], vcc
	v_pk_add_f32 v[172:173], v[172:173], v[174:175]
	ds_write_b64 v160, v[172:173] offset:208
	s_or_b64 exec, exec, s[6:7]
	v_add_u32_e32 v91, v116, v115
	v_add_f32_e32 v80, 0, v129
	ds_read2_b32 v[128:129], v91 offset1:32
	ds_read2_b32 v[178:179], v91 offset0:64 offset1:96
	v_mov_b32_e32 v96, v113
	v_mul_f32_e32 v175, 0.5, v80
	v_add_f32_e32 v180, 0, v81
	s_waitcnt lgkmcnt(1)
	v_mul_f32_e32 v173, 0x3fd744fd, v128
	v_pk_add_f32 v[80:81], v[96:97], 0 op_sel_hi:[1,0]
	v_mov_b32_e32 v174, v97
	v_mov_b32_e32 v172, v1
	v_mov_b32_e32 v96, v129
	s_waitcnt lgkmcnt(0)
;   DI void xpass(int ps, int grow0, int gcol0, int lane, int w, char* lds) const {
;     char* xs = lds + (ps & 1) * 65536 + __builtin_amdgcn_readfirstlane(w) * 8192;
;     const float* xsrc = Xin + (size_t)(grow0 + (ps >> 1) * 32 + (ps & 1) * 16 + (lane >> 5)) * D_ + gcol0 + (lane & 31) * 4;
; #pragma unroll
;     for (int pc = 0; pc < 8; ++pc)
;       __builtin_amdgcn_global_load_lds((const unsigned*)(xsrc + (size_t)(2 * pc) * D_), (__attribute__((address_space(3))) unsigned*)(xs + pc * 1024), 16, 0, 0);
;   }
;   DI void operator()(f32x16 (&acc)[2][4], int grow0, int gcol0, int lane, int w, char* lds) {
;     ...
;       if (ps + 1 < 4) {
;         if (ps >= 1) asm volatile("s_waitcnt lgkmcnt(0)" ::: "memory");
;         xpass(ps + 1, grow0, gcol0, lane, w, lds);
;         if (ps >= 1) asm volatile("s_waitcnt vmcnt(8)" ::: "memory");
;       } else asm volatile("s_waitcnt vmcnt(0)" ::: "memory");
;       const char* xs = lds + (ps & 1) * 65536 + w * 8192;
; #pragma unroll
;       for (int qq = 0; qq < 2; ++qq)
; #pragma unroll
;         for (int e = 0; e < 4; ++e) {
;           const int i = 4 * (2 * (ps & 1) + qq) + e;
;           const float* xr = (const float*)(xs + (8 * qq + 4 * hh + e) * 512) + l31;
;           float s1 = 0.f, s2 = 0.f;
; #pragma unroll
;           for (int nt = 0; nt < 4; ++nt) {
;             float v = (acc[mt][nt][i] + bia[nt]) * csc[nt];
;             float z = ALPHA * xr[nt * 32] + hs * v;
;             acc[mt][nt][i] = z; s1 += z; s2 += z * z;
;           }
;           s1 = row16_sum(s1); s2 = row16_sum(s2);
;           if ((lane & 15) == 0) { f32x2 sv = {s1, s2}; *(f32x2*)(redw + (mt * 32 + (i & 3) + 8 * (i >> 2)) * 2) = sv; }
;         }
	v_mov_b32_e32 v97, v178
	s_mov_b32 s2, s67
	v_pk_add_f32 v[112:113], v[174:175], v[172:173]
	v_pk_mul_f32 v[96:97], v[96:97], s[2:3] op_sel_hi:[1,0]
	v_pk_mul_f32 v[128:129], v[80:81], 0.5 op_sel_hi:[1,0]
	v_pk_fma_f32 v[80:81], v[80:81], 0.5, v[96:97] op_sel_hi:[1,0,1]
	v_mov_b32_e32 v128, v113
	v_mov_b32_e32 v174, v1
	v_mov_b32_e32 v175, v97
	v_pk_mul_f32 v[172:173], v[80:81], v[80:81]
	v_pk_add_f32 v[128:129], v[128:129], v[174:175]
	v_mov_b32_e32 v163, v113
	v_pk_mov_b32 v[96:97], v[96:97], v[172:173] op_sel:[1,0]
	v_pk_add_f32 v[172:173], v[80:81], v[128:129]
	v_pk_mul_f32 v[128:129], v[80:81], v[128:129]
	v_pk_fma_f32 v[96:97], v[112:113], v[162:163], v[96:97]
	v_mov_b32_e32 v173, v129
	v_mov_b32_e32 v181, v179
	v_pk_add_f32 v[128:129], v[172:173], v[96:97]
	v_mul_f32_e32 v96, 0x3fd744fd, v179
	v_pk_fma_f32 v[96:97], v[180:181], s[66:67], v[96:97] op_sel_hi:[1,1,0]
	s_nop 0
	v_pk_mul_f32 v[172:173], v[96:97], v[96:97]
	s_nop 0
	v_mov_b32_e32 v97, v172
	v_pk_add_f32 v[128:129], v[128:129], v[96:97]
	s_nop 1
	v_mov_b32_dpp v172, v128 quad_perm:[1,0,3,2] row_mask:0xf bank_mask:0xf bound_ctrl:1
	v_mov_b32_dpp v173, v129 quad_perm:[1,0,3,2] row_mask:0xf bank_mask:0xf bound_ctrl:1
	v_pk_add_f32 v[128:129], v[128:129], v[172:173]
	s_nop 1
	v_mov_b32_dpp v172, v128 quad_perm:[2,3,0,1] row_mask:0xf bank_mask:0xf bound_ctrl:1
	v_mov_b32_dpp v173, v129 quad_perm:[2,3,0,1] row_mask:0xf bank_mask:0xf bound_ctrl:1
	v_pk_add_f32 v[128:129], v[128:129], v[172:173]
	s_nop 1
	v_mov_b32_dpp v172, v128 row_half_mirror row_mask:0xf bank_mask:0xf bound_ctrl:1
	v_mov_b32_dpp v173, v129 row_half_mirror row_mask:0xf bank_mask:0xf bound_ctrl:1
	v_pk_add_f32 v[128:129], v[128:129], v[172:173]
	s_nop 1
	v_mov_b32_dpp v172, v128 row_mirror row_mask:0xf bank_mask:0xf bound_ctrl:1
	v_mov_b32_dpp v173, v129 row_mirror row_mask:0xf bank_mask:0xf bound_ctrl:1
	s_and_saveexec_b64 s[6:7], vcc
	v_pk_add_f32 v[128:129], v[128:129], v[172:173]
	ds_write_b64 v160, v[128:129] offset:216
	s_or_b64 exec, exec, s[6:7]
	v_or_b32_e32 v128, 48, v176
	v_ashrrev_i32_e32 v129, 31, v128
	v_readlane_b32 s6, v255, 29
	v_lshlrev_b64 v[128:129], 12, v[128:129]
	v_readlane_b32 s7, v255, 30
	v_readfirstlane_b32 s2, v169
	s_lshl_b32 s2, s2, 13
	v_lshl_add_u64 v[128:129], s[6:7], 0, v[128:129]
	v_lshl_add_u64 v[128:129], v[154:155], 2, v[128:129]
	s_waitcnt lgkmcnt(0)
	s_add_i32 m0, s2, 0x10000
	v_lshl_add_u64 v[128:129], v[128:129], 0, v[0:1]
	s_mov_b64 s[6:7], 0x2000
	global_load_lds_dwordx4 v[128:129], off
	v_lshl_add_u64 v[172:173], v[128:129], 0, s[6:7]
	s_add_i32 m0, s2, 0x10400
	s_mov_b64 s[6:7], 0x4000
	global_load_lds_dwordx4 v[172:173], off
	v_lshl_add_u64 v[172:173], v[128:129], 0, s[6:7]
	s_add_i32 m0, s2, 0x10800
	s_mov_b64 s[6:7], 0x6000
	global_load_lds_dwordx4 v[172:173], off
	v_lshl_add_u64 v[172:173], v[128:129], 0, s[6:7]
	s_add_i32 m0, s2, 0x10c00
	s_mov_b64 s[6:7], 0x8000
	global_load_lds_dwordx4 v[172:173], off
	v_lshl_add_u64 v[172:173], v[128:129], 0, s[6:7]
	s_add_i32 m0, s2, 0x11000
	s_mov_b64 s[6:7], 0xa000
	global_load_lds_dwordx4 v[172:173], off
	v_lshl_add_u64 v[172:173], v[128:129], 0, s[6:7]
	s_add_i32 m0, s2, 0x11400
	s_mov_b64 s[6:7], 0xc000
	global_load_lds_dwordx4 v[172:173], off
	v_lshl_add_u64 v[172:173], v[128:129], 0, s[6:7]
	s_add_i32 m0, s2, 0x11800
	s_mov_b64 s[6:7], 0xe000
	global_load_lds_dwordx4 v[172:173], off
	v_lshl_add_u64 v[128:129], v[128:129], 0, s[6:7]
	s_add_i32 m0, s2, 0x11c00
	v_add_f32_e32 v0, 0, v50
	global_load_lds_dwordx4 v[128:129], off
	s_waitcnt vmcnt(8)
	ds_read2_b32 v[128:129], v167 offset1:32
	ds_read2_b32 v[172:173], v167 offset0:64 offset1:96
	v_mov_b32_e32 v180, v34
	v_mov_b32_e32 v181, v18
	v_mul_f32_e32 v177, 0.5, v0
	s_waitcnt lgkmcnt(0)
	v_mul_f32_e32 v175, 0x3fd744fd, v128
	v_pk_add_f32 v[180:181], v[180:181], 0 op_sel_hi:[1,0]
	v_mov_b32_e32 v176, v18
	v_mov_b32_e32 v174, v1
	v_mov_b32_e32 v128, v129
	v_mov_b32_e32 v129, v172
	s_mov_b32 s2, s67
	v_pk_add_f32 v[174:175], v[176:177], v[174:175]
	v_pk_mul_f32 v[176:177], v[128:129], s[2:3] op_sel_hi:[1,0]
	v_pk_mul_f32 v[182:183], v[180:181], 0.5 op_sel_hi:[1,0]
	v_pk_fma_f32 v[128:129], v[180:181], 0.5, v[176:177] op_sel_hi:[1,0,1]
	v_mov_b32_e32 v182, v175
	v_mov_b32_e32 v184, v1
	v_mov_b32_e32 v185, v177
	v_add_f32_e32 v178, 0, v2
	v_mov_b32_e32 v179, v173
	v_pk_mul_f32 v[180:181], v[128:129], v[128:129]
	v_pk_add_f32 v[182:183], v[182:183], v[184:185]
	v_mul_f32_e32 v0, 0x3fd744fd, v173
	v_mov_b32_e32 v163, v175
	v_pk_mov_b32 v[176:177], v[176:177], v[180:181] op_sel:[1,0]
	v_pk_add_f32 v[180:181], v[128:129], v[182:183]
	v_pk_mul_f32 v[182:183], v[128:129], v[182:183]
	v_pk_fma_f32 v[172:173], v[178:179], s[66:67], v[0:1] op_sel_hi:[1,1,0]
	v_pk_fma_f32 v[176:177], v[174:175], v[162:163], v[176:177]
	v_mov_b32_e32 v181, v183
	v_pk_mul_f32 v[178:179], v[172:173], v[172:173]
	v_pk_add_f32 v[176:177], v[180:181], v[176:177]
	v_mov_b32_e32 v173, v178
	v_pk_add_f32 v[176:177], v[176:177], v[172:173]
	s_nop 1
	v_mov_b32_dpp v178, v176 quad_perm:[1,0,3,2] row_mask:0xf bank_mask:0xf bound_ctrl:1
	v_mov_b32_dpp v179, v177 quad_perm:[1,0,3,2] row_mask:0xf bank_mask:0xf bound_ctrl:1
	v_pk_add_f32 v[176:177], v[176:177], v[178:179]
	s_nop 1
	v_mov_b32_dpp v178, v176 quad_perm:[2,3,0,1] row_mask:0xf bank_mask:0xf bound_ctrl:1
	v_mov_b32_dpp v179, v177 quad_perm:[2,3,0,1] row_mask:0xf bank_mask:0xf bound_ctrl:1
	v_pk_add_f32 v[176:177], v[176:177], v[178:179]
	s_nop 1
	v_mov_b32_dpp v178, v176 row_half_mirror row_mask:0xf bank_mask:0xf bound_ctrl:1
	v_mov_b32_dpp v179, v177 row_half_mirror row_mask:0xf bank_mask:0xf bound_ctrl:1
	v_pk_add_f32 v[176:177], v[176:177], v[178:179]
	s_nop 1
	v_mov_b32_dpp v178, v176 row_mirror row_mask:0xf bank_mask:0xf bound_ctrl:1
	v_mov_b32_dpp v179, v177 row_mirror row_mask:0xf bank_mask:0xf bound_ctrl:1
	s_and_saveexec_b64 s[6:7], vcc
	v_pk_add_f32 v[176:177], v[176:177], v[178:179]
	ds_write_b64 v160, v[176:177] offset:256
	s_or_b64 exec, exec, s[6:7]
	ds_read2_b32 v[176:177], v167 offset0:128 offset1:160
	ds_read2_b32 v[178:179], v167 offset0:192 offset1:224
	v_add_f32_e32 v0, 0, v51
	v_add_f32_e32 v50, 0, v3
	v_mul_f32_e32 v3, 0.5, v0
	s_waitcnt lgkmcnt(1)
;   DI void operator()(f32x16 (&acc)[2][4], int grow0, int gcol0, int lane, int w, char* lds) {
;     ...
;       for (int qq = 0; qq < 2; ++qq)
; #pragma unroll
;         for (int e = 0; e < 4; ++e) {
;           const int i = 4 * (2 * (ps & 1) + qq) + e;
;           const float* xr = (const float*)(xs + (8 * qq + 4 * hh + e) * 512) + l31;
;           float s1 = 0.f, s2 = 0.f;
; #pragma unroll
;           for (int nt = 0; nt < 4; ++nt) {
;             float v = (acc[mt][nt][i] + bia[nt]) * csc[nt];
;             float z = ALPHA * xr[nt * 32] + hs * v;
;             acc[mt][nt][i] = z; s1 += z; s2 += z * z;
;           }
;           s1 = row16_sum(s1); s2 = row16_sum(s2);
;           if ((lane & 15) == 0) { f32x2 sv = {s1, s2}; *(f32x2*)(redw + (mt * 32 + (i & 3) + 8 * (i >> 2)) * 2) = sv; }
;         }
	v_mul_f32_e32 v181, 0x3fd744fd, v176
	v_mov_b32_e32 v18, v35
	v_mov_b32_e32 v2, v19
	v_mov_b32_e32 v180, v1
	v_pk_add_f32 v[182:183], v[18:19], 0 op_sel_hi:[1,0]
	v_pk_add_f32 v[34:35], v[2:3], v[180:181]
	v_mov_b32_e32 v2, v177
	s_waitcnt lgkmcnt(0)
	v_mov_b32_e32 v3, v178
	s_mov_b32 s2, s67
	v_pk_mul_f32 v[18:19], v[2:3], s[2:3] op_sel_hi:[1,0]
	v_pk_mul_f32 v[176:177], v[182:183], 0.5 op_sel_hi:[1,0]
	v_pk_fma_f32 v[2:3], v[182:183], 0.5, v[18:19] op_sel_hi:[1,0,1]
	v_mov_b32_e32 v176, v35
	v_mov_b32_e32 v182, v1
	v_mov_b32_e32 v183, v19
	v_pk_mul_f32 v[180:181], v[2:3], v[2:3]
	v_pk_add_f32 v[176:177], v[176:177], v[182:183]
	v_mov_b32_e32 v163, v35
	v_pk_mov_b32 v[18:19], v[18:19], v[180:181] op_sel:[1,0]
	v_pk_add_f32 v[180:181], v[2:3], v[176:177]
	v_pk_mul_f32 v[176:177], v[2:3], v[176:177]
	v_mov_b32_e32 v51, v179
	v_pk_fma_f32 v[18:19], v[34:35], v[162:163], v[18:19]
	v_mov_b32_e32 v181, v177
	v_mul_f32_e32 v0, 0x3fd744fd, v179
	v_pk_add_f32 v[176:177], v[180:181], v[18:19]
	v_pk_fma_f32 v[18:19], v[50:51], s[66:67], v[0:1] op_sel_hi:[1,1,0]
	s_nop 0
	v_pk_mul_f32 v[50:51], v[18:19], v[18:19]
	s_nop 0
	v_mov_b32_e32 v19, v50
	v_pk_add_f32 v[50:51], v[176:177], v[18:19]
	s_nop 1
	v_mov_b32_dpp v176, v50 quad_perm:[1,0,3,2] row_mask:0xf bank_mask:0xf bound_ctrl:1
	v_mov_b32_dpp v177, v51 quad_perm:[1,0,3,2] row_mask:0xf bank_mask:0xf bound_ctrl:1
	v_pk_add_f32 v[50:51], v[50:51], v[176:177]
	s_nop 1
	v_mov_b32_dpp v176, v50 quad_perm:[2,3,0,1] row_mask:0xf bank_mask:0xf bound_ctrl:1
	v_mov_b32_dpp v177, v51 quad_perm:[2,3,0,1] row_mask:0xf bank_mask:0xf bound_ctrl:1
	v_pk_add_f32 v[50:51], v[50:51], v[176:177]
	s_nop 1
	v_mov_b32_dpp v176, v50 row_half_mirror row_mask:0xf bank_mask:0xf bound_ctrl:1
	v_mov_b32_dpp v177, v51 row_half_mirror row_mask:0xf bank_mask:0xf bound_ctrl:1
	v_pk_add_f32 v[50:51], v[50:51], v[176:177]
	s_nop 1
	v_mov_b32_dpp v176, v50 row_mirror row_mask:0xf bank_mask:0xf bound_ctrl:1
	v_mov_b32_dpp v177, v51 row_mirror row_mask:0xf bank_mask:0xf bound_ctrl:1
	s_and_saveexec_b64 s[6:7], vcc
	v_pk_add_f32 v[50:51], v[50:51], v[176:177]
	ds_write_b64 v160, v[50:51] offset:264
	s_or_b64 exec, exec, s[6:7]
	ds_read2_b32 v[50:51], v143 offset1:32
	ds_read2_b32 v[176:177], v143 offset0:64 offset1:96
	v_add_f32_e32 v0, 0, v52
	v_mov_b32_e32 v184, v36
	v_mov_b32_e32 v185, v20
	v_mul_f32_e32 v179, 0.5, v0
	s_waitcnt lgkmcnt(1)
	v_mul_f32_e32 v183, 0x3fd744fd, v50
	v_pk_add_f32 v[184:185], v[184:185], 0 op_sel_hi:[1,0]
	v_mov_b32_e32 v178, v20
	v_mov_b32_e32 v182, v1
	v_mov_b32_e32 v50, v51
	s_waitcnt lgkmcnt(0)
	v_mov_b32_e32 v51, v176
	s_mov_b32 s2, s67
	v_pk_add_f32 v[178:179], v[178:179], v[182:183]
	v_pk_mul_f32 v[182:183], v[50:51], s[2:3] op_sel_hi:[1,0]
	v_pk_mul_f32 v[186:187], v[184:185], 0.5 op_sel_hi:[1,0]
	v_pk_fma_f32 v[50:51], v[184:185], 0.5, v[182:183] op_sel_hi:[1,0,1]
	v_mov_b32_e32 v186, v179
	v_mov_b32_e32 v188, v1
	v_mov_b32_e32 v189, v183
	v_add_f32_e32 v180, 0, v4
	v_mov_b32_e32 v181, v177
	v_pk_mul_f32 v[184:185], v[50:51], v[50:51]
	v_pk_add_f32 v[186:187], v[186:187], v[188:189]
	v_mul_f32_e32 v0, 0x3fd744fd, v177
	v_mov_b32_e32 v163, v179
	v_pk_mov_b32 v[182:183], v[182:183], v[184:185] op_sel:[1,0]
	v_pk_add_f32 v[184:185], v[50:51], v[186:187]
	v_pk_mul_f32 v[186:187], v[50:51], v[186:187]
	v_pk_fma_f32 v[176:177], v[180:181], s[66:67], v[0:1] op_sel_hi:[1,1,0]
	v_pk_fma_f32 v[182:183], v[178:179], v[162:163], v[182:183]
	v_mov_b32_e32 v185, v187
	v_pk_mul_f32 v[180:181], v[176:177], v[176:177]
	v_pk_add_f32 v[182:183], v[184:185], v[182:183]
	v_mov_b32_e32 v177, v180
	v_pk_add_f32 v[180:181], v[182:183], v[176:177]
	s_nop 1
	v_mov_b32_dpp v182, v180 quad_perm:[1,0,3,2] row_mask:0xf bank_mask:0xf bound_ctrl:1
	v_mov_b32_dpp v183, v181 quad_perm:[1,0,3,2] row_mask:0xf bank_mask:0xf bound_ctrl:1
	v_pk_add_f32 v[180:181], v[180:181], v[182:183]
	s_nop 1
	v_mov_b32_dpp v182, v180 quad_perm:[2,3,0,1] row_mask:0xf bank_mask:0xf bound_ctrl:1
	v_mov_b32_dpp v183, v181 quad_perm:[2,3,0,1] row_mask:0xf bank_mask:0xf bound_ctrl:1
	v_pk_add_f32 v[180:181], v[180:181], v[182:183]
	s_nop 1
	v_mov_b32_dpp v182, v180 row_half_mirror row_mask:0xf bank_mask:0xf bound_ctrl:1
	v_mov_b32_dpp v183, v181 row_half_mirror row_mask:0xf bank_mask:0xf bound_ctrl:1
	v_pk_add_f32 v[180:181], v[180:181], v[182:183]
	s_nop 1
	v_mov_b32_dpp v182, v180 row_mirror row_mask:0xf bank_mask:0xf bound_ctrl:1
	v_mov_b32_dpp v183, v181 row_mirror row_mask:0xf bank_mask:0xf bound_ctrl:1
	s_and_saveexec_b64 s[6:7], vcc
	v_pk_add_f32 v[180:181], v[180:181], v[182:183]
	ds_write_b64 v160, v[180:181] offset:272
	s_or_b64 exec, exec, s[6:7]
	ds_read2_b32 v[180:181], v144 offset1:32
	ds_read2_b32 v[182:183], v144 offset0:64 offset1:96
	v_add_f32_e32 v0, 0, v53
	v_add_f32_e32 v52, 0, v5
	v_mul_f32_e32 v5, 0.5, v0
	s_waitcnt lgkmcnt(1)
	v_mul_f32_e32 v185, 0x3fd744fd, v180
	v_mov_b32_e32 v20, v37
	v_mov_b32_e32 v4, v21
	v_mov_b32_e32 v184, v1
	v_pk_add_f32 v[186:187], v[20:21], 0 op_sel_hi:[1,0]
	v_pk_add_f32 v[36:37], v[4:5], v[184:185]
	v_mov_b32_e32 v4, v181
	s_waitcnt lgkmcnt(0)
;   DI void operator()(f32x16 (&acc)[2][4], int grow0, int gcol0, int lane, int w, char* lds) {
;     ...
;       for (int qq = 0; qq < 2; ++qq)
; #pragma unroll
;         for (int e = 0; e < 4; ++e) {
;           const int i = 4 * (2 * (ps & 1) + qq) + e;
;           const float* xr = (const float*)(xs + (8 * qq + 4 * hh + e) * 512) + l31;
;           float s1 = 0.f, s2 = 0.f;
; #pragma unroll
;           for (int nt = 0; nt < 4; ++nt) {
;             float v = (acc[mt][nt][i] + bia[nt]) * csc[nt];
;             float z = ALPHA * xr[nt * 32] + hs * v;
;             acc[mt][nt][i] = z; s1 += z; s2 += z * z;
;           }
;           s1 = row16_sum(s1); s2 = row16_sum(s2);
;           if ((lane & 15) == 0) { f32x2 sv = {s1, s2}; *(f32x2*)(redw + (mt * 32 + (i & 3) + 8 * (i >> 2)) * 2) = sv; }
;         }
	v_mov_b32_e32 v5, v182
	s_mov_b32 s2, s67
	v_pk_mul_f32 v[20:21], v[4:5], s[2:3] op_sel_hi:[1,0]
	v_pk_mul_f32 v[180:181], v[186:187], 0.5 op_sel_hi:[1,0]
	v_pk_fma_f32 v[4:5], v[186:187], 0.5, v[20:21] op_sel_hi:[1,0,1]
	v_mov_b32_e32 v180, v37
	v_mov_b32_e32 v186, v1
	v_mov_b32_e32 v187, v21
	v_pk_mul_f32 v[184:185], v[4:5], v[4:5]
	v_pk_add_f32 v[180:181], v[180:181], v[186:187]
	v_mov_b32_e32 v163, v37
	v_pk_mov_b32 v[20:21], v[20:21], v[184:185] op_sel:[1,0]
	v_pk_add_f32 v[184:185], v[4:5], v[180:181]
	v_pk_mul_f32 v[180:181], v[4:5], v[180:181]
	v_mov_b32_e32 v53, v183
	v_pk_fma_f32 v[20:21], v[36:37], v[162:163], v[20:21]
	v_mov_b32_e32 v185, v181
	v_mul_f32_e32 v0, 0x3fd744fd, v183
	v_pk_add_f32 v[180:181], v[184:185], v[20:21]
	v_pk_fma_f32 v[20:21], v[52:53], s[66:67], v[0:1] op_sel_hi:[1,1,0]
	s_nop 0
	v_pk_mul_f32 v[52:53], v[20:21], v[20:21]
	s_nop 0
	v_mov_b32_e32 v21, v52
	v_pk_add_f32 v[52:53], v[180:181], v[20:21]
	s_nop 1
	v_mov_b32_dpp v180, v52 quad_perm:[1,0,3,2] row_mask:0xf bank_mask:0xf bound_ctrl:1
	v_mov_b32_dpp v181, v53 quad_perm:[1,0,3,2] row_mask:0xf bank_mask:0xf bound_ctrl:1
	v_pk_add_f32 v[52:53], v[52:53], v[180:181]
	s_nop 1
	v_mov_b32_dpp v180, v52 quad_perm:[2,3,0,1] row_mask:0xf bank_mask:0xf bound_ctrl:1
	v_mov_b32_dpp v181, v53 quad_perm:[2,3,0,1] row_mask:0xf bank_mask:0xf bound_ctrl:1
	v_pk_add_f32 v[52:53], v[52:53], v[180:181]
	s_nop 1
	v_mov_b32_dpp v180, v52 row_half_mirror row_mask:0xf bank_mask:0xf bound_ctrl:1
	v_mov_b32_dpp v181, v53 row_half_mirror row_mask:0xf bank_mask:0xf bound_ctrl:1
	v_pk_add_f32 v[52:53], v[52:53], v[180:181]
	s_nop 1
	v_mov_b32_dpp v180, v52 row_mirror row_mask:0xf bank_mask:0xf bound_ctrl:1
	v_mov_b32_dpp v181, v53 row_mirror row_mask:0xf bank_mask:0xf bound_ctrl:1
	s_and_saveexec_b64 s[6:7], vcc
	v_pk_add_f32 v[52:53], v[52:53], v[180:181]
	ds_write_b64 v160, v[52:53] offset:280
	s_or_b64 exec, exec, s[6:7]
	ds_read2_b32 v[52:53], v83 offset1:32
	ds_read2_b32 v[180:181], v83 offset0:64 offset1:96
	v_add_f32_e32 v0, 0, v54
	v_mov_b32_e32 v188, v38
	v_mov_b32_e32 v189, v22
	v_mul_f32_e32 v183, 0.5, v0
	s_waitcnt lgkmcnt(1)
	v_mul_f32_e32 v187, 0x3fd744fd, v52
	v_pk_add_f32 v[188:189], v[188:189], 0 op_sel_hi:[1,0]
	v_mov_b32_e32 v182, v22
	v_mov_b32_e32 v186, v1
	v_mov_b32_e32 v52, v53
	s_waitcnt lgkmcnt(0)
	v_mov_b32_e32 v53, v180
	s_mov_b32 s2, s67
	v_pk_add_f32 v[182:183], v[182:183], v[186:187]
	v_pk_mul_f32 v[186:187], v[52:53], s[2:3] op_sel_hi:[1,0]
	v_pk_mul_f32 v[190:191], v[188:189], 0.5 op_sel_hi:[1,0]
	v_pk_fma_f32 v[52:53], v[188:189], 0.5, v[186:187] op_sel_hi:[1,0,1]
	v_mov_b32_e32 v190, v183
	v_mov_b32_e32 v192, v1
	v_mov_b32_e32 v193, v187
	v_add_f32_e32 v184, 0, v6
	v_mov_b32_e32 v185, v181
	v_pk_mul_f32 v[188:189], v[52:53], v[52:53]
	v_pk_add_f32 v[190:191], v[190:191], v[192:193]
	v_mul_f32_e32 v0, 0x3fd744fd, v181
	v_mov_b32_e32 v163, v183
	v_pk_mov_b32 v[186:187], v[186:187], v[188:189] op_sel:[1,0]
	v_pk_add_f32 v[188:189], v[52:53], v[190:191]
	v_pk_mul_f32 v[190:191], v[52:53], v[190:191]
	v_pk_fma_f32 v[180:181], v[184:185], s[66:67], v[0:1] op_sel_hi:[1,1,0]
	v_pk_fma_f32 v[186:187], v[182:183], v[162:163], v[186:187]
	v_mov_b32_e32 v189, v191
	v_pk_mul_f32 v[184:185], v[180:181], v[180:181]
	v_pk_add_f32 v[186:187], v[188:189], v[186:187]
	v_mov_b32_e32 v181, v184
	v_pk_add_f32 v[184:185], v[186:187], v[180:181]
	s_nop 1
	v_mov_b32_dpp v186, v184 quad_perm:[1,0,3,2] row_mask:0xf bank_mask:0xf bound_ctrl:1
	v_mov_b32_dpp v187, v185 quad_perm:[1,0,3,2] row_mask:0xf bank_mask:0xf bound_ctrl:1
	v_pk_add_f32 v[184:185], v[184:185], v[186:187]
	s_nop 1
	v_mov_b32_dpp v186, v184 quad_perm:[2,3,0,1] row_mask:0xf bank_mask:0xf bound_ctrl:1
	v_mov_b32_dpp v187, v185 quad_perm:[2,3,0,1] row_mask:0xf bank_mask:0xf bound_ctrl:1
	v_pk_add_f32 v[184:185], v[184:185], v[186:187]
	s_nop 1
	v_mov_b32_dpp v186, v184 row_half_mirror row_mask:0xf bank_mask:0xf bound_ctrl:1
	v_mov_b32_dpp v187, v185 row_half_mirror row_mask:0xf bank_mask:0xf bound_ctrl:1
	v_pk_add_f32 v[184:185], v[184:185], v[186:187]
	s_nop 1
	v_mov_b32_dpp v186, v184 row_mirror row_mask:0xf bank_mask:0xf bound_ctrl:1
	v_mov_b32_dpp v187, v185 row_mirror row_mask:0xf bank_mask:0xf bound_ctrl:1
	s_and_saveexec_b64 s[6:7], vcc
	v_pk_add_f32 v[184:185], v[184:185], v[186:187]
	ds_write_b64 v160, v[184:185] offset:320
	s_or_b64 exec, exec, s[6:7]
	ds_read2_b32 v[184:185], v83 offset0:128 offset1:160
	ds_read2_b32 v[186:187], v83 offset0:192 offset1:224
	v_add_f32_e32 v0, 0, v55
	v_add_f32_e32 v54, 0, v7
	v_mul_f32_e32 v7, 0.5, v0
	s_waitcnt lgkmcnt(1)
	v_mul_f32_e32 v189, 0x3fd744fd, v184
	v_mov_b32_e32 v22, v39
	v_mov_b32_e32 v6, v23
	v_mov_b32_e32 v188, v1
	v_pk_add_f32 v[190:191], v[22:23], 0 op_sel_hi:[1,0]
	v_pk_add_f32 v[38:39], v[6:7], v[188:189]
	v_mov_b32_e32 v6, v185
	s_waitcnt lgkmcnt(0)
; template <int CTRL> DI float dpp_f(float v) { return __int_as_float(__builtin_amdgcn_update_dpp(0, __float_as_int(v), CTRL, 0xF, 0xF, true)); }
; DI float row16_sum(float v) {
;   v += dpp_f<0xB1>(v);
;   v += dpp_f<0x4E>(v);
;   v += dpp_f<0x141>(v);
;   v += dpp_f<0x140>(v);
;   return v;
;   DI void operator()(f32x16 (&acc)[2][4], int grow0, int gcol0, int lane, int w, char* lds) {
;     ...
;         for (int e = 0; e < 4; ++e) {
;           const int i = 4 * (2 * (ps & 1) + qq) + e;
;           const float* xr = (const float*)(xs + (8 * qq + 4 * hh + e) * 512) + l31;
;           float s1 = 0.f, s2 = 0.f;
; #pragma unroll
;           for (int nt = 0; nt < 4; ++nt) {
;             float v = (acc[mt][nt][i] + bia[nt]) * csc[nt];
;             float z = ALPHA * xr[nt * 32] + hs * v;
;             acc[mt][nt][i] = z; s1 += z; s2 += z * z;
;           }
;           s1 = row16_sum(s1); s2 = row16_sum(s2);
;           if ((lane & 15) == 0) { f32x2 sv = {s1, s2}; *(f32x2*)(redw + (mt * 32 + (i & 3) + 8 * (i >> 2)) * 2) = sv; }
	v_mov_b32_e32 v7, v186
	s_mov_b32 s2, s67
	v_pk_mul_f32 v[22:23], v[6:7], s[2:3] op_sel_hi:[1,0]
	v_pk_mul_f32 v[184:185], v[190:191], 0.5 op_sel_hi:[1,0]
	v_pk_fma_f32 v[6:7], v[190:191], 0.5, v[22:23] op_sel_hi:[1,0,1]
	v_mov_b32_e32 v184, v39
	v_mov_b32_e32 v190, v1
	v_mov_b32_e32 v191, v23
	v_pk_mul_f32 v[188:189], v[6:7], v[6:7]
	v_pk_add_f32 v[184:185], v[184:185], v[190:191]
	v_mov_b32_e32 v163, v39
	v_pk_mov_b32 v[22:23], v[22:23], v[188:189] op_sel:[1,0]
	v_pk_add_f32 v[188:189], v[6:7], v[184:185]
	v_pk_mul_f32 v[184:185], v[6:7], v[184:185]
	v_mov_b32_e32 v55, v187
	v_pk_fma_f32 v[22:23], v[38:39], v[162:163], v[22:23]
	v_mov_b32_e32 v189, v185
	v_mul_f32_e32 v0, 0x3fd744fd, v187
	v_pk_add_f32 v[184:185], v[188:189], v[22:23]
	v_pk_fma_f32 v[22:23], v[54:55], s[66:67], v[0:1] op_sel_hi:[1,1,0]
	s_nop 0
	v_pk_mul_f32 v[54:55], v[22:23], v[22:23]
	s_nop 0
	v_mov_b32_e32 v23, v54
	v_pk_add_f32 v[54:55], v[184:185], v[22:23]
	s_nop 1
	v_mov_b32_dpp v184, v54 quad_perm:[1,0,3,2] row_mask:0xf bank_mask:0xf bound_ctrl:1
	v_mov_b32_dpp v185, v55 quad_perm:[1,0,3,2] row_mask:0xf bank_mask:0xf bound_ctrl:1
	v_pk_add_f32 v[54:55], v[54:55], v[184:185]
	s_nop 1
	v_mov_b32_dpp v184, v54 quad_perm:[2,3,0,1] row_mask:0xf bank_mask:0xf bound_ctrl:1
	v_mov_b32_dpp v185, v55 quad_perm:[2,3,0,1] row_mask:0xf bank_mask:0xf bound_ctrl:1
	v_pk_add_f32 v[54:55], v[54:55], v[184:185]
	s_nop 1
	v_mov_b32_dpp v184, v54 row_half_mirror row_mask:0xf bank_mask:0xf bound_ctrl:1
	v_mov_b32_dpp v185, v55 row_half_mirror row_mask:0xf bank_mask:0xf bound_ctrl:1
	v_pk_add_f32 v[54:55], v[54:55], v[184:185]
	s_nop 1
	v_mov_b32_dpp v184, v54 row_mirror row_mask:0xf bank_mask:0xf bound_ctrl:1
	v_mov_b32_dpp v185, v55 row_mirror row_mask:0xf bank_mask:0xf bound_ctrl:1
	s_and_saveexec_b64 s[6:7], vcc
	v_pk_add_f32 v[54:55], v[54:55], v[184:185]
	ds_write_b64 v160, v[54:55] offset:328
	s_or_b64 exec, exec, s[6:7]
	ds_read2_b32 v[54:55], v85 offset1:32
	ds_read2_b32 v[184:185], v85 offset0:64 offset1:96
	v_add_f32_e32 v0, 0, v56
	v_mov_b32_e32 v192, v40
	v_mov_b32_e32 v193, v24
	v_mul_f32_e32 v187, 0.5, v0
	s_waitcnt lgkmcnt(1)
	v_mul_f32_e32 v191, 0x3fd744fd, v54
	v_pk_add_f32 v[192:193], v[192:193], 0 op_sel_hi:[1,0]
	v_mov_b32_e32 v186, v24
	v_mov_b32_e32 v190, v1
	v_mov_b32_e32 v54, v55
	s_waitcnt lgkmcnt(0)
	v_mov_b32_e32 v55, v184
	s_mov_b32 s2, s67
	v_pk_add_f32 v[186:187], v[186:187], v[190:191]
	v_pk_mul_f32 v[190:191], v[54:55], s[2:3] op_sel_hi:[1,0]
	v_pk_mul_f32 v[194:195], v[192:193], 0.5 op_sel_hi:[1,0]
	v_pk_fma_f32 v[54:55], v[192:193], 0.5, v[190:191] op_sel_hi:[1,0,1]
	v_mov_b32_e32 v194, v187
	v_mov_b32_e32 v196, v1
	v_mov_b32_e32 v197, v191
	v_add_f32_e32 v188, 0, v8
	v_mov_b32_e32 v189, v185
	v_pk_mul_f32 v[192:193], v[54:55], v[54:55]
	v_pk_add_f32 v[194:195], v[194:195], v[196:197]
	v_mul_f32_e32 v0, 0x3fd744fd, v185
	v_mov_b32_e32 v163, v187
	v_pk_mov_b32 v[190:191], v[190:191], v[192:193] op_sel:[1,0]
	v_pk_add_f32 v[192:193], v[54:55], v[194:195]
	v_pk_mul_f32 v[194:195], v[54:55], v[194:195]
	v_pk_fma_f32 v[184:185], v[188:189], s[66:67], v[0:1] op_sel_hi:[1,1,0]
	v_pk_fma_f32 v[190:191], v[186:187], v[162:163], v[190:191]
	v_mov_b32_e32 v193, v195
	v_pk_mul_f32 v[188:189], v[184:185], v[184:185]
	v_pk_add_f32 v[190:191], v[192:193], v[190:191]
	v_mov_b32_e32 v185, v188
	v_pk_add_f32 v[188:189], v[190:191], v[184:185]
	s_nop 1
	v_mov_b32_dpp v190, v188 quad_perm:[1,0,3,2] row_mask:0xf bank_mask:0xf bound_ctrl:1
	v_mov_b32_dpp v191, v189 quad_perm:[1,0,3,2] row_mask:0xf bank_mask:0xf bound_ctrl:1
	v_pk_add_f32 v[188:189], v[188:189], v[190:191]
	s_nop 1
	v_mov_b32_dpp v190, v188 quad_perm:[2,3,0,1] row_mask:0xf bank_mask:0xf bound_ctrl:1
	v_mov_b32_dpp v191, v189 quad_perm:[2,3,0,1] row_mask:0xf bank_mask:0xf bound_ctrl:1
	v_pk_add_f32 v[188:189], v[188:189], v[190:191]
	s_nop 1
	v_mov_b32_dpp v190, v188 row_half_mirror row_mask:0xf bank_mask:0xf bound_ctrl:1
	v_mov_b32_dpp v191, v189 row_half_mirror row_mask:0xf bank_mask:0xf bound_ctrl:1
	v_pk_add_f32 v[188:189], v[188:189], v[190:191]
	s_nop 1
	v_mov_b32_dpp v190, v188 row_mirror row_mask:0xf bank_mask:0xf bound_ctrl:1
	v_mov_b32_dpp v191, v189 row_mirror row_mask:0xf bank_mask:0xf bound_ctrl:1
	s_and_saveexec_b64 s[6:7], vcc
	v_pk_add_f32 v[188:189], v[188:189], v[190:191]
	ds_write_b64 v160, v[188:189] offset:336
	s_or_b64 exec, exec, s[6:7]
	ds_read2_b32 v[188:189], v87 offset1:32
	ds_read2_b32 v[190:191], v87 offset0:64 offset1:96
	v_add_f32_e32 v0, 0, v57
	v_add_f32_e32 v56, 0, v9
	v_mul_f32_e32 v9, 0.5, v0
	s_waitcnt lgkmcnt(1)
	v_mul_f32_e32 v193, 0x3fd744fd, v188
	v_mov_b32_e32 v24, v41
	v_mov_b32_e32 v8, v25
	v_mov_b32_e32 v192, v1
	v_pk_add_f32 v[194:195], v[24:25], 0 op_sel_hi:[1,0]
	v_pk_add_f32 v[40:41], v[8:9], v[192:193]
	v_mov_b32_e32 v8, v189
	s_waitcnt lgkmcnt(0)
;   DI void operator()(f32x16 (&acc)[2][4], int grow0, int gcol0, int lane, int w, char* lds) {
;     ...
;       if (ps + 1 < 4) {
;         if (ps >= 1) asm volatile("s_waitcnt lgkmcnt(0)" ::: "memory");
;         xpass(ps + 1, grow0, gcol0, lane, w, lds);
;         if (ps >= 1) asm volatile("s_waitcnt vmcnt(8)" ::: "memory");
;       } else asm volatile("s_waitcnt vmcnt(0)" ::: "memory");
;       const char* xs = lds + (ps & 1) * 65536 + w * 8192;
; #pragma unroll
;       for (int qq = 0; qq < 2; ++qq)
; #pragma unroll
;         for (int e = 0; e < 4; ++e) {
;           const int i = 4 * (2 * (ps & 1) + qq) + e;
;           const float* xr = (const float*)(xs + (8 * qq + 4 * hh + e) * 512) + l31;
;           float s1 = 0.f, s2 = 0.f;
; #pragma unroll
;           for (int nt = 0; nt < 4; ++nt) {
;             float v = (acc[mt][nt][i] + bia[nt]) * csc[nt];
;             float z = ALPHA * xr[nt * 32] + hs * v;
;             acc[mt][nt][i] = z; s1 += z; s2 += z * z;
;           }
;           s1 = row16_sum(s1); s2 = row16_sum(s2);
;           if ((lane & 15) == 0) { f32x2 sv = {s1, s2}; *(f32x2*)(redw + (mt * 32 + (i & 3) + 8 * (i >> 2)) * 2) = sv; }
	v_mov_b32_e32 v9, v190
	s_mov_b32 s2, s67
	v_pk_mul_f32 v[24:25], v[8:9], s[2:3] op_sel_hi:[1,0]
	v_pk_mul_f32 v[188:189], v[194:195], 0.5 op_sel_hi:[1,0]
	v_pk_fma_f32 v[8:9], v[194:195], 0.5, v[24:25] op_sel_hi:[1,0,1]
	v_mov_b32_e32 v188, v41
	v_mov_b32_e32 v194, v1
	v_mov_b32_e32 v195, v25
	v_pk_mul_f32 v[192:193], v[8:9], v[8:9]
	v_pk_add_f32 v[188:189], v[188:189], v[194:195]
	v_mov_b32_e32 v163, v41
	v_pk_mov_b32 v[24:25], v[24:25], v[192:193] op_sel:[1,0]
	v_pk_add_f32 v[192:193], v[8:9], v[188:189]
	v_pk_mul_f32 v[188:189], v[8:9], v[188:189]
	v_mov_b32_e32 v57, v191
	v_pk_fma_f32 v[24:25], v[40:41], v[162:163], v[24:25]
	v_mov_b32_e32 v193, v189
	v_mul_f32_e32 v0, 0x3fd744fd, v191
	v_pk_add_f32 v[188:189], v[192:193], v[24:25]
	v_pk_fma_f32 v[24:25], v[56:57], s[66:67], v[0:1] op_sel_hi:[1,1,0]
	s_nop 0
	v_pk_mul_f32 v[56:57], v[24:25], v[24:25]
	s_nop 0
	v_mov_b32_e32 v25, v56
	v_pk_add_f32 v[56:57], v[188:189], v[24:25]
	s_nop 1
	v_mov_b32_dpp v188, v56 quad_perm:[1,0,3,2] row_mask:0xf bank_mask:0xf bound_ctrl:1
	v_mov_b32_dpp v189, v57 quad_perm:[1,0,3,2] row_mask:0xf bank_mask:0xf bound_ctrl:1
	v_pk_add_f32 v[56:57], v[56:57], v[188:189]
	s_nop 1
	v_mov_b32_dpp v188, v56 quad_perm:[2,3,0,1] row_mask:0xf bank_mask:0xf bound_ctrl:1
	v_mov_b32_dpp v189, v57 quad_perm:[2,3,0,1] row_mask:0xf bank_mask:0xf bound_ctrl:1
	v_pk_add_f32 v[56:57], v[56:57], v[188:189]
	s_nop 1
	v_mov_b32_dpp v188, v56 row_half_mirror row_mask:0xf bank_mask:0xf bound_ctrl:1
	v_mov_b32_dpp v189, v57 row_half_mirror row_mask:0xf bank_mask:0xf bound_ctrl:1
	v_pk_add_f32 v[56:57], v[56:57], v[188:189]
	s_nop 1
	v_mov_b32_dpp v188, v56 row_mirror row_mask:0xf bank_mask:0xf bound_ctrl:1
	v_mov_b32_dpp v189, v57 row_mirror row_mask:0xf bank_mask:0xf bound_ctrl:1
	s_and_saveexec_b64 s[6:7], vcc
	v_pk_add_f32 v[56:57], v[56:57], v[188:189]
	ds_write_b64 v160, v[56:57] offset:344
	s_or_b64 exec, exec, s[6:7]
	s_waitcnt vmcnt(0)
	ds_read2_b32 v[56:57], v89 offset1:32
	ds_read2_b32 v[190:191], v89 offset0:64 offset1:96
	v_add_f32_e32 v0, 0, v58
	v_mul_f32_e32 v189, 0.5, v0
	v_mov_b32_e32 v188, v26
	s_waitcnt lgkmcnt(1)
	v_mul_f32_e32 v193, 0x3fd744fd, v56
	v_add_f32_e32 v56, 0, v42
	v_mul_f32_e32 v0, 0x3fd744fd, v57
	v_mov_b32_e32 v192, v1
	v_pk_fma_f32 v[56:57], v[56:57], s[66:67], v[0:1] op_sel_hi:[1,1,0]
	v_pk_add_f32 v[192:193], v[188:189], v[192:193]
	s_waitcnt lgkmcnt(0)
	v_mov_b32_e32 v188, v190
	v_mov_b32_e32 v189, v56
	v_mov_b32_e32 v196, v165
	v_mov_b32_e32 v197, v56
	v_mov_b32_e32 v163, v193
	v_pk_mul_f32 v[196:197], v[188:189], v[196:197]
	v_pk_mul_f32 v[198:199], v[192:193], v[162:163]
	v_mov_b32_e32 v200, v1
	v_pk_mov_b32 v[198:199], v[192:193], v[198:199] op_sel:[1,0]
	v_mov_b32_e32 v201, v196
	v_add_f32_e32 v194, 0, v10
	v_mov_b32_e32 v195, v191
	v_pk_fma_f32 v[188:189], v[192:193], v[162:163], v[196:197]
	v_pk_add_f32 v[196:197], v[198:199], v[200:201]
	v_mul_f32_e32 v0, 0x3fd744fd, v191
	v_pk_add_f32 v[198:199], v[56:57], v[196:197]
	v_pk_mul_f32 v[196:197], v[188:189], v[196:197] op_sel_hi:[0,1]
	v_pk_fma_f32 v[190:191], v[194:195], s[66:67], v[0:1] op_sel_hi:[1,1,0]
	v_mov_b32_e32 v199, v197
	v_pk_mul_f32 v[194:195], v[190:191], v[190:191]
	v_pk_add_f32 v[196:197], v[188:189], v[198:199]
	v_mov_b32_e32 v191, v194
	v_pk_add_f32 v[194:195], v[196:197], v[190:191]
	s_nop 1
	v_mov_b32_dpp v196, v194 quad_perm:[1,0,3,2] row_mask:0xf bank_mask:0xf bound_ctrl:1
	v_mov_b32_dpp v197, v195 quad_perm:[1,0,3,2] row_mask:0xf bank_mask:0xf bound_ctrl:1
	v_pk_add_f32 v[194:195], v[194:195], v[196:197]
	s_nop 1
	v_mov_b32_dpp v196, v194 quad_perm:[2,3,0,1] row_mask:0xf bank_mask:0xf bound_ctrl:1
	v_mov_b32_dpp v197, v195 quad_perm:[2,3,0,1] row_mask:0xf bank_mask:0xf bound_ctrl:1
	v_pk_add_f32 v[194:195], v[194:195], v[196:197]
	s_nop 1
	v_mov_b32_dpp v196, v194 row_half_mirror row_mask:0xf bank_mask:0xf bound_ctrl:1
	v_mov_b32_dpp v197, v195 row_half_mirror row_mask:0xf bank_mask:0xf bound_ctrl:1
	v_pk_add_f32 v[194:195], v[194:195], v[196:197]
	s_nop 1
	v_mov_b32_dpp v196, v194 row_mirror row_mask:0xf bank_mask:0xf bound_ctrl:1
	v_mov_b32_dpp v197, v195 row_mirror row_mask:0xf bank_mask:0xf bound_ctrl:1
	s_and_saveexec_b64 s[6:7], vcc
	v_pk_add_f32 v[194:195], v[194:195], v[196:197]
	ds_write_b64 v160, v[194:195] offset:384
	s_or_b64 exec, exec, s[6:7]
	ds_read2_b32 v[194:195], v98 offset1:32
	ds_read2_b32 v[196:197], v98 offset0:64 offset1:96
	v_add_f32_e32 v0, 0, v59
	v_add_f32_e32 v58, 0, v11
	v_mul_f32_e32 v11, 0.5, v0
	s_waitcnt lgkmcnt(1)
	v_mul_f32_e32 v199, 0x3fd744fd, v194
	v_mov_b32_e32 v26, v43
	v_mov_b32_e32 v10, v27
	v_mov_b32_e32 v198, v1
	v_pk_add_f32 v[200:201], v[26:27], 0 op_sel_hi:[1,0]
	v_pk_add_f32 v[42:43], v[10:11], v[198:199]
	v_mov_b32_e32 v10, v195
	s_waitcnt lgkmcnt(0)
; template <int CTRL> DI float dpp_f(float v) { return __int_as_float(__builtin_amdgcn_update_dpp(0, __float_as_int(v), CTRL, 0xF, 0xF, true)); }
; DI float row16_sum(float v) {
;   v += dpp_f<0xB1>(v);
;   v += dpp_f<0x4E>(v);
;   v += dpp_f<0x141>(v);
;   v += dpp_f<0x140>(v);
;   return v;
;   DI void operator()(f32x16 (&acc)[2][4], int grow0, int gcol0, int lane, int w, char* lds) {
;     ...
;         for (int e = 0; e < 4; ++e) {
;           const int i = 4 * (2 * (ps & 1) + qq) + e;
;           const float* xr = (const float*)(xs + (8 * qq + 4 * hh + e) * 512) + l31;
;           float s1 = 0.f, s2 = 0.f;
; #pragma unroll
;           for (int nt = 0; nt < 4; ++nt) {
;             float v = (acc[mt][nt][i] + bia[nt]) * csc[nt];
;             float z = ALPHA * xr[nt * 32] + hs * v;
;             acc[mt][nt][i] = z; s1 += z; s2 += z * z;
;           }
;           s1 = row16_sum(s1); s2 = row16_sum(s2);
;           if ((lane & 15) == 0) { f32x2 sv = {s1, s2}; *(f32x2*)(redw + (mt * 32 + (i & 3) + 8 * (i >> 2)) * 2) = sv; }
	v_mov_b32_e32 v11, v196
	s_mov_b32 s2, s67
	v_pk_mul_f32 v[26:27], v[10:11], s[2:3] op_sel_hi:[1,0]
	v_pk_mul_f32 v[194:195], v[200:201], 0.5 op_sel_hi:[1,0]
	v_pk_fma_f32 v[10:11], v[200:201], 0.5, v[26:27] op_sel_hi:[1,0,1]
	v_mov_b32_e32 v194, v43
	v_mov_b32_e32 v200, v1
	v_mov_b32_e32 v201, v27
	v_pk_mul_f32 v[198:199], v[10:11], v[10:11]
	v_pk_add_f32 v[194:195], v[194:195], v[200:201]
	v_mov_b32_e32 v163, v43
	v_pk_mov_b32 v[26:27], v[26:27], v[198:199] op_sel:[1,0]
	v_pk_add_f32 v[198:199], v[10:11], v[194:195]
	v_pk_mul_f32 v[194:195], v[10:11], v[194:195]
	v_mov_b32_e32 v59, v197
	v_pk_fma_f32 v[26:27], v[42:43], v[162:163], v[26:27]
	v_mov_b32_e32 v199, v195
	v_mul_f32_e32 v0, 0x3fd744fd, v197
	v_pk_add_f32 v[194:195], v[198:199], v[26:27]
	v_pk_fma_f32 v[26:27], v[58:59], s[66:67], v[0:1] op_sel_hi:[1,1,0]
	s_nop 0
	v_pk_mul_f32 v[58:59], v[26:27], v[26:27]
	s_nop 0
	v_mov_b32_e32 v27, v58
	v_pk_add_f32 v[58:59], v[194:195], v[26:27]
	s_nop 1
	v_mov_b32_dpp v194, v58 quad_perm:[1,0,3,2] row_mask:0xf bank_mask:0xf bound_ctrl:1
	v_mov_b32_dpp v195, v59 quad_perm:[1,0,3,2] row_mask:0xf bank_mask:0xf bound_ctrl:1
	v_pk_add_f32 v[58:59], v[58:59], v[194:195]
	s_nop 1
	v_mov_b32_dpp v194, v58 quad_perm:[2,3,0,1] row_mask:0xf bank_mask:0xf bound_ctrl:1
	v_mov_b32_dpp v195, v59 quad_perm:[2,3,0,1] row_mask:0xf bank_mask:0xf bound_ctrl:1
	v_pk_add_f32 v[58:59], v[58:59], v[194:195]
	s_nop 1
	v_mov_b32_dpp v194, v58 row_half_mirror row_mask:0xf bank_mask:0xf bound_ctrl:1
	v_mov_b32_dpp v195, v59 row_half_mirror row_mask:0xf bank_mask:0xf bound_ctrl:1
	v_pk_add_f32 v[58:59], v[58:59], v[194:195]
	s_nop 1
	v_mov_b32_dpp v194, v58 row_mirror row_mask:0xf bank_mask:0xf bound_ctrl:1
	v_mov_b32_dpp v195, v59 row_mirror row_mask:0xf bank_mask:0xf bound_ctrl:1
	s_and_saveexec_b64 s[6:7], vcc
	v_pk_add_f32 v[58:59], v[58:59], v[194:195]
	ds_write_b64 v160, v[58:59] offset:392
	s_or_b64 exec, exec, s[6:7]
	ds_read2_b32 v[58:59], v102 offset1:32
	ds_read2_b32 v[194:195], v102 offset0:64 offset1:96
	v_add_f32_e32 v0, 0, v60
	v_mov_b32_e32 v202, v44
	v_mov_b32_e32 v203, v28
	v_mul_f32_e32 v197, 0.5, v0
	s_waitcnt lgkmcnt(1)
	v_mul_f32_e32 v201, 0x3fd744fd, v58
	v_pk_add_f32 v[202:203], v[202:203], 0 op_sel_hi:[1,0]
	v_mov_b32_e32 v196, v28
	v_mov_b32_e32 v200, v1
	v_mov_b32_e32 v58, v59
	s_waitcnt lgkmcnt(0)
	v_mov_b32_e32 v59, v194
	s_mov_b32 s2, s67
	v_pk_add_f32 v[196:197], v[196:197], v[200:201]
	v_pk_mul_f32 v[200:201], v[58:59], s[2:3] op_sel_hi:[1,0]
	v_pk_mul_f32 v[204:205], v[202:203], 0.5 op_sel_hi:[1,0]
	v_pk_fma_f32 v[58:59], v[202:203], 0.5, v[200:201] op_sel_hi:[1,0,1]
	v_mov_b32_e32 v204, v197
	v_mov_b32_e32 v206, v1
	v_mov_b32_e32 v207, v201
	v_add_f32_e32 v198, 0, v12
	v_mov_b32_e32 v199, v195
	v_pk_mul_f32 v[202:203], v[58:59], v[58:59]
	v_pk_add_f32 v[204:205], v[204:205], v[206:207]
	v_mul_f32_e32 v0, 0x3fd744fd, v195
	v_mov_b32_e32 v163, v197
	v_pk_mov_b32 v[200:201], v[200:201], v[202:203] op_sel:[1,0]
	v_pk_add_f32 v[202:203], v[58:59], v[204:205]
	v_pk_mul_f32 v[204:205], v[58:59], v[204:205]
	v_pk_fma_f32 v[194:195], v[198:199], s[66:67], v[0:1] op_sel_hi:[1,1,0]
	v_pk_fma_f32 v[200:201], v[196:197], v[162:163], v[200:201]
	v_mov_b32_e32 v203, v205
	v_pk_mul_f32 v[198:199], v[194:195], v[194:195]
	v_pk_add_f32 v[200:201], v[202:203], v[200:201]
	v_mov_b32_e32 v195, v198
	v_pk_add_f32 v[198:199], v[200:201], v[194:195]
	s_nop 1
	v_mov_b32_dpp v200, v198 quad_perm:[1,0,3,2] row_mask:0xf bank_mask:0xf bound_ctrl:1
	v_mov_b32_dpp v201, v199 quad_perm:[1,0,3,2] row_mask:0xf bank_mask:0xf bound_ctrl:1
	v_pk_add_f32 v[198:199], v[198:199], v[200:201]
	s_nop 1
	v_mov_b32_dpp v200, v198 quad_perm:[2,3,0,1] row_mask:0xf bank_mask:0xf bound_ctrl:1
	v_mov_b32_dpp v201, v199 quad_perm:[2,3,0,1] row_mask:0xf bank_mask:0xf bound_ctrl:1
	v_pk_add_f32 v[198:199], v[198:199], v[200:201]
	s_nop 1
	v_mov_b32_dpp v200, v198 row_half_mirror row_mask:0xf bank_mask:0xf bound_ctrl:1
	v_mov_b32_dpp v201, v199 row_half_mirror row_mask:0xf bank_mask:0xf bound_ctrl:1
	v_pk_add_f32 v[198:199], v[198:199], v[200:201]
	s_nop 1
	v_mov_b32_dpp v200, v198 row_mirror row_mask:0xf bank_mask:0xf bound_ctrl:1
	v_mov_b32_dpp v201, v199 row_mirror row_mask:0xf bank_mask:0xf bound_ctrl:1
	s_and_saveexec_b64 s[6:7], vcc
	v_pk_add_f32 v[198:199], v[198:199], v[200:201]
	ds_write_b64 v160, v[198:199] offset:400
	s_or_b64 exec, exec, s[6:7]
	ds_read2_b32 v[198:199], v104 offset1:32
	ds_read2_b32 v[200:201], v104 offset0:64 offset1:96
	v_add_f32_e32 v0, 0, v61
	v_add_f32_e32 v60, 0, v13
	v_mul_f32_e32 v13, 0.5, v0
	s_waitcnt lgkmcnt(1)
	v_mul_f32_e32 v203, 0x3fd744fd, v198
	v_mov_b32_e32 v28, v45
	v_mov_b32_e32 v12, v29
	v_mov_b32_e32 v202, v1
	v_pk_add_f32 v[204:205], v[28:29], 0 op_sel_hi:[1,0]
	v_pk_add_f32 v[44:45], v[12:13], v[202:203]
	v_mov_b32_e32 v12, v199
	s_waitcnt lgkmcnt(0)
; template <int CTRL> DI float dpp_f(float v) { return __int_as_float(__builtin_amdgcn_update_dpp(0, __float_as_int(v), CTRL, 0xF, 0xF, true)); }
; DI float row16_sum(float v) {
;   v += dpp_f<0xB1>(v);
;   v += dpp_f<0x4E>(v);
;   v += dpp_f<0x141>(v);
;   v += dpp_f<0x140>(v);
;   return v;
;   DI void operator()(f32x16 (&acc)[2][4], int grow0, int gcol0, int lane, int w, char* lds) {
;     ...
;         for (int e = 0; e < 4; ++e) {
;           const int i = 4 * (2 * (ps & 1) + qq) + e;
;           const float* xr = (const float*)(xs + (8 * qq + 4 * hh + e) * 512) + l31;
;           float s1 = 0.f, s2 = 0.f;
; #pragma unroll
;           for (int nt = 0; nt < 4; ++nt) {
;             float v = (acc[mt][nt][i] + bia[nt]) * csc[nt];
;             float z = ALPHA * xr[nt * 32] + hs * v;
;             acc[mt][nt][i] = z; s1 += z; s2 += z * z;
;           }
;           s1 = row16_sum(s1); s2 = row16_sum(s2);
;           if ((lane & 15) == 0) { f32x2 sv = {s1, s2}; *(f32x2*)(redw + (mt * 32 + (i & 3) + 8 * (i >> 2)) * 2) = sv; }
	v_mov_b32_e32 v13, v200
	s_mov_b32 s2, s67
	v_pk_mul_f32 v[28:29], v[12:13], s[2:3] op_sel_hi:[1,0]
	v_pk_mul_f32 v[198:199], v[204:205], 0.5 op_sel_hi:[1,0]
	v_pk_fma_f32 v[12:13], v[204:205], 0.5, v[28:29] op_sel_hi:[1,0,1]
	v_mov_b32_e32 v198, v45
	v_mov_b32_e32 v204, v1
	v_mov_b32_e32 v205, v29
	v_pk_mul_f32 v[202:203], v[12:13], v[12:13]
	v_pk_add_f32 v[198:199], v[198:199], v[204:205]
	v_mov_b32_e32 v163, v45
	v_pk_mov_b32 v[28:29], v[28:29], v[202:203] op_sel:[1,0]
	v_pk_add_f32 v[202:203], v[12:13], v[198:199]
	v_pk_mul_f32 v[198:199], v[12:13], v[198:199]
	v_mov_b32_e32 v61, v201
	v_pk_fma_f32 v[28:29], v[44:45], v[162:163], v[28:29]
	v_mov_b32_e32 v203, v199
	v_mul_f32_e32 v0, 0x3fd744fd, v201
	v_pk_add_f32 v[198:199], v[202:203], v[28:29]
	v_pk_fma_f32 v[28:29], v[60:61], s[66:67], v[0:1] op_sel_hi:[1,1,0]
	s_nop 0
	v_pk_mul_f32 v[60:61], v[28:29], v[28:29]
	s_nop 0
	v_mov_b32_e32 v29, v60
	v_pk_add_f32 v[60:61], v[198:199], v[28:29]
	s_nop 1
	v_mov_b32_dpp v198, v60 quad_perm:[1,0,3,2] row_mask:0xf bank_mask:0xf bound_ctrl:1
	v_mov_b32_dpp v199, v61 quad_perm:[1,0,3,2] row_mask:0xf bank_mask:0xf bound_ctrl:1
	v_pk_add_f32 v[60:61], v[60:61], v[198:199]
	s_nop 1
	v_mov_b32_dpp v198, v60 quad_perm:[2,3,0,1] row_mask:0xf bank_mask:0xf bound_ctrl:1
	v_mov_b32_dpp v199, v61 quad_perm:[2,3,0,1] row_mask:0xf bank_mask:0xf bound_ctrl:1
	v_pk_add_f32 v[60:61], v[60:61], v[198:199]
	s_nop 1
	v_mov_b32_dpp v198, v60 row_half_mirror row_mask:0xf bank_mask:0xf bound_ctrl:1
	v_mov_b32_dpp v199, v61 row_half_mirror row_mask:0xf bank_mask:0xf bound_ctrl:1
	v_pk_add_f32 v[60:61], v[60:61], v[198:199]
	s_nop 1
	v_mov_b32_dpp v198, v60 row_mirror row_mask:0xf bank_mask:0xf bound_ctrl:1
	v_mov_b32_dpp v199, v61 row_mirror row_mask:0xf bank_mask:0xf bound_ctrl:1
	s_and_saveexec_b64 s[6:7], vcc
	v_pk_add_f32 v[60:61], v[60:61], v[198:199]
	ds_write_b64 v160, v[60:61] offset:408
	s_or_b64 exec, exec, s[6:7]
	ds_read2_b32 v[60:61], v93 offset1:32
	ds_read2_b32 v[198:199], v93 offset0:64 offset1:96
	v_add_f32_e32 v0, 0, v62
	v_mov_b32_e32 v206, v46
	v_mov_b32_e32 v207, v30
	v_mul_f32_e32 v201, 0.5, v0
	s_waitcnt lgkmcnt(1)
	v_mul_f32_e32 v205, 0x3fd744fd, v60
	v_pk_add_f32 v[206:207], v[206:207], 0 op_sel_hi:[1,0]
	v_mov_b32_e32 v200, v30
	v_mov_b32_e32 v204, v1
	v_mov_b32_e32 v60, v61
	s_waitcnt lgkmcnt(0)
	v_mov_b32_e32 v61, v198
	s_mov_b32 s2, s67
	v_pk_add_f32 v[200:201], v[200:201], v[204:205]
	v_pk_mul_f32 v[204:205], v[60:61], s[2:3] op_sel_hi:[1,0]
	v_pk_mul_f32 v[208:209], v[206:207], 0.5 op_sel_hi:[1,0]
	v_pk_fma_f32 v[60:61], v[206:207], 0.5, v[204:205] op_sel_hi:[1,0,1]
	v_mov_b32_e32 v208, v201
	v_mov_b32_e32 v212, v1
	v_mov_b32_e32 v213, v205
	v_add_f32_e32 v202, 0, v14
	v_mov_b32_e32 v203, v199
	v_pk_mul_f32 v[206:207], v[60:61], v[60:61]
	v_pk_add_f32 v[208:209], v[208:209], v[212:213]
	v_mul_f32_e32 v0, 0x3fd744fd, v199
	v_mov_b32_e32 v163, v201
	v_pk_mov_b32 v[204:205], v[204:205], v[206:207] op_sel:[1,0]
	v_pk_add_f32 v[206:207], v[60:61], v[208:209]
	v_pk_mul_f32 v[208:209], v[60:61], v[208:209]
	v_pk_fma_f32 v[198:199], v[202:203], s[66:67], v[0:1] op_sel_hi:[1,1,0]
	v_pk_fma_f32 v[204:205], v[200:201], v[162:163], v[204:205]
	v_mov_b32_e32 v207, v209
	v_pk_mul_f32 v[202:203], v[198:199], v[198:199]
	v_pk_add_f32 v[204:205], v[206:207], v[204:205]
	v_mov_b32_e32 v199, v202
	v_pk_add_f32 v[202:203], v[204:205], v[198:199]
	s_nop 1
	v_mov_b32_dpp v204, v202 quad_perm:[1,0,3,2] row_mask:0xf bank_mask:0xf bound_ctrl:1
	v_mov_b32_dpp v205, v203 quad_perm:[1,0,3,2] row_mask:0xf bank_mask:0xf bound_ctrl:1
	v_pk_add_f32 v[202:203], v[202:203], v[204:205]
	s_nop 1
	v_mov_b32_dpp v204, v202 quad_perm:[2,3,0,1] row_mask:0xf bank_mask:0xf bound_ctrl:1
	v_mov_b32_dpp v205, v203 quad_perm:[2,3,0,1] row_mask:0xf bank_mask:0xf bound_ctrl:1
	v_pk_add_f32 v[202:203], v[202:203], v[204:205]
	s_nop 1
	v_mov_b32_dpp v204, v202 row_half_mirror row_mask:0xf bank_mask:0xf bound_ctrl:1
	v_mov_b32_dpp v205, v203 row_half_mirror row_mask:0xf bank_mask:0xf bound_ctrl:1
	v_pk_add_f32 v[202:203], v[202:203], v[204:205]
	s_nop 1
	v_mov_b32_dpp v204, v202 row_mirror row_mask:0xf bank_mask:0xf bound_ctrl:1
	v_mov_b32_dpp v205, v203 row_mirror row_mask:0xf bank_mask:0xf bound_ctrl:1
	s_and_saveexec_b64 s[6:7], vcc
	v_pk_add_f32 v[202:203], v[202:203], v[204:205]
	ds_write_b64 v160, v[202:203] offset:448
	s_or_b64 exec, exec, s[6:7]
	ds_read2_b32 v[202:203], v106 offset1:32
	ds_read2_b32 v[204:205], v106 offset0:64 offset1:96
	v_add_f32_e32 v0, 0, v63
	v_add_f32_e32 v62, 0, v15
	v_mul_f32_e32 v15, 0.5, v0
	s_waitcnt lgkmcnt(1)
	v_mul_f32_e32 v207, 0x3fd744fd, v202
	v_mov_b32_e32 v30, v47
	v_mov_b32_e32 v14, v31
	v_mov_b32_e32 v206, v1
	v_pk_add_f32 v[208:209], v[30:31], 0 op_sel_hi:[1,0]
	v_pk_add_f32 v[46:47], v[14:15], v[206:207]
	v_mov_b32_e32 v14, v203
	s_waitcnt lgkmcnt(0)
;   DI void operator()(f32x16 (&acc)[2][4], int grow0, int gcol0, int lane, int w, char* lds) {
;     ...
;         for (int e = 0; e < 4; ++e) {
;           const int i = 4 * (2 * (ps & 1) + qq) + e;
;           const float* xr = (const float*)(xs + (8 * qq + 4 * hh + e) * 512) + l31;
;           float s1 = 0.f, s2 = 0.f;
; #pragma unroll
;           for (int nt = 0; nt < 4; ++nt) {
;             float v = (acc[mt][nt][i] + bia[nt]) * csc[nt];
;             float z = ALPHA * xr[nt * 32] + hs * v;
;             acc[mt][nt][i] = z; s1 += z; s2 += z * z;
;           }
;           s1 = row16_sum(s1); s2 = row16_sum(s2);
;           if ((lane & 15) == 0) { f32x2 sv = {s1, s2}; *(f32x2*)(redw + (mt * 32 + (i & 3) + 8 * (i >> 2)) * 2) = sv; }
;         }
;     }
;     __syncthreads();
;     u64_t* myslots = xstat + ((size_t)pm * 256) * 4;
;     if (tid < 256) {
	v_mov_b32_e32 v15, v204
	s_mov_b32 s2, s67
	v_pk_mul_f32 v[30:31], v[14:15], s[2:3] op_sel_hi:[1,0]
	v_pk_mul_f32 v[202:203], v[208:209], 0.5 op_sel_hi:[1,0]
	v_pk_fma_f32 v[14:15], v[208:209], 0.5, v[30:31] op_sel_hi:[1,0,1]
	v_mov_b32_e32 v202, v47
	v_mov_b32_e32 v208, v1
	v_mov_b32_e32 v209, v31
	v_pk_mul_f32 v[206:207], v[14:15], v[14:15]
	v_pk_add_f32 v[202:203], v[202:203], v[208:209]
	v_mov_b32_e32 v163, v47
	v_pk_mov_b32 v[30:31], v[30:31], v[206:207] op_sel:[1,0]
	v_pk_add_f32 v[206:207], v[14:15], v[202:203]
	v_pk_mul_f32 v[202:203], v[14:15], v[202:203]
	v_mov_b32_e32 v63, v205
	v_pk_fma_f32 v[30:31], v[46:47], v[162:163], v[30:31]
	v_mov_b32_e32 v207, v203
	v_mul_f32_e32 v0, 0x3fd744fd, v205
	v_pk_add_f32 v[202:203], v[206:207], v[30:31]
	v_pk_fma_f32 v[30:31], v[62:63], s[66:67], v[0:1] op_sel_hi:[1,1,0]
	s_nop 0
	v_pk_mul_f32 v[62:63], v[30:31], v[30:31]
	s_nop 0
	v_mov_b32_e32 v31, v62
	v_pk_add_f32 v[62:63], v[202:203], v[30:31]
	s_nop 1
	v_mov_b32_dpp v202, v62 quad_perm:[1,0,3,2] row_mask:0xf bank_mask:0xf bound_ctrl:1
	v_mov_b32_dpp v203, v63 quad_perm:[1,0,3,2] row_mask:0xf bank_mask:0xf bound_ctrl:1
	v_pk_add_f32 v[62:63], v[62:63], v[202:203]
	s_nop 1
	v_mov_b32_dpp v202, v62 quad_perm:[2,3,0,1] row_mask:0xf bank_mask:0xf bound_ctrl:1
	v_mov_b32_dpp v203, v63 quad_perm:[2,3,0,1] row_mask:0xf bank_mask:0xf bound_ctrl:1
	v_pk_add_f32 v[62:63], v[62:63], v[202:203]
	s_nop 1
	v_mov_b32_dpp v202, v62 row_half_mirror row_mask:0xf bank_mask:0xf bound_ctrl:1
	v_mov_b32_dpp v203, v63 row_half_mirror row_mask:0xf bank_mask:0xf bound_ctrl:1
	v_pk_add_f32 v[62:63], v[62:63], v[202:203]
	s_nop 1
	v_mov_b32_dpp v202, v62 row_mirror row_mask:0xf bank_mask:0xf bound_ctrl:1
	v_mov_b32_dpp v203, v63 row_mirror row_mask:0xf bank_mask:0xf bound_ctrl:1
	s_and_saveexec_b64 s[6:7], vcc
	v_pk_add_f32 v[62:63], v[62:63], v[202:203]
	ds_write_b64 v160, v[62:63] offset:456
	s_or_b64 exec, exec, s[6:7]
	ds_read2_b32 v[62:63], v95 offset1:32
	ds_read2_b32 v[202:203], v95 offset0:64 offset1:96
	v_add_f32_e32 v0, 0, v64
	v_mov_b32_e32 v212, v48
	v_mov_b32_e32 v213, v32
	v_mul_f32_e32 v205, 0.5, v0
	s_waitcnt lgkmcnt(1)
	v_mul_f32_e32 v209, 0x3fd744fd, v62
	v_pk_add_f32 v[212:213], v[212:213], 0 op_sel_hi:[1,0]
	v_mov_b32_e32 v204, v32
	v_mov_b32_e32 v208, v1
	v_mov_b32_e32 v62, v63
	s_waitcnt lgkmcnt(0)
	v_mov_b32_e32 v63, v202
	s_mov_b32 s2, s67
	v_pk_add_f32 v[204:205], v[204:205], v[208:209]
	v_pk_mul_f32 v[208:209], v[62:63], s[2:3] op_sel_hi:[1,0]
	v_pk_mul_f32 v[214:215], v[212:213], 0.5 op_sel_hi:[1,0]
	v_pk_fma_f32 v[62:63], v[212:213], 0.5, v[208:209] op_sel_hi:[1,0,1]
	v_mov_b32_e32 v214, v205
	v_mov_b32_e32 v226, v1
	v_mov_b32_e32 v227, v209
	v_add_f32_e32 v206, 0, v16
	v_mov_b32_e32 v207, v203
	v_pk_mul_f32 v[212:213], v[62:63], v[62:63]
	v_pk_add_f32 v[214:215], v[214:215], v[226:227]
	v_mul_f32_e32 v0, 0x3fd744fd, v203
	v_mov_b32_e32 v163, v205
	v_pk_mov_b32 v[208:209], v[208:209], v[212:213] op_sel:[1,0]
	v_pk_add_f32 v[212:213], v[62:63], v[214:215]
	v_pk_mul_f32 v[214:215], v[62:63], v[214:215]
	v_pk_fma_f32 v[202:203], v[206:207], s[66:67], v[0:1] op_sel_hi:[1,1,0]
	v_pk_fma_f32 v[208:209], v[204:205], v[162:163], v[208:209]
	v_mov_b32_e32 v213, v215
	v_pk_mul_f32 v[206:207], v[202:203], v[202:203]
	v_pk_add_f32 v[208:209], v[212:213], v[208:209]
	v_mov_b32_e32 v203, v206
	v_pk_add_f32 v[206:207], v[208:209], v[202:203]
	s_nop 1
	v_mov_b32_dpp v208, v206 quad_perm:[1,0,3,2] row_mask:0xf bank_mask:0xf bound_ctrl:1
	v_mov_b32_dpp v209, v207 quad_perm:[1,0,3,2] row_mask:0xf bank_mask:0xf bound_ctrl:1
	v_pk_add_f32 v[206:207], v[206:207], v[208:209]
	s_nop 1
	v_mov_b32_dpp v208, v206 quad_perm:[2,3,0,1] row_mask:0xf bank_mask:0xf bound_ctrl:1
	v_mov_b32_dpp v209, v207 quad_perm:[2,3,0,1] row_mask:0xf bank_mask:0xf bound_ctrl:1
	v_pk_add_f32 v[206:207], v[206:207], v[208:209]
	s_nop 1
	v_mov_b32_dpp v208, v206 row_half_mirror row_mask:0xf bank_mask:0xf bound_ctrl:1
	v_mov_b32_dpp v209, v207 row_half_mirror row_mask:0xf bank_mask:0xf bound_ctrl:1
	v_pk_add_f32 v[206:207], v[206:207], v[208:209]
	s_nop 1
	v_mov_b32_dpp v208, v206 row_mirror row_mask:0xf bank_mask:0xf bound_ctrl:1
	v_mov_b32_dpp v209, v207 row_mirror row_mask:0xf bank_mask:0xf bound_ctrl:1
	s_and_saveexec_b64 s[6:7], vcc
	v_pk_add_f32 v[206:207], v[206:207], v[208:209]
	ds_write_b64 v160, v[206:207] offset:464
	s_or_b64 exec, exec, s[6:7]
	v_add_f32_e32 v0, 0, v65
	ds_read2_b32 v[64:65], v91 offset1:32
	ds_read2_b32 v[212:213], v91 offset0:64 offset1:96
	v_mov_b32_e32 v32, v49
	v_mul_f32_e32 v209, 0.5, v0
	v_add_f32_e32 v214, 0, v17
	s_waitcnt lgkmcnt(1)
	v_mul_f32_e32 v207, 0x3fd744fd, v64
	v_pk_add_f32 v[16:17], v[32:33], 0 op_sel_hi:[1,0]
	v_mov_b32_e32 v208, v33
	v_mov_b32_e32 v206, v1
	v_mov_b32_e32 v32, v65
	s_waitcnt lgkmcnt(0)
	v_mov_b32_e32 v33, v212
	s_mov_b32 s2, s67
	v_pk_add_f32 v[48:49], v[208:209], v[206:207]
	v_pk_mul_f32 v[32:33], v[32:33], s[2:3] op_sel_hi:[1,0]
	v_pk_mul_f32 v[64:65], v[16:17], 0.5 op_sel_hi:[1,0]
	v_pk_fma_f32 v[16:17], v[16:17], 0.5, v[32:33] op_sel_hi:[1,0,1]
	v_mov_b32_e32 v64, v49
	v_mov_b32_e32 v208, v1
	v_mov_b32_e32 v209, v33
	v_pk_mul_f32 v[206:207], v[16:17], v[16:17]
	v_pk_add_f32 v[64:65], v[64:65], v[208:209]
	v_mov_b32_e32 v163, v49
	v_pk_mov_b32 v[32:33], v[32:33], v[206:207] op_sel:[1,0]
	v_pk_add_f32 v[206:207], v[16:17], v[64:65]
	v_pk_mul_f32 v[64:65], v[16:17], v[64:65]
	v_mov_b32_e32 v215, v213
	v_pk_fma_f32 v[32:33], v[48:49], v[162:163], v[32:33]
	v_mov_b32_e32 v207, v65
	v_mul_f32_e32 v0, 0x3fd744fd, v213
	v_pk_add_f32 v[64:65], v[206:207], v[32:33]
	v_pk_fma_f32 v[32:33], v[214:215], s[66:67], v[0:1] op_sel_hi:[1,1,0]
	s_nop 0
	v_pk_mul_f32 v[206:207], v[32:33], v[32:33]
	s_nop 0
	v_mov_b32_e32 v33, v206
	v_pk_add_f32 v[64:65], v[64:65], v[32:33]
	s_nop 1
	v_mov_b32_dpp v206, v64 quad_perm:[1,0,3,2] row_mask:0xf bank_mask:0xf bound_ctrl:1
	v_mov_b32_dpp v207, v65 quad_perm:[1,0,3,2] row_mask:0xf bank_mask:0xf bound_ctrl:1
	v_pk_add_f32 v[64:65], v[64:65], v[206:207]
	s_nop 1
	v_mov_b32_dpp v206, v64 quad_perm:[2,3,0,1] row_mask:0xf bank_mask:0xf bound_ctrl:1
	v_mov_b32_dpp v207, v65 quad_perm:[2,3,0,1] row_mask:0xf bank_mask:0xf bound_ctrl:1
	v_pk_add_f32 v[64:65], v[64:65], v[206:207]
	s_nop 1
	v_mov_b32_dpp v206, v64 row_half_mirror row_mask:0xf bank_mask:0xf bound_ctrl:1
	v_mov_b32_dpp v207, v65 row_half_mirror row_mask:0xf bank_mask:0xf bound_ctrl:1
	v_pk_add_f32 v[64:65], v[64:65], v[206:207]
	s_nop 1
	v_mov_b32_dpp v206, v64 row_mirror row_mask:0xf bank_mask:0xf bound_ctrl:1
	v_mov_b32_dpp v207, v65 row_mirror row_mask:0xf bank_mask:0xf bound_ctrl:1
	s_and_saveexec_b64 s[6:7], vcc
	v_pk_add_f32 v[64:65], v[64:65], v[206:207]
	ds_write_b64 v160, v[64:65] offset:472
	s_or_b64 exec, exec, s[6:7]
	v_ashrrev_i32_e32 v206, 8, v164
	v_ashrrev_i32_e32 v207, 31, v206
	v_lshlrev_b64 v[64:65], 13, v[206:207]
	v_lshl_add_u64 v[64:65], s[8:9], 0, v[64:65]
	v_cmp_gt_i32_e64 s[40:41], s60, v210
	v_ashrrev_i32_e32 v169, 31, v168
	s_waitcnt lgkmcnt(0)
	s_barrier
; DI void ag_st64(u64_t* p, u64_t v) { __hip_atomic_store(p, v, __ATOMIC_RELAXED, __HIP_MEMORY_SCOPE_AGENT); }
;   DI void operator()(f32x16 (&acc)[2][4], int grow0, int gcol0, int lane, int w, char* lds) {
;     ...
;     if (tid < 256) {
;       float s1 = (red[tid * 2] + red[(256 + tid) * 2]) + (red[(512 + tid) * 2] + red[(768 + tid) * 2]);
;       float s2 = (red[tid * 2 + 1] + red[(256 + tid) * 2 + 1]) + (red[(512 + tid) * 2 + 1] + red[(768 + tid) * 2 + 1]);
;       ag_st64(myslots + tid * 4 + pn, ((u64_t)__float_as_uint(s2) << 32) | (u64_t)__float_as_uint(s1));
;     }
	s_and_saveexec_b64 s[6:7], s[40:41]
	s_cbranch_execz .LBB0_359
	v_lshl_add_u32 v0, v210, 3, v221
	ds_read2st64_b64 v[212:215], v0 offset1:4
	ds_read2st64_b64 v[226:229], v0 offset0:8 offset1:12
	v_ashrrev_i32_e32 v208, 8, v154
	v_ashrrev_i32_e32 v209, 31, v208
	s_waitcnt lgkmcnt(1)
	v_mov_b32_e32 v230, v212
	s_waitcnt lgkmcnt(0)
	v_mov_b32_e32 v231, v226
	v_mov_b32_e32 v232, v214
	v_mov_b32_e32 v233, v228
	v_mov_b32_e32 v226, v213
	v_mov_b32_e32 v228, v215
	v_pk_add_f32 v[230:231], v[230:231], v[232:233]
	v_pk_add_f32 v[212:213], v[226:227], v[228:229]
	v_pk_add_f32 v[230:231], v[230:231], v[230:231] op_sel:[0,1] op_sel_hi:[1,0]
	v_pk_add_f32 v[212:213], v[212:213], v[212:213] op_sel:[0,1] op_sel_hi:[1,0]
	v_lshl_add_u64 v[214:215], v[168:169], 3, v[64:65]
	v_lshl_add_u64 v[208:209], v[208:209], 3, v[214:215]
	v_mov_b32_e32 v231, v212
	global_store_dwordx2 v[208:209], v[230:231], off sc1

; DI f32x16 mfma(bf16x8 a, bf16x8 b, f32x16 c) { return __builtin_amdgcn_mfma_f32_32x32x16_bf16(a, b, c, 0, 0, 0); }
; DI int launder(int x) { asm volatile("" : "+v"(x)); return x; }
; template <int BK> DI int swz(int row) { constexpr int CPR = BK / 8; return (row / (16 / CPR)) % CPR; }
; DI void wait_vm0() { asm volatile("s_waitcnt vmcnt(0)" ::: "memory"); }
;     ...
; #pragma unroll
;     for (int mt = 0; mt < 2; ++mt) { int row = wm * 64 + mt * 32 + l31; fa[0][mt] = *(const bf16x8*)(cur + row * (BK * 2) + ((hh ^ swz<BK>(row)) << 4)); }
; #pragma unroll
;     for (int nt = 0; nt < NTW; ++nt) { int row = wn * (32 * NTW) + nt * 32 + l31; fb[0][nt] = *(const bf16x8*)(cur + ABYTES + row * (BK * 2) + ((hh ^ swz<BK>(row)) << 4)); }
; #pragma unroll
;     for (int kk = 0; kk < NKK; ++kk) {
;       if (kk + 1 < NKK) {
;         const int ch = (kk + 1) * 2 + hh;
; #pragma unroll
;         for (int mt = 0; mt < 2; ++mt) { int row = wm * 64 + mt * 32 + l31; fa[(kk + 1) & 1][mt] = *(const bf16x8*)(cur + row * (BK * 2) + ((ch ^ swz<BK>(row)) << 4)); }
; #pragma unroll
;         for (int nt = 0; nt < NTW; ++nt) { int row = wn * (32 * NTW) + nt * 32 + l31; fb[(kk + 1) & 1][nt] = *(const bf16x8*)(cur + ABYTES + row * (BK * 2) + ((ch ^ swz<BK>(row)) << 4)); }
;       }
;       if (more) {
; #pragma unroll
;         for (int q = 0; q < PPK; ++q) {
;           const int pi = kk * PPK + q;
;           if (pi < NPA) stage_piece<BM, BK>(An, lda, nxt, tid, pi, wv);
;           else if (pi < NP) stage_piece<BN, BK>(Bn, ldb, nxt + ABYTES, tid, pi - NPA, wv);
;         }
;       }
;       __builtin_amdgcn_s_setprio(1);
; #pragma unroll
;       for (int mt = 0; mt < 2; ++mt)
; #pragma unroll
;         for (int nt = 0; nt < NTW; ++nt) acc[mt][nt] = mfma(fa[kk & 1][mt], fb[kk & 1][nt], acc[mt][nt]);
;       __builtin_amdgcn_s_setprio(0);
;       __builtin_amdgcn_sched_barrier(0);
;     }
;     wait_vm0();
;     __syncthreads();
;   }
;   if (has_next) { const int tid3 = launder(threadIdx.x); stage_tile<BM, BK>(A + (size_t)row0n * lda, lda, lds, tid3); stage_tile<BN, BK>(Bt + (size_t)col0n * ldb, ldb, lds + ABYTES, tid3); }
.Lk382_exit:
	v_mfma_f32_32x32x16_bf16 v[114:129], v[190:193], v[198:201], v[114:129]
	v_mfma_f32_32x32x16_bf16 v[98:113], v[190:193], v[202:205], v[98:113]
	v_mfma_f32_32x32x16_bf16 v[82:97], v[190:193], v[206:209], v[82:97]
	v_mfma_f32_32x32x16_bf16 v[66:81], v[190:193], v[210:213], v[66:81]
	v_mfma_f32_32x32x16_bf16 v[50:65], v[194:197], v[198:201], v[50:65]
	v_mfma_f32_32x32x16_bf16 v[34:49], v[194:197], v[202:205], v[34:49]
	v_mfma_f32_32x32x16_bf16 v[18:33], v[194:197], v[206:209], v[18:33]
	v_mfma_f32_32x32x16_bf16 v[2:17], v[194:197], v[210:213], v[2:17]
	s_waitcnt lgkmcnt(0)
	v_add_u32_e32 v0, 0x10000, v140
	v_add_u32_e32 v198, 0x10000, v142
	v_add_u32_e32 v130, v0, v141
	v_add_u32_e32 v140, v198, v144
	v_add_u32_e32 v199, 0x18000, v143
	v_add_u32_e32 v200, 0x18000, v152
	ds_read_b128 v[130:133], v130
	ds_read_b128 v[166:169], v140
	v_add_u32_e32 v140, v199, v151
	v_add_u32_e32 v144, v200, v154
	v_add_u32_e32 v201, 0x18000, v153
	ds_read_b128 v[140:143], v140
	ds_read_b128 v[170:173], v144
	v_add_u32_e32 v144, v201, v155
	v_add_u32_e32 v202, 0x18000, v156
	v_add_u32_e32 v151, v202, v164
	ds_read_b128 v[152:155], v144
	ds_read_b128 v[174:177], v151
	v_add_u32_e32 v144, v0, v161
	v_add_u32_e32 v151, v198, v163
	ds_read_b128 v[178:181], v144
	ds_read_b128 v[182:185], v151
	v_add_u32_e32 v144, v199, v159
	v_add_u32_e32 v151, v200, v160
	ds_read_b128 v[186:189], v144
	ds_read_b128 v[190:193], v151
	v_add_u32_e32 v144, v201, v157
	v_add_u32_e32 v151, v202, v158
	ds_read_b128 v[156:159], v144
	ds_read_b128 v[194:197], v151
	s_add_i32 s36, s36, s94
	s_cmpk_gt_i32 s36, 0x4ff
	s_cselect_b64 s[42:43], -1, 0
	s_cmpk_lt_i32 s36, 0x500
	s_waitcnt lgkmcnt(9)
	v_mfma_f32_32x32x16_bf16 v[114:129], v[130:133], v[140:143], v[114:129]
	s_waitcnt lgkmcnt(8)
	v_mfma_f32_32x32x16_bf16 v[98:113], v[130:133], v[170:173], v[98:113]
	s_waitcnt lgkmcnt(7)
	v_mfma_f32_32x32x16_bf16 v[82:97], v[130:133], v[152:155], v[82:97]
	s_waitcnt lgkmcnt(6)
	v_mfma_f32_32x32x16_bf16 v[66:81], v[130:133], v[174:177], v[66:81]
	v_mfma_f32_32x32x16_bf16 v[50:65], v[166:169], v[140:143], v[50:65]
	v_mfma_f32_32x32x16_bf16 v[34:49], v[166:169], v[170:173], v[34:49]
	v_mfma_f32_32x32x16_bf16 v[18:33], v[166:169], v[152:155], v[18:33]
	v_mfma_f32_32x32x16_bf16 v[2:17], v[166:169], v[174:177], v[2:17]
	v_add_u32_e32 v130, v0, v149
	v_add_u32_e32 v140, v198, v150
	v_add_u32_e32 v144, v199, v147
	ds_read_b128 v[130:133], v130
	ds_read_b128 v[140:143], v140
	v_add_u32_e32 v147, v200, v148
	ds_read_b128 v[148:151], v144
	ds_read_b128 v[152:155], v147
	v_add_u32_e32 v144, v201, v145
	v_add_u32_e32 v160, v202, v146
	ds_read_b128 v[144:147], v144
	ds_read_b128 v[166:169], v160
	s_waitcnt lgkmcnt(9)
	v_mfma_f32_32x32x16_bf16 v[114:129], v[178:181], v[186:189], v[114:129]
	s_waitcnt lgkmcnt(8)
	v_mfma_f32_32x32x16_bf16 v[98:113], v[178:181], v[190:193], v[98:113]
	s_waitcnt lgkmcnt(7)
	v_mfma_f32_32x32x16_bf16 v[82:97], v[178:181], v[156:159], v[82:97]
	s_waitcnt lgkmcnt(6)
	v_mfma_f32_32x32x16_bf16 v[66:81], v[178:181], v[194:197], v[66:81]
	v_mfma_f32_32x32x16_bf16 v[50:65], v[182:185], v[186:189], v[50:65]
	v_mfma_f32_32x32x16_bf16 v[34:49], v[182:185], v[190:193], v[34:49]
	v_mfma_f32_32x32x16_bf16 v[18:33], v[182:185], v[156:159], v[18:33]
	v_mfma_f32_32x32x16_bf16 v[2:17], v[182:185], v[194:197], v[2:17]
	v_add_u32_e32 v0, v0, v138
	v_add_u32_e32 v138, v198, v139
	ds_read_b128 v[156:159], v0
	ds_read_b128 v[170:173], v138
	v_add_u32_e32 v0, v199, v136
	v_add_u32_e32 v160, v200, v137
	ds_read_b128 v[136:139], v0
	ds_read_b128 v[174:177], v160
	v_add_u32_e32 v0, v201, v134
	v_add_u32_e32 v134, v202, v135
	ds_read_b128 v[178:181], v0
	ds_read_b128 v[182:185], v134
	s_waitcnt lgkmcnt(9)
	v_mfma_f32_32x32x16_bf16 v[114:129], v[130:133], v[148:151], v[114:129]
	s_waitcnt lgkmcnt(8)
	v_mfma_f32_32x32x16_bf16 v[98:113], v[130:133], v[152:155], v[98:113]
	s_waitcnt lgkmcnt(7)
	v_mfma_f32_32x32x16_bf16 v[82:97], v[130:133], v[144:147], v[82:97]
	s_waitcnt lgkmcnt(6)
	v_mfma_f32_32x32x16_bf16 v[66:81], v[130:133], v[166:169], v[66:81]
	v_mfma_f32_32x32x16_bf16 v[50:65], v[140:143], v[148:151], v[50:65]
	v_mfma_f32_32x32x16_bf16 v[34:49], v[140:143], v[152:155], v[34:49]
	v_mfma_f32_32x32x16_bf16 v[18:33], v[140:143], v[144:147], v[18:33]
	v_mfma_f32_32x32x16_bf16 v[2:17], v[140:143], v[166:169], v[2:17]
	s_waitcnt lgkmcnt(3)
	v_mfma_f32_32x32x16_bf16 v[114:129], v[156:159], v[136:139], v[114:129]
	s_waitcnt lgkmcnt(2)
	v_mfma_f32_32x32x16_bf16 v[98:113], v[156:159], v[174:177], v[98:113]
	s_waitcnt lgkmcnt(1)
	v_mfma_f32_32x32x16_bf16 v[82:97], v[156:159], v[178:181], v[82:97]
	s_waitcnt lgkmcnt(0)
	v_mfma_f32_32x32x16_bf16 v[66:81], v[156:159], v[182:185], v[66:81]
	v_mfma_f32_32x32x16_bf16 v[50:65], v[170:173], v[136:139], v[50:65]
	v_mfma_f32_32x32x16_bf16 v[34:49], v[170:173], v[174:177], v[34:49]
	v_mfma_f32_32x32x16_bf16 v[18:33], v[170:173], v[178:181], v[18:33]
	v_mfma_f32_32x32x16_bf16 v[2:17], v[170:173], v[182:185], v[2:17]
	s_waitcnt vmcnt(0)
	s_barrier
	s_cbranch_scc0 .LBB0_378
	v_mov_b32_e32 v132, v216
	s_lshl_b32 s3, s36, 3
	v_ashrrev_i32_e32 v0, 31, v132
	v_lshrrev_b32_e32 v130, 29, v0
	v_lshrrev_b32_e32 v0, 28, v0
	v_add_u32_e32 v0, v132, v0
	v_ashrrev_i32_e32 v0, 4, v0
	s_and_b32 s3, s3, 56
	s_bfe_u32 s7, s36, 0x30003
	v_lshrrev_b32_e32 v133, 29, v0
	s_or_b32 s3, s3, s7
	s_lshl_b32 s7, s36, 2
	v_add_u32_e32 v130, v132, v130
	v_add_u32_e32 v133, v0, v133
	s_and_b32 s30, s7, 0xffffff00
	s_lshl_b32 s3, s3, 19
	v_and_b32_e32 v131, 0xffffff8, v130
	v_and_b32_e32 v133, 0xffffff8, v133
	s_add_u32 s44, s12, s3
	v_sub_u32_e32 v131, v132, v131
	v_sub_u32_e32 v0, v0, v133
	v_lshlrev_b32_e32 v130, 8, v130
	v_readfirstlane_b32 s3, v132
	s_addc_u32 s45, s13, 0
	v_xor_b32_e32 v0, v0, v131
	v_and_b32_e32 v130, 0xfffff800, v130
	s_lshl_b32 s3, s3, 4
	v_lshl_add_u32 v0, v0, 4, v130
	s_and_b32 s3, s3, 0xfffffc00
	v_lshl_add_u64 v[130:131], s[44:45], 0, v[0:1]
	s_mov_b32 m0, s3
	v_lshl_add_u64 v[132:133], v[130:131], 0, s[58:59]
	global_load_lds_dwordx4 v0, s[44:45]
	s_add_i32 m0, s3, 0x2000
	s_ashr_i32 s31, s30, 31
	global_load_lds_dwordx4 v[132:133], off
	v_lshl_add_u64 v[132:133], v[130:131], 0, s[48:49]
	s_add_i32 m0, s3, 0x4000
	s_lshl_b64 s[30:31], s[30:31], 11
	global_load_lds_dwordx4 v[132:133], off
	s_add_i32 m0, s3, 0x6000
	s_add_u32 s30, s40, s30
	v_lshl_add_u64 v[130:131], v[130:131], 0, s[50:51]
	s_addc_u32 s31, s41, s31
	global_load_lds_dwordx4 v[130:131], off
	v_lshl_add_u64 v[130:131], s[30:31], 0, v[0:1]
	s_add_i32 m0, s3, 0x8000
	v_lshl_add_u64 v[132:133], v[130:131], 0, s[58:59]
	global_load_lds_dwordx4 v0, s[30:31]
	s_add_i32 m0, s3, 0xa000
	s_nop 0
	global_load_lds_dwordx4 v[132:133], off
	v_lshl_add_u64 v[132:133], v[130:131], 0, s[48:49]
	s_add_i32 m0, s3, 0xc000
	v_lshl_add_u64 v[130:131], v[130:131], 0, s[50:51]
	global_load_lds_dwordx4 v[132:133], off
	s_add_i32 m0, s3, 0xe000
	s_nop 0
	global_load_lds_dwordx4 v[130:131], off
	s_branch .LBB0_378

; DI bf16_t f2bf(float x) { return (bf16_t)(pack2(x, 0.f) & 0xffffu); }
; DI int crow(int i, int hh) { return (i & 3) + 8 * (i >> 2) + 4 * hh; }
; DI f32x16 mfma(bf16x8 a, bf16x8 b, f32x16 c) { return __builtin_amdgcn_mfma_f32_32x32x16_bf16(a, b, c, 0, 0, 0); }
; template <int BK> DI int swz(int row) { constexpr int CPR = BK / 8; return (row / (16 / CPR)) % CPR; }
;     ...
;     for (int kk = 0; kk < NKK; ++kk) {
;       if (kk + 1 < NKK) {
;         const int ch = (kk + 1) * 2 + hh;
; #pragma unroll
;         for (int mt = 0; mt < 2; ++mt) { int row = wm * 64 + mt * 32 + l31; fa[(kk + 1) & 1][mt] = *(const bf16x8*)(cur + row * (BK * 2) + ((ch ^ swz<BK>(row)) << 4)); }
; #pragma unroll
;         for (int nt = 0; nt < NTW; ++nt) { int row = wn * (32 * NTW) + nt * 32 + l31; fb[(kk + 1) & 1][nt] = *(const bf16x8*)(cur + ABYTES + row * (BK * 2) + ((ch ^ swz<BK>(row)) << 4)); }
;       }
;       if (more) {
; #pragma unroll
;         for (int q = 0; q < PPK; ++q) {
;           const int pi = kk * PPK + q;
;           if (pi < NPA) stage_piece<BM, BK>(An, lda, nxt, tid, pi, wv);
;           else if (pi < NP) stage_piece<BN, BK>(Bn, ldb, nxt + ABYTES, tid, pi - NPA, wv);
;         }
;       }
;       __builtin_amdgcn_s_setprio(1);
; #pragma unroll
;       for (int mt = 0; mt < 2; ++mt)
; #pragma unroll
;         for (int nt = 0; nt < NTW; ++nt) acc[mt][nt] = mfma(fa[kk & 1][mt], fb[kk & 1][nt], acc[mt][nt]);
;       __builtin_amdgcn_s_setprio(0);
;       __builtin_amdgcn_sched_barrier(0);
;     }
;   template <int NTW>
;   DI void operator()(f32x16 (&acc)[2][NTW], int grow0, int gcol0, int lane, int w, char* lds) {
;     ...
; #pragma unroll
;     for (int mt = 0; mt < 2; ++mt)
; #pragma unroll
;       for (int pr = 0; pr < NTW / 2; ++pr) {
;         const int col = (gcol0 / 64 + pr) * 32 + l31;
; #pragma unroll
;         for (int i = 0; i < 16; ++i) {
;           float g = acc[mt][2 * pr][i], u = acc[mt][2 * pr + 1][i];
;           float v = g * __builtin_amdgcn_rcpf(1.f + __expf(-g)) * u;
;           int row = grow0 + mt * 32 + crow(i, hh);
;           H[(size_t)row * F_ + col] = f2bf(v);
;         }
.Lk388_exit:
	v_mfma_f32_32x32x16_bf16 v[50:65], v[106:109], v[114:117], v[50:65]
	v_mfma_f32_32x32x16_bf16 v[34:49], v[106:109], v[118:121], v[34:49]
	v_mfma_f32_32x32x16_bf16 v[18:33], v[110:113], v[114:117], v[18:33]
	v_mfma_f32_32x32x16_bf16 v[2:17], v[110:113], v[118:121], v[2:17]
	s_waitcnt lgkmcnt(0)
	v_add_u32_e32 v0, v70, v76
	v_add_u32_e32 v76, v71, v80
	ds_read_b128 v[66:69], v0 offset:49152
	ds_read_b128 v[90:93], v76 offset:49152
	v_add_u32_e32 v0, 0x14000, v77
	v_add_u32_e32 v76, v0, v83
	v_add_u32_e32 v114, 0x14000, v84
	v_add_u32_e32 v77, v114, v89
	ds_read_b128 v[94:97], v76
	ds_read_b128 v[98:101], v77
	v_add_u32_e32 v76, v70, v87
	v_add_u32_e32 v77, v71, v88
	ds_read_b128 v[102:105], v76 offset:49152
	ds_read_b128 v[106:109], v77 offset:49152
	v_add_u32_e32 v76, v0, v85
	v_add_u32_e32 v77, v114, v86
	ds_read_b128 v[84:87], v76
	ds_read_b128 v[110:113], v77
	s_lshl_b32 s2, s2, 8
	s_waitcnt lgkmcnt(5)
	v_mfma_f32_32x32x16_bf16 v[50:65], v[66:69], v[94:97], v[50:65]
	s_waitcnt lgkmcnt(4)
	v_mfma_f32_32x32x16_bf16 v[34:49], v[66:69], v[98:101], v[34:49]
	v_mfma_f32_32x32x16_bf16 v[18:33], v[90:93], v[94:97], v[18:33]
	v_mfma_f32_32x32x16_bf16 v[2:17], v[90:93], v[98:101], v[2:17]
	v_add_u32_e32 v66, v70, v81
	v_add_u32_e32 v76, v71, v82
	ds_read_b128 v[66:69], v66 offset:49152
	ds_read_b128 v[80:83], v76 offset:49152
	v_add_u32_e32 v76, v0, v78
	v_add_u32_e32 v88, v114, v79
	ds_read_b128 v[76:79], v76
	ds_read_b128 v[88:91], v88
	s_waitcnt lgkmcnt(5)
	v_mfma_f32_32x32x16_bf16 v[50:65], v[102:105], v[84:87], v[50:65]
	s_waitcnt lgkmcnt(4)
	v_mfma_f32_32x32x16_bf16 v[34:49], v[102:105], v[110:113], v[34:49]
	v_mfma_f32_32x32x16_bf16 v[18:33], v[106:109], v[84:87], v[18:33]
	v_mfma_f32_32x32x16_bf16 v[2:17], v[106:109], v[110:113], v[2:17]
	v_add_u32_e32 v70, v70, v74
	v_add_u32_e32 v71, v71, v75
	v_add_u32_e32 v0, v0, v72
	ds_read_b128 v[84:87], v70 offset:49152
	ds_read_b128 v[92:95], v71 offset:49152
	v_add_u32_e32 v74, v114, v73
	ds_read_b128 v[70:73], v0
	ds_read_b128 v[96:99], v74
	s_waitcnt lgkmcnt(5)
	v_mfma_f32_32x32x16_bf16 v[50:65], v[66:69], v[76:79], v[50:65]
	s_waitcnt lgkmcnt(4)
	v_mfma_f32_32x32x16_bf16 v[34:49], v[66:69], v[88:91], v[34:49]
	v_mfma_f32_32x32x16_bf16 v[18:33], v[80:83], v[76:79], v[18:33]
	v_mfma_f32_32x32x16_bf16 v[2:17], v[80:83], v[88:91], v[2:17]
	s_waitcnt lgkmcnt(1)
	v_mfma_f32_32x32x16_bf16 v[50:65], v[84:87], v[70:73], v[50:65]
	s_waitcnt lgkmcnt(0)
	v_mfma_f32_32x32x16_bf16 v[34:49], v[84:87], v[96:99], v[34:49]
	v_mfma_f32_32x32x16_bf16 v[18:33], v[92:95], v[70:73], v[18:33]
	v_mfma_f32_32x32x16_bf16 v[2:17], v[92:95], v[96:99], v[2:17]
	v_mov_b32_e32 v0, v216
	s_waitcnt vmcnt(0)
	s_barrier
	s_add_i32 s36, s36, s94
	v_ashrrev_i32_e32 v66, 6, v0
	v_lshrrev_b32_e32 v67, 30, v66
	v_add_u32_e32 v67, v66, v67
	v_ashrrev_i32_e32 v67, 2, v67
	v_mul_i32_i24_e32 v68, 4, v67
	v_sub_u32_e32 v68, v66, v68
	v_lshl_add_u32 v66, v67, 6, s6
	v_ashrrev_i32_e32 v66, 1, v66
	v_and_or_b32 v66, v0, 31, v66
	v_lshrrev_b32_e32 v0, 3, v0
	v_and_or_b32 v0, v0, 4, s2
	v_lshl_add_u32 v0, v68, 6, v0
	v_mul_f32_e32 v68, 0xbfb8aa3b, v50
	v_exp_f32_e32 v68, v68
	s_movk_i32 s2, 0x1600
	v_ashrrev_i32_e32 v67, 31, v66
	v_lshl_add_u64 v[66:67], v[66:67], 1, s[76:77]
	v_add_f32_e32 v68, 1.0, v68
	v_rcp_f32_e32 v68, v68
	s_add_i32 s35, s35, s63
	v_mul_f32_e32 v50, v50, v68
	v_mul_lo_u32 v68, v0, s2
	v_mul_f32_e32 v0, 0xbfb8aa3b, v51
	v_exp_f32_e32 v0, v0
	v_mul_f32_e32 v34, v34, v50
	v_ashrrev_i32_e32 v69, 31, v68
	v_cvt_pk_bf16_f32 v34, v34, s0
	v_add_f32_e32 v0, 1.0, v0
	v_rcp_f32_e32 v0, v0
	v_lshl_add_u64 v[66:67], v[66:67], 0, v[68:69]
	s_movk_i32 s2, 0x1000
	global_store_short v[66:67], v34, off
	v_mul_f32_e32 v0, v51, v0
	v_mul_f32_e32 v0, v35, v0
	v_add_co_u32_e32 v34, vcc, s2, v66
	v_cvt_pk_bf16_f32 v0, v0, s0
	s_nop 0
	v_addc_co_u32_e32 v35, vcc, 0, v67, vcc
	global_store_short v[34:35], v0, off offset:1536
	v_mul_f32_e32 v0, 0xbfb8aa3b, v52
	v_exp_f32_e32 v0, v0
	s_movk_i32 s2, 0x2000
	v_add_co_u32_e32 v34, vcc, s2, v66
	v_add_f32_e32 v0, 1.0, v0
	v_rcp_f32_e32 v0, v0
	v_addc_co_u32_e32 v35, vcc, 0, v67, vcc
	s_mov_b32 s2, 0xb000
	v_mul_f32_e32 v0, v52, v0
	v_mul_f32_e32 v0, v36, v0
	v_cvt_pk_bf16_f32 v0, v0, s0
	global_store_short v[34:35], v0, off offset:3072
	v_mul_f32_e32 v0, 0xbfb8aa3b, v53
	v_exp_f32_e32 v0, v0
	v_add_co_u32_e32 v34, vcc, s91, v66
	v_add_f32_e32 v0, 1.0, v0
	v_rcp_f32_e32 v0, v0
	v_addc_co_u32_e32 v35, vcc, 0, v67, vcc
	v_mul_f32_e32 v0, v53, v0
	v_mul_f32_e32 v0, v37, v0
	v_cvt_pk_bf16_f32 v0, v0, s0
	global_store_short v[34:35], v0, off offset:512
	v_mul_f32_e32 v0, 0xbfb8aa3b, v54
	v_exp_f32_e32 v0, v0
	v_add_co_u32_e32 v34, vcc, s2, v66
	s_mov_b32 s2, 0xc000
	v_add_f32_e32 v0, 1.0, v0
	v_rcp_f32_e32 v0, v0
	v_addc_co_u32_e32 v35, vcc, 0, v67, vcc
	v_mul_f32_e32 v0, v54, v0
	v_mul_f32_e32 v0, v38, v0
	v_cvt_pk_bf16_f32 v0, v0, s0
	global_store_short v[34:35], v0, off
	v_mul_f32_e32 v0, 0xbfb8aa3b, v55
	v_exp_f32_e32 v0, v0
	v_add_co_u32_e32 v34, vcc, s2, v66
	s_mov_b32 s2, 0xd000
	v_add_f32_e32 v0, 1.0, v0
	v_rcp_f32_e32 v0, v0
	v_addc_co_u32_e32 v35, vcc, 0, v67, vcc
	v_mul_f32_e32 v0, v55, v0
	v_mul_f32_e32 v0, v39, v0
	v_cvt_pk_bf16_f32 v0, v0, s0
	global_store_short v[34:35], v0, off offset:1536
	v_mul_f32_e32 v0, 0xbfb8aa3b, v56
	v_exp_f32_e32 v0, v0
	v_add_co_u32_e32 v34, vcc, s2, v66
	s_mov_b32 s2, 0xf000
	v_add_f32_e32 v0, 1.0, v0
	v_rcp_f32_e32 v0, v0
	v_addc_co_u32_e32 v35, vcc, 0, v67, vcc
	v_mul_f32_e32 v0, v56, v0
	v_mul_f32_e32 v0, v40, v0
	v_cvt_pk_bf16_f32 v0, v0, s0
	global_store_short v[34:35], v0, off offset:3072
	v_mul_f32_e32 v0, 0xbfb8aa3b, v57
	v_exp_f32_e32 v0, v0
; DI bf16_t f2bf(float x) { return (bf16_t)(pack2(x, 0.f) & 0xffffu); }
; DI int crow(int i, int hh) { return (i & 3) + 8 * (i >> 2) + 4 * hh; }
;   template <int NTW>
;   DI void operator()(f32x16 (&acc)[2][NTW], int grow0, int gcol0, int lane, int w, char* lds) {
;     ...
; #pragma unroll
;     for (int mt = 0; mt < 2; ++mt)
; #pragma unroll
;       for (int pr = 0; pr < NTW / 2; ++pr) {
;         const int col = (gcol0 / 64 + pr) * 32 + l31;
; #pragma unroll
;         for (int i = 0; i < 16; ++i) {
;           float g = acc[mt][2 * pr][i], u = acc[mt][2 * pr + 1][i];
;           float v = g * __builtin_amdgcn_rcpf(1.f + __expf(-g)) * u;
;           int row = grow0 + mt * 32 + crow(i, hh);
;           H[(size_t)row * F_ + col] = f2bf(v);
;         }
	v_add_co_u32_e32 v34, vcc, s2, v66
	s_mov_b32 s2, 0x16000
	v_add_f32_e32 v0, 1.0, v0
	v_rcp_f32_e32 v0, v0
	v_addc_co_u32_e32 v35, vcc, 0, v67, vcc
	v_mul_f32_e32 v0, v57, v0
	v_mul_f32_e32 v0, v41, v0
	v_cvt_pk_bf16_f32 v0, v0, s0
	global_store_short v[34:35], v0, off offset:512
	v_mul_f32_e32 v0, 0xbfb8aa3b, v58
	v_exp_f32_e32 v0, v0
	v_add_co_u32_e32 v34, vcc, s2, v66
	s_mov_b32 s2, 0x17000
	v_add_f32_e32 v0, 1.0, v0
	v_rcp_f32_e32 v0, v0
	v_addc_co_u32_e32 v35, vcc, 0, v67, vcc
	v_mul_f32_e32 v0, v58, v0
	v_mul_f32_e32 v0, v42, v0
	v_cvt_pk_bf16_f32 v0, v0, s0
	global_store_short v[34:35], v0, off
	v_mul_f32_e32 v0, 0xbfb8aa3b, v59
	v_exp_f32_e32 v0, v0
	v_add_co_u32_e32 v34, vcc, s2, v66
	s_mov_b32 s2, 0x18000
	v_add_f32_e32 v0, 1.0, v0
	v_rcp_f32_e32 v0, v0
	v_addc_co_u32_e32 v35, vcc, 0, v67, vcc
	v_mul_f32_e32 v0, v59, v0
	v_mul_f32_e32 v0, v43, v0
	v_cvt_pk_bf16_f32 v0, v0, s0
	global_store_short v[34:35], v0, off offset:1536
	v_mul_f32_e32 v0, 0xbfb8aa3b, v60
	v_exp_f32_e32 v0, v0
	v_add_co_u32_e32 v34, vcc, s2, v66
	s_mov_b32 s2, 0x1a000
	v_add_f32_e32 v0, 1.0, v0
	v_rcp_f32_e32 v0, v0
	v_addc_co_u32_e32 v35, vcc, 0, v67, vcc
	v_mul_f32_e32 v0, v60, v0
	v_mul_f32_e32 v0, v44, v0
	v_cvt_pk_bf16_f32 v0, v0, s0
	global_store_short v[34:35], v0, off offset:3072
	v_mul_f32_e32 v0, 0xbfb8aa3b, v61
	v_exp_f32_e32 v0, v0
	v_add_co_u32_e32 v34, vcc, s2, v66
	s_mov_b32 s2, 0x21000
	v_add_f32_e32 v0, 1.0, v0
	v_rcp_f32_e32 v0, v0
	v_addc_co_u32_e32 v35, vcc, 0, v67, vcc
	v_mul_f32_e32 v0, v61, v0
	v_mul_f32_e32 v0, v45, v0
	v_cvt_pk_bf16_f32 v0, v0, s0
	global_store_short v[34:35], v0, off offset:512
	v_mul_f32_e32 v0, 0xbfb8aa3b, v62
	v_exp_f32_e32 v0, v0
	v_add_co_u32_e32 v34, vcc, s2, v66
	s_mov_b32 s2, 0x22000
	v_add_f32_e32 v0, 1.0, v0
	v_rcp_f32_e32 v0, v0
	v_addc_co_u32_e32 v35, vcc, 0, v67, vcc
	v_mul_f32_e32 v0, v62, v0
	v_mul_f32_e32 v0, v46, v0
	v_cvt_pk_bf16_f32 v0, v0, s0
	global_store_short v[34:35], v0, off
	v_mul_f32_e32 v0, 0xbfb8aa3b, v63
	v_exp_f32_e32 v0, v0
	v_add_co_u32_e32 v34, vcc, s2, v66
	s_mov_b32 s2, 0x23000
	v_add_f32_e32 v0, 1.0, v0
	v_rcp_f32_e32 v0, v0
	v_addc_co_u32_e32 v35, vcc, 0, v67, vcc
	v_mul_f32_e32 v0, v63, v0
	v_mul_f32_e32 v0, v47, v0
	v_cvt_pk_bf16_f32 v0, v0, s0
	global_store_short v[34:35], v0, off offset:1536
	v_mul_f32_e32 v0, 0xbfb8aa3b, v64
	v_exp_f32_e32 v0, v0
	v_add_co_u32_e32 v34, vcc, s2, v66
	s_mov_b32 s2, 0x25000
	v_add_f32_e32 v0, 1.0, v0
	v_rcp_f32_e32 v0, v0
	v_addc_co_u32_e32 v35, vcc, 0, v67, vcc
	v_mul_f32_e32 v0, v64, v0
	v_mul_f32_e32 v0, v48, v0
	v_cvt_pk_bf16_f32 v0, v0, s0
	global_store_short v[34:35], v0, off offset:3072
	v_mul_f32_e32 v0, 0xbfb8aa3b, v65
	v_exp_f32_e32 v0, v0
	v_add_co_u32_e32 v34, vcc, s2, v66
	s_mov_b32 s2, 0x2c000
	v_add_f32_e32 v0, 1.0, v0
	v_rcp_f32_e32 v0, v0
	v_addc_co_u32_e32 v35, vcc, 0, v67, vcc
	v_mul_f32_e32 v0, v65, v0
	v_mul_f32_e32 v0, v49, v0
	v_cvt_pk_bf16_f32 v0, v0, s0
	global_store_short v[34:35], v0, off offset:512
	v_mul_f32_e32 v0, 0xbfb8aa3b, v18
	v_exp_f32_e32 v0, v0
	v_add_co_u32_e32 v34, vcc, s2, v66
	s_mov_b32 s2, 0x2d000
	v_add_f32_e32 v0, 1.0, v0
	v_rcp_f32_e32 v0, v0
	v_addc_co_u32_e32 v35, vcc, 0, v67, vcc
	v_mul_f32_e32 v0, v18, v0
	v_mul_f32_e32 v0, v2, v0
	v_cvt_pk_bf16_f32 v0, v0, s0
	global_store_short v[34:35], v0, off
	v_mul_f32_e32 v0, 0xbfb8aa3b, v19
	v_exp_f32_e32 v0, v0
	v_add_co_u32_e32 v2, vcc, s2, v66
	s_mov_b32 s2, 0x2e000
	v_add_f32_e32 v0, 1.0, v0
	v_rcp_f32_e32 v0, v0
	s_nop 0
	v_mul_f32_e32 v0, v19, v0
	v_mul_f32_e32 v0, v3, v0
	v_cvt_pk_bf16_f32 v0, v0, s0
	v_addc_co_u32_e32 v3, vcc, 0, v67, vcc
	global_store_short v[2:3], v0, off offset:1536
	v_mul_f32_e32 v0, 0xbfb8aa3b, v20
	v_exp_f32_e32 v0, v0
	v_add_co_u32_e32 v2, vcc, s2, v66
	s_mov_b32 s2, 0x30000
	v_add_f32_e32 v0, 1.0, v0
	v_rcp_f32_e32 v0, v0
	v_addc_co_u32_e32 v3, vcc, 0, v67, vcc
	v_mul_f32_e32 v0, v20, v0
	v_mul_f32_e32 v0, v4, v0
	v_cvt_pk_bf16_f32 v0, v0, s0
	global_store_short v[2:3], v0, off offset:3072
	v_mul_f32_e32 v0, 0xbfb8aa3b, v21
	v_exp_f32_e32 v0, v0
	v_add_co_u32_e32 v2, vcc, s2, v66
	s_mov_b32 s2, 0x37000
	v_add_f32_e32 v0, 1.0, v0
	v_rcp_f32_e32 v0, v0
	v_addc_co_u32_e32 v3, vcc, 0, v67, vcc
; DI bf16_t f2bf(float x) { return (bf16_t)(pack2(x, 0.f) & 0xffffu); }
; DI int crow(int i, int hh) { return (i & 3) + 8 * (i >> 2) + 4 * hh; }
;   template <int NTW>
;   DI void operator()(f32x16 (&acc)[2][NTW], int grow0, int gcol0, int lane, int w, char* lds) {
;     ...
; #pragma unroll
;     for (int mt = 0; mt < 2; ++mt)
; #pragma unroll
;       for (int pr = 0; pr < NTW / 2; ++pr) {
;         const int col = (gcol0 / 64 + pr) * 32 + l31;
; #pragma unroll
;         for (int i = 0; i < 16; ++i) {
;           float g = acc[mt][2 * pr][i], u = acc[mt][2 * pr + 1][i];
;           float v = g * __builtin_amdgcn_rcpf(1.f + __expf(-g)) * u;
;           int row = grow0 + mt * 32 + crow(i, hh);
;           H[(size_t)row * F_ + col] = f2bf(v);
;         }
; __global__ void __launch_bounds__(NT) fwd_megakernel(Params p) {
;     ...
;             for (int t = vb; t < 256; t += gridDim.x) {
;               const int x = t & 7, L = t >> 3; const int pm = 8 * x + (L & 7), pnh = L >> 3;
;               gemm_tile<4, 64, EpiSwiglu, 2>(p.Xb, D_, p.win[i * 2 + f], D_, D_, pm * 256, 5120 + pnh * 128, lds, e1);
;             }
	v_mul_f32_e32 v0, v21, v0
	v_mul_f32_e32 v0, v5, v0
	v_cvt_pk_bf16_f32 v0, v0, s0
	global_store_short v[2:3], v0, off offset:512
	v_mul_f32_e32 v0, 0xbfb8aa3b, v22
	v_exp_f32_e32 v0, v0
	v_add_co_u32_e32 v2, vcc, s2, v66
	s_mov_b32 s2, 0x38000
	v_add_f32_e32 v0, 1.0, v0
	v_rcp_f32_e32 v0, v0
	v_addc_co_u32_e32 v3, vcc, 0, v67, vcc
	v_mul_f32_e32 v0, v22, v0
	v_mul_f32_e32 v0, v6, v0
	v_cvt_pk_bf16_f32 v0, v0, s0
	global_store_short v[2:3], v0, off
	v_mul_f32_e32 v0, 0xbfb8aa3b, v23
	v_exp_f32_e32 v0, v0
	v_add_co_u32_e32 v2, vcc, s2, v66
	s_mov_b32 s2, 0x39000
	v_add_f32_e32 v0, 1.0, v0
	v_rcp_f32_e32 v0, v0
	v_addc_co_u32_e32 v3, vcc, 0, v67, vcc
	v_mul_f32_e32 v0, v23, v0
	v_mul_f32_e32 v0, v7, v0
	v_cvt_pk_bf16_f32 v0, v0, s0
	global_store_short v[2:3], v0, off offset:1536
	v_mul_f32_e32 v0, 0xbfb8aa3b, v24
	v_exp_f32_e32 v0, v0
	v_add_co_u32_e32 v2, vcc, s2, v66
	s_mov_b32 s2, 0x3b000
	v_add_f32_e32 v0, 1.0, v0
	v_rcp_f32_e32 v0, v0
	v_addc_co_u32_e32 v3, vcc, 0, v67, vcc
	v_mul_f32_e32 v0, v24, v0
	v_mul_f32_e32 v0, v8, v0
	v_cvt_pk_bf16_f32 v0, v0, s0
	global_store_short v[2:3], v0, off offset:3072
	v_mul_f32_e32 v0, 0xbfb8aa3b, v25
	v_exp_f32_e32 v0, v0
	v_add_co_u32_e32 v2, vcc, s2, v66
	s_mov_b32 s2, 0x42000
	v_add_f32_e32 v0, 1.0, v0
	v_rcp_f32_e32 v0, v0
	v_addc_co_u32_e32 v3, vcc, 0, v67, vcc
	v_mul_f32_e32 v0, v25, v0
	v_mul_f32_e32 v0, v9, v0
	v_cvt_pk_bf16_f32 v0, v0, s0
	global_store_short v[2:3], v0, off offset:512
	v_mul_f32_e32 v0, 0xbfb8aa3b, v26
	v_exp_f32_e32 v0, v0
	v_add_co_u32_e32 v2, vcc, s2, v66
	s_mov_b32 s2, 0x43000
	v_add_f32_e32 v0, 1.0, v0
	v_rcp_f32_e32 v0, v0
	v_addc_co_u32_e32 v3, vcc, 0, v67, vcc
	v_mul_f32_e32 v0, v26, v0
	v_mul_f32_e32 v0, v10, v0
	v_cvt_pk_bf16_f32 v0, v0, s0
	global_store_short v[2:3], v0, off
	v_mul_f32_e32 v0, 0xbfb8aa3b, v27
	v_exp_f32_e32 v0, v0
	v_add_co_u32_e32 v2, vcc, s2, v66
	s_mov_b32 s2, 0x44000
	v_add_f32_e32 v0, 1.0, v0
	v_rcp_f32_e32 v0, v0
	v_addc_co_u32_e32 v3, vcc, 0, v67, vcc
	v_mul_f32_e32 v0, v27, v0
	v_mul_f32_e32 v0, v11, v0
	v_cvt_pk_bf16_f32 v0, v0, s0
	global_store_short v[2:3], v0, off offset:1536
	v_mul_f32_e32 v0, 0xbfb8aa3b, v28
	v_exp_f32_e32 v0, v0
	v_add_co_u32_e32 v2, vcc, s2, v66
	s_mov_b32 s2, 0x46000
	v_add_f32_e32 v0, 1.0, v0
	v_rcp_f32_e32 v0, v0
	v_addc_co_u32_e32 v3, vcc, 0, v67, vcc
	v_mul_f32_e32 v0, v28, v0
	v_mul_f32_e32 v0, v12, v0
	v_cvt_pk_bf16_f32 v0, v0, s0
	global_store_short v[2:3], v0, off offset:3072
	v_mul_f32_e32 v0, 0xbfb8aa3b, v29
	v_exp_f32_e32 v0, v0
	v_add_co_u32_e32 v2, vcc, s2, v66
	s_mov_b32 s2, 0x4d000
	v_add_f32_e32 v0, 1.0, v0
	v_rcp_f32_e32 v0, v0
	v_addc_co_u32_e32 v3, vcc, 0, v67, vcc
	v_mul_f32_e32 v0, v29, v0
	v_mul_f32_e32 v0, v13, v0
	v_cvt_pk_bf16_f32 v0, v0, s0
	global_store_short v[2:3], v0, off offset:512
	v_mul_f32_e32 v0, 0xbfb8aa3b, v30
	v_exp_f32_e32 v0, v0
	v_add_co_u32_e32 v2, vcc, s2, v66
	s_mov_b32 s2, 0x4e000
	v_add_f32_e32 v0, 1.0, v0
	v_rcp_f32_e32 v0, v0
	v_addc_co_u32_e32 v3, vcc, 0, v67, vcc
	v_mul_f32_e32 v0, v30, v0
	v_mul_f32_e32 v0, v14, v0
	v_cvt_pk_bf16_f32 v0, v0, s0
	global_store_short v[2:3], v0, off
	v_mul_f32_e32 v0, 0xbfb8aa3b, v31
	v_exp_f32_e32 v0, v0
	v_add_co_u32_e32 v2, vcc, s2, v66
	s_mov_b32 s2, 0x4f000
	v_add_f32_e32 v0, 1.0, v0
	v_rcp_f32_e32 v0, v0
	v_addc_co_u32_e32 v3, vcc, 0, v67, vcc
	v_mul_f32_e32 v0, v31, v0
	v_mul_f32_e32 v0, v15, v0
	v_cvt_pk_bf16_f32 v0, v0, s0
	global_store_short v[2:3], v0, off offset:1536
	v_mul_f32_e32 v0, 0xbfb8aa3b, v32
	v_exp_f32_e32 v0, v0
	v_add_co_u32_e32 v2, vcc, s2, v66
	v_readlane_b32 s2, v254, 39
	v_add_f32_e32 v0, 1.0, v0
	v_rcp_f32_e32 v0, v0
	v_addc_co_u32_e32 v3, vcc, 0, v67, vcc
	s_add_i32 s34, s34, s2
	v_mul_f32_e32 v0, v32, v0
	v_mul_f32_e32 v0, v16, v0
	v_cvt_pk_bf16_f32 v0, v0, s0
	global_store_short v[2:3], v0, off offset:3072
	v_mul_f32_e32 v0, 0xbfb8aa3b, v33
	v_exp_f32_e32 v0, v0
	v_add_co_u32_e32 v2, vcc, 0x51000, v66
	s_cmpk_gt_i32 s36, 0xff
	v_add_f32_e32 v0, 1.0, v0
	v_rcp_f32_e32 v0, v0
	v_addc_co_u32_e32 v3, vcc, 0, v67, vcc
	v_mul_f32_e32 v0, v33, v0
	v_mul_f32_e32 v0, v17, v0
	v_cvt_pk_bf16_f32 v0, v0, s0
	global_store_short v[2:3], v0, off offset:512
	s_cbranch_scc0 .LBB0_387

; DI f32x16 mfma(bf16x8 a, bf16x8 b, f32x16 c) { return __builtin_amdgcn_mfma_f32_32x32x16_bf16(a, b, c, 0, 0, 0); }
; DI int launder(int x) { asm volatile("" : "+v"(x)); return x; }
; template <int BK> DI int swz(int row) { constexpr int CPR = BK / 8; return (row / (16 / CPR)) % CPR; }
; DI void wait_vm0() { asm volatile("s_waitcnt vmcnt(0)" ::: "memory"); }
;     ...
; #pragma unroll
;     for (int mt = 0; mt < 2; ++mt) { int row = wm * 64 + mt * 32 + l31; fa[0][mt] = *(const bf16x8*)(cur + row * (BK * 2) + ((hh ^ swz<BK>(row)) << 4)); }
; #pragma unroll
;     for (int nt = 0; nt < NTW; ++nt) { int row = wn * (32 * NTW) + nt * 32 + l31; fb[0][nt] = *(const bf16x8*)(cur + ABYTES + row * (BK * 2) + ((hh ^ swz<BK>(row)) << 4)); }
; #pragma unroll
;     for (int kk = 0; kk < NKK; ++kk) {
;       if (kk + 1 < NKK) {
;         const int ch = (kk + 1) * 2 + hh;
; #pragma unroll
;         for (int mt = 0; mt < 2; ++mt) { int row = wm * 64 + mt * 32 + l31; fa[(kk + 1) & 1][mt] = *(const bf16x8*)(cur + row * (BK * 2) + ((ch ^ swz<BK>(row)) << 4)); }
; #pragma unroll
;         for (int nt = 0; nt < NTW; ++nt) { int row = wn * (32 * NTW) + nt * 32 + l31; fb[(kk + 1) & 1][nt] = *(const bf16x8*)(cur + ABYTES + row * (BK * 2) + ((ch ^ swz<BK>(row)) << 4)); }
;       }
;       if (more) {
; #pragma unroll
;         for (int q = 0; q < PPK; ++q) {
;           const int pi = kk * PPK + q;
;           if (pi < NPA) stage_piece<BM, BK>(An, lda, nxt, tid, pi, wv);
;           else if (pi < NP) stage_piece<BN, BK>(Bn, ldb, nxt + ABYTES, tid, pi - NPA, wv);
;         }
;       }
;       __builtin_amdgcn_s_setprio(1);
; #pragma unroll
;       for (int mt = 0; mt < 2; ++mt)
; #pragma unroll
;         for (int nt = 0; nt < NTW; ++nt) acc[mt][nt] = mfma(fa[kk & 1][mt], fb[kk & 1][nt], acc[mt][nt]);
;       __builtin_amdgcn_s_setprio(0);
;       __builtin_amdgcn_sched_barrier(0);
;     }
;     wait_vm0();
;     __syncthreads();
;   }
;   if (has_next) { const int tid3 = launder(threadIdx.x); stage_tile<BM, BK>(A + (size_t)row0n * lda, lda, lds, tid3); stage_tile<BN, BK>(Bt + (size_t)col0n * ldb, ldb, lds + ABYTES, tid3); }
.Lk439_exit:
	v_mfma_f32_32x32x16_bf16 v[114:129], v[190:193], v[198:201], v[114:129]
	v_mfma_f32_32x32x16_bf16 v[98:113], v[190:193], v[202:205], v[98:113]
	v_mfma_f32_32x32x16_bf16 v[50:65], v[190:193], v[206:209], v[50:65]
	v_mfma_f32_32x32x16_bf16 v[34:49], v[190:193], v[210:213], v[34:49]
	v_mfma_f32_32x32x16_bf16 v[82:97], v[194:197], v[198:201], v[82:97]
	v_mfma_f32_32x32x16_bf16 v[66:81], v[194:197], v[202:205], v[66:81]
	v_mfma_f32_32x32x16_bf16 v[18:33], v[194:197], v[206:209], v[18:33]
	v_mfma_f32_32x32x16_bf16 v[2:17], v[194:197], v[210:213], v[2:17]
	s_waitcnt lgkmcnt(0)
	v_add_u32_e32 v0, 0x10000, v140
	v_add_u32_e32 v198, 0x10000, v142
	v_add_u32_e32 v130, v0, v141
	v_add_u32_e32 v140, v198, v144
	v_add_u32_e32 v199, 0x18000, v143
	v_add_u32_e32 v200, 0x18000, v152
	ds_read_b128 v[130:133], v130
	ds_read_b128 v[166:169], v140
	v_add_u32_e32 v140, v199, v151
	v_add_u32_e32 v144, v200, v154
	v_add_u32_e32 v201, 0x18000, v153
	ds_read_b128 v[140:143], v140
	ds_read_b128 v[170:173], v144
	v_add_u32_e32 v144, v201, v155
	v_add_u32_e32 v202, 0x18000, v156
	v_add_u32_e32 v151, v202, v164
	ds_read_b128 v[152:155], v144
	ds_read_b128 v[174:177], v151
	v_add_u32_e32 v144, v0, v161
	v_add_u32_e32 v151, v198, v163
	ds_read_b128 v[178:181], v144
	ds_read_b128 v[182:185], v151
	v_add_u32_e32 v144, v199, v159
	v_add_u32_e32 v151, v200, v160
	ds_read_b128 v[186:189], v144
	ds_read_b128 v[190:193], v151
	v_add_u32_e32 v144, v201, v157
	v_add_u32_e32 v151, v202, v158
	ds_read_b128 v[156:159], v144
	ds_read_b128 v[194:197], v151
	s_add_i32 s36, s36, s94
	s_cmpk_gt_i32 s36, 0x5ff
	s_cselect_b64 s[42:43], -1, 0
	s_cmpk_lt_i32 s36, 0x600
	s_waitcnt lgkmcnt(9)
	v_mfma_f32_32x32x16_bf16 v[114:129], v[130:133], v[140:143], v[114:129]
	s_waitcnt lgkmcnt(8)
	v_mfma_f32_32x32x16_bf16 v[98:113], v[130:133], v[170:173], v[98:113]
	s_waitcnt lgkmcnt(7)
	v_mfma_f32_32x32x16_bf16 v[50:65], v[130:133], v[152:155], v[50:65]
	s_waitcnt lgkmcnt(6)
	v_mfma_f32_32x32x16_bf16 v[34:49], v[130:133], v[174:177], v[34:49]
	v_mfma_f32_32x32x16_bf16 v[82:97], v[166:169], v[140:143], v[82:97]
	v_mfma_f32_32x32x16_bf16 v[66:81], v[166:169], v[170:173], v[66:81]
	v_mfma_f32_32x32x16_bf16 v[18:33], v[166:169], v[152:155], v[18:33]
	v_mfma_f32_32x32x16_bf16 v[2:17], v[166:169], v[174:177], v[2:17]
	v_add_u32_e32 v130, v0, v149
	v_add_u32_e32 v140, v198, v150
	v_add_u32_e32 v144, v199, v147
	ds_read_b128 v[130:133], v130
	ds_read_b128 v[140:143], v140
	v_add_u32_e32 v147, v200, v148
	ds_read_b128 v[148:151], v144
	ds_read_b128 v[152:155], v147
	v_add_u32_e32 v144, v201, v145
	v_add_u32_e32 v160, v202, v146
	ds_read_b128 v[144:147], v144
	ds_read_b128 v[166:169], v160
	s_waitcnt lgkmcnt(9)
	v_mfma_f32_32x32x16_bf16 v[114:129], v[178:181], v[186:189], v[114:129]
	s_waitcnt lgkmcnt(8)
	v_mfma_f32_32x32x16_bf16 v[98:113], v[178:181], v[190:193], v[98:113]
	s_waitcnt lgkmcnt(7)
	v_mfma_f32_32x32x16_bf16 v[50:65], v[178:181], v[156:159], v[50:65]
	s_waitcnt lgkmcnt(6)
	v_mfma_f32_32x32x16_bf16 v[34:49], v[178:181], v[194:197], v[34:49]
	v_mfma_f32_32x32x16_bf16 v[82:97], v[182:185], v[186:189], v[82:97]
	v_mfma_f32_32x32x16_bf16 v[66:81], v[182:185], v[190:193], v[66:81]
	v_mfma_f32_32x32x16_bf16 v[18:33], v[182:185], v[156:159], v[18:33]
	v_mfma_f32_32x32x16_bf16 v[2:17], v[182:185], v[194:197], v[2:17]
	v_add_u32_e32 v0, v0, v138
	v_add_u32_e32 v138, v198, v139
	ds_read_b128 v[156:159], v0
	ds_read_b128 v[170:173], v138
	v_add_u32_e32 v0, v199, v136
	v_add_u32_e32 v160, v200, v137
	ds_read_b128 v[136:139], v0
	ds_read_b128 v[174:177], v160
	v_add_u32_e32 v0, v201, v134
	v_add_u32_e32 v134, v202, v135
	ds_read_b128 v[178:181], v0
	ds_read_b128 v[182:185], v134
	s_waitcnt lgkmcnt(9)
	v_mfma_f32_32x32x16_bf16 v[114:129], v[130:133], v[148:151], v[114:129]
	s_waitcnt lgkmcnt(8)
	v_mfma_f32_32x32x16_bf16 v[98:113], v[130:133], v[152:155], v[98:113]
	s_waitcnt lgkmcnt(7)
	v_mfma_f32_32x32x16_bf16 v[50:65], v[130:133], v[144:147], v[50:65]
	s_waitcnt lgkmcnt(6)
	v_mfma_f32_32x32x16_bf16 v[34:49], v[130:133], v[166:169], v[34:49]
	v_mfma_f32_32x32x16_bf16 v[82:97], v[140:143], v[148:151], v[82:97]
	v_mfma_f32_32x32x16_bf16 v[66:81], v[140:143], v[152:155], v[66:81]
	v_mfma_f32_32x32x16_bf16 v[18:33], v[140:143], v[144:147], v[18:33]
	v_mfma_f32_32x32x16_bf16 v[2:17], v[140:143], v[166:169], v[2:17]
	s_waitcnt lgkmcnt(3)
	v_mfma_f32_32x32x16_bf16 v[114:129], v[156:159], v[136:139], v[114:129]
	s_waitcnt lgkmcnt(2)
	v_mfma_f32_32x32x16_bf16 v[98:113], v[156:159], v[174:177], v[98:113]
	s_waitcnt lgkmcnt(1)
	v_mfma_f32_32x32x16_bf16 v[50:65], v[156:159], v[178:181], v[50:65]
	s_waitcnt lgkmcnt(0)
	v_mfma_f32_32x32x16_bf16 v[34:49], v[156:159], v[182:185], v[34:49]
	v_mfma_f32_32x32x16_bf16 v[82:97], v[170:173], v[136:139], v[82:97]
	v_mfma_f32_32x32x16_bf16 v[66:81], v[170:173], v[174:177], v[66:81]
	v_mfma_f32_32x32x16_bf16 v[18:33], v[170:173], v[178:181], v[18:33]
	v_mfma_f32_32x32x16_bf16 v[2:17], v[170:173], v[182:185], v[2:17]
	s_waitcnt vmcnt(0)
	s_barrier
	s_cbranch_scc0 .LBB0_442
	v_mov_b32_e32 v132, v216
	s_lshl_b32 s3, s36, 3
	v_ashrrev_i32_e32 v0, 31, v132
	v_lshrrev_b32_e32 v130, 29, v0
	v_lshrrev_b32_e32 v0, 28, v0
	v_add_u32_e32 v0, v132, v0
	v_ashrrev_i32_e32 v0, 4, v0
	s_and_b32 s3, s3, 56
	s_bfe_u32 s7, s36, 0x30003
	v_lshrrev_b32_e32 v133, 29, v0
	s_or_b32 s3, s3, s7
	s_lshl_b32 s7, s36, 2
	v_add_u32_e32 v130, v132, v130
	v_add_u32_e32 v133, v0, v133
	s_and_b32 s30, s7, 0xffffff00
	s_lshl_b32 s3, s3, 19
	v_and_b32_e32 v131, 0xffffff8, v130
	v_and_b32_e32 v133, 0xffffff8, v133
	s_add_u32 s40, s12, s3
	v_sub_u32_e32 v131, v132, v131
	v_sub_u32_e32 v0, v0, v133
	v_lshlrev_b32_e32 v130, 8, v130
	v_readfirstlane_b32 s3, v132
	s_addc_u32 s41, s13, 0
	v_xor_b32_e32 v0, v0, v131
	v_and_b32_e32 v130, 0xfffff800, v130
	s_lshl_b32 s3, s3, 4
	v_lshl_add_u32 v0, v0, 4, v130
	s_and_b32 s3, s3, 0xfffffc00
	s_load_dwordx4 s[44:47], s[0:1], 0x1a0
	v_lshl_add_u64 v[130:131], s[40:41], 0, v[0:1]
	s_mov_b32 m0, s3
	v_lshl_add_u64 v[132:133], v[130:131], 0, s[58:59]
	global_load_lds_dwordx4 v0, s[40:41]
	s_add_i32 m0, s3, 0x2000
	s_ashr_i32 s31, s30, 31
	global_load_lds_dwordx4 v[132:133], off
	v_lshl_add_u64 v[132:133], v[130:131], 0, s[48:49]
	s_add_i32 m0, s3, 0x4000
	s_lshl_b64 s[30:31], s[30:31], 11
	global_load_lds_dwordx4 v[132:133], off
	s_add_i32 m0, s3, 0x6000
	s_waitcnt lgkmcnt(0)
	s_add_u32 s30, s46, s30
	v_lshl_add_u64 v[130:131], v[130:131], 0, s[50:51]
	s_addc_u32 s31, s47, s31
	global_load_lds_dwordx4 v[130:131], off
	v_lshl_add_u64 v[130:131], s[30:31], 0, v[0:1]
	s_add_i32 m0, s3, 0x8000
	v_lshl_add_u64 v[132:133], v[130:131], 0, s[58:59]
	global_load_lds_dwordx4 v0, s[30:31]
	s_add_i32 m0, s3, 0xa000
	s_nop 0
	global_load_lds_dwordx4 v[132:133], off
	v_lshl_add_u64 v[132:133], v[130:131], 0, s[48:49]
	s_add_i32 m0, s3, 0xc000
	v_lshl_add_u64 v[130:131], v[130:131], 0, s[50:51]
	global_load_lds_dwordx4 v[132:133], off
	s_add_i32 m0, s3, 0xe000
	s_nop 0
	global_load_lds_dwordx4 v[130:131], off

; DI f32x16 mfma(bf16x8 a, bf16x8 b, f32x16 c) { return __builtin_amdgcn_mfma_f32_32x32x16_bf16(a, b, c, 0, 0, 0); }
; DI int launder(int x) { asm volatile("" : "+v"(x)); return x; }
; template <int BK> DI int swz(int row) { constexpr int CPR = BK / 8; return (row / (16 / CPR)) % CPR; }
; DI void wait_vm0() { asm volatile("s_waitcnt vmcnt(0)" ::: "memory"); }
;     ...
; #pragma unroll
;     for (int mt = 0; mt < 2; ++mt) { int row = wm * 64 + mt * 32 + l31; fa[0][mt] = *(const bf16x8*)(cur + row * (BK * 2) + ((hh ^ swz<BK>(row)) << 4)); }
; #pragma unroll
;     for (int nt = 0; nt < NTW; ++nt) { int row = wn * (32 * NTW) + nt * 32 + l31; fb[0][nt] = *(const bf16x8*)(cur + ABYTES + row * (BK * 2) + ((hh ^ swz<BK>(row)) << 4)); }
; #pragma unroll
;     for (int kk = 0; kk < NKK; ++kk) {
;       if (kk + 1 < NKK) {
;         const int ch = (kk + 1) * 2 + hh;
; #pragma unroll
;         for (int mt = 0; mt < 2; ++mt) { int row = wm * 64 + mt * 32 + l31; fa[(kk + 1) & 1][mt] = *(const bf16x8*)(cur + row * (BK * 2) + ((ch ^ swz<BK>(row)) << 4)); }
; #pragma unroll
;         for (int nt = 0; nt < NTW; ++nt) { int row = wn * (32 * NTW) + nt * 32 + l31; fb[(kk + 1) & 1][nt] = *(const bf16x8*)(cur + ABYTES + row * (BK * 2) + ((ch ^ swz<BK>(row)) << 4)); }
;       }
;       if (more) {
; #pragma unroll
;         for (int q = 0; q < PPK; ++q) {
;           const int pi = kk * PPK + q;
;           if (pi < NPA) stage_piece<BM, BK>(An, lda, nxt, tid, pi, wv);
;           else if (pi < NP) stage_piece<BN, BK>(Bn, ldb, nxt + ABYTES, tid, pi - NPA, wv);
;         }
;       }
;       __builtin_amdgcn_s_setprio(1);
; #pragma unroll
;       for (int mt = 0; mt < 2; ++mt)
; #pragma unroll
;         for (int nt = 0; nt < NTW; ++nt) acc[mt][nt] = mfma(fa[kk & 1][mt], fb[kk & 1][nt], acc[mt][nt]);
;       __builtin_amdgcn_s_setprio(0);
;       __builtin_amdgcn_sched_barrier(0);
;     }
;     wait_vm0();
;     __syncthreads();
;   }
;   if (has_next) { const int tid3 = launder(threadIdx.x); stage_tile<BM, BK>(A + (size_t)row0n * lda, lda, lds, tid3); stage_tile<BN, BK>(Bt + (size_t)col0n * ldb, ldb, lds + ABYTES, tid3); }
.Lk519_exit:
	v_mfma_f32_32x32x16_bf16 v[114:129], v[190:193], v[198:201], v[114:129]
	v_mfma_f32_32x32x16_bf16 v[98:113], v[190:193], v[202:205], v[98:113]
	v_mfma_f32_32x32x16_bf16 v[82:97], v[190:193], v[206:209], v[82:97]
	v_mfma_f32_32x32x16_bf16 v[66:81], v[190:193], v[210:213], v[66:81]
	v_mfma_f32_32x32x16_bf16 v[50:65], v[194:197], v[198:201], v[50:65]
	v_mfma_f32_32x32x16_bf16 v[34:49], v[194:197], v[202:205], v[34:49]
	v_mfma_f32_32x32x16_bf16 v[18:33], v[194:197], v[206:209], v[18:33]
	v_mfma_f32_32x32x16_bf16 v[2:17], v[194:197], v[210:213], v[2:17]
	s_waitcnt lgkmcnt(0)
	v_add_u32_e32 v0, 0x10000, v140
	v_add_u32_e32 v198, 0x10000, v142
	v_add_u32_e32 v130, v0, v141
	v_add_u32_e32 v140, v198, v144
	v_add_u32_e32 v199, 0x18000, v143
	v_add_u32_e32 v200, 0x18000, v152
	ds_read_b128 v[130:133], v130
	ds_read_b128 v[166:169], v140
	v_add_u32_e32 v140, v199, v151
	v_add_u32_e32 v144, v200, v154
	v_add_u32_e32 v201, 0x18000, v153
	ds_read_b128 v[140:143], v140
	ds_read_b128 v[170:173], v144
	v_add_u32_e32 v144, v201, v155
	v_add_u32_e32 v202, 0x18000, v156
	v_add_u32_e32 v151, v202, v164
	ds_read_b128 v[152:155], v144
	ds_read_b128 v[174:177], v151
	v_add_u32_e32 v144, v0, v161
	v_add_u32_e32 v151, v198, v163
	ds_read_b128 v[178:181], v144
	ds_read_b128 v[182:185], v151
	v_add_u32_e32 v144, v199, v159
	v_add_u32_e32 v151, v200, v160
	ds_read_b128 v[186:189], v144
	ds_read_b128 v[190:193], v151
	v_add_u32_e32 v144, v201, v157
	v_add_u32_e32 v151, v202, v158
	ds_read_b128 v[156:159], v144
	ds_read_b128 v[194:197], v151
	s_add_i32 s36, s36, s94
	s_cmpk_gt_i32 s36, 0x2ff
	s_cselect_b64 s[42:43], -1, 0
	s_cmpk_lt_i32 s36, 0x300
	s_waitcnt lgkmcnt(9)
	v_mfma_f32_32x32x16_bf16 v[114:129], v[130:133], v[140:143], v[114:129]
	s_waitcnt lgkmcnt(8)
	v_mfma_f32_32x32x16_bf16 v[98:113], v[130:133], v[170:173], v[98:113]
	s_waitcnt lgkmcnt(7)
	v_mfma_f32_32x32x16_bf16 v[82:97], v[130:133], v[152:155], v[82:97]
	s_waitcnt lgkmcnt(6)
	v_mfma_f32_32x32x16_bf16 v[66:81], v[130:133], v[174:177], v[66:81]
	v_mfma_f32_32x32x16_bf16 v[50:65], v[166:169], v[140:143], v[50:65]
	v_mfma_f32_32x32x16_bf16 v[34:49], v[166:169], v[170:173], v[34:49]
	v_mfma_f32_32x32x16_bf16 v[18:33], v[166:169], v[152:155], v[18:33]
	v_mfma_f32_32x32x16_bf16 v[2:17], v[166:169], v[174:177], v[2:17]
	v_add_u32_e32 v130, v0, v149
	v_add_u32_e32 v140, v198, v150
	v_add_u32_e32 v144, v199, v147
	ds_read_b128 v[130:133], v130
	ds_read_b128 v[140:143], v140
	v_add_u32_e32 v147, v200, v148
	ds_read_b128 v[148:151], v144
	ds_read_b128 v[152:155], v147
	v_add_u32_e32 v144, v201, v145
	v_add_u32_e32 v160, v202, v146
	ds_read_b128 v[144:147], v144
	ds_read_b128 v[166:169], v160
	s_waitcnt lgkmcnt(9)
	v_mfma_f32_32x32x16_bf16 v[114:129], v[178:181], v[186:189], v[114:129]
	s_waitcnt lgkmcnt(8)
	v_mfma_f32_32x32x16_bf16 v[98:113], v[178:181], v[190:193], v[98:113]
	s_waitcnt lgkmcnt(7)
	v_mfma_f32_32x32x16_bf16 v[82:97], v[178:181], v[156:159], v[82:97]
	s_waitcnt lgkmcnt(6)
	v_mfma_f32_32x32x16_bf16 v[66:81], v[178:181], v[194:197], v[66:81]
	v_mfma_f32_32x32x16_bf16 v[50:65], v[182:185], v[186:189], v[50:65]
	v_mfma_f32_32x32x16_bf16 v[34:49], v[182:185], v[190:193], v[34:49]
	v_mfma_f32_32x32x16_bf16 v[18:33], v[182:185], v[156:159], v[18:33]
	v_mfma_f32_32x32x16_bf16 v[2:17], v[182:185], v[194:197], v[2:17]
	v_add_u32_e32 v0, v0, v138
	v_add_u32_e32 v138, v198, v139
	ds_read_b128 v[156:159], v0
	ds_read_b128 v[170:173], v138
	v_add_u32_e32 v0, v199, v136
	v_add_u32_e32 v160, v200, v137
	ds_read_b128 v[136:139], v0
	ds_read_b128 v[174:177], v160
	v_add_u32_e32 v0, v201, v134
	v_add_u32_e32 v134, v202, v135
	ds_read_b128 v[178:181], v0
	ds_read_b128 v[182:185], v134
	s_waitcnt lgkmcnt(9)
	v_mfma_f32_32x32x16_bf16 v[114:129], v[130:133], v[148:151], v[114:129]
	s_waitcnt lgkmcnt(8)
	v_mfma_f32_32x32x16_bf16 v[98:113], v[130:133], v[152:155], v[98:113]
	s_waitcnt lgkmcnt(7)
	v_mfma_f32_32x32x16_bf16 v[82:97], v[130:133], v[144:147], v[82:97]
	s_waitcnt lgkmcnt(6)
	v_mfma_f32_32x32x16_bf16 v[66:81], v[130:133], v[166:169], v[66:81]
	v_mfma_f32_32x32x16_bf16 v[50:65], v[140:143], v[148:151], v[50:65]
	v_mfma_f32_32x32x16_bf16 v[34:49], v[140:143], v[152:155], v[34:49]
	v_mfma_f32_32x32x16_bf16 v[18:33], v[140:143], v[144:147], v[18:33]
	v_mfma_f32_32x32x16_bf16 v[2:17], v[140:143], v[166:169], v[2:17]
	s_waitcnt lgkmcnt(3)
	v_mfma_f32_32x32x16_bf16 v[114:129], v[156:159], v[136:139], v[114:129]
	s_waitcnt lgkmcnt(2)
	v_mfma_f32_32x32x16_bf16 v[98:113], v[156:159], v[174:177], v[98:113]
	s_waitcnt lgkmcnt(1)
	v_mfma_f32_32x32x16_bf16 v[82:97], v[156:159], v[178:181], v[82:97]
	s_waitcnt lgkmcnt(0)
	v_mfma_f32_32x32x16_bf16 v[66:81], v[156:159], v[182:185], v[66:81]
	v_mfma_f32_32x32x16_bf16 v[50:65], v[170:173], v[136:139], v[50:65]
	v_mfma_f32_32x32x16_bf16 v[34:49], v[170:173], v[174:177], v[34:49]
	v_mfma_f32_32x32x16_bf16 v[18:33], v[170:173], v[178:181], v[18:33]
	v_mfma_f32_32x32x16_bf16 v[2:17], v[170:173], v[182:185], v[2:17]
	s_waitcnt vmcnt(0)
	s_barrier
	s_cbranch_scc0 .LBB0_522
	v_mov_b32_e32 v132, v216
	s_lshl_b32 s3, s36, 3
	v_ashrrev_i32_e32 v0, 31, v132
	v_lshrrev_b32_e32 v130, 29, v0
	v_lshrrev_b32_e32 v0, 28, v0
	v_add_u32_e32 v0, v132, v0
	v_ashrrev_i32_e32 v0, 4, v0
	s_and_b32 s3, s3, 56
	s_bfe_u32 s7, s36, 0x30003
	v_lshrrev_b32_e32 v133, 29, v0
	s_or_b32 s3, s3, s7
	s_lshl_b32 s7, s36, 2
	v_add_u32_e32 v130, v132, v130
	v_add_u32_e32 v133, v0, v133
	s_and_b32 s30, s7, 0xffffff00
	s_lshl_b32 s3, s3, 19
	v_and_b32_e32 v131, 0xffffff8, v130
	v_and_b32_e32 v133, 0xffffff8, v133
	s_add_u32 s44, s12, s3
	v_sub_u32_e32 v131, v132, v131
	v_sub_u32_e32 v0, v0, v133
	v_lshlrev_b32_e32 v130, 8, v130
	v_readfirstlane_b32 s3, v132
	s_addc_u32 s45, s13, 0
	v_xor_b32_e32 v0, v0, v131
	v_and_b32_e32 v130, 0xfffff800, v130
	s_lshl_b32 s3, s3, 4
	v_lshl_add_u32 v0, v0, 4, v130
	s_and_b32 s3, s3, 0xfffffc00
	v_lshl_add_u64 v[130:131], s[44:45], 0, v[0:1]
	s_mov_b32 m0, s3
	v_lshl_add_u64 v[132:133], v[130:131], 0, s[58:59]
	global_load_lds_dwordx4 v0, s[44:45]
	s_add_i32 m0, s3, 0x2000
	s_ashr_i32 s31, s30, 31
	global_load_lds_dwordx4 v[132:133], off
	v_lshl_add_u64 v[132:133], v[130:131], 0, s[48:49]
	s_add_i32 m0, s3, 0x4000
	s_lshl_b64 s[30:31], s[30:31], 11
	global_load_lds_dwordx4 v[132:133], off
	s_add_i32 m0, s3, 0x6000
	s_add_u32 s30, s40, s30
	v_lshl_add_u64 v[130:131], v[130:131], 0, s[50:51]
	s_addc_u32 s31, s41, s31
	global_load_lds_dwordx4 v[130:131], off
	v_lshl_add_u64 v[130:131], s[30:31], 0, v[0:1]
	s_add_i32 m0, s3, 0x8000
	v_lshl_add_u64 v[132:133], v[130:131], 0, s[58:59]
	global_load_lds_dwordx4 v0, s[30:31]
	s_add_i32 m0, s3, 0xa000
	s_nop 0
	global_load_lds_dwordx4 v[132:133], off
	v_lshl_add_u64 v[132:133], v[130:131], 0, s[48:49]
	s_add_i32 m0, s3, 0xc000
	v_lshl_add_u64 v[130:131], v[130:131], 0, s[50:51]
	global_load_lds_dwordx4 v[132:133], off
	s_add_i32 m0, s3, 0xe000
	s_nop 0
	global_load_lds_dwordx4 v[130:131], off

; DI f32x16 mfma(bf16x8 a, bf16x8 b, f32x16 c) { return __builtin_amdgcn_mfma_f32_32x32x16_bf16(a, b, c, 0, 0, 0); }
;     ...
;     if (!more) epi.pre(row0 + wm * 64, col0 + wn * (32 * NTW), lane, w, lds);
;     bf16x8 fa[2][2], fb[2][NTW];
; #pragma unroll
;     for (int mt = 0; mt < 2; ++mt) { int row = wm * 64 + mt * 32 + l31; fa[0][mt] = *(const bf16x8*)(cur + row * (BK * 2) + ((hh ^ swz<BK>(row)) << 4)); }
; #pragma unroll
;     for (int nt = 0; nt < NTW; ++nt) { int row = wn * (32 * NTW) + nt * 32 + l31; fb[0][nt] = *(const bf16x8*)(cur + ABYTES + row * (BK * 2) + ((hh ^ swz<BK>(row)) << 4)); }
; #pragma unroll
;     for (int kk = 0; kk < NKK; ++kk) {
;       if (kk + 1 < NKK) {
;         const int ch = (kk + 1) * 2 + hh;
; #pragma unroll
;         for (int mt = 0; mt < 2; ++mt) { int row = wm * 64 + mt * 32 + l31; fa[(kk + 1) & 1][mt] = *(const bf16x8*)(cur + row * (BK * 2) + ((ch ^ swz<BK>(row)) << 4)); }
; #pragma unroll
;         for (int nt = 0; nt < NTW; ++nt) { int row = wn * (32 * NTW) + nt * 32 + l31; fb[(kk + 1) & 1][nt] = *(const bf16x8*)(cur + ABYTES + row * (BK * 2) + ((ch ^ swz<BK>(row)) << 4)); }
;       }
;       if (more) {
; #pragma unroll
;         for (int q = 0; q < PPK; ++q) {
;           const int pi = kk * PPK + q;
;           if (pi < NPA) stage_piece<BM, BK>(An, lda, nxt, tid, pi, wv);
;           else if (pi < NP) stage_piece<BN, BK>(Bn, ldb, nxt + ABYTES, tid, pi - NPA, wv);
;         }
;       }
;       __builtin_amdgcn_s_setprio(1);
; #pragma unroll
;       for (int mt = 0; mt < 2; ++mt)
; #pragma unroll
;         for (int nt = 0; nt < NTW; ++nt) acc[mt][nt] = mfma(fa[kk & 1][mt], fb[kk & 1][nt], acc[mt][nt]);
;       __builtin_amdgcn_s_setprio(0);
;       __builtin_amdgcn_sched_barrier(0);
;     }
;   DI void xpass(int ps, int grow0, int gcol0, int lane, int w, char* lds) const {
;     char* xs = lds + (ps & 1) * 65536 + __builtin_amdgcn_readfirstlane(w) * 8192;
;     const float* xsrc = Xin + (size_t)(grow0 + (ps >> 1) * 32 + (ps & 1) * 16 + (lane >> 5)) * D_ + gcol0 + (lane & 31) * 4;
; #pragma unroll
;     for (int pc = 0; pc < 8; ++pc)
;       __builtin_amdgcn_global_load_lds((const unsigned*)(xsrc + (size_t)(2 * pc) * D_), (__attribute__((address_space(3))) unsigned*)(xs + pc * 1024), 16, 0, 0);
;   }
;   DI void pre(int grow0, int gcol0, int lane, int w, char* lds) { xpass(0, grow0, gcol0, lane, w, lds); }
.Lk532_exit:
	v_mfma_f32_32x32x16_bf16 v[114:129], v[194:197], v[202:205], v[114:129]
	v_mfma_f32_32x32x16_bf16 v[98:113], v[194:197], v[206:209], v[98:113]
	v_mfma_f32_32x32x16_bf16 v[82:97], v[194:197], v[210:213], v[82:97]
	v_mfma_f32_32x32x16_bf16 v[66:81], v[194:197], v[226:229], v[66:81]
	v_mfma_f32_32x32x16_bf16 v[50:65], v[198:201], v[202:205], v[50:65]
	v_mfma_f32_32x32x16_bf16 v[34:49], v[198:201], v[206:209], v[34:49]
	v_mfma_f32_32x32x16_bf16 v[18:33], v[198:201], v[210:213], v[18:33]
	v_mfma_f32_32x32x16_bf16 v[2:17], v[198:201], v[226:229], v[2:17]
	s_waitcnt lgkmcnt(0)
	v_readlane_b32 s3, v253, 9
	v_readlane_b32 s30, v253, 27
	v_readfirstlane_b32 s2, v134
	v_or_b32_e32 v130, s3, v135
	v_add_u32_e32 v130, v130, v169
	v_ashrrev_i32_e32 v131, 31, v130
	v_lshlrev_b64 v[130:131], 12, v[130:131]
	v_add_u32_e32 v132, s30, v161
	v_ashrrev_i32_e32 v133, 31, v132
	v_lshl_add_u64 v[130:131], s[10:11], 0, v[130:131]
	v_lshlrev_b32_e32 v0, 4, v0
	s_lshl_b32 s2, s2, 13
	v_lshl_add_u64 v[130:131], v[132:133], 2, v[130:131]
	v_and_b32_e32 v132, 0x1f0, v0
	v_mov_b32_e32 v133, v1
	v_lshl_add_u64 v[130:131], v[130:131], 0, v[132:133]
	s_mov_b32 m0, s2
	s_mov_b64 s[34:35], 0x2000
	global_load_lds_dwordx4 v[130:131], off
	v_lshl_add_u64 v[132:133], v[130:131], 0, s[34:35]
	s_or_b32 m0, s2, 0x400
	s_mov_b64 s[36:37], 0x4000
	global_load_lds_dwordx4 v[132:133], off
	v_lshl_add_u64 v[132:133], v[130:131], 0, s[36:37]
	s_or_b32 m0, s2, 0x800
	s_mov_b64 s[40:41], 0x6000
	global_load_lds_dwordx4 v[132:133], off
	v_lshl_add_u64 v[132:133], v[130:131], 0, s[40:41]
	s_or_b32 m0, s2, 0xc00
	s_mov_b64 s[44:45], 0x8000
	global_load_lds_dwordx4 v[132:133], off
	v_lshl_add_u64 v[132:133], v[130:131], 0, s[44:45]
	s_or_b32 m0, s2, 0x1000
	s_mov_b64 s[46:47], 0xa000
	global_load_lds_dwordx4 v[132:133], off
	v_lshl_add_u64 v[132:133], v[130:131], 0, s[46:47]
	s_or_b32 m0, s2, 0x1400
	s_mov_b64 s[52:53], 0xc000
	global_load_lds_dwordx4 v[132:133], off
	v_lshl_add_u64 v[132:133], v[130:131], 0, s[52:53]
	s_or_b32 m0, s2, 0x1800
	s_mov_b64 s[54:55], 0xe000
	global_load_lds_dwordx4 v[132:133], off
	v_lshl_add_u64 v[130:131], v[130:131], 0, s[54:55]
	s_or_b32 m0, s2, 0x1c00
	v_add_u32_e32 v0, s7, v136
	global_load_lds_dwordx4 v[130:131], off
	v_add_u32_e32 v134, s7, v144
	v_add_u32_e32 v130, v0, v143
	v_add_u32_e32 v135, v134, v146
	ds_read_b128 v[130:133], v130
	ds_read_b128 v[170:173], v135
	v_add_u32_e32 v135, s7, v145
	v_add_u32_e32 v136, v135, v149
	v_add_u32_e32 v143, s7, v150
	v_add_u32_e32 v144, v143, v155
	ds_read_b128 v[174:177], v136 offset:32768
	ds_read_b128 v[178:181], v144 offset:32768
	v_add_u32_e32 v136, s7, v156
	v_add_u32_e32 v144, v136, v157
	v_add_u32_e32 v149, s7, v158
	v_add_u32_e32 v145, v149, v168
	ds_read_b128 v[182:185], v144 offset:32768
	ds_read_b128 v[186:189], v145 offset:32768
	v_add_u32_e32 v144, v0, v166
	v_add_u32_e32 v145, v134, v167
	ds_read_b128 v[166:169], v144
	ds_read_b128 v[190:193], v145
	v_add_u32_e32 v144, v135, v163
	v_add_u32_e32 v145, v143, v164
	ds_read_b128 v[194:197], v144 offset:32768
	ds_read_b128 v[198:201], v145 offset:32768
	v_add_u32_e32 v144, v136, v159
	v_add_u32_e32 v145, v149, v160
	ds_read_b128 v[156:159], v144 offset:32768
	ds_read_b128 v[202:205], v145 offset:32768
	v_readlane_b32 s31, v253, 28
	s_waitcnt lgkmcnt(0)
	v_mfma_f32_32x32x16_bf16 v[114:129], v[130:133], v[174:177], v[114:129]
	v_mfma_f32_32x32x16_bf16 v[98:113], v[130:133], v[178:181], v[98:113]
	v_mfma_f32_32x32x16_bf16 v[82:97], v[130:133], v[182:185], v[82:97]
	v_mfma_f32_32x32x16_bf16 v[66:81], v[130:133], v[186:189], v[66:81]
	v_mfma_f32_32x32x16_bf16 v[50:65], v[170:173], v[174:177], v[50:65]
	v_mfma_f32_32x32x16_bf16 v[34:49], v[170:173], v[178:181], v[34:49]
	v_mfma_f32_32x32x16_bf16 v[18:33], v[170:173], v[182:185], v[18:33]
	v_mfma_f32_32x32x16_bf16 v[2:17], v[170:173], v[186:189], v[2:17]
	v_add_u32_e32 v130, v0, v153
	v_add_u32_e32 v144, v134, v154
	ds_read_b128 v[130:133], v130
	ds_read_b128 v[170:173], v144
	v_add_u32_e32 v144, v135, v151
	v_add_u32_e32 v145, v143, v152
	ds_read_b128 v[150:153], v144 offset:32768
	ds_read_b128 v[174:177], v145 offset:32768
	v_add_u32_e32 v144, v136, v147
	v_add_u32_e32 v148, v149, v148
	ds_read_b128 v[144:147], v144 offset:32768
	ds_read_b128 v[178:181], v148 offset:32768
	v_mfma_f32_32x32x16_bf16 v[114:129], v[166:169], v[194:197], v[114:129]
	v_mfma_f32_32x32x16_bf16 v[98:113], v[166:169], v[198:201], v[98:113]
	v_mfma_f32_32x32x16_bf16 v[82:97], v[166:169], v[156:159], v[82:97]
	v_mfma_f32_32x32x16_bf16 v[66:81], v[166:169], v[202:205], v[66:81]
	v_mfma_f32_32x32x16_bf16 v[50:65], v[190:193], v[194:197], v[50:65]
	v_mfma_f32_32x32x16_bf16 v[34:49], v[190:193], v[198:201], v[34:49]
	v_mfma_f32_32x32x16_bf16 v[18:33], v[190:193], v[156:159], v[18:33]
	v_mfma_f32_32x32x16_bf16 v[2:17], v[190:193], v[202:205], v[2:17]
	v_add_u32_e32 v0, v0, v141
	v_add_u32_e32 v134, v134, v142
	ds_read_b128 v[154:157], v0
	ds_read_b128 v[158:161], v134
	v_add_u32_e32 v0, v135, v139
	v_add_u32_e32 v134, v143, v140
	ds_read_b128 v[140:143], v0 offset:32768
	ds_read_b128 v[166:169], v134 offset:32768
	v_add_u32_e32 v0, v136, v137
	v_add_u32_e32 v138, v149, v138
	ds_read_b128 v[134:137], v0 offset:32768
	ds_read_b128 v[182:185], v138 offset:32768
	s_waitcnt lgkmcnt(9)
	v_mfma_f32_32x32x16_bf16 v[114:129], v[130:133], v[150:153], v[114:129]
	s_waitcnt lgkmcnt(8)
	v_mfma_f32_32x32x16_bf16 v[98:113], v[130:133], v[174:177], v[98:113]
	s_waitcnt lgkmcnt(7)
	v_mfma_f32_32x32x16_bf16 v[82:97], v[130:133], v[144:147], v[82:97]
	s_waitcnt lgkmcnt(6)
	v_mfma_f32_32x32x16_bf16 v[66:81], v[130:133], v[178:181], v[66:81]
	v_mfma_f32_32x32x16_bf16 v[50:65], v[170:173], v[150:153], v[50:65]
	v_mfma_f32_32x32x16_bf16 v[34:49], v[170:173], v[174:177], v[34:49]
	v_mfma_f32_32x32x16_bf16 v[18:33], v[170:173], v[144:147], v[18:33]
	v_mfma_f32_32x32x16_bf16 v[2:17], v[170:173], v[178:181], v[2:17]
	s_waitcnt lgkmcnt(3)
	v_mfma_f32_32x32x16_bf16 v[114:129], v[154:157], v[140:143], v[114:129]
	s_waitcnt lgkmcnt(2)
	v_mfma_f32_32x32x16_bf16 v[98:113], v[154:157], v[166:169], v[98:113]
	s_waitcnt lgkmcnt(1)
	v_mfma_f32_32x32x16_bf16 v[82:97], v[154:157], v[134:137], v[82:97]
	s_waitcnt lgkmcnt(0)
	v_mfma_f32_32x32x16_bf16 v[66:81], v[154:157], v[182:185], v[66:81]
	v_mfma_f32_32x32x16_bf16 v[50:65], v[158:161], v[140:143], v[50:65]
	v_mfma_f32_32x32x16_bf16 v[34:49], v[158:161], v[166:169], v[34:49]
	v_mfma_f32_32x32x16_bf16 v[18:33], v[158:161], v[134:137], v[18:33]
	v_mfma_f32_32x32x16_bf16 v[2:17], v[158:161], v[182:185], v[2:17]
	v_mov_b32_e32 v164, v216
	s_waitcnt vmcnt(0)
	s_barrier
;   DI void xpass(int ps, int grow0, int gcol0, int lane, int w, char* lds) const {
;     char* xs = lds + (ps & 1) * 65536 + __builtin_amdgcn_readfirstlane(w) * 8192;
;     const float* xsrc = Xin + (size_t)(grow0 + (ps >> 1) * 32 + (ps & 1) * 16 + (lane >> 5)) * D_ + gcol0 + (lane & 31) * 4;
; #pragma unroll
;     for (int pc = 0; pc < 8; ++pc)
;       __builtin_amdgcn_global_load_lds((const unsigned*)(xsrc + (size_t)(2 * pc) * D_), (__attribute__((address_space(3))) unsigned*)(xs + pc * 1024), 16, 0, 0);
;   }
;   DI void pre(int grow0, int gcol0, int lane, int w, char* lds) { xpass(0, grow0, gcol0, lane, w, lds); }
;   DI void operator()(f32x16 (&acc)[2][4], int grow0, int gcol0, int lane, int w, char* lds) {
;     float* red = (float*)(lds + 131072); float* stat = (float*)lds;
;     const int l31 = lane & 31, hh = lane >> 5, tid = w * 64 + lane;
;     const int pm = grow0 >> 8, pn = gcol0 >> 8, wn = (gcol0 >> 7) & 1, lrow0 = grow0 & 255;
;     float bia[4], csc[4];
; #pragma unroll
;     for (int nt = 0; nt < 4; ++nt) { int c = gcol0 + nt * 32 + l31; bia[nt] = bias ? bias[c] : 0.f; csc[nt] = cscale ? cscale[c] : 1.f; }
;     float* redw = red + ((wn * 2 + ((lane >> 4) & 1)) * 256 + lrow0 + 4 * hh) * 2;
; #pragma unroll
;     for (int ps = 0; ps < 4; ++ps) {
;       const int mt = ps >> 1;
;       if (ps + 1 < 4) {
;         if (ps >= 1) asm volatile("s_waitcnt lgkmcnt(0)" ::: "memory");
;         xpass(ps + 1, grow0, gcol0, lane, w, lds);
;         if (ps >= 1) asm volatile("s_waitcnt vmcnt(8)" ::: "memory");
;       } else asm volatile("s_waitcnt vmcnt(0)" ::: "memory");
;       const char* xs = lds + (ps & 1) * 65536 + w * 8192;
; #pragma unroll
;       for (int qq = 0; qq < 2; ++qq)
; #pragma unroll
;         for (int e = 0; e < 4; ++e) {
;           const int i = 4 * (2 * (ps & 1) + qq) + e;
;           const float* xr = (const float*)(xs + (8 * qq + 4 * hh + e) * 512) + l31;
;           float s1 = 0.f, s2 = 0.f;
; #pragma unroll
;           for (int nt = 0; nt < 4; ++nt) {
;             float v = (acc[mt][nt][i] + bia[nt]) * csc[nt];
;             float z = ALPHA * xr[nt * 32] + hs * v;
;             acc[mt][nt][i] = z; s1 += z; s2 += z * z;
;           }
;           s1 = row16_sum(s1); s2 = row16_sum(s2);
;           if ((lane & 15) == 0) { f32x2 sv = {s1, s2}; *(f32x2*)(redw + (mt * 32 + (i & 3) + 8 * (i >> 2)) * 2) = sv; }
	v_mov_b32_e32 v133, v1
	v_ashrrev_i32_e32 v158, 6, v164
	v_lshrrev_b32_e32 v0, 30, v158
	v_add_u32_e32 v0, v158, v0
	v_ashrrev_i32_e32 v134, 2, v0
	v_mul_i32_i24_e32 v0, 4, v134
	v_sub_u32_e32 v0, v158, v0
	v_lshlrev_b32_e32 v135, 6, v0
	v_add_u32_e32 v163, s3, v135
	v_bfe_u32 v0, v164, 5, 1
	v_or_b32_e32 v159, v163, v0
	v_or_b32_e32 v130, 16, v159
	v_lshlrev_b32_e32 v200, 2, v164
	v_ashrrev_i32_e32 v131, 31, v130
	v_lshl_add_u32 v182, v134, 7, s30
	v_and_b32_e32 v0, 0x7c, v200
	v_lshlrev_b64 v[130:131], 12, v[130:131]
	v_ashrrev_i32_e32 v183, 31, v182
	v_readfirstlane_b32 s2, v158
	v_lshl_add_u64 v[130:131], s[10:11], 0, v[130:131]
	v_lshlrev_b32_e32 v0, 2, v0
	s_lshl_b32 s2, s2, 13
	v_lshl_add_u64 v[130:131], v[182:183], 2, v[130:131]
	v_mov_b32_e32 v132, v0
	s_add_i32 m0, s2, 0x10000
	v_lshl_add_u64 v[130:131], v[130:131], 0, v[132:133]
	global_load_lds_dwordx4 v[130:131], off
	v_lshl_add_u64 v[132:133], v[130:131], 0, s[34:35]
	s_add_i32 m0, s2, 0x10400
	v_and_b32_e32 v210, 0xc0, v135
	global_load_lds_dwordx4 v[132:133], off
	v_lshl_add_u64 v[132:133], v[130:131], 0, s[36:37]
	s_add_i32 m0, s2, 0x10800
	v_mov_b32_e32 v136, v114
	global_load_lds_dwordx4 v[132:133], off
	v_lshl_add_u64 v[132:133], v[130:131], 0, s[40:41]
	s_add_i32 m0, s2, 0x10c00
	v_mov_b32_e32 v137, v82
	global_load_lds_dwordx4 v[132:133], off
	v_lshl_add_u64 v[132:133], v[130:131], 0, s[44:45]
	s_add_i32 m0, s2, 0x11000
	v_mov_b32_e32 v140, v98
	global_load_lds_dwordx4 v[132:133], off
	v_lshl_add_u64 v[132:133], v[130:131], 0, s[46:47]
	s_add_i32 m0, s2, 0x11400
	v_mov_b32_e32 v141, v82
	global_load_lds_dwordx4 v[132:133], off
	v_lshl_add_u64 v[132:133], v[130:131], 0, s[52:53]
	s_add_i32 m0, s2, 0x11800
	v_lshl_add_u64 v[130:131], v[130:131], 0, s[54:55]
	global_load_lds_dwordx4 v[132:133], off
	s_add_i32 m0, s2, 0x11c00
	v_bfe_u32 v132, v164, 4, 1
	global_load_lds_dwordx4 v[130:131], off
	v_and_b32_e32 v130, 31, v164
	v_lshlrev_b32_e32 v131, 1, v134
	v_bfe_u32 v134, v164, 3, 3
	v_and_or_b32 v131, v131, 2, v132
	v_and_b32_e32 v132, 4, v134
	v_lshlrev_b32_e32 v130, 2, v130
	v_lshl_or_b32 v138, v158, 13, v130
	v_lshlrev_b32_e32 v154, 9, v132
	v_or_b32_e32 v133, v210, v132
	v_and_b32_e32 v130, 15, v164
	v_or_b32_e32 v132, v138, v154
	v_lshlrev_b32_e32 v135, 3, v133
	v_lshl_or_b32 v139, v131, 11, v221
	v_cmp_eq_u32_e32 vcc, 0, v130
	s_waitcnt vmcnt(8)
	ds_read2_b32 v[130:131], v132 offset1:32
	ds_read2_b32 v[132:133], v132 offset0:64 offset1:96
	v_pk_add_f32 v[136:137], v[136:137], 0 op_sel_hi:[1,0]
	v_pk_add_f32 v[140:141], v[140:141], 0 op_sel_hi:[1,0]
	s_mov_b32 s2, s67
	s_waitcnt lgkmcnt(0)
	v_mov_b32_e32 v142, v130
	v_mov_b32_e32 v143, v132
	v_mov_b32_e32 v130, v131
	v_mov_b32_e32 v131, v132
	v_pk_fma_f32 v[186:187], v[142:143], s[2:3], v[136:137] op_sel_hi:[1,0,1]
	v_pk_fma_f32 v[188:189], v[130:131], s[2:3], v[140:141] op_sel_hi:[1,0,1]
	v_pk_mul_f32 v[144:145], v[142:143], s[2:3] op_sel_hi:[1,0]
	v_pk_mul_f32 v[142:143], v[186:187], v[186:187]
	v_pk_mul_f32 v[130:131], v[188:189], v[188:189]
	v_pk_mov_b32 v[136:137], v[136:137], v[142:143] op_sel:[1,0]
	v_pk_mov_b32 v[130:131], v[144:145], v[130:131] op_sel:[1,0]
	v_add_f32_e32 v178, 0, v66
	v_pk_add_f32 v[130:131], v[136:137], v[130:131]
	v_pk_add_f32 v[136:137], v[186:187], v[188:189]
	v_pk_mul_f32 v[140:141], v[186:187], v[188:189]
	v_fmac_f32_e32 v178, 0x3fd744fd, v133
	v_mov_b32_e32 v137, v141
	v_pk_add_f32 v[130:131], v[136:137], v[130:131]
	v_mul_f32_e32 v179, v178, v178
	v_pk_add_f32 v[130:131], v[130:131], v[178:179]
	v_add_u32_e32 v179, v139, v135
	s_nop 0
	v_mov_b32_dpp v132, v130 quad_perm:[1,0,3,2] row_mask:0xf bank_mask:0xf bound_ctrl:1
	v_mov_b32_dpp v133, v131 quad_perm:[1,0,3,2] row_mask:0xf bank_mask:0xf bound_ctrl:1
	v_pk_add_f32 v[130:131], v[130:131], v[132:133]
	s_nop 1
	v_mov_b32_dpp v132, v130 quad_perm:[2,3,0,1] row_mask:0xf bank_mask:0xf bound_ctrl:1
	v_mov_b32_dpp v133, v131 quad_perm:[2,3,0,1] row_mask:0xf bank_mask:0xf bound_ctrl:1
	v_pk_add_f32 v[130:131], v[130:131], v[132:133]
	s_nop 1
	v_mov_b32_dpp v132, v130 row_half_mirror row_mask:0xf bank_mask:0xf bound_ctrl:1
	v_mov_b32_dpp v133, v131 row_half_mirror row_mask:0xf bank_mask:0xf bound_ctrl:1
	v_pk_add_f32 v[130:131], v[130:131], v[132:133]
	s_nop 1
	v_mov_b32_dpp v132, v130 row_mirror row_mask:0xf bank_mask:0xf bound_ctrl:1
	v_mov_b32_dpp v133, v131 row_mirror row_mask:0xf bank_mask:0xf bound_ctrl:1
	s_and_saveexec_b64 s[6:7], vcc
	v_pk_add_f32 v[130:131], v[130:131], v[132:133]
	ds_write_b64 v179, v[130:131]
	s_or_b64 exec, exec, s[6:7]
	v_add_u32_e32 v168, v138, v154
	ds_read2_b32 v[130:131], v168 offset0:128 offset1:160
	ds_read2_b32 v[132:133], v168 offset0:192 offset1:224
	v_mov_b32_e32 v82, v115
	v_add_f32_e32 v152, 0, v67
	v_pk_add_f32 v[66:67], v[82:83], 0 op_sel_hi:[1,0]
	v_mov_b32_e32 v82, v99
	v_pk_add_f32 v[82:83], v[82:83], 0 op_sel_hi:[1,0]
	s_waitcnt lgkmcnt(1)
	v_mov_b32_e32 v98, v130
	s_waitcnt lgkmcnt(0)
;   DI void operator()(f32x16 (&acc)[2][4], int grow0, int gcol0, int lane, int w, char* lds) {
;     ...
;         for (int e = 0; e < 4; ++e) {
;           const int i = 4 * (2 * (ps & 1) + qq) + e;
;           const float* xr = (const float*)(xs + (8 * qq + 4 * hh + e) * 512) + l31;
;           float s1 = 0.f, s2 = 0.f;
; #pragma unroll
;           for (int nt = 0; nt < 4; ++nt) {
;             float v = (acc[mt][nt][i] + bia[nt]) * csc[nt];
;             float z = ALPHA * xr[nt * 32] + hs * v;
;             acc[mt][nt][i] = z; s1 += z; s2 += z * z;
;           }
;           s1 = row16_sum(s1); s2 = row16_sum(s2);
;           if ((lane & 15) == 0) { f32x2 sv = {s1, s2}; *(f32x2*)(redw + (mt * 32 + (i & 3) + 8 * (i >> 2)) * 2) = sv; }
	v_mov_b32_e32 v99, v132
	s_mov_b32 s2, s67
	v_mov_b32_e32 v130, v131
	v_mov_b32_e32 v131, v132
	v_pk_fma_f32 v[166:167], v[98:99], s[2:3], v[66:67] op_sel_hi:[1,0,1]
	v_pk_fma_f32 v[172:173], v[130:131], s[2:3], v[82:83] op_sel_hi:[1,0,1]
	v_pk_mul_f32 v[114:115], v[98:99], s[2:3] op_sel_hi:[1,0]
	v_pk_mul_f32 v[98:99], v[166:167], v[166:167]
	v_pk_mul_f32 v[82:83], v[172:173], v[172:173]
	v_pk_mov_b32 v[66:67], v[66:67], v[98:99] op_sel:[1,0]
	v_pk_mov_b32 v[82:83], v[114:115], v[82:83] op_sel:[1,0]
	v_pk_mul_f32 v[98:99], v[166:167], v[172:173]
	v_pk_add_f32 v[66:67], v[66:67], v[82:83]
	v_pk_add_f32 v[82:83], v[166:167], v[172:173]
	v_fmac_f32_e32 v152, 0x3fd744fd, v133
	v_mov_b32_e32 v83, v99
	v_pk_add_f32 v[66:67], v[82:83], v[66:67]
	v_mul_f32_e32 v153, v152, v152
	v_pk_add_f32 v[66:67], v[66:67], v[152:153]
	s_nop 1
	v_mov_b32_dpp v82, v66 quad_perm:[1,0,3,2] row_mask:0xf bank_mask:0xf bound_ctrl:1
	v_mov_b32_dpp v83, v67 quad_perm:[1,0,3,2] row_mask:0xf bank_mask:0xf bound_ctrl:1
	v_pk_add_f32 v[66:67], v[66:67], v[82:83]
	s_nop 1
	v_mov_b32_dpp v82, v66 quad_perm:[2,3,0,1] row_mask:0xf bank_mask:0xf bound_ctrl:1
	v_mov_b32_dpp v83, v67 quad_perm:[2,3,0,1] row_mask:0xf bank_mask:0xf bound_ctrl:1
	v_pk_add_f32 v[66:67], v[66:67], v[82:83]
	s_nop 1
	v_mov_b32_dpp v82, v66 row_half_mirror row_mask:0xf bank_mask:0xf bound_ctrl:1
	v_mov_b32_dpp v83, v67 row_half_mirror row_mask:0xf bank_mask:0xf bound_ctrl:1
	v_pk_add_f32 v[66:67], v[66:67], v[82:83]
	s_nop 1
	v_mov_b32_dpp v82, v66 row_mirror row_mask:0xf bank_mask:0xf bound_ctrl:1
	v_mov_b32_dpp v83, v67 row_mirror row_mask:0xf bank_mask:0xf bound_ctrl:1
	s_and_saveexec_b64 s[6:7], vcc
	v_readlane_b32 s63, v254, 51
	v_readlane_b32 s65, v254, 48
	v_readlane_b32 s70, v254, 52
	v_readlane_b32 s71, v255, 50
	v_pk_add_f32 v[66:67], v[66:67], v[82:83]
	ds_write_b64 v179, v[66:67] offset:8
	s_or_b64 exec, exec, s[6:7]
	v_add_u32_e32 v153, 0x400, v168
	ds_read2_b32 v[82:83], v153 offset1:32
	ds_read2_b32 v[98:99], v153 offset0:64 offset1:96
	v_mov_b32_e32 v114, v116
	v_mov_b32_e32 v115, v84
	v_mov_b32_e32 v130, v100
	v_mov_b32_e32 v131, v84
	v_pk_add_f32 v[114:115], v[114:115], 0 op_sel_hi:[1,0]
	v_pk_add_f32 v[130:131], v[130:131], 0 op_sel_hi:[1,0]
	s_waitcnt lgkmcnt(1)
	v_mov_b32_e32 v132, v82
	s_waitcnt lgkmcnt(0)
	v_mov_b32_e32 v133, v98
	s_mov_b32 s2, s67
	v_mov_b32_e32 v140, v83
	v_mov_b32_e32 v141, v98
	v_pk_fma_f32 v[82:83], v[132:133], s[2:3], v[114:115] op_sel_hi:[1,0,1]
	v_pk_fma_f32 v[150:151], v[140:141], s[2:3], v[130:131] op_sel_hi:[1,0,1]
	v_pk_mul_f32 v[136:137], v[132:133], s[2:3] op_sel_hi:[1,0]
	v_pk_mul_f32 v[132:133], v[82:83], v[82:83]
	v_pk_mul_f32 v[130:131], v[150:151], v[150:151]
	v_pk_mov_b32 v[114:115], v[114:115], v[132:133] op_sel:[1,0]
	v_pk_mov_b32 v[130:131], v[136:137], v[130:131] op_sel:[1,0]
	v_add_f32_e32 v66, 0, v68
	v_pk_add_f32 v[114:115], v[114:115], v[130:131]
	v_pk_add_f32 v[130:131], v[82:83], v[150:151]
	v_pk_mul_f32 v[132:133], v[82:83], v[150:151]
	v_fmac_f32_e32 v66, 0x3fd744fd, v99
	v_mov_b32_e32 v131, v133
	v_pk_add_f32 v[114:115], v[130:131], v[114:115]
	v_mul_f32_e32 v67, v66, v66
	v_pk_add_f32 v[98:99], v[114:115], v[66:67]
	s_nop 1
	v_mov_b32_dpp v114, v98 quad_perm:[1,0,3,2] row_mask:0xf bank_mask:0xf bound_ctrl:1
	v_mov_b32_dpp v115, v99 quad_perm:[1,0,3,2] row_mask:0xf bank_mask:0xf bound_ctrl:1
	v_pk_add_f32 v[98:99], v[98:99], v[114:115]
	s_nop 1
	v_mov_b32_dpp v114, v98 quad_perm:[2,3,0,1] row_mask:0xf bank_mask:0xf bound_ctrl:1
	v_mov_b32_dpp v115, v99 quad_perm:[2,3,0,1] row_mask:0xf bank_mask:0xf bound_ctrl:1
	v_pk_add_f32 v[98:99], v[98:99], v[114:115]
	s_nop 1
	v_mov_b32_dpp v114, v98 row_half_mirror row_mask:0xf bank_mask:0xf bound_ctrl:1
	v_mov_b32_dpp v115, v99 row_half_mirror row_mask:0xf bank_mask:0xf bound_ctrl:1
	v_pk_add_f32 v[98:99], v[98:99], v[114:115]
	s_nop 1
	v_mov_b32_dpp v114, v98 row_mirror row_mask:0xf bank_mask:0xf bound_ctrl:1
	v_mov_b32_dpp v115, v99 row_mirror row_mask:0xf bank_mask:0xf bound_ctrl:1
	s_and_saveexec_b64 s[6:7], vcc
	v_pk_add_f32 v[98:99], v[98:99], v[114:115]
	ds_write_b64 v179, v[98:99] offset:16
	s_or_b64 exec, exec, s[6:7]
	v_lshlrev_b32_e32 v139, 9, v134
	v_or_b32_e32 v146, 0x600, v139
	v_add_u32_e32 v151, v138, v146
	ds_read2_b32 v[98:99], v151 offset1:32
	ds_read2_b32 v[114:115], v151 offset0:64 offset1:96
	v_mov_b32_e32 v84, v117
	v_pk_add_f32 v[116:117], v[84:85], 0 op_sel_hi:[1,0]
	v_mov_b32_e32 v84, v101
	v_pk_add_f32 v[84:85], v[84:85], 0 op_sel_hi:[1,0]
	s_waitcnt lgkmcnt(1)
	v_mov_b32_e32 v100, v98
	s_waitcnt lgkmcnt(0)
;   DI void operator()(f32x16 (&acc)[2][4], int grow0, int gcol0, int lane, int w, char* lds) {
;     ...
;         for (int e = 0; e < 4; ++e) {
;           const int i = 4 * (2 * (ps & 1) + qq) + e;
;           const float* xr = (const float*)(xs + (8 * qq + 4 * hh + e) * 512) + l31;
;           float s1 = 0.f, s2 = 0.f;
; #pragma unroll
;           for (int nt = 0; nt < 4; ++nt) {
;             float v = (acc[mt][nt][i] + bia[nt]) * csc[nt];
;             float z = ALPHA * xr[nt * 32] + hs * v;
;             acc[mt][nt][i] = z; s1 += z; s2 += z * z;
;           }
;           s1 = row16_sum(s1); s2 = row16_sum(s2);
;           if ((lane & 15) == 0) { f32x2 sv = {s1, s2}; *(f32x2*)(redw + (mt * 32 + (i & 3) + 8 * (i >> 2)) * 2) = sv; }
	v_mov_b32_e32 v101, v114
	s_mov_b32 s2, s67
	v_mov_b32_e32 v132, v99
	v_mov_b32_e32 v133, v114
	v_pk_mul_f32 v[130:131], v[100:101], s[2:3] op_sel_hi:[1,0]
	v_pk_fma_f32 v[98:99], v[100:101], s[2:3], v[116:117] op_sel_hi:[1,0,1]
	v_pk_fma_f32 v[100:101], v[132:133], s[2:3], v[84:85] op_sel_hi:[1,0,1]
	v_pk_mul_f32 v[134:135], v[98:99], v[98:99]
	v_pk_mul_f32 v[84:85], v[100:101], v[100:101]
	v_pk_mov_b32 v[116:117], v[116:117], v[134:135] op_sel:[1,0]
	v_pk_mov_b32 v[84:85], v[130:131], v[84:85] op_sel:[1,0]
	v_add_f32_e32 v68, 0, v69
	v_pk_add_f32 v[84:85], v[116:117], v[84:85]
	v_pk_add_f32 v[116:117], v[98:99], v[100:101]
	v_pk_mul_f32 v[130:131], v[98:99], v[100:101]
	v_fmac_f32_e32 v68, 0x3fd744fd, v115
	v_mov_b32_e32 v117, v131
	v_pk_add_f32 v[84:85], v[116:117], v[84:85]
	v_mul_f32_e32 v69, v68, v68
	v_pk_add_f32 v[84:85], v[84:85], v[68:69]
	s_nop 1
	v_mov_b32_dpp v114, v84 quad_perm:[1,0,3,2] row_mask:0xf bank_mask:0xf bound_ctrl:1
	v_mov_b32_dpp v115, v85 quad_perm:[1,0,3,2] row_mask:0xf bank_mask:0xf bound_ctrl:1
	v_pk_add_f32 v[84:85], v[84:85], v[114:115]
	s_nop 1
	v_mov_b32_dpp v114, v84 quad_perm:[2,3,0,1] row_mask:0xf bank_mask:0xf bound_ctrl:1
	v_mov_b32_dpp v115, v85 quad_perm:[2,3,0,1] row_mask:0xf bank_mask:0xf bound_ctrl:1
	v_pk_add_f32 v[84:85], v[84:85], v[114:115]
	s_nop 1
	v_mov_b32_dpp v114, v84 row_half_mirror row_mask:0xf bank_mask:0xf bound_ctrl:1
	v_mov_b32_dpp v115, v85 row_half_mirror row_mask:0xf bank_mask:0xf bound_ctrl:1
	v_pk_add_f32 v[84:85], v[84:85], v[114:115]
	s_nop 1
	v_mov_b32_dpp v114, v84 row_mirror row_mask:0xf bank_mask:0xf bound_ctrl:1
	v_mov_b32_dpp v115, v85 row_mirror row_mask:0xf bank_mask:0xf bound_ctrl:1
	s_and_saveexec_b64 s[6:7], vcc
	v_pk_add_f32 v[84:85], v[84:85], v[114:115]
	ds_write_b64 v179, v[84:85] offset:24
	s_or_b64 exec, exec, s[6:7]
	v_add_u32_e32 v67, 0x1000, v168
	ds_read2_b32 v[114:115], v67 offset1:32
	ds_read2_b32 v[130:131], v67 offset0:64 offset1:96
	v_mov_b32_e32 v116, v118
	v_mov_b32_e32 v117, v86
	v_pk_add_f32 v[132:133], v[116:117], 0 op_sel_hi:[1,0]
	v_mov_b32_e32 v116, v102
	v_pk_add_f32 v[116:117], v[116:117], 0 op_sel_hi:[1,0]
	s_waitcnt lgkmcnt(1)
	v_mov_b32_e32 v134, v114
	s_waitcnt lgkmcnt(0)
	v_mov_b32_e32 v135, v130
	s_mov_b32 s2, s67
	v_mov_b32_e32 v140, v115
	v_mov_b32_e32 v141, v130
	v_pk_fma_f32 v[114:115], v[134:135], s[2:3], v[132:133] op_sel_hi:[1,0,1]
	v_pk_fma_f32 v[116:117], v[140:141], s[2:3], v[116:117] op_sel_hi:[1,0,1]
	v_pk_mul_f32 v[136:137], v[134:135], s[2:3] op_sel_hi:[1,0]
	v_pk_mul_f32 v[134:135], v[114:115], v[114:115]
	v_pk_mul_f32 v[140:141], v[116:117], v[116:117]
	v_pk_mov_b32 v[132:133], v[132:133], v[134:135] op_sel:[1,0]
	v_pk_mov_b32 v[134:135], v[136:137], v[140:141] op_sel:[1,0]
	v_add_f32_e32 v84, 0, v70
	v_pk_add_f32 v[132:133], v[132:133], v[134:135]
	v_pk_add_f32 v[134:135], v[114:115], v[116:117]
	v_pk_mul_f32 v[136:137], v[114:115], v[116:117]
	v_fmac_f32_e32 v84, 0x3fd744fd, v131
	v_mov_b32_e32 v135, v137
	v_pk_add_f32 v[132:133], v[134:135], v[132:133]
	v_mul_f32_e32 v85, v84, v84
	v_pk_add_f32 v[130:131], v[132:133], v[84:85]
	s_nop 1
	v_mov_b32_dpp v132, v130 quad_perm:[1,0,3,2] row_mask:0xf bank_mask:0xf bound_ctrl:1
	v_mov_b32_dpp v133, v131 quad_perm:[1,0,3,2] row_mask:0xf bank_mask:0xf bound_ctrl:1
	v_pk_add_f32 v[130:131], v[130:131], v[132:133]
	s_nop 1
	v_mov_b32_dpp v132, v130 quad_perm:[2,3,0,1] row_mask:0xf bank_mask:0xf bound_ctrl:1
	v_mov_b32_dpp v133, v131 quad_perm:[2,3,0,1] row_mask:0xf bank_mask:0xf bound_ctrl:1
	v_pk_add_f32 v[130:131], v[130:131], v[132:133]
	s_nop 1
	v_mov_b32_dpp v132, v130 row_half_mirror row_mask:0xf bank_mask:0xf bound_ctrl:1
	v_mov_b32_dpp v133, v131 row_half_mirror row_mask:0xf bank_mask:0xf bound_ctrl:1
	v_pk_add_f32 v[130:131], v[130:131], v[132:133]
	s_nop 1
	v_mov_b32_dpp v132, v130 row_mirror row_mask:0xf bank_mask:0xf bound_ctrl:1
	v_mov_b32_dpp v133, v131 row_mirror row_mask:0xf bank_mask:0xf bound_ctrl:1
	s_and_saveexec_b64 s[6:7], vcc
	v_pk_add_f32 v[130:131], v[130:131], v[132:133]
	ds_write_b64 v179, v[130:131] offset:64
	s_or_b64 exec, exec, s[6:7]
	ds_read2_b32 v[130:131], v67 offset0:128 offset1:160
	ds_read2_b32 v[132:133], v67 offset0:192 offset1:224
	v_mov_b32_e32 v86, v119
	v_pk_add_f32 v[134:135], v[86:87], 0 op_sel_hi:[1,0]
	v_mov_b32_e32 v86, v103
	v_pk_add_f32 v[86:87], v[86:87], 0 op_sel_hi:[1,0]
	s_waitcnt lgkmcnt(1)
	v_mov_b32_e32 v102, v130
	s_waitcnt lgkmcnt(0)
	v_mov_b32_e32 v103, v132
	s_mov_b32 s2, s67
	v_mov_b32_e32 v118, v131
	v_mov_b32_e32 v119, v132
	v_pk_mul_f32 v[136:137], v[102:103], s[2:3] op_sel_hi:[1,0]
	v_pk_fma_f32 v[102:103], v[102:103], s[2:3], v[134:135] op_sel_hi:[1,0,1]
	v_pk_fma_f32 v[118:119], v[118:119], s[2:3], v[86:87] op_sel_hi:[1,0,1]
	v_pk_mul_f32 v[130:131], v[102:103], v[102:103]
	v_pk_mul_f32 v[86:87], v[118:119], v[118:119]
	v_pk_mov_b32 v[130:131], v[134:135], v[130:131] op_sel:[1,0]
	v_pk_mov_b32 v[86:87], v[136:137], v[86:87] op_sel:[1,0]
	v_add_f32_e32 v70, 0, v71
	v_pk_add_f32 v[86:87], v[130:131], v[86:87]
	v_pk_add_f32 v[130:131], v[102:103], v[118:119]
	v_pk_mul_f32 v[134:135], v[102:103], v[118:119]
	v_fmac_f32_e32 v70, 0x3fd744fd, v133
	v_mov_b32_e32 v131, v135
	v_pk_add_f32 v[86:87], v[130:131], v[86:87]
	v_mul_f32_e32 v71, v70, v70
	v_pk_add_f32 v[86:87], v[86:87], v[70:71]
	s_nop 1
	v_mov_b32_dpp v130, v86 quad_perm:[1,0,3,2] row_mask:0xf bank_mask:0xf bound_ctrl:1
	v_mov_b32_dpp v131, v87 quad_perm:[1,0,3,2] row_mask:0xf bank_mask:0xf bound_ctrl:1
	v_pk_add_f32 v[86:87], v[86:87], v[130:131]
	s_nop 1
	v_mov_b32_dpp v130, v86 quad_perm:[2,3,0,1] row_mask:0xf bank_mask:0xf bound_ctrl:1
	v_mov_b32_dpp v131, v87 quad_perm:[2,3,0,1] row_mask:0xf bank_mask:0xf bound_ctrl:1
	v_pk_add_f32 v[86:87], v[86:87], v[130:131]
	s_nop 1
	v_mov_b32_dpp v130, v86 row_half_mirror row_mask:0xf bank_mask:0xf bound_ctrl:1
	v_mov_b32_dpp v131, v87 row_half_mirror row_mask:0xf bank_mask:0xf bound_ctrl:1
	v_pk_add_f32 v[86:87], v[86:87], v[130:131]
	s_nop 1
	v_mov_b32_dpp v130, v86 row_mirror row_mask:0xf bank_mask:0xf bound_ctrl:1
	v_mov_b32_dpp v131, v87 row_mirror row_mask:0xf bank_mask:0xf bound_ctrl:1
	s_and_saveexec_b64 s[6:7], vcc
	v_pk_add_f32 v[86:87], v[86:87], v[130:131]
	ds_write_b64 v179, v[86:87] offset:72
	s_or_b64 exec, exec, s[6:7]
	v_add_u32_e32 v69, 0x1400, v168
	ds_read2_b32 v[130:131], v69 offset1:32
	ds_read2_b32 v[134:135], v69 offset0:64 offset1:96
	v_mov_b32_e32 v132, v120
	v_mov_b32_e32 v133, v88
	v_pk_add_f32 v[136:137], v[132:133], 0 op_sel_hi:[1,0]
	v_mov_b32_e32 v132, v104
	v_pk_add_f32 v[132:133], v[132:133], 0 op_sel_hi:[1,0]
	s_waitcnt lgkmcnt(1)
;   DI void operator()(f32x16 (&acc)[2][4], int grow0, int gcol0, int lane, int w, char* lds) {
;     ...
;       if (ps + 1 < 4) {
;         if (ps >= 1) asm volatile("s_waitcnt lgkmcnt(0)" ::: "memory");
;         xpass(ps + 1, grow0, gcol0, lane, w, lds);
;         if (ps >= 1) asm volatile("s_waitcnt vmcnt(8)" ::: "memory");
;       } else asm volatile("s_waitcnt vmcnt(0)" ::: "memory");
;       const char* xs = lds + (ps & 1) * 65536 + w * 8192;
; #pragma unroll
;       for (int qq = 0; qq < 2; ++qq)
; #pragma unroll
;         for (int e = 0; e < 4; ++e) {
;           const int i = 4 * (2 * (ps & 1) + qq) + e;
;           const float* xr = (const float*)(xs + (8 * qq + 4 * hh + e) * 512) + l31;
;           float s1 = 0.f, s2 = 0.f;
; #pragma unroll
;           for (int nt = 0; nt < 4; ++nt) {
;             float v = (acc[mt][nt][i] + bia[nt]) * csc[nt];
;             float z = ALPHA * xr[nt * 32] + hs * v;
;             acc[mt][nt][i] = z; s1 += z; s2 += z * z;
;           }
;           s1 = row16_sum(s1); s2 = row16_sum(s2);
;           if ((lane & 15) == 0) { f32x2 sv = {s1, s2}; *(f32x2*)(redw + (mt * 32 + (i & 3) + 8 * (i >> 2)) * 2) = sv; }
	v_mov_b32_e32 v140, v130
	s_waitcnt lgkmcnt(0)
	v_mov_b32_e32 v141, v134
	s_mov_b32 s2, s67
	v_mov_b32_e32 v144, v131
	v_mov_b32_e32 v145, v134
	v_pk_fma_f32 v[130:131], v[140:141], s[2:3], v[136:137] op_sel_hi:[1,0,1]
	v_pk_fma_f32 v[132:133], v[144:145], s[2:3], v[132:133] op_sel_hi:[1,0,1]
	v_pk_mul_f32 v[142:143], v[140:141], s[2:3] op_sel_hi:[1,0]
	v_pk_mul_f32 v[140:141], v[130:131], v[130:131]
	v_pk_mul_f32 v[144:145], v[132:133], v[132:133]
	v_pk_mov_b32 v[136:137], v[136:137], v[140:141] op_sel:[1,0]
	v_pk_mov_b32 v[140:141], v[142:143], v[144:145] op_sel:[1,0]
	v_add_f32_e32 v86, 0, v72
	v_pk_add_f32 v[136:137], v[136:137], v[140:141]
	v_pk_add_f32 v[140:141], v[130:131], v[132:133]
	v_pk_mul_f32 v[142:143], v[130:131], v[132:133]
	v_fmac_f32_e32 v86, 0x3fd744fd, v135
	v_mov_b32_e32 v141, v143
	v_pk_add_f32 v[136:137], v[140:141], v[136:137]
	v_mul_f32_e32 v87, v86, v86
	v_pk_add_f32 v[134:135], v[136:137], v[86:87]
	s_nop 1
	v_mov_b32_dpp v136, v134 quad_perm:[1,0,3,2] row_mask:0xf bank_mask:0xf bound_ctrl:1
	v_mov_b32_dpp v137, v135 quad_perm:[1,0,3,2] row_mask:0xf bank_mask:0xf bound_ctrl:1
	v_pk_add_f32 v[134:135], v[134:135], v[136:137]
	s_nop 1
	v_mov_b32_dpp v136, v134 quad_perm:[2,3,0,1] row_mask:0xf bank_mask:0xf bound_ctrl:1
	v_mov_b32_dpp v137, v135 quad_perm:[2,3,0,1] row_mask:0xf bank_mask:0xf bound_ctrl:1
	v_pk_add_f32 v[134:135], v[134:135], v[136:137]
	s_nop 1
	v_mov_b32_dpp v136, v134 row_half_mirror row_mask:0xf bank_mask:0xf bound_ctrl:1
	v_mov_b32_dpp v137, v135 row_half_mirror row_mask:0xf bank_mask:0xf bound_ctrl:1
	v_pk_add_f32 v[134:135], v[134:135], v[136:137]
	s_nop 1
	v_mov_b32_dpp v136, v134 row_mirror row_mask:0xf bank_mask:0xf bound_ctrl:1
	v_mov_b32_dpp v137, v135 row_mirror row_mask:0xf bank_mask:0xf bound_ctrl:1
	s_and_saveexec_b64 s[6:7], vcc
	v_pk_add_f32 v[134:135], v[134:135], v[136:137]
	ds_write_b64 v179, v[134:135] offset:80
	s_or_b64 exec, exec, s[6:7]
	v_or_b32_e32 v101, 0x1600, v139
	v_add_u32_e32 v71, v138, v101
	ds_read2_b32 v[134:135], v71 offset1:32
	ds_read2_b32 v[136:137], v71 offset0:64 offset1:96
	v_mov_b32_e32 v88, v121
	v_pk_add_f32 v[120:121], v[88:89], 0 op_sel_hi:[1,0]
	v_mov_b32_e32 v88, v105
	v_pk_add_f32 v[104:105], v[88:89], 0 op_sel_hi:[1,0]
	s_waitcnt lgkmcnt(1)
	v_mov_b32_e32 v88, v134
	s_waitcnt lgkmcnt(0)
	v_mov_b32_e32 v89, v136
	s_mov_b32 s2, s67
	v_mov_b32_e32 v134, v135
	v_mov_b32_e32 v135, v136
	v_pk_mul_f32 v[140:141], v[88:89], s[2:3] op_sel_hi:[1,0]
	v_pk_fma_f32 v[88:89], v[88:89], s[2:3], v[120:121] op_sel_hi:[1,0,1]
	v_pk_fma_f32 v[104:105], v[134:135], s[2:3], v[104:105] op_sel_hi:[1,0,1]
	v_pk_mul_f32 v[142:143], v[88:89], v[88:89]
	v_pk_mul_f32 v[134:135], v[104:105], v[104:105]
	v_pk_mov_b32 v[120:121], v[120:121], v[142:143] op_sel:[1,0]
	v_pk_mov_b32 v[134:135], v[140:141], v[134:135] op_sel:[1,0]
	v_add_f32_e32 v72, 0, v73
	v_pk_add_f32 v[120:121], v[120:121], v[134:135]
	v_pk_add_f32 v[134:135], v[88:89], v[104:105]
	v_pk_mul_f32 v[140:141], v[88:89], v[104:105]
	v_fmac_f32_e32 v72, 0x3fd744fd, v137
	v_mov_b32_e32 v135, v141
	v_pk_add_f32 v[120:121], v[134:135], v[120:121]
	v_mul_f32_e32 v73, v72, v72
	v_pk_add_f32 v[120:121], v[120:121], v[72:73]
	s_nop 1
	v_mov_b32_dpp v134, v120 quad_perm:[1,0,3,2] row_mask:0xf bank_mask:0xf bound_ctrl:1
	v_mov_b32_dpp v135, v121 quad_perm:[1,0,3,2] row_mask:0xf bank_mask:0xf bound_ctrl:1
	v_pk_add_f32 v[120:121], v[120:121], v[134:135]
	s_nop 1
	v_mov_b32_dpp v134, v120 quad_perm:[2,3,0,1] row_mask:0xf bank_mask:0xf bound_ctrl:1
	v_mov_b32_dpp v135, v121 quad_perm:[2,3,0,1] row_mask:0xf bank_mask:0xf bound_ctrl:1
	v_pk_add_f32 v[120:121], v[120:121], v[134:135]
	s_nop 1
	v_mov_b32_dpp v134, v120 row_half_mirror row_mask:0xf bank_mask:0xf bound_ctrl:1
	v_mov_b32_dpp v135, v121 row_half_mirror row_mask:0xf bank_mask:0xf bound_ctrl:1
	v_pk_add_f32 v[120:121], v[120:121], v[134:135]
	s_nop 1
	v_mov_b32_dpp v134, v120 row_mirror row_mask:0xf bank_mask:0xf bound_ctrl:1
	v_mov_b32_dpp v135, v121 row_mirror row_mask:0xf bank_mask:0xf bound_ctrl:1
	s_and_saveexec_b64 s[6:7], vcc
	v_pk_add_f32 v[120:121], v[120:121], v[134:135]
	ds_write_b64 v179, v[120:121] offset:88
	s_or_b64 exec, exec, s[6:7]
	v_or_b32_e32 v120, 32, v159
	v_ashrrev_i32_e32 v121, 31, v120
	v_lshlrev_b64 v[120:121], 12, v[120:121]
	v_readfirstlane_b32 s2, v158
	v_lshl_add_u64 v[120:121], s[10:11], 0, v[120:121]
	s_lshl_b32 s2, s2, 13
	v_lshl_add_u64 v[120:121], v[182:183], 2, v[120:121]
	s_waitcnt lgkmcnt(0)
	v_lshl_add_u64 v[120:121], v[120:121], 0, v[0:1]
	s_mov_b32 m0, s2
	s_mov_b64 s[6:7], 0x2000
	global_load_lds_dwordx4 v[120:121], off
	v_lshl_add_u64 v[134:135], v[120:121], 0, s[6:7]
	s_or_b32 m0, s2, 0x400
	s_mov_b64 s[6:7], 0x4000
	global_load_lds_dwordx4 v[134:135], off
	v_lshl_add_u64 v[134:135], v[120:121], 0, s[6:7]
	s_or_b32 m0, s2, 0x800
	s_mov_b64 s[6:7], 0x6000
	global_load_lds_dwordx4 v[134:135], off
	v_lshl_add_u64 v[134:135], v[120:121], 0, s[6:7]
	s_or_b32 m0, s2, 0xc00
	s_mov_b64 s[6:7], 0x8000
	global_load_lds_dwordx4 v[134:135], off
	v_lshl_add_u64 v[134:135], v[120:121], 0, s[6:7]
	s_or_b32 m0, s2, 0x1000
	s_mov_b64 s[6:7], 0xa000
	global_load_lds_dwordx4 v[134:135], off
	v_lshl_add_u64 v[134:135], v[120:121], 0, s[6:7]
	s_or_b32 m0, s2, 0x1400
	s_mov_b64 s[6:7], 0xc000
	global_load_lds_dwordx4 v[134:135], off
	v_lshl_add_u64 v[134:135], v[120:121], 0, s[6:7]
	s_or_b32 m0, s2, 0x1800
	s_mov_b64 s[6:7], 0xe000
	global_load_lds_dwordx4 v[134:135], off
	v_lshl_add_u64 v[120:121], v[120:121], 0, s[6:7]
	s_or_b32 m0, s2, 0x1c00
	v_add_u32_e32 v105, 0x10000, v138
	global_load_lds_dwordx4 v[120:121], off
	s_waitcnt vmcnt(8)
;   DI void operator()(f32x16 (&acc)[2][4], int grow0, int gcol0, int lane, int w, char* lds) {
;     ...
;         for (int e = 0; e < 4; ++e) {
;           const int i = 4 * (2 * (ps & 1) + qq) + e;
;           const float* xr = (const float*)(xs + (8 * qq + 4 * hh + e) * 512) + l31;
;           float s1 = 0.f, s2 = 0.f;
; #pragma unroll
;           for (int nt = 0; nt < 4; ++nt) {
;             float v = (acc[mt][nt][i] + bia[nt]) * csc[nt];
;             float z = ALPHA * xr[nt * 32] + hs * v;
;             acc[mt][nt][i] = z; s1 += z; s2 += z * z;
;           }
;           s1 = row16_sum(s1); s2 = row16_sum(s2);
;           if ((lane & 15) == 0) { f32x2 sv = {s1, s2}; *(f32x2*)(redw + (mt * 32 + (i & 3) + 8 * (i >> 2)) * 2) = sv; }
	v_add_u32_e32 v73, v105, v154
	ds_read2_b32 v[134:135], v73 offset1:32
	ds_read2_b32 v[138:139], v73 offset0:64 offset1:96
	v_mov_b32_e32 v136, v122
	v_mov_b32_e32 v137, v90
	v_pk_add_f32 v[140:141], v[136:137], 0 op_sel_hi:[1,0]
	v_mov_b32_e32 v136, v106
	v_pk_add_f32 v[136:137], v[136:137], 0 op_sel_hi:[1,0]
	s_waitcnt lgkmcnt(0)
	v_mov_b32_e32 v142, v134
	v_mov_b32_e32 v143, v138
	s_mov_b32 s2, s67
	v_mov_b32_e32 v148, v135
	v_mov_b32_e32 v149, v138
	v_pk_fma_f32 v[134:135], v[142:143], s[2:3], v[140:141] op_sel_hi:[1,0,1]
	v_pk_fma_f32 v[136:137], v[148:149], s[2:3], v[136:137] op_sel_hi:[1,0,1]
	v_pk_mul_f32 v[144:145], v[142:143], s[2:3] op_sel_hi:[1,0]
	v_pk_mul_f32 v[142:143], v[134:135], v[134:135]
	v_pk_mul_f32 v[148:149], v[136:137], v[136:137]
	v_pk_mov_b32 v[140:141], v[140:141], v[142:143] op_sel:[1,0]
	v_pk_mov_b32 v[142:143], v[144:145], v[148:149] op_sel:[1,0]
	v_add_f32_e32 v120, 0, v74
	v_pk_add_f32 v[140:141], v[140:141], v[142:143]
	v_pk_add_f32 v[142:143], v[134:135], v[136:137]
	v_pk_mul_f32 v[144:145], v[134:135], v[136:137]
	v_fmac_f32_e32 v120, 0x3fd744fd, v139
	v_mov_b32_e32 v143, v145
	v_pk_add_f32 v[140:141], v[142:143], v[140:141]
	v_mul_f32_e32 v121, v120, v120
	v_pk_add_f32 v[138:139], v[140:141], v[120:121]
	s_nop 1
	v_mov_b32_dpp v140, v138 quad_perm:[1,0,3,2] row_mask:0xf bank_mask:0xf bound_ctrl:1
	v_mov_b32_dpp v141, v139 quad_perm:[1,0,3,2] row_mask:0xf bank_mask:0xf bound_ctrl:1
	v_pk_add_f32 v[138:139], v[138:139], v[140:141]
	s_nop 1
	v_mov_b32_dpp v140, v138 quad_perm:[2,3,0,1] row_mask:0xf bank_mask:0xf bound_ctrl:1
	v_mov_b32_dpp v141, v139 quad_perm:[2,3,0,1] row_mask:0xf bank_mask:0xf bound_ctrl:1
	v_pk_add_f32 v[138:139], v[138:139], v[140:141]
	s_nop 1
	v_mov_b32_dpp v140, v138 row_half_mirror row_mask:0xf bank_mask:0xf bound_ctrl:1
	v_mov_b32_dpp v141, v139 row_half_mirror row_mask:0xf bank_mask:0xf bound_ctrl:1
	v_pk_add_f32 v[138:139], v[138:139], v[140:141]
	s_nop 1
	v_mov_b32_dpp v140, v138 row_mirror row_mask:0xf bank_mask:0xf bound_ctrl:1
	v_mov_b32_dpp v141, v139 row_mirror row_mask:0xf bank_mask:0xf bound_ctrl:1
	s_and_saveexec_b64 s[6:7], vcc
	v_pk_add_f32 v[138:139], v[138:139], v[140:141]
	ds_write_b64 v179, v[138:139] offset:128
	s_or_b64 exec, exec, s[6:7]
	v_or_b32_e32 v74, 0x200, v154
	v_add_u32_e32 v85, v105, v74
	ds_read2_b32 v[138:139], v85 offset1:32
	ds_read2_b32 v[140:141], v85 offset0:64 offset1:96
	v_mov_b32_e32 v90, v123
	v_pk_add_f32 v[142:143], v[90:91], 0 op_sel_hi:[1,0]
	v_mov_b32_e32 v90, v107
	v_pk_add_f32 v[90:91], v[90:91], 0 op_sel_hi:[1,0]
	s_waitcnt lgkmcnt(1)
	v_mov_b32_e32 v106, v138
	s_waitcnt lgkmcnt(0)
	v_mov_b32_e32 v107, v140
	s_mov_b32 s2, s67
	v_mov_b32_e32 v122, v139
	v_mov_b32_e32 v123, v140
	v_pk_mul_f32 v[144:145], v[106:107], s[2:3] op_sel_hi:[1,0]
	v_pk_fma_f32 v[106:107], v[106:107], s[2:3], v[142:143] op_sel_hi:[1,0,1]
	v_pk_fma_f32 v[122:123], v[122:123], s[2:3], v[90:91] op_sel_hi:[1,0,1]
	v_pk_mul_f32 v[138:139], v[106:107], v[106:107]
	v_pk_mul_f32 v[90:91], v[122:123], v[122:123]
	v_pk_mov_b32 v[138:139], v[142:143], v[138:139] op_sel:[1,0]
	v_pk_mov_b32 v[90:91], v[144:145], v[90:91] op_sel:[1,0]
	v_add_f32_e32 v74, 0, v75
	v_pk_add_f32 v[90:91], v[138:139], v[90:91]
	v_pk_add_f32 v[138:139], v[106:107], v[122:123]
	v_pk_mul_f32 v[142:143], v[106:107], v[122:123]
	v_fmac_f32_e32 v74, 0x3fd744fd, v141
	v_mov_b32_e32 v139, v143
	v_pk_add_f32 v[90:91], v[138:139], v[90:91]
	v_mul_f32_e32 v75, v74, v74
	v_pk_add_f32 v[90:91], v[90:91], v[74:75]
	s_nop 1
	v_mov_b32_dpp v138, v90 quad_perm:[1,0,3,2] row_mask:0xf bank_mask:0xf bound_ctrl:1
	v_mov_b32_dpp v139, v91 quad_perm:[1,0,3,2] row_mask:0xf bank_mask:0xf bound_ctrl:1
	v_pk_add_f32 v[90:91], v[90:91], v[138:139]
	s_nop 1
	v_mov_b32_dpp v138, v90 quad_perm:[2,3,0,1] row_mask:0xf bank_mask:0xf bound_ctrl:1
	v_mov_b32_dpp v139, v91 quad_perm:[2,3,0,1] row_mask:0xf bank_mask:0xf bound_ctrl:1
	v_pk_add_f32 v[90:91], v[90:91], v[138:139]
	s_nop 1
	v_mov_b32_dpp v138, v90 row_half_mirror row_mask:0xf bank_mask:0xf bound_ctrl:1
	v_mov_b32_dpp v139, v91 row_half_mirror row_mask:0xf bank_mask:0xf bound_ctrl:1
	v_pk_add_f32 v[90:91], v[90:91], v[138:139]
	s_nop 1
	v_mov_b32_dpp v138, v90 row_mirror row_mask:0xf bank_mask:0xf bound_ctrl:1
	v_mov_b32_dpp v139, v91 row_mirror row_mask:0xf bank_mask:0xf bound_ctrl:1
	s_and_saveexec_b64 s[6:7], vcc
	v_pk_add_f32 v[90:91], v[90:91], v[138:139]
	ds_write_b64 v179, v[90:91] offset:136
	s_or_b64 exec, exec, s[6:7]
	v_or_b32_e32 v75, 0x400, v154
	v_add_u32_e32 v75, v105, v75
	ds_read2_b32 v[138:139], v75 offset1:32
	ds_read2_b32 v[142:143], v75 offset0:64 offset1:96
	v_mov_b32_e32 v140, v124
	v_mov_b32_e32 v141, v92
	v_pk_add_f32 v[144:145], v[140:141], 0 op_sel_hi:[1,0]
	v_mov_b32_e32 v140, v108
	v_pk_add_f32 v[140:141], v[140:141], 0 op_sel_hi:[1,0]
	s_waitcnt lgkmcnt(1)
	v_mov_b32_e32 v148, v138
	s_waitcnt lgkmcnt(0)
;   DI void operator()(f32x16 (&acc)[2][4], int grow0, int gcol0, int lane, int w, char* lds) {
;     ...
;         for (int e = 0; e < 4; ++e) {
;           const int i = 4 * (2 * (ps & 1) + qq) + e;
;           const float* xr = (const float*)(xs + (8 * qq + 4 * hh + e) * 512) + l31;
;           float s1 = 0.f, s2 = 0.f;
; #pragma unroll
;           for (int nt = 0; nt < 4; ++nt) {
;             float v = (acc[mt][nt][i] + bia[nt]) * csc[nt];
;             float z = ALPHA * xr[nt * 32] + hs * v;
;             acc[mt][nt][i] = z; s1 += z; s2 += z * z;
;           }
;           s1 = row16_sum(s1); s2 = row16_sum(s2);
;           if ((lane & 15) == 0) { f32x2 sv = {s1, s2}; *(f32x2*)(redw + (mt * 32 + (i & 3) + 8 * (i >> 2)) * 2) = sv; }
	v_mov_b32_e32 v149, v142
	s_mov_b32 s2, s67
	v_mov_b32_e32 v160, v139
	v_mov_b32_e32 v161, v142
	v_pk_fma_f32 v[138:139], v[148:149], s[2:3], v[144:145] op_sel_hi:[1,0,1]
	v_pk_fma_f32 v[140:141], v[160:161], s[2:3], v[140:141] op_sel_hi:[1,0,1]
	v_pk_mul_f32 v[156:157], v[148:149], s[2:3] op_sel_hi:[1,0]
	v_pk_mul_f32 v[148:149], v[138:139], v[138:139]
	v_pk_mul_f32 v[160:161], v[140:141], v[140:141]
	v_pk_mov_b32 v[144:145], v[144:145], v[148:149] op_sel:[1,0]
	v_pk_mov_b32 v[148:149], v[156:157], v[160:161] op_sel:[1,0]
	v_add_f32_e32 v90, 0, v76
	v_pk_add_f32 v[144:145], v[144:145], v[148:149]
	v_pk_add_f32 v[148:149], v[138:139], v[140:141]
	v_pk_mul_f32 v[156:157], v[138:139], v[140:141]
	v_fmac_f32_e32 v90, 0x3fd744fd, v143
	v_mov_b32_e32 v149, v157
	v_pk_add_f32 v[144:145], v[148:149], v[144:145]
	v_mul_f32_e32 v91, v90, v90
	v_pk_add_f32 v[142:143], v[144:145], v[90:91]
	s_nop 1
	v_mov_b32_dpp v144, v142 quad_perm:[1,0,3,2] row_mask:0xf bank_mask:0xf bound_ctrl:1
	v_mov_b32_dpp v145, v143 quad_perm:[1,0,3,2] row_mask:0xf bank_mask:0xf bound_ctrl:1
	v_pk_add_f32 v[142:143], v[142:143], v[144:145]
	s_nop 1
	v_mov_b32_dpp v144, v142 quad_perm:[2,3,0,1] row_mask:0xf bank_mask:0xf bound_ctrl:1
	v_mov_b32_dpp v145, v143 quad_perm:[2,3,0,1] row_mask:0xf bank_mask:0xf bound_ctrl:1
	v_pk_add_f32 v[142:143], v[142:143], v[144:145]
	s_nop 1
	v_mov_b32_dpp v144, v142 row_half_mirror row_mask:0xf bank_mask:0xf bound_ctrl:1
	v_mov_b32_dpp v145, v143 row_half_mirror row_mask:0xf bank_mask:0xf bound_ctrl:1
	v_pk_add_f32 v[142:143], v[142:143], v[144:145]
	s_nop 1
	v_mov_b32_dpp v144, v142 row_mirror row_mask:0xf bank_mask:0xf bound_ctrl:1
	v_mov_b32_dpp v145, v143 row_mirror row_mask:0xf bank_mask:0xf bound_ctrl:1
	s_and_saveexec_b64 s[6:7], vcc
	v_pk_add_f32 v[142:143], v[142:143], v[144:145]
	ds_write_b64 v179, v[142:143] offset:144
	s_or_b64 exec, exec, s[6:7]
	v_add_u32_e32 v87, v105, v146
	ds_read2_b32 v[142:143], v87 offset1:32
	ds_read2_b32 v[144:145], v87 offset0:64 offset1:96
	v_mov_b32_e32 v92, v125
	v_pk_add_f32 v[146:147], v[92:93], 0 op_sel_hi:[1,0]
	v_mov_b32_e32 v92, v109
	v_pk_add_f32 v[92:93], v[92:93], 0 op_sel_hi:[1,0]
	s_waitcnt lgkmcnt(1)
	v_mov_b32_e32 v108, v142
	s_waitcnt lgkmcnt(0)
	v_mov_b32_e32 v109, v144
	s_mov_b32 s2, s67
	v_mov_b32_e32 v124, v143
	v_mov_b32_e32 v125, v144
	v_pk_mul_f32 v[148:149], v[108:109], s[2:3] op_sel_hi:[1,0]
	v_pk_fma_f32 v[108:109], v[108:109], s[2:3], v[146:147] op_sel_hi:[1,0,1]
	v_pk_fma_f32 v[124:125], v[124:125], s[2:3], v[92:93] op_sel_hi:[1,0,1]
	v_pk_mul_f32 v[142:143], v[108:109], v[108:109]
	v_pk_mul_f32 v[92:93], v[124:125], v[124:125]
	v_pk_mov_b32 v[142:143], v[146:147], v[142:143] op_sel:[1,0]
	v_pk_mov_b32 v[92:93], v[148:149], v[92:93] op_sel:[1,0]
	v_add_f32_e32 v76, 0, v77
	v_pk_add_f32 v[92:93], v[142:143], v[92:93]
	v_pk_add_f32 v[142:143], v[108:109], v[124:125]
	v_pk_mul_f32 v[146:147], v[108:109], v[124:125]
	v_fmac_f32_e32 v76, 0x3fd744fd, v145
	v_mov_b32_e32 v143, v147
	v_pk_add_f32 v[92:93], v[142:143], v[92:93]
	v_mul_f32_e32 v77, v76, v76
	v_pk_add_f32 v[92:93], v[92:93], v[76:77]
	s_nop 1
	v_mov_b32_dpp v142, v92 quad_perm:[1,0,3,2] row_mask:0xf bank_mask:0xf bound_ctrl:1
	v_mov_b32_dpp v143, v93 quad_perm:[1,0,3,2] row_mask:0xf bank_mask:0xf bound_ctrl:1
	v_pk_add_f32 v[92:93], v[92:93], v[142:143]
	s_nop 1
	v_mov_b32_dpp v142, v92 quad_perm:[2,3,0,1] row_mask:0xf bank_mask:0xf bound_ctrl:1
	v_mov_b32_dpp v143, v93 quad_perm:[2,3,0,1] row_mask:0xf bank_mask:0xf bound_ctrl:1
	v_pk_add_f32 v[92:93], v[92:93], v[142:143]
	s_nop 1
	v_mov_b32_dpp v142, v92 row_half_mirror row_mask:0xf bank_mask:0xf bound_ctrl:1
	v_mov_b32_dpp v143, v93 row_half_mirror row_mask:0xf bank_mask:0xf bound_ctrl:1
	v_pk_add_f32 v[92:93], v[92:93], v[142:143]
	s_nop 1
	v_mov_b32_dpp v142, v92 row_mirror row_mask:0xf bank_mask:0xf bound_ctrl:1
	v_mov_b32_dpp v143, v93 row_mirror row_mask:0xf bank_mask:0xf bound_ctrl:1
	s_and_saveexec_b64 s[6:7], vcc
	v_pk_add_f32 v[92:93], v[92:93], v[142:143]
	ds_write_b64 v179, v[92:93] offset:152
	s_or_b64 exec, exec, s[6:7]
	v_or_b32_e32 v77, 0x1000, v154
	v_add_u32_e32 v77, v105, v77
	ds_read2_b32 v[142:143], v77 offset1:32
	ds_read2_b32 v[146:147], v77 offset0:64 offset1:96
	v_mov_b32_e32 v144, v126
	v_mov_b32_e32 v145, v94
	v_pk_add_f32 v[148:149], v[144:145], 0 op_sel_hi:[1,0]
	v_mov_b32_e32 v144, v110
	v_pk_add_f32 v[144:145], v[144:145], 0 op_sel_hi:[1,0]
	s_waitcnt lgkmcnt(1)
	v_mov_b32_e32 v156, v142
	s_waitcnt lgkmcnt(0)
	v_mov_b32_e32 v157, v146
	s_mov_b32 s2, s67
	v_mov_b32_e32 v170, v143
	v_mov_b32_e32 v171, v146
	v_pk_fma_f32 v[142:143], v[156:157], s[2:3], v[148:149] op_sel_hi:[1,0,1]
	v_pk_fma_f32 v[144:145], v[170:171], s[2:3], v[144:145] op_sel_hi:[1,0,1]
	v_pk_mul_f32 v[160:161], v[156:157], s[2:3] op_sel_hi:[1,0]
	v_pk_mul_f32 v[156:157], v[142:143], v[142:143]
	v_pk_mul_f32 v[170:171], v[144:145], v[144:145]
	v_pk_mov_b32 v[148:149], v[148:149], v[156:157] op_sel:[1,0]
	v_pk_mov_b32 v[156:157], v[160:161], v[170:171] op_sel:[1,0]
	v_add_f32_e32 v92, 0, v78
	v_pk_add_f32 v[148:149], v[148:149], v[156:157]
	v_pk_add_f32 v[156:157], v[142:143], v[144:145]
	v_pk_mul_f32 v[160:161], v[142:143], v[144:145]
	v_fmac_f32_e32 v92, 0x3fd744fd, v147
	v_mov_b32_e32 v157, v161
	v_pk_add_f32 v[148:149], v[156:157], v[148:149]
	v_mul_f32_e32 v93, v92, v92
	v_pk_add_f32 v[146:147], v[148:149], v[92:93]
	s_nop 1
	v_mov_b32_dpp v148, v146 quad_perm:[1,0,3,2] row_mask:0xf bank_mask:0xf bound_ctrl:1
	v_mov_b32_dpp v149, v147 quad_perm:[1,0,3,2] row_mask:0xf bank_mask:0xf bound_ctrl:1
	v_pk_add_f32 v[146:147], v[146:147], v[148:149]
	s_nop 1
	v_mov_b32_dpp v148, v146 quad_perm:[2,3,0,1] row_mask:0xf bank_mask:0xf bound_ctrl:1
	v_mov_b32_dpp v149, v147 quad_perm:[2,3,0,1] row_mask:0xf bank_mask:0xf bound_ctrl:1
	v_pk_add_f32 v[146:147], v[146:147], v[148:149]
	s_nop 1
	v_mov_b32_dpp v148, v146 row_half_mirror row_mask:0xf bank_mask:0xf bound_ctrl:1
	v_mov_b32_dpp v149, v147 row_half_mirror row_mask:0xf bank_mask:0xf bound_ctrl:1
	v_pk_add_f32 v[146:147], v[146:147], v[148:149]
	s_nop 1
	v_mov_b32_dpp v148, v146 row_mirror row_mask:0xf bank_mask:0xf bound_ctrl:1
	v_mov_b32_dpp v149, v147 row_mirror row_mask:0xf bank_mask:0xf bound_ctrl:1
	s_and_saveexec_b64 s[6:7], vcc
	v_pk_add_f32 v[146:147], v[146:147], v[148:149]
	ds_write_b64 v179, v[146:147] offset:192
	s_or_b64 exec, exec, s[6:7]
	v_or_b32_e32 v78, 0x1200, v154
	v_add_u32_e32 v91, v105, v78
	ds_read2_b32 v[146:147], v91 offset1:32
	ds_read2_b32 v[148:149], v91 offset0:64 offset1:96
	v_mov_b32_e32 v94, v127
	v_pk_add_f32 v[156:157], v[94:95], 0 op_sel_hi:[1,0]
	v_mov_b32_e32 v94, v111
	v_pk_add_f32 v[94:95], v[94:95], 0 op_sel_hi:[1,0]
	s_waitcnt lgkmcnt(1)
;   DI void operator()(f32x16 (&acc)[2][4], int grow0, int gcol0, int lane, int w, char* lds) {
;     ...
;       if (ps + 1 < 4) {
;         if (ps >= 1) asm volatile("s_waitcnt lgkmcnt(0)" ::: "memory");
;         xpass(ps + 1, grow0, gcol0, lane, w, lds);
;         if (ps >= 1) asm volatile("s_waitcnt vmcnt(8)" ::: "memory");
;       } else asm volatile("s_waitcnt vmcnt(0)" ::: "memory");
;       const char* xs = lds + (ps & 1) * 65536 + w * 8192;
; #pragma unroll
;       for (int qq = 0; qq < 2; ++qq)
; #pragma unroll
;         for (int e = 0; e < 4; ++e) {
;           const int i = 4 * (2 * (ps & 1) + qq) + e;
;           const float* xr = (const float*)(xs + (8 * qq + 4 * hh + e) * 512) + l31;
;           float s1 = 0.f, s2 = 0.f;
; #pragma unroll
;           for (int nt = 0; nt < 4; ++nt) {
;             float v = (acc[mt][nt][i] + bia[nt]) * csc[nt];
;             float z = ALPHA * xr[nt * 32] + hs * v;
;             acc[mt][nt][i] = z; s1 += z; s2 += z * z;
;           }
;           s1 = row16_sum(s1); s2 = row16_sum(s2);
;           if ((lane & 15) == 0) { f32x2 sv = {s1, s2}; *(f32x2*)(redw + (mt * 32 + (i & 3) + 8 * (i >> 2)) * 2) = sv; }
	v_mov_b32_e32 v110, v146
	s_waitcnt lgkmcnt(0)
	v_mov_b32_e32 v111, v148
	s_mov_b32 s2, s67
	v_mov_b32_e32 v126, v147
	v_mov_b32_e32 v127, v148
	v_pk_mul_f32 v[160:161], v[110:111], s[2:3] op_sel_hi:[1,0]
	v_pk_fma_f32 v[110:111], v[110:111], s[2:3], v[156:157] op_sel_hi:[1,0,1]
	v_pk_fma_f32 v[126:127], v[126:127], s[2:3], v[94:95] op_sel_hi:[1,0,1]
	v_pk_mul_f32 v[146:147], v[110:111], v[110:111]
	v_pk_mul_f32 v[94:95], v[126:127], v[126:127]
	v_pk_mov_b32 v[146:147], v[156:157], v[146:147] op_sel:[1,0]
	v_pk_mov_b32 v[94:95], v[160:161], v[94:95] op_sel:[1,0]
	v_add_f32_e32 v78, 0, v79
	v_pk_add_f32 v[94:95], v[146:147], v[94:95]
	v_pk_add_f32 v[146:147], v[110:111], v[126:127]
	v_pk_mul_f32 v[156:157], v[110:111], v[126:127]
	v_fmac_f32_e32 v78, 0x3fd744fd, v149
	v_mov_b32_e32 v147, v157
	v_pk_add_f32 v[94:95], v[146:147], v[94:95]
	v_mul_f32_e32 v79, v78, v78
	v_pk_add_f32 v[94:95], v[94:95], v[78:79]
	s_nop 1
	v_mov_b32_dpp v146, v94 quad_perm:[1,0,3,2] row_mask:0xf bank_mask:0xf bound_ctrl:1
	v_mov_b32_dpp v147, v95 quad_perm:[1,0,3,2] row_mask:0xf bank_mask:0xf bound_ctrl:1
	v_pk_add_f32 v[94:95], v[94:95], v[146:147]
	s_nop 1
	v_mov_b32_dpp v146, v94 quad_perm:[2,3,0,1] row_mask:0xf bank_mask:0xf bound_ctrl:1
	v_mov_b32_dpp v147, v95 quad_perm:[2,3,0,1] row_mask:0xf bank_mask:0xf bound_ctrl:1
	v_pk_add_f32 v[94:95], v[94:95], v[146:147]
	s_nop 1
	v_mov_b32_dpp v146, v94 row_half_mirror row_mask:0xf bank_mask:0xf bound_ctrl:1
	v_mov_b32_dpp v147, v95 row_half_mirror row_mask:0xf bank_mask:0xf bound_ctrl:1
	v_pk_add_f32 v[94:95], v[94:95], v[146:147]
	s_nop 1
	v_mov_b32_dpp v146, v94 row_mirror row_mask:0xf bank_mask:0xf bound_ctrl:1
	v_mov_b32_dpp v147, v95 row_mirror row_mask:0xf bank_mask:0xf bound_ctrl:1
	s_and_saveexec_b64 s[6:7], vcc
	v_pk_add_f32 v[94:95], v[94:95], v[146:147]
	ds_write_b64 v179, v[94:95] offset:200
	s_or_b64 exec, exec, s[6:7]
	v_or_b32_e32 v79, 0x1400, v154
	v_add_u32_e32 v79, v105, v79
	ds_read2_b32 v[146:147], v79 offset1:32
	ds_read2_b32 v[154:155], v79 offset0:64 offset1:96
	v_mov_b32_e32 v148, v128
	v_mov_b32_e32 v149, v96
	v_pk_add_f32 v[156:157], v[148:149], 0 op_sel_hi:[1,0]
	v_mov_b32_e32 v148, v112
	v_pk_add_f32 v[148:149], v[148:149], 0 op_sel_hi:[1,0]
	s_waitcnt lgkmcnt(1)
	v_mov_b32_e32 v160, v146
	s_waitcnt lgkmcnt(0)
	v_mov_b32_e32 v161, v154
	s_mov_b32 s2, s67
	v_mov_b32_e32 v174, v147
	v_mov_b32_e32 v175, v154
	v_pk_fma_f32 v[146:147], v[160:161], s[2:3], v[156:157] op_sel_hi:[1,0,1]
	v_pk_fma_f32 v[148:149], v[174:175], s[2:3], v[148:149] op_sel_hi:[1,0,1]
	v_pk_mul_f32 v[170:171], v[160:161], s[2:3] op_sel_hi:[1,0]
	v_pk_mul_f32 v[160:161], v[146:147], v[146:147]
	v_pk_mul_f32 v[174:175], v[148:149], v[148:149]
	v_pk_mov_b32 v[156:157], v[156:157], v[160:161] op_sel:[1,0]
	v_pk_mov_b32 v[160:161], v[170:171], v[174:175] op_sel:[1,0]
	v_add_f32_e32 v94, 0, v80
	v_pk_add_f32 v[156:157], v[156:157], v[160:161]
	v_pk_add_f32 v[160:161], v[146:147], v[148:149]
	v_pk_mul_f32 v[170:171], v[146:147], v[148:149]
	v_fmac_f32_e32 v94, 0x3fd744fd, v155
	v_mov_b32_e32 v161, v171
	v_pk_add_f32 v[156:157], v[160:161], v[156:157]
	v_mul_f32_e32 v95, v94, v94
	v_pk_add_f32 v[154:155], v[156:157], v[94:95]
	s_nop 1
	v_mov_b32_dpp v156, v154 quad_perm:[1,0,3,2] row_mask:0xf bank_mask:0xf bound_ctrl:1
	v_mov_b32_dpp v157, v155 quad_perm:[1,0,3,2] row_mask:0xf bank_mask:0xf bound_ctrl:1
	v_pk_add_f32 v[154:155], v[154:155], v[156:157]
	s_nop 1
	v_mov_b32_dpp v156, v154 quad_perm:[2,3,0,1] row_mask:0xf bank_mask:0xf bound_ctrl:1
	v_mov_b32_dpp v157, v155 quad_perm:[2,3,0,1] row_mask:0xf bank_mask:0xf bound_ctrl:1
	v_pk_add_f32 v[154:155], v[154:155], v[156:157]
	s_nop 1
	v_mov_b32_dpp v156, v154 row_half_mirror row_mask:0xf bank_mask:0xf bound_ctrl:1
	v_mov_b32_dpp v157, v155 row_half_mirror row_mask:0xf bank_mask:0xf bound_ctrl:1
	v_pk_add_f32 v[154:155], v[154:155], v[156:157]
	s_nop 1
	v_mov_b32_dpp v156, v154 row_mirror row_mask:0xf bank_mask:0xf bound_ctrl:1
	v_mov_b32_dpp v157, v155 row_mirror row_mask:0xf bank_mask:0xf bound_ctrl:1
	s_and_saveexec_b64 s[6:7], vcc
	v_pk_add_f32 v[154:155], v[154:155], v[156:157]
	ds_write_b64 v179, v[154:155] offset:208
	s_or_b64 exec, exec, s[6:7]
	v_add_u32_e32 v93, v105, v101
	ds_read2_b32 v[154:155], v93 offset1:32
	ds_read2_b32 v[156:157], v93 offset0:64 offset1:96
	v_mov_b32_e32 v96, v129
	v_pk_add_f32 v[128:129], v[96:97], 0 op_sel_hi:[1,0]
	v_mov_b32_e32 v96, v113
	v_pk_add_f32 v[112:113], v[96:97], 0 op_sel_hi:[1,0]
	s_waitcnt lgkmcnt(1)
	v_mov_b32_e32 v96, v154
	s_waitcnt lgkmcnt(0)
	v_mov_b32_e32 v97, v156
	s_mov_b32 s2, s67
	v_mov_b32_e32 v154, v155
	v_mov_b32_e32 v155, v156
	v_pk_mul_f32 v[160:161], v[96:97], s[2:3] op_sel_hi:[1,0]
	v_pk_fma_f32 v[96:97], v[96:97], s[2:3], v[128:129] op_sel_hi:[1,0,1]
	v_pk_fma_f32 v[112:113], v[154:155], s[2:3], v[112:113] op_sel_hi:[1,0,1]
	v_pk_mul_f32 v[170:171], v[96:97], v[96:97]
	v_pk_mul_f32 v[154:155], v[112:113], v[112:113]
	v_pk_mov_b32 v[128:129], v[128:129], v[170:171] op_sel:[1,0]
	v_pk_mov_b32 v[154:155], v[160:161], v[154:155] op_sel:[1,0]
	v_add_f32_e32 v80, 0, v81
	v_pk_add_f32 v[128:129], v[128:129], v[154:155]
	v_pk_add_f32 v[154:155], v[96:97], v[112:113]
	v_pk_mul_f32 v[160:161], v[96:97], v[112:113]
	v_fmac_f32_e32 v80, 0x3fd744fd, v157
	v_mov_b32_e32 v155, v161
	v_pk_add_f32 v[128:129], v[154:155], v[128:129]
	v_mul_f32_e32 v81, v80, v80
	v_pk_add_f32 v[128:129], v[128:129], v[80:81]
	s_nop 1
	v_mov_b32_dpp v154, v128 quad_perm:[1,0,3,2] row_mask:0xf bank_mask:0xf bound_ctrl:1
	v_mov_b32_dpp v155, v129 quad_perm:[1,0,3,2] row_mask:0xf bank_mask:0xf bound_ctrl:1
	v_pk_add_f32 v[128:129], v[128:129], v[154:155]
	s_nop 1
	v_mov_b32_dpp v154, v128 quad_perm:[2,3,0,1] row_mask:0xf bank_mask:0xf bound_ctrl:1
	v_mov_b32_dpp v155, v129 quad_perm:[2,3,0,1] row_mask:0xf bank_mask:0xf bound_ctrl:1
	v_pk_add_f32 v[128:129], v[128:129], v[154:155]
	s_nop 1
	v_mov_b32_dpp v154, v128 row_half_mirror row_mask:0xf bank_mask:0xf bound_ctrl:1
	v_mov_b32_dpp v155, v129 row_half_mirror row_mask:0xf bank_mask:0xf bound_ctrl:1
	v_pk_add_f32 v[128:129], v[128:129], v[154:155]
	s_nop 1
	v_mov_b32_dpp v154, v128 row_mirror row_mask:0xf bank_mask:0xf bound_ctrl:1
	v_mov_b32_dpp v155, v129 row_mirror row_mask:0xf bank_mask:0xf bound_ctrl:1
	s_and_saveexec_b64 s[6:7], vcc
	v_pk_add_f32 v[128:129], v[128:129], v[154:155]
	ds_write_b64 v179, v[128:129] offset:216
	s_or_b64 exec, exec, s[6:7]
	v_or_b32_e32 v128, 48, v159
	v_ashrrev_i32_e32 v129, 31, v128
	v_lshlrev_b64 v[128:129], 12, v[128:129]
	v_readfirstlane_b32 s2, v158
	v_lshl_add_u64 v[128:129], s[10:11], 0, v[128:129]
	s_lshl_b32 s2, s2, 13
	v_lshl_add_u64 v[128:129], v[182:183], 2, v[128:129]
	s_waitcnt lgkmcnt(0)
;   DI void operator()(f32x16 (&acc)[2][4], int grow0, int gcol0, int lane, int w, char* lds) {
;     ...
;       if (ps + 1 < 4) {
;         if (ps >= 1) asm volatile("s_waitcnt lgkmcnt(0)" ::: "memory");
;         xpass(ps + 1, grow0, gcol0, lane, w, lds);
;         if (ps >= 1) asm volatile("s_waitcnt vmcnt(8)" ::: "memory");
;       } else asm volatile("s_waitcnt vmcnt(0)" ::: "memory");
;       const char* xs = lds + (ps & 1) * 65536 + w * 8192;
; #pragma unroll
;       for (int qq = 0; qq < 2; ++qq)
; #pragma unroll
;         for (int e = 0; e < 4; ++e) {
;           const int i = 4 * (2 * (ps & 1) + qq) + e;
;           const float* xr = (const float*)(xs + (8 * qq + 4 * hh + e) * 512) + l31;
;           float s1 = 0.f, s2 = 0.f;
; #pragma unroll
;           for (int nt = 0; nt < 4; ++nt) {
;             float v = (acc[mt][nt][i] + bia[nt]) * csc[nt];
;             float z = ALPHA * xr[nt * 32] + hs * v;
;             acc[mt][nt][i] = z; s1 += z; s2 += z * z;
;           }
;           s1 = row16_sum(s1); s2 = row16_sum(s2);
;           if ((lane & 15) == 0) { f32x2 sv = {s1, s2}; *(f32x2*)(redw + (mt * 32 + (i & 3) + 8 * (i >> 2)) * 2) = sv; }
	s_add_i32 m0, s2, 0x10000
	v_lshl_add_u64 v[128:129], v[128:129], 0, v[0:1]
	s_mov_b64 s[6:7], 0x2000
	global_load_lds_dwordx4 v[128:129], off
	v_lshl_add_u64 v[154:155], v[128:129], 0, s[6:7]
	s_add_i32 m0, s2, 0x10400
	s_mov_b64 s[6:7], 0x4000
	global_load_lds_dwordx4 v[154:155], off
	v_lshl_add_u64 v[154:155], v[128:129], 0, s[6:7]
	s_add_i32 m0, s2, 0x10800
	s_mov_b64 s[6:7], 0x6000
	global_load_lds_dwordx4 v[154:155], off
	v_lshl_add_u64 v[154:155], v[128:129], 0, s[6:7]
	s_add_i32 m0, s2, 0x10c00
	s_mov_b64 s[6:7], 0x8000
	global_load_lds_dwordx4 v[154:155], off
	v_lshl_add_u64 v[154:155], v[128:129], 0, s[6:7]
	s_add_i32 m0, s2, 0x11000
	s_mov_b64 s[6:7], 0xa000
	global_load_lds_dwordx4 v[154:155], off
	v_lshl_add_u64 v[154:155], v[128:129], 0, s[6:7]
	s_add_i32 m0, s2, 0x11400
	s_mov_b64 s[6:7], 0xc000
	global_load_lds_dwordx4 v[154:155], off
	v_lshl_add_u64 v[154:155], v[128:129], 0, s[6:7]
	s_add_i32 m0, s2, 0x11800
	s_mov_b64 s[6:7], 0xe000
	global_load_lds_dwordx4 v[154:155], off
	v_lshl_add_u64 v[128:129], v[128:129], 0, s[6:7]
	s_add_i32 m0, s2, 0x11c00
	v_mov_b32_e32 v156, v50
	global_load_lds_dwordx4 v[128:129], off
	s_waitcnt vmcnt(8)
	ds_read2_b32 v[154:155], v168 offset1:32
	ds_read2_b32 v[158:159], v168 offset0:64 offset1:96
	v_mov_b32_e32 v157, v18
	v_pk_add_f32 v[160:161], v[156:157], 0 op_sel_hi:[1,0]
	v_mov_b32_e32 v156, v34
	v_pk_add_f32 v[156:157], v[156:157], 0 op_sel_hi:[1,0]
	s_waitcnt lgkmcnt(0)
	v_mov_b32_e32 v170, v154
	v_mov_b32_e32 v171, v158
	s_mov_b32 s2, s67
	v_mov_b32_e32 v176, v155
	v_mov_b32_e32 v177, v158
	v_pk_fma_f32 v[154:155], v[170:171], s[2:3], v[160:161] op_sel_hi:[1,0,1]
	v_pk_fma_f32 v[156:157], v[176:177], s[2:3], v[156:157] op_sel_hi:[1,0,1]
	v_pk_mul_f32 v[174:175], v[170:171], s[2:3] op_sel_hi:[1,0]
	v_pk_mul_f32 v[170:171], v[154:155], v[154:155]
	v_pk_mul_f32 v[176:177], v[156:157], v[156:157]
	v_pk_mov_b32 v[160:161], v[160:161], v[170:171] op_sel:[1,0]
	v_pk_mov_b32 v[170:171], v[174:175], v[176:177] op_sel:[1,0]
	v_add_f32_e32 v128, 0, v2
	v_pk_add_f32 v[160:161], v[160:161], v[170:171]
	v_pk_add_f32 v[170:171], v[154:155], v[156:157]
	v_pk_mul_f32 v[174:175], v[154:155], v[156:157]
	v_fmac_f32_e32 v128, 0x3fd744fd, v159
	v_mov_b32_e32 v171, v175
	v_pk_add_f32 v[160:161], v[170:171], v[160:161]
	v_mul_f32_e32 v129, v128, v128
	v_pk_add_f32 v[158:159], v[160:161], v[128:129]
	s_nop 1
	v_mov_b32_dpp v160, v158 quad_perm:[1,0,3,2] row_mask:0xf bank_mask:0xf bound_ctrl:1
	v_mov_b32_dpp v161, v159 quad_perm:[1,0,3,2] row_mask:0xf bank_mask:0xf bound_ctrl:1
	v_pk_add_f32 v[158:159], v[158:159], v[160:161]
	s_nop 1
	v_mov_b32_dpp v160, v158 quad_perm:[2,3,0,1] row_mask:0xf bank_mask:0xf bound_ctrl:1
	v_mov_b32_dpp v161, v159 quad_perm:[2,3,0,1] row_mask:0xf bank_mask:0xf bound_ctrl:1
	v_pk_add_f32 v[158:159], v[158:159], v[160:161]
	s_nop 1
	v_mov_b32_dpp v160, v158 row_half_mirror row_mask:0xf bank_mask:0xf bound_ctrl:1
	v_mov_b32_dpp v161, v159 row_half_mirror row_mask:0xf bank_mask:0xf bound_ctrl:1
	v_pk_add_f32 v[158:159], v[158:159], v[160:161]
	s_nop 1
	v_mov_b32_dpp v160, v158 row_mirror row_mask:0xf bank_mask:0xf bound_ctrl:1
	v_mov_b32_dpp v161, v159 row_mirror row_mask:0xf bank_mask:0xf bound_ctrl:1
	s_and_saveexec_b64 s[6:7], vcc
	v_pk_add_f32 v[158:159], v[158:159], v[160:161]
	ds_write_b64 v179, v[158:159] offset:256
	s_or_b64 exec, exec, s[6:7]
	ds_read2_b32 v[158:159], v168 offset0:128 offset1:160
	ds_read2_b32 v[160:161], v168 offset0:192 offset1:224
	v_mov_b32_e32 v18, v51
	v_pk_add_f32 v[168:169], v[18:19], 0 op_sel_hi:[1,0]
	v_mov_b32_e32 v18, v35
	v_pk_add_f32 v[18:19], v[18:19], 0 op_sel_hi:[1,0]
	s_waitcnt lgkmcnt(1)
	v_mov_b32_e32 v34, v158
	s_waitcnt lgkmcnt(0)
	v_mov_b32_e32 v35, v160
	s_mov_b32 s2, s67
	v_mov_b32_e32 v50, v159
	v_mov_b32_e32 v51, v160
	v_pk_mul_f32 v[170:171], v[34:35], s[2:3] op_sel_hi:[1,0]
	v_pk_fma_f32 v[34:35], v[34:35], s[2:3], v[168:169] op_sel_hi:[1,0,1]
	v_pk_fma_f32 v[50:51], v[50:51], s[2:3], v[18:19] op_sel_hi:[1,0,1]
	v_pk_mul_f32 v[158:159], v[34:35], v[34:35]
	v_pk_mul_f32 v[18:19], v[50:51], v[50:51]
	v_pk_mov_b32 v[158:159], v[168:169], v[158:159] op_sel:[1,0]
	v_pk_mov_b32 v[18:19], v[170:171], v[18:19] op_sel:[1,0]
	v_add_f32_e32 v2, 0, v3
	v_pk_add_f32 v[18:19], v[158:159], v[18:19]
	v_pk_add_f32 v[158:159], v[34:35], v[50:51]
	v_pk_mul_f32 v[168:169], v[34:35], v[50:51]
	v_fmac_f32_e32 v2, 0x3fd744fd, v161
	v_mov_b32_e32 v159, v169
	v_pk_add_f32 v[18:19], v[158:159], v[18:19]
	v_mul_f32_e32 v3, v2, v2
	v_pk_add_f32 v[18:19], v[18:19], v[2:3]
	s_nop 1
	v_mov_b32_dpp v158, v18 quad_perm:[1,0,3,2] row_mask:0xf bank_mask:0xf bound_ctrl:1
	v_mov_b32_dpp v159, v19 quad_perm:[1,0,3,2] row_mask:0xf bank_mask:0xf bound_ctrl:1
	v_pk_add_f32 v[18:19], v[18:19], v[158:159]
	s_nop 1
	v_mov_b32_dpp v158, v18 quad_perm:[2,3,0,1] row_mask:0xf bank_mask:0xf bound_ctrl:1
	v_mov_b32_dpp v159, v19 quad_perm:[2,3,0,1] row_mask:0xf bank_mask:0xf bound_ctrl:1
	v_pk_add_f32 v[18:19], v[18:19], v[158:159]
	s_nop 1
	v_mov_b32_dpp v158, v18 row_half_mirror row_mask:0xf bank_mask:0xf bound_ctrl:1
	v_mov_b32_dpp v159, v19 row_half_mirror row_mask:0xf bank_mask:0xf bound_ctrl:1
	v_pk_add_f32 v[18:19], v[18:19], v[158:159]
	s_nop 1
	v_mov_b32_dpp v158, v18 row_mirror row_mask:0xf bank_mask:0xf bound_ctrl:1
	v_mov_b32_dpp v159, v19 row_mirror row_mask:0xf bank_mask:0xf bound_ctrl:1
	s_and_saveexec_b64 s[6:7], vcc
	v_pk_add_f32 v[18:19], v[18:19], v[158:159]
	ds_write_b64 v179, v[18:19] offset:264
	s_or_b64 exec, exec, s[6:7]
	ds_read2_b32 v[158:159], v153 offset1:32
	ds_read2_b32 v[168:169], v153 offset0:64 offset1:96
	v_mov_b32_e32 v160, v52
	v_mov_b32_e32 v161, v20
	v_pk_add_f32 v[170:171], v[160:161], 0 op_sel_hi:[1,0]
	v_mov_b32_e32 v160, v36
	v_pk_add_f32 v[160:161], v[160:161], 0 op_sel_hi:[1,0]
	s_waitcnt lgkmcnt(1)
;   DI void operator()(f32x16 (&acc)[2][4], int grow0, int gcol0, int lane, int w, char* lds) {
;     ...
;         for (int e = 0; e < 4; ++e) {
;           const int i = 4 * (2 * (ps & 1) + qq) + e;
;           const float* xr = (const float*)(xs + (8 * qq + 4 * hh + e) * 512) + l31;
;           float s1 = 0.f, s2 = 0.f;
; #pragma unroll
;           for (int nt = 0; nt < 4; ++nt) {
;             float v = (acc[mt][nt][i] + bia[nt]) * csc[nt];
;             float z = ALPHA * xr[nt * 32] + hs * v;
;             acc[mt][nt][i] = z; s1 += z; s2 += z * z;
;           }
;           s1 = row16_sum(s1); s2 = row16_sum(s2);
;           if ((lane & 15) == 0) { f32x2 sv = {s1, s2}; *(f32x2*)(redw + (mt * 32 + (i & 3) + 8 * (i >> 2)) * 2) = sv; }
	v_mov_b32_e32 v174, v158
	s_waitcnt lgkmcnt(0)
	v_mov_b32_e32 v175, v168
	s_mov_b32 s2, s67
	v_mov_b32_e32 v180, v159
	v_mov_b32_e32 v181, v168
	v_pk_fma_f32 v[158:159], v[174:175], s[2:3], v[170:171] op_sel_hi:[1,0,1]
	v_pk_fma_f32 v[160:161], v[180:181], s[2:3], v[160:161] op_sel_hi:[1,0,1]
	v_pk_mul_f32 v[176:177], v[174:175], s[2:3] op_sel_hi:[1,0]
	v_pk_mul_f32 v[174:175], v[158:159], v[158:159]
	v_pk_mul_f32 v[180:181], v[160:161], v[160:161]
	v_pk_mov_b32 v[170:171], v[170:171], v[174:175] op_sel:[1,0]
	v_pk_mov_b32 v[174:175], v[176:177], v[180:181] op_sel:[1,0]
	v_add_f32_e32 v18, 0, v4
	v_pk_add_f32 v[170:171], v[170:171], v[174:175]
	v_pk_add_f32 v[174:175], v[158:159], v[160:161]
	v_pk_mul_f32 v[176:177], v[158:159], v[160:161]
	v_fmac_f32_e32 v18, 0x3fd744fd, v169
	v_mov_b32_e32 v175, v177
	v_pk_add_f32 v[170:171], v[174:175], v[170:171]
	v_mul_f32_e32 v19, v18, v18
	v_pk_add_f32 v[168:169], v[170:171], v[18:19]
	s_nop 1
	v_mov_b32_dpp v170, v168 quad_perm:[1,0,3,2] row_mask:0xf bank_mask:0xf bound_ctrl:1
	v_mov_b32_dpp v171, v169 quad_perm:[1,0,3,2] row_mask:0xf bank_mask:0xf bound_ctrl:1
	v_pk_add_f32 v[168:169], v[168:169], v[170:171]
	s_nop 1
	v_mov_b32_dpp v170, v168 quad_perm:[2,3,0,1] row_mask:0xf bank_mask:0xf bound_ctrl:1
	v_mov_b32_dpp v171, v169 quad_perm:[2,3,0,1] row_mask:0xf bank_mask:0xf bound_ctrl:1
	v_pk_add_f32 v[168:169], v[168:169], v[170:171]
	s_nop 1
	v_mov_b32_dpp v170, v168 row_half_mirror row_mask:0xf bank_mask:0xf bound_ctrl:1
	v_mov_b32_dpp v171, v169 row_half_mirror row_mask:0xf bank_mask:0xf bound_ctrl:1
	v_pk_add_f32 v[168:169], v[168:169], v[170:171]
	s_nop 1
	v_mov_b32_dpp v170, v168 row_mirror row_mask:0xf bank_mask:0xf bound_ctrl:1
	v_mov_b32_dpp v171, v169 row_mirror row_mask:0xf bank_mask:0xf bound_ctrl:1
	s_and_saveexec_b64 s[6:7], vcc
	v_pk_add_f32 v[168:169], v[168:169], v[170:171]
	ds_write_b64 v179, v[168:169] offset:272
	s_or_b64 exec, exec, s[6:7]
	ds_read2_b32 v[168:169], v151 offset1:32
	ds_read2_b32 v[170:171], v151 offset0:64 offset1:96
	v_mov_b32_e32 v20, v53
	v_pk_add_f32 v[174:175], v[20:21], 0 op_sel_hi:[1,0]
	v_mov_b32_e32 v20, v37
	v_pk_add_f32 v[20:21], v[20:21], 0 op_sel_hi:[1,0]
	s_waitcnt lgkmcnt(1)
	v_mov_b32_e32 v36, v168
	s_waitcnt lgkmcnt(0)
	v_mov_b32_e32 v37, v170
	s_mov_b32 s2, s67
	v_mov_b32_e32 v52, v169
	v_mov_b32_e32 v53, v170
	v_pk_mul_f32 v[176:177], v[36:37], s[2:3] op_sel_hi:[1,0]
	v_pk_fma_f32 v[36:37], v[36:37], s[2:3], v[174:175] op_sel_hi:[1,0,1]
	v_pk_fma_f32 v[52:53], v[52:53], s[2:3], v[20:21] op_sel_hi:[1,0,1]
	v_pk_mul_f32 v[168:169], v[36:37], v[36:37]
	v_pk_mul_f32 v[20:21], v[52:53], v[52:53]
	v_pk_mov_b32 v[168:169], v[174:175], v[168:169] op_sel:[1,0]
	v_pk_mov_b32 v[20:21], v[176:177], v[20:21] op_sel:[1,0]
	v_add_f32_e32 v4, 0, v5
	v_pk_add_f32 v[20:21], v[168:169], v[20:21]
	v_pk_add_f32 v[168:169], v[36:37], v[52:53]
	v_pk_mul_f32 v[174:175], v[36:37], v[52:53]
	v_fmac_f32_e32 v4, 0x3fd744fd, v171
	v_mov_b32_e32 v169, v175
	v_pk_add_f32 v[20:21], v[168:169], v[20:21]
	v_mul_f32_e32 v5, v4, v4
	v_pk_add_f32 v[20:21], v[20:21], v[4:5]
	s_nop 1
	v_mov_b32_dpp v168, v20 quad_perm:[1,0,3,2] row_mask:0xf bank_mask:0xf bound_ctrl:1
	v_mov_b32_dpp v169, v21 quad_perm:[1,0,3,2] row_mask:0xf bank_mask:0xf bound_ctrl:1
	v_pk_add_f32 v[20:21], v[20:21], v[168:169]
	s_nop 1
	v_mov_b32_dpp v168, v20 quad_perm:[2,3,0,1] row_mask:0xf bank_mask:0xf bound_ctrl:1
	v_mov_b32_dpp v169, v21 quad_perm:[2,3,0,1] row_mask:0xf bank_mask:0xf bound_ctrl:1
	v_pk_add_f32 v[20:21], v[20:21], v[168:169]
	s_nop 1
	v_mov_b32_dpp v168, v20 row_half_mirror row_mask:0xf bank_mask:0xf bound_ctrl:1
	v_mov_b32_dpp v169, v21 row_half_mirror row_mask:0xf bank_mask:0xf bound_ctrl:1
	v_pk_add_f32 v[20:21], v[20:21], v[168:169]
	s_nop 1
	v_mov_b32_dpp v168, v20 row_mirror row_mask:0xf bank_mask:0xf bound_ctrl:1
	v_mov_b32_dpp v169, v21 row_mirror row_mask:0xf bank_mask:0xf bound_ctrl:1
	s_and_saveexec_b64 s[6:7], vcc
	v_pk_add_f32 v[20:21], v[20:21], v[168:169]
	ds_write_b64 v179, v[20:21] offset:280
	s_or_b64 exec, exec, s[6:7]
	ds_read2_b32 v[168:169], v67 offset1:32
	ds_read2_b32 v[174:175], v67 offset0:64 offset1:96
	v_mov_b32_e32 v170, v54
	v_mov_b32_e32 v171, v22
	v_pk_add_f32 v[176:177], v[170:171], 0 op_sel_hi:[1,0]
	v_mov_b32_e32 v170, v38
	v_pk_add_f32 v[170:171], v[170:171], 0 op_sel_hi:[1,0]
	s_waitcnt lgkmcnt(1)
	v_mov_b32_e32 v180, v168
	s_waitcnt lgkmcnt(0)
	v_mov_b32_e32 v181, v174
	s_mov_b32 s2, s67
	v_mov_b32_e32 v190, v169
	v_mov_b32_e32 v191, v174
	v_pk_fma_f32 v[168:169], v[180:181], s[2:3], v[176:177] op_sel_hi:[1,0,1]
	v_pk_fma_f32 v[170:171], v[190:191], s[2:3], v[170:171] op_sel_hi:[1,0,1]
	v_pk_mul_f32 v[184:185], v[180:181], s[2:3] op_sel_hi:[1,0]
	v_pk_mul_f32 v[180:181], v[168:169], v[168:169]
	v_pk_mul_f32 v[190:191], v[170:171], v[170:171]
	v_pk_mov_b32 v[176:177], v[176:177], v[180:181] op_sel:[1,0]
	v_pk_mov_b32 v[180:181], v[184:185], v[190:191] op_sel:[1,0]
	v_add_f32_e32 v20, 0, v6
	v_pk_add_f32 v[176:177], v[176:177], v[180:181]
	v_pk_add_f32 v[180:181], v[168:169], v[170:171]
	v_pk_mul_f32 v[184:185], v[168:169], v[170:171]
	v_fmac_f32_e32 v20, 0x3fd744fd, v175
	v_mov_b32_e32 v181, v185
	v_pk_add_f32 v[176:177], v[180:181], v[176:177]
	v_mul_f32_e32 v21, v20, v20
	v_pk_add_f32 v[174:175], v[176:177], v[20:21]
	s_nop 1
	v_mov_b32_dpp v176, v174 quad_perm:[1,0,3,2] row_mask:0xf bank_mask:0xf bound_ctrl:1
	v_mov_b32_dpp v177, v175 quad_perm:[1,0,3,2] row_mask:0xf bank_mask:0xf bound_ctrl:1
	v_pk_add_f32 v[174:175], v[174:175], v[176:177]
	s_nop 1
	v_mov_b32_dpp v176, v174 quad_perm:[2,3,0,1] row_mask:0xf bank_mask:0xf bound_ctrl:1
	v_mov_b32_dpp v177, v175 quad_perm:[2,3,0,1] row_mask:0xf bank_mask:0xf bound_ctrl:1
	v_pk_add_f32 v[174:175], v[174:175], v[176:177]
	s_nop 1
	v_mov_b32_dpp v176, v174 row_half_mirror row_mask:0xf bank_mask:0xf bound_ctrl:1
	v_mov_b32_dpp v177, v175 row_half_mirror row_mask:0xf bank_mask:0xf bound_ctrl:1
	v_pk_add_f32 v[174:175], v[174:175], v[176:177]
	s_nop 1
	v_mov_b32_dpp v176, v174 row_mirror row_mask:0xf bank_mask:0xf bound_ctrl:1
	v_mov_b32_dpp v177, v175 row_mirror row_mask:0xf bank_mask:0xf bound_ctrl:1
	s_and_saveexec_b64 s[6:7], vcc
	v_pk_add_f32 v[174:175], v[174:175], v[176:177]
	ds_write_b64 v179, v[174:175] offset:320
	s_or_b64 exec, exec, s[6:7]
	ds_read2_b32 v[174:175], v67 offset0:128 offset1:160
	ds_read2_b32 v[176:177], v67 offset0:192 offset1:224
	v_mov_b32_e32 v22, v55
	v_pk_add_f32 v[180:181], v[22:23], 0 op_sel_hi:[1,0]
	v_mov_b32_e32 v22, v39
	v_pk_add_f32 v[22:23], v[22:23], 0 op_sel_hi:[1,0]
	s_waitcnt lgkmcnt(1)
; template <int CTRL> DI float dpp_f(float v) { return __int_as_float(__builtin_amdgcn_update_dpp(0, __float_as_int(v), CTRL, 0xF, 0xF, true)); }
; DI float row16_sum(float v) {
;   v += dpp_f<0xB1>(v);
;   v += dpp_f<0x4E>(v);
;   v += dpp_f<0x141>(v);
;   v += dpp_f<0x140>(v);
;   return v;
; }
;   DI void operator()(f32x16 (&acc)[2][4], int grow0, int gcol0, int lane, int w, char* lds) {
;     ...
; #pragma unroll
;       for (int qq = 0; qq < 2; ++qq)
; #pragma unroll
;         for (int e = 0; e < 4; ++e) {
;           const int i = 4 * (2 * (ps & 1) + qq) + e;
;           const float* xr = (const float*)(xs + (8 * qq + 4 * hh + e) * 512) + l31;
;           float s1 = 0.f, s2 = 0.f;
; #pragma unroll
;           for (int nt = 0; nt < 4; ++nt) {
;             float v = (acc[mt][nt][i] + bia[nt]) * csc[nt];
;             float z = ALPHA * xr[nt * 32] + hs * v;
;             acc[mt][nt][i] = z; s1 += z; s2 += z * z;
;           }
;           s1 = row16_sum(s1); s2 = row16_sum(s2);
;           if ((lane & 15) == 0) { f32x2 sv = {s1, s2}; *(f32x2*)(redw + (mt * 32 + (i & 3) + 8 * (i >> 2)) * 2) = sv; }
;         }
	v_mov_b32_e32 v38, v174
	s_waitcnt lgkmcnt(0)
	v_mov_b32_e32 v39, v176
	s_mov_b32 s2, s67
	v_mov_b32_e32 v54, v175
	v_mov_b32_e32 v55, v176
	v_pk_mul_f32 v[184:185], v[38:39], s[2:3] op_sel_hi:[1,0]
	v_pk_fma_f32 v[38:39], v[38:39], s[2:3], v[180:181] op_sel_hi:[1,0,1]
	v_pk_fma_f32 v[54:55], v[54:55], s[2:3], v[22:23] op_sel_hi:[1,0,1]
	v_pk_mul_f32 v[174:175], v[38:39], v[38:39]
	v_pk_mul_f32 v[22:23], v[54:55], v[54:55]
	v_pk_mov_b32 v[174:175], v[180:181], v[174:175] op_sel:[1,0]
	v_pk_mov_b32 v[22:23], v[184:185], v[22:23] op_sel:[1,0]
	v_add_f32_e32 v6, 0, v7
	v_pk_add_f32 v[22:23], v[174:175], v[22:23]
	v_pk_add_f32 v[174:175], v[38:39], v[54:55]
	v_pk_mul_f32 v[180:181], v[38:39], v[54:55]
	v_fmac_f32_e32 v6, 0x3fd744fd, v177
	v_mov_b32_e32 v175, v181
	v_pk_add_f32 v[22:23], v[174:175], v[22:23]
	v_mul_f32_e32 v7, v6, v6
	v_pk_add_f32 v[22:23], v[22:23], v[6:7]
	s_nop 1
	v_mov_b32_dpp v174, v22 quad_perm:[1,0,3,2] row_mask:0xf bank_mask:0xf bound_ctrl:1
	v_mov_b32_dpp v175, v23 quad_perm:[1,0,3,2] row_mask:0xf bank_mask:0xf bound_ctrl:1
	v_pk_add_f32 v[22:23], v[22:23], v[174:175]
	s_nop 1
	v_mov_b32_dpp v174, v22 quad_perm:[2,3,0,1] row_mask:0xf bank_mask:0xf bound_ctrl:1
	v_mov_b32_dpp v175, v23 quad_perm:[2,3,0,1] row_mask:0xf bank_mask:0xf bound_ctrl:1
	v_pk_add_f32 v[22:23], v[22:23], v[174:175]
	s_nop 1
	v_mov_b32_dpp v174, v22 row_half_mirror row_mask:0xf bank_mask:0xf bound_ctrl:1
	v_mov_b32_dpp v175, v23 row_half_mirror row_mask:0xf bank_mask:0xf bound_ctrl:1
	v_pk_add_f32 v[22:23], v[22:23], v[174:175]
	s_nop 1
	v_mov_b32_dpp v174, v22 row_mirror row_mask:0xf bank_mask:0xf bound_ctrl:1
	v_mov_b32_dpp v175, v23 row_mirror row_mask:0xf bank_mask:0xf bound_ctrl:1
	s_and_saveexec_b64 s[6:7], vcc
	v_pk_add_f32 v[22:23], v[22:23], v[174:175]
	ds_write_b64 v179, v[22:23] offset:328
	s_or_b64 exec, exec, s[6:7]
	ds_read2_b32 v[174:175], v69 offset1:32
	ds_read2_b32 v[180:181], v69 offset0:64 offset1:96
	v_mov_b32_e32 v176, v56
	v_mov_b32_e32 v177, v24
	v_pk_add_f32 v[184:185], v[176:177], 0 op_sel_hi:[1,0]
	v_mov_b32_e32 v176, v40
	v_pk_add_f32 v[176:177], v[176:177], 0 op_sel_hi:[1,0]
	s_waitcnt lgkmcnt(1)
	v_mov_b32_e32 v190, v174
	s_waitcnt lgkmcnt(0)
	v_mov_b32_e32 v191, v180
	s_mov_b32 s2, s67
	v_mov_b32_e32 v194, v175
	v_mov_b32_e32 v195, v180
	v_pk_fma_f32 v[174:175], v[190:191], s[2:3], v[184:185] op_sel_hi:[1,0,1]
	v_pk_fma_f32 v[176:177], v[194:195], s[2:3], v[176:177] op_sel_hi:[1,0,1]
	v_pk_mul_f32 v[192:193], v[190:191], s[2:3] op_sel_hi:[1,0]
	v_pk_mul_f32 v[190:191], v[174:175], v[174:175]
	v_pk_mul_f32 v[194:195], v[176:177], v[176:177]
	v_pk_mov_b32 v[184:185], v[184:185], v[190:191] op_sel:[1,0]
	v_pk_mov_b32 v[190:191], v[192:193], v[194:195] op_sel:[1,0]
	v_add_f32_e32 v22, 0, v8
	v_pk_add_f32 v[184:185], v[184:185], v[190:191]
	v_pk_add_f32 v[190:191], v[174:175], v[176:177]
	v_pk_mul_f32 v[192:193], v[174:175], v[176:177]
	v_fmac_f32_e32 v22, 0x3fd744fd, v181
	v_mov_b32_e32 v191, v193
	v_pk_add_f32 v[184:185], v[190:191], v[184:185]
	v_mul_f32_e32 v23, v22, v22
	v_pk_add_f32 v[180:181], v[184:185], v[22:23]
	s_nop 1
	v_mov_b32_dpp v184, v180 quad_perm:[1,0,3,2] row_mask:0xf bank_mask:0xf bound_ctrl:1
	v_mov_b32_dpp v185, v181 quad_perm:[1,0,3,2] row_mask:0xf bank_mask:0xf bound_ctrl:1
	v_pk_add_f32 v[180:181], v[180:181], v[184:185]
	s_nop 1
	v_mov_b32_dpp v184, v180 quad_perm:[2,3,0,1] row_mask:0xf bank_mask:0xf bound_ctrl:1
	v_mov_b32_dpp v185, v181 quad_perm:[2,3,0,1] row_mask:0xf bank_mask:0xf bound_ctrl:1
	v_pk_add_f32 v[180:181], v[180:181], v[184:185]
	s_nop 1
	v_mov_b32_dpp v184, v180 row_half_mirror row_mask:0xf bank_mask:0xf bound_ctrl:1
	v_mov_b32_dpp v185, v181 row_half_mirror row_mask:0xf bank_mask:0xf bound_ctrl:1
	v_pk_add_f32 v[180:181], v[180:181], v[184:185]
	s_nop 1
	v_mov_b32_dpp v184, v180 row_mirror row_mask:0xf bank_mask:0xf bound_ctrl:1
	v_mov_b32_dpp v185, v181 row_mirror row_mask:0xf bank_mask:0xf bound_ctrl:1
	s_and_saveexec_b64 s[6:7], vcc
	v_pk_add_f32 v[180:181], v[180:181], v[184:185]
	ds_write_b64 v179, v[180:181] offset:336
	s_or_b64 exec, exec, s[6:7]
	ds_read2_b32 v[180:181], v71 offset1:32
	ds_read2_b32 v[184:185], v71 offset0:64 offset1:96
	v_mov_b32_e32 v24, v57
	v_pk_add_f32 v[190:191], v[24:25], 0 op_sel_hi:[1,0]
	v_mov_b32_e32 v24, v41
	v_pk_add_f32 v[24:25], v[24:25], 0 op_sel_hi:[1,0]
	s_waitcnt lgkmcnt(1)
	v_mov_b32_e32 v40, v180
	s_waitcnt lgkmcnt(0)
	v_mov_b32_e32 v41, v184
	s_mov_b32 s2, s67
	v_mov_b32_e32 v56, v181
	v_mov_b32_e32 v57, v184
	v_pk_mul_f32 v[192:193], v[40:41], s[2:3] op_sel_hi:[1,0]
	v_pk_fma_f32 v[40:41], v[40:41], s[2:3], v[190:191] op_sel_hi:[1,0,1]
	v_pk_fma_f32 v[56:57], v[56:57], s[2:3], v[24:25] op_sel_hi:[1,0,1]
	v_pk_mul_f32 v[180:181], v[40:41], v[40:41]
	v_pk_mul_f32 v[24:25], v[56:57], v[56:57]
	v_pk_mov_b32 v[180:181], v[190:191], v[180:181] op_sel:[1,0]
	v_pk_mov_b32 v[24:25], v[192:193], v[24:25] op_sel:[1,0]
	v_add_f32_e32 v8, 0, v9
	v_pk_add_f32 v[24:25], v[180:181], v[24:25]
	v_pk_add_f32 v[180:181], v[40:41], v[56:57]
	v_pk_mul_f32 v[190:191], v[40:41], v[56:57]
	v_fmac_f32_e32 v8, 0x3fd744fd, v185
	v_mov_b32_e32 v181, v191
	v_pk_add_f32 v[24:25], v[180:181], v[24:25]
	v_mul_f32_e32 v9, v8, v8
	v_pk_add_f32 v[24:25], v[24:25], v[8:9]
	s_nop 1
	v_mov_b32_dpp v180, v24 quad_perm:[1,0,3,2] row_mask:0xf bank_mask:0xf bound_ctrl:1
	v_mov_b32_dpp v181, v25 quad_perm:[1,0,3,2] row_mask:0xf bank_mask:0xf bound_ctrl:1
	v_pk_add_f32 v[24:25], v[24:25], v[180:181]
	s_nop 1
	v_mov_b32_dpp v180, v24 quad_perm:[2,3,0,1] row_mask:0xf bank_mask:0xf bound_ctrl:1
	v_mov_b32_dpp v181, v25 quad_perm:[2,3,0,1] row_mask:0xf bank_mask:0xf bound_ctrl:1
	v_pk_add_f32 v[24:25], v[24:25], v[180:181]
	s_nop 1
	v_mov_b32_dpp v180, v24 row_half_mirror row_mask:0xf bank_mask:0xf bound_ctrl:1
	v_mov_b32_dpp v181, v25 row_half_mirror row_mask:0xf bank_mask:0xf bound_ctrl:1
	v_pk_add_f32 v[24:25], v[24:25], v[180:181]
	s_nop 1
	v_mov_b32_dpp v180, v24 row_mirror row_mask:0xf bank_mask:0xf bound_ctrl:1
	v_mov_b32_dpp v181, v25 row_mirror row_mask:0xf bank_mask:0xf bound_ctrl:1
	s_and_saveexec_b64 s[6:7], vcc
	v_pk_add_f32 v[24:25], v[24:25], v[180:181]
	ds_write_b64 v179, v[24:25] offset:344
	s_or_b64 exec, exec, s[6:7]
	s_waitcnt vmcnt(0)
; template <int CTRL> DI float dpp_f(float v) { return __int_as_float(__builtin_amdgcn_update_dpp(0, __float_as_int(v), CTRL, 0xF, 0xF, true)); }
; DI float row16_sum(float v) {
;   v += dpp_f<0xB1>(v);
;   v += dpp_f<0x4E>(v);
;   v += dpp_f<0x141>(v);
;   v += dpp_f<0x140>(v);
;   return v;
; }
;   DI void operator()(f32x16 (&acc)[2][4], int grow0, int gcol0, int lane, int w, char* lds) {
;     ...
; #pragma unroll
;       for (int qq = 0; qq < 2; ++qq)
; #pragma unroll
;         for (int e = 0; e < 4; ++e) {
;           const int i = 4 * (2 * (ps & 1) + qq) + e;
;           const float* xr = (const float*)(xs + (8 * qq + 4 * hh + e) * 512) + l31;
;           float s1 = 0.f, s2 = 0.f;
; #pragma unroll
;           for (int nt = 0; nt < 4; ++nt) {
;             float v = (acc[mt][nt][i] + bia[nt]) * csc[nt];
;             float z = ALPHA * xr[nt * 32] + hs * v;
;             acc[mt][nt][i] = z; s1 += z; s2 += z * z;
;           }
;           s1 = row16_sum(s1); s2 = row16_sum(s2);
;           if ((lane & 15) == 0) { f32x2 sv = {s1, s2}; *(f32x2*)(redw + (mt * 32 + (i & 3) + 8 * (i >> 2)) * 2) = sv; }
;         }
	ds_read2_b32 v[184:185], v73 offset1:32
	ds_read2_b32 v[192:193], v73 offset0:64 offset1:96
	v_add_f32_e32 v181, 0, v42
	v_mov_b32_e32 v190, v58
	v_mov_b32_e32 v191, v26
	s_waitcnt lgkmcnt(1)
	v_fmac_f32_e32 v181, 0x3fd744fd, v185
	v_pk_add_f32 v[194:195], v[190:191], 0 op_sel_hi:[1,0]
	s_waitcnt lgkmcnt(0)
	v_mov_b32_e32 v185, v192
	s_mov_b32 s2, s67
	v_pk_fma_f32 v[190:191], v[184:185], s[2:3], v[194:195] op_sel_hi:[1,0,1]
	v_mov_b32_e32 v180, v192
	v_pk_mul_f32 v[184:185], v[190:191], v[190:191]
	v_mov_b32_e32 v196, v165
	v_mov_b32_e32 v197, v181
	v_pk_mov_b32 v[184:185], v[194:195], v[184:185] op_sel:[1,0]
	v_add_f32_e32 v24, 0, v10
	v_pk_fma_f32 v[184:185], v[180:181], v[196:197], v[184:185]
	v_fmac_f32_e32 v24, 0x3fd744fd, v193
	v_pk_mov_b32 v[194:195], v[180:181], v[184:185] op_sel:[1,0]
	v_mul_f32_e32 v25, v24, v24
	v_pk_add_f32 v[196:197], v[190:191], v[194:195]
	v_pk_mul_f32 v[194:195], v[190:191], v[194:195]
	s_nop 0
	v_mov_b32_e32 v197, v195
	v_pk_add_f32 v[194:195], v[184:185], v[196:197]
	s_nop 0
	v_pk_add_f32 v[192:193], v[194:195], v[24:25]
	s_nop 1
	v_mov_b32_dpp v194, v192 quad_perm:[1,0,3,2] row_mask:0xf bank_mask:0xf bound_ctrl:1
	v_mov_b32_dpp v195, v193 quad_perm:[1,0,3,2] row_mask:0xf bank_mask:0xf bound_ctrl:1
	v_pk_add_f32 v[192:193], v[192:193], v[194:195]
	s_nop 1
	v_mov_b32_dpp v194, v192 quad_perm:[2,3,0,1] row_mask:0xf bank_mask:0xf bound_ctrl:1
	v_mov_b32_dpp v195, v193 quad_perm:[2,3,0,1] row_mask:0xf bank_mask:0xf bound_ctrl:1
	v_pk_add_f32 v[192:193], v[192:193], v[194:195]
	s_nop 1
	v_mov_b32_dpp v194, v192 row_half_mirror row_mask:0xf bank_mask:0xf bound_ctrl:1
	v_mov_b32_dpp v195, v193 row_half_mirror row_mask:0xf bank_mask:0xf bound_ctrl:1
	v_pk_add_f32 v[192:193], v[192:193], v[194:195]
	s_nop 1
	v_mov_b32_dpp v194, v192 row_mirror row_mask:0xf bank_mask:0xf bound_ctrl:1
	v_mov_b32_dpp v195, v193 row_mirror row_mask:0xf bank_mask:0xf bound_ctrl:1
	s_and_saveexec_b64 s[6:7], vcc
	v_pk_add_f32 v[192:193], v[192:193], v[194:195]
	ds_write_b64 v179, v[192:193] offset:384
	s_or_b64 exec, exec, s[6:7]
	ds_read2_b32 v[192:193], v85 offset1:32
	ds_read2_b32 v[194:195], v85 offset0:64 offset1:96
	v_mov_b32_e32 v26, v59
	v_pk_add_f32 v[196:197], v[26:27], 0 op_sel_hi:[1,0]
	v_mov_b32_e32 v26, v43
	v_pk_add_f32 v[26:27], v[26:27], 0 op_sel_hi:[1,0]
	s_waitcnt lgkmcnt(1)
	v_mov_b32_e32 v42, v192
	s_waitcnt lgkmcnt(0)
	v_mov_b32_e32 v43, v194
	s_mov_b32 s2, s67
	v_mov_b32_e32 v58, v193
	v_mov_b32_e32 v59, v194
	v_pk_mul_f32 v[198:199], v[42:43], s[2:3] op_sel_hi:[1,0]
	v_pk_fma_f32 v[42:43], v[42:43], s[2:3], v[196:197] op_sel_hi:[1,0,1]
	v_pk_fma_f32 v[58:59], v[58:59], s[2:3], v[26:27] op_sel_hi:[1,0,1]
	v_pk_mul_f32 v[192:193], v[42:43], v[42:43]
	v_pk_mul_f32 v[26:27], v[58:59], v[58:59]
	v_pk_mov_b32 v[192:193], v[196:197], v[192:193] op_sel:[1,0]
	v_pk_mov_b32 v[26:27], v[198:199], v[26:27] op_sel:[1,0]
	v_add_f32_e32 v10, 0, v11
	v_pk_add_f32 v[26:27], v[192:193], v[26:27]
	v_pk_add_f32 v[192:193], v[42:43], v[58:59]
	v_pk_mul_f32 v[196:197], v[42:43], v[58:59]
	v_fmac_f32_e32 v10, 0x3fd744fd, v195
	v_mov_b32_e32 v193, v197
	v_pk_add_f32 v[26:27], v[192:193], v[26:27]
	v_mul_f32_e32 v11, v10, v10
	v_pk_add_f32 v[26:27], v[26:27], v[10:11]
	s_nop 1
	v_mov_b32_dpp v192, v26 quad_perm:[1,0,3,2] row_mask:0xf bank_mask:0xf bound_ctrl:1
	v_mov_b32_dpp v193, v27 quad_perm:[1,0,3,2] row_mask:0xf bank_mask:0xf bound_ctrl:1
	v_pk_add_f32 v[26:27], v[26:27], v[192:193]
	s_nop 1
	v_mov_b32_dpp v192, v26 quad_perm:[2,3,0,1] row_mask:0xf bank_mask:0xf bound_ctrl:1
	v_mov_b32_dpp v193, v27 quad_perm:[2,3,0,1] row_mask:0xf bank_mask:0xf bound_ctrl:1
	v_pk_add_f32 v[26:27], v[26:27], v[192:193]
	s_nop 1
	v_mov_b32_dpp v192, v26 row_half_mirror row_mask:0xf bank_mask:0xf bound_ctrl:1
	v_mov_b32_dpp v193, v27 row_half_mirror row_mask:0xf bank_mask:0xf bound_ctrl:1
	v_pk_add_f32 v[26:27], v[26:27], v[192:193]
	s_nop 1
	v_mov_b32_dpp v192, v26 row_mirror row_mask:0xf bank_mask:0xf bound_ctrl:1
	v_mov_b32_dpp v193, v27 row_mirror row_mask:0xf bank_mask:0xf bound_ctrl:1
	s_and_saveexec_b64 s[6:7], vcc
	v_pk_add_f32 v[26:27], v[26:27], v[192:193]
	ds_write_b64 v179, v[26:27] offset:392
	s_or_b64 exec, exec, s[6:7]
	ds_read2_b32 v[192:193], v75 offset1:32
	ds_read2_b32 v[196:197], v75 offset0:64 offset1:96
	v_mov_b32_e32 v194, v60
	v_mov_b32_e32 v195, v28
	v_pk_add_f32 v[198:199], v[194:195], 0 op_sel_hi:[1,0]
	v_mov_b32_e32 v194, v44
	v_pk_add_f32 v[194:195], v[194:195], 0 op_sel_hi:[1,0]
	s_waitcnt lgkmcnt(1)
	v_mov_b32_e32 v202, v192
	s_waitcnt lgkmcnt(0)
	v_mov_b32_e32 v203, v196
	s_mov_b32 s2, s67
	v_mov_b32_e32 v206, v193
	v_mov_b32_e32 v207, v196
	v_pk_fma_f32 v[192:193], v[202:203], s[2:3], v[198:199] op_sel_hi:[1,0,1]
	v_pk_fma_f32 v[194:195], v[206:207], s[2:3], v[194:195] op_sel_hi:[1,0,1]
	v_pk_mul_f32 v[204:205], v[202:203], s[2:3] op_sel_hi:[1,0]
	v_pk_mul_f32 v[202:203], v[192:193], v[192:193]
	v_pk_mul_f32 v[206:207], v[194:195], v[194:195]
	v_pk_mov_b32 v[198:199], v[198:199], v[202:203] op_sel:[1,0]
	v_pk_mov_b32 v[202:203], v[204:205], v[206:207] op_sel:[1,0]
	v_add_f32_e32 v26, 0, v12
	v_pk_add_f32 v[198:199], v[198:199], v[202:203]
	v_pk_add_f32 v[202:203], v[192:193], v[194:195]
	v_pk_mul_f32 v[204:205], v[192:193], v[194:195]
	v_fmac_f32_e32 v26, 0x3fd744fd, v197
	v_mov_b32_e32 v203, v205
	v_pk_add_f32 v[198:199], v[202:203], v[198:199]
	v_mul_f32_e32 v27, v26, v26
	v_pk_add_f32 v[196:197], v[198:199], v[26:27]
	s_nop 1
	v_mov_b32_dpp v198, v196 quad_perm:[1,0,3,2] row_mask:0xf bank_mask:0xf bound_ctrl:1
	v_mov_b32_dpp v199, v197 quad_perm:[1,0,3,2] row_mask:0xf bank_mask:0xf bound_ctrl:1
	v_pk_add_f32 v[196:197], v[196:197], v[198:199]
	s_nop 1
	v_mov_b32_dpp v198, v196 quad_perm:[2,3,0,1] row_mask:0xf bank_mask:0xf bound_ctrl:1
	v_mov_b32_dpp v199, v197 quad_perm:[2,3,0,1] row_mask:0xf bank_mask:0xf bound_ctrl:1
	v_pk_add_f32 v[196:197], v[196:197], v[198:199]
	s_nop 1
	v_mov_b32_dpp v198, v196 row_half_mirror row_mask:0xf bank_mask:0xf bound_ctrl:1
	v_mov_b32_dpp v199, v197 row_half_mirror row_mask:0xf bank_mask:0xf bound_ctrl:1
	v_pk_add_f32 v[196:197], v[196:197], v[198:199]
	s_nop 1
	v_mov_b32_dpp v198, v196 row_mirror row_mask:0xf bank_mask:0xf bound_ctrl:1
	v_mov_b32_dpp v199, v197 row_mirror row_mask:0xf bank_mask:0xf bound_ctrl:1
	s_and_saveexec_b64 s[6:7], vcc
	v_pk_add_f32 v[196:197], v[196:197], v[198:199]
	ds_write_b64 v179, v[196:197] offset:400
	s_or_b64 exec, exec, s[6:7]
	ds_read2_b32 v[196:197], v87 offset1:32
	ds_read2_b32 v[198:199], v87 offset0:64 offset1:96
	v_mov_b32_e32 v28, v61
	v_pk_add_f32 v[202:203], v[28:29], 0 op_sel_hi:[1,0]
	v_mov_b32_e32 v28, v45
	v_pk_add_f32 v[28:29], v[28:29], 0 op_sel_hi:[1,0]
	s_waitcnt lgkmcnt(1)
; template <int CTRL> DI float dpp_f(float v) { return __int_as_float(__builtin_amdgcn_update_dpp(0, __float_as_int(v), CTRL, 0xF, 0xF, true)); }
; DI float row16_sum(float v) {
;   v += dpp_f<0xB1>(v);
;   v += dpp_f<0x4E>(v);
;   v += dpp_f<0x141>(v);
;   v += dpp_f<0x140>(v);
;   return v;
; }
;   DI void operator()(f32x16 (&acc)[2][4], int grow0, int gcol0, int lane, int w, char* lds) {
;     ...
; #pragma unroll
;       for (int qq = 0; qq < 2; ++qq)
; #pragma unroll
;         for (int e = 0; e < 4; ++e) {
;           const int i = 4 * (2 * (ps & 1) + qq) + e;
;           const float* xr = (const float*)(xs + (8 * qq + 4 * hh + e) * 512) + l31;
;           float s1 = 0.f, s2 = 0.f;
; #pragma unroll
;           for (int nt = 0; nt < 4; ++nt) {
;             float v = (acc[mt][nt][i] + bia[nt]) * csc[nt];
;             float z = ALPHA * xr[nt * 32] + hs * v;
;             acc[mt][nt][i] = z; s1 += z; s2 += z * z;
;           }
;           s1 = row16_sum(s1); s2 = row16_sum(s2);
;           if ((lane & 15) == 0) { f32x2 sv = {s1, s2}; *(f32x2*)(redw + (mt * 32 + (i & 3) + 8 * (i >> 2)) * 2) = sv; }
;         }
	v_mov_b32_e32 v44, v196
	s_waitcnt lgkmcnt(0)
	v_mov_b32_e32 v45, v198
	s_mov_b32 s2, s67
	v_mov_b32_e32 v60, v197
	v_mov_b32_e32 v61, v198
	v_pk_mul_f32 v[204:205], v[44:45], s[2:3] op_sel_hi:[1,0]
	v_pk_fma_f32 v[44:45], v[44:45], s[2:3], v[202:203] op_sel_hi:[1,0,1]
	v_pk_fma_f32 v[60:61], v[60:61], s[2:3], v[28:29] op_sel_hi:[1,0,1]
	v_pk_mul_f32 v[196:197], v[44:45], v[44:45]
	v_pk_mul_f32 v[28:29], v[60:61], v[60:61]
	v_pk_mov_b32 v[196:197], v[202:203], v[196:197] op_sel:[1,0]
	v_pk_mov_b32 v[28:29], v[204:205], v[28:29] op_sel:[1,0]
	v_add_f32_e32 v12, 0, v13
	v_pk_add_f32 v[28:29], v[196:197], v[28:29]
	v_pk_add_f32 v[196:197], v[44:45], v[60:61]
	v_pk_mul_f32 v[202:203], v[44:45], v[60:61]
	v_fmac_f32_e32 v12, 0x3fd744fd, v199
	v_mov_b32_e32 v197, v203
	v_pk_add_f32 v[28:29], v[196:197], v[28:29]
	v_mul_f32_e32 v13, v12, v12
	v_pk_add_f32 v[28:29], v[28:29], v[12:13]
	s_nop 1
	v_mov_b32_dpp v196, v28 quad_perm:[1,0,3,2] row_mask:0xf bank_mask:0xf bound_ctrl:1
	v_mov_b32_dpp v197, v29 quad_perm:[1,0,3,2] row_mask:0xf bank_mask:0xf bound_ctrl:1
	v_pk_add_f32 v[28:29], v[28:29], v[196:197]
	s_nop 1
	v_mov_b32_dpp v196, v28 quad_perm:[2,3,0,1] row_mask:0xf bank_mask:0xf bound_ctrl:1
	v_mov_b32_dpp v197, v29 quad_perm:[2,3,0,1] row_mask:0xf bank_mask:0xf bound_ctrl:1
	v_pk_add_f32 v[28:29], v[28:29], v[196:197]
	s_nop 1
	v_mov_b32_dpp v196, v28 row_half_mirror row_mask:0xf bank_mask:0xf bound_ctrl:1
	v_mov_b32_dpp v197, v29 row_half_mirror row_mask:0xf bank_mask:0xf bound_ctrl:1
	v_pk_add_f32 v[28:29], v[28:29], v[196:197]
	s_nop 1
	v_mov_b32_dpp v196, v28 row_mirror row_mask:0xf bank_mask:0xf bound_ctrl:1
	v_mov_b32_dpp v197, v29 row_mirror row_mask:0xf bank_mask:0xf bound_ctrl:1
	s_and_saveexec_b64 s[6:7], vcc
	v_pk_add_f32 v[28:29], v[28:29], v[196:197]
	ds_write_b64 v179, v[28:29] offset:408
	s_or_b64 exec, exec, s[6:7]
	ds_read2_b32 v[196:197], v77 offset1:32
	ds_read2_b32 v[202:203], v77 offset0:64 offset1:96
	v_mov_b32_e32 v198, v62
	v_mov_b32_e32 v199, v30
	v_pk_add_f32 v[204:205], v[198:199], 0 op_sel_hi:[1,0]
	v_mov_b32_e32 v198, v46
	v_pk_add_f32 v[198:199], v[198:199], 0 op_sel_hi:[1,0]
	s_waitcnt lgkmcnt(1)
	v_mov_b32_e32 v206, v196
	s_waitcnt lgkmcnt(0)
	v_mov_b32_e32 v207, v202
	s_mov_b32 s2, s67
	v_mov_b32_e32 v212, v197
	v_mov_b32_e32 v213, v202
	v_pk_fma_f32 v[196:197], v[206:207], s[2:3], v[204:205] op_sel_hi:[1,0,1]
	v_pk_fma_f32 v[198:199], v[212:213], s[2:3], v[198:199] op_sel_hi:[1,0,1]
	v_pk_mul_f32 v[208:209], v[206:207], s[2:3] op_sel_hi:[1,0]
	v_pk_mul_f32 v[206:207], v[196:197], v[196:197]
	v_pk_mul_f32 v[212:213], v[198:199], v[198:199]
	v_pk_mov_b32 v[204:205], v[204:205], v[206:207] op_sel:[1,0]
	v_pk_mov_b32 v[206:207], v[208:209], v[212:213] op_sel:[1,0]
	v_add_f32_e32 v28, 0, v14
	v_pk_add_f32 v[204:205], v[204:205], v[206:207]
	v_pk_add_f32 v[206:207], v[196:197], v[198:199]
	v_pk_mul_f32 v[208:209], v[196:197], v[198:199]
	v_fmac_f32_e32 v28, 0x3fd744fd, v203
	v_mov_b32_e32 v207, v209
	v_pk_add_f32 v[204:205], v[206:207], v[204:205]
	v_mul_f32_e32 v29, v28, v28
	v_pk_add_f32 v[202:203], v[204:205], v[28:29]
	s_nop 1
	v_mov_b32_dpp v204, v202 quad_perm:[1,0,3,2] row_mask:0xf bank_mask:0xf bound_ctrl:1
	v_mov_b32_dpp v205, v203 quad_perm:[1,0,3,2] row_mask:0xf bank_mask:0xf bound_ctrl:1
	v_pk_add_f32 v[202:203], v[202:203], v[204:205]
	s_nop 1
	v_mov_b32_dpp v204, v202 quad_perm:[2,3,0,1] row_mask:0xf bank_mask:0xf bound_ctrl:1
	v_mov_b32_dpp v205, v203 quad_perm:[2,3,0,1] row_mask:0xf bank_mask:0xf bound_ctrl:1
	v_pk_add_f32 v[202:203], v[202:203], v[204:205]
	s_nop 1
	v_mov_b32_dpp v204, v202 row_half_mirror row_mask:0xf bank_mask:0xf bound_ctrl:1
	v_mov_b32_dpp v205, v203 row_half_mirror row_mask:0xf bank_mask:0xf bound_ctrl:1
	v_pk_add_f32 v[202:203], v[202:203], v[204:205]
	s_nop 1
	v_mov_b32_dpp v204, v202 row_mirror row_mask:0xf bank_mask:0xf bound_ctrl:1
	v_mov_b32_dpp v205, v203 row_mirror row_mask:0xf bank_mask:0xf bound_ctrl:1
	s_and_saveexec_b64 s[6:7], vcc
	v_pk_add_f32 v[202:203], v[202:203], v[204:205]
	ds_write_b64 v179, v[202:203] offset:448
	s_or_b64 exec, exec, s[6:7]
	ds_read2_b32 v[202:203], v91 offset1:32
	ds_read2_b32 v[204:205], v91 offset0:64 offset1:96
	v_mov_b32_e32 v30, v63
	v_pk_add_f32 v[206:207], v[30:31], 0 op_sel_hi:[1,0]
	v_mov_b32_e32 v30, v47
	v_pk_add_f32 v[30:31], v[30:31], 0 op_sel_hi:[1,0]
	s_waitcnt lgkmcnt(1)
	v_mov_b32_e32 v46, v202
	s_waitcnt lgkmcnt(0)
	v_mov_b32_e32 v47, v204
	s_mov_b32 s2, s67
	v_mov_b32_e32 v62, v203
	v_mov_b32_e32 v63, v204
	v_pk_mul_f32 v[208:209], v[46:47], s[2:3] op_sel_hi:[1,0]
	v_pk_fma_f32 v[46:47], v[46:47], s[2:3], v[206:207] op_sel_hi:[1,0,1]
	v_pk_fma_f32 v[62:63], v[62:63], s[2:3], v[30:31] op_sel_hi:[1,0,1]
	v_pk_mul_f32 v[202:203], v[46:47], v[46:47]
	v_pk_mul_f32 v[30:31], v[62:63], v[62:63]
	v_pk_mov_b32 v[202:203], v[206:207], v[202:203] op_sel:[1,0]
	v_pk_mov_b32 v[30:31], v[208:209], v[30:31] op_sel:[1,0]
	v_add_f32_e32 v14, 0, v15
	v_pk_add_f32 v[30:31], v[202:203], v[30:31]
	v_pk_add_f32 v[202:203], v[46:47], v[62:63]
	v_pk_mul_f32 v[206:207], v[46:47], v[62:63]
	v_fmac_f32_e32 v14, 0x3fd744fd, v205
	v_mov_b32_e32 v203, v207
	v_pk_add_f32 v[30:31], v[202:203], v[30:31]
	v_mul_f32_e32 v15, v14, v14
	v_pk_add_f32 v[30:31], v[30:31], v[14:15]
	s_nop 1
	v_mov_b32_dpp v202, v30 quad_perm:[1,0,3,2] row_mask:0xf bank_mask:0xf bound_ctrl:1
	v_mov_b32_dpp v203, v31 quad_perm:[1,0,3,2] row_mask:0xf bank_mask:0xf bound_ctrl:1
	v_pk_add_f32 v[30:31], v[30:31], v[202:203]
	s_nop 1
	v_mov_b32_dpp v202, v30 quad_perm:[2,3,0,1] row_mask:0xf bank_mask:0xf bound_ctrl:1
	v_mov_b32_dpp v203, v31 quad_perm:[2,3,0,1] row_mask:0xf bank_mask:0xf bound_ctrl:1
	v_pk_add_f32 v[30:31], v[30:31], v[202:203]
	s_nop 1
	v_mov_b32_dpp v202, v30 row_half_mirror row_mask:0xf bank_mask:0xf bound_ctrl:1
	v_mov_b32_dpp v203, v31 row_half_mirror row_mask:0xf bank_mask:0xf bound_ctrl:1
	v_pk_add_f32 v[30:31], v[30:31], v[202:203]
	s_nop 1
	v_mov_b32_dpp v202, v30 row_mirror row_mask:0xf bank_mask:0xf bound_ctrl:1
	v_mov_b32_dpp v203, v31 row_mirror row_mask:0xf bank_mask:0xf bound_ctrl:1
	s_and_saveexec_b64 s[6:7], vcc
	v_pk_add_f32 v[30:31], v[30:31], v[202:203]
	ds_write_b64 v179, v[30:31] offset:456
	s_or_b64 exec, exec, s[6:7]
	ds_read2_b32 v[202:203], v79 offset1:32
	ds_read2_b32 v[206:207], v79 offset0:64 offset1:96
	v_mov_b32_e32 v204, v64
	v_mov_b32_e32 v205, v32
	v_pk_add_f32 v[208:209], v[204:205], 0 op_sel_hi:[1,0]
	v_mov_b32_e32 v204, v48
	v_pk_add_f32 v[204:205], v[204:205], 0 op_sel_hi:[1,0]
	s_waitcnt lgkmcnt(1)
; DI void ag_st64(u64_t* p, u64_t v) { __hip_atomic_store(p, v, __ATOMIC_RELAXED, __HIP_MEMORY_SCOPE_AGENT); }
;   DI void operator()(f32x16 (&acc)[2][4], int grow0, int gcol0, int lane, int w, char* lds) {
;     ...
;           for (int nt = 0; nt < 4; ++nt) {
;             float v = (acc[mt][nt][i] + bia[nt]) * csc[nt];
;             float z = ALPHA * xr[nt * 32] + hs * v;
;             acc[mt][nt][i] = z; s1 += z; s2 += z * z;
;           }
;           s1 = row16_sum(s1); s2 = row16_sum(s2);
;           if ((lane & 15) == 0) { f32x2 sv = {s1, s2}; *(f32x2*)(redw + (mt * 32 + (i & 3) + 8 * (i >> 2)) * 2) = sv; }
;         }
;     }
;     __syncthreads();
;     u64_t* myslots = xstat + ((size_t)pm * 256) * 4;
;     if (tid < 256) {
;       float s1 = (red[tid * 2] + red[(256 + tid) * 2]) + (red[(512 + tid) * 2] + red[(768 + tid) * 2]);
;       float s2 = (red[tid * 2 + 1] + red[(256 + tid) * 2 + 1]) + (red[(512 + tid) * 2 + 1] + red[(768 + tid) * 2 + 1]);
;       ag_st64(myslots + tid * 4 + pn, ((u64_t)__float_as_uint(s2) << 32) | (u64_t)__float_as_uint(s1));
	v_mov_b32_e32 v212, v202
	s_waitcnt lgkmcnt(0)
	v_mov_b32_e32 v213, v206
	s_mov_b32 s2, s67
	v_mov_b32_e32 v226, v203
	v_mov_b32_e32 v227, v206
	v_pk_fma_f32 v[202:203], v[212:213], s[2:3], v[208:209] op_sel_hi:[1,0,1]
	v_pk_fma_f32 v[204:205], v[226:227], s[2:3], v[204:205] op_sel_hi:[1,0,1]
	v_pk_mul_f32 v[214:215], v[212:213], s[2:3] op_sel_hi:[1,0]
	v_pk_mul_f32 v[212:213], v[202:203], v[202:203]
	v_pk_mul_f32 v[226:227], v[204:205], v[204:205]
	v_pk_mov_b32 v[208:209], v[208:209], v[212:213] op_sel:[1,0]
	v_pk_mov_b32 v[212:213], v[214:215], v[226:227] op_sel:[1,0]
	v_add_f32_e32 v30, 0, v16
	v_pk_add_f32 v[208:209], v[208:209], v[212:213]
	v_pk_add_f32 v[212:213], v[202:203], v[204:205]
	v_pk_mul_f32 v[214:215], v[202:203], v[204:205]
	v_fmac_f32_e32 v30, 0x3fd744fd, v207
	v_mov_b32_e32 v213, v215
	v_pk_add_f32 v[208:209], v[212:213], v[208:209]
	v_mul_f32_e32 v31, v30, v30
	v_pk_add_f32 v[206:207], v[208:209], v[30:31]
	s_nop 1
	v_mov_b32_dpp v208, v206 quad_perm:[1,0,3,2] row_mask:0xf bank_mask:0xf bound_ctrl:1
	v_mov_b32_dpp v209, v207 quad_perm:[1,0,3,2] row_mask:0xf bank_mask:0xf bound_ctrl:1
	v_pk_add_f32 v[206:207], v[206:207], v[208:209]
	s_nop 1
	v_mov_b32_dpp v208, v206 quad_perm:[2,3,0,1] row_mask:0xf bank_mask:0xf bound_ctrl:1
	v_mov_b32_dpp v209, v207 quad_perm:[2,3,0,1] row_mask:0xf bank_mask:0xf bound_ctrl:1
	v_pk_add_f32 v[206:207], v[206:207], v[208:209]
	s_nop 1
	v_mov_b32_dpp v208, v206 row_half_mirror row_mask:0xf bank_mask:0xf bound_ctrl:1
	v_mov_b32_dpp v209, v207 row_half_mirror row_mask:0xf bank_mask:0xf bound_ctrl:1
	v_pk_add_f32 v[206:207], v[206:207], v[208:209]
	s_nop 1
	v_mov_b32_dpp v208, v206 row_mirror row_mask:0xf bank_mask:0xf bound_ctrl:1
	v_mov_b32_dpp v209, v207 row_mirror row_mask:0xf bank_mask:0xf bound_ctrl:1
	s_and_saveexec_b64 s[6:7], vcc
	v_pk_add_f32 v[206:207], v[206:207], v[208:209]
	ds_write_b64 v179, v[206:207] offset:464
	s_or_b64 exec, exec, s[6:7]
	ds_read2_b32 v[206:207], v93 offset1:32
	ds_read2_b32 v[208:209], v93 offset0:64 offset1:96
	v_mov_b32_e32 v32, v65
	v_pk_add_f32 v[64:65], v[32:33], 0 op_sel_hi:[1,0]
	v_mov_b32_e32 v32, v49
	v_pk_add_f32 v[48:49], v[32:33], 0 op_sel_hi:[1,0]
	s_waitcnt lgkmcnt(1)
	v_mov_b32_e32 v32, v206
	s_waitcnt lgkmcnt(0)
	v_mov_b32_e32 v33, v208
	s_mov_b32 s2, s67
	v_mov_b32_e32 v206, v207
	v_mov_b32_e32 v207, v208
	v_pk_mul_f32 v[212:213], v[32:33], s[2:3] op_sel_hi:[1,0]
	v_pk_fma_f32 v[32:33], v[32:33], s[2:3], v[64:65] op_sel_hi:[1,0,1]
	v_pk_fma_f32 v[48:49], v[206:207], s[2:3], v[48:49] op_sel_hi:[1,0,1]
	v_pk_mul_f32 v[214:215], v[32:33], v[32:33]
	v_pk_mul_f32 v[206:207], v[48:49], v[48:49]
	v_pk_mov_b32 v[64:65], v[64:65], v[214:215] op_sel:[1,0]
	v_pk_mov_b32 v[206:207], v[212:213], v[206:207] op_sel:[1,0]
	v_add_f32_e32 v16, 0, v17
	v_pk_add_f32 v[64:65], v[64:65], v[206:207]
	v_pk_add_f32 v[206:207], v[32:33], v[48:49]
	v_pk_mul_f32 v[212:213], v[32:33], v[48:49]
	v_fmac_f32_e32 v16, 0x3fd744fd, v209
	v_mov_b32_e32 v207, v213
	v_pk_add_f32 v[64:65], v[206:207], v[64:65]
	v_mul_f32_e32 v17, v16, v16
	v_pk_add_f32 v[64:65], v[64:65], v[16:17]
	s_nop 1
	v_mov_b32_dpp v206, v64 quad_perm:[1,0,3,2] row_mask:0xf bank_mask:0xf bound_ctrl:1
	v_mov_b32_dpp v207, v65 quad_perm:[1,0,3,2] row_mask:0xf bank_mask:0xf bound_ctrl:1
	v_pk_add_f32 v[64:65], v[64:65], v[206:207]
	s_nop 1
	v_mov_b32_dpp v206, v64 quad_perm:[2,3,0,1] row_mask:0xf bank_mask:0xf bound_ctrl:1
	v_mov_b32_dpp v207, v65 quad_perm:[2,3,0,1] row_mask:0xf bank_mask:0xf bound_ctrl:1
	v_pk_add_f32 v[64:65], v[64:65], v[206:207]
	s_nop 1
	v_mov_b32_dpp v206, v64 row_half_mirror row_mask:0xf bank_mask:0xf bound_ctrl:1
	v_mov_b32_dpp v207, v65 row_half_mirror row_mask:0xf bank_mask:0xf bound_ctrl:1
	v_pk_add_f32 v[64:65], v[64:65], v[206:207]
	s_nop 1
	v_mov_b32_dpp v206, v64 row_mirror row_mask:0xf bank_mask:0xf bound_ctrl:1
	v_mov_b32_dpp v207, v65 row_mirror row_mask:0xf bank_mask:0xf bound_ctrl:1
	s_and_saveexec_b64 s[6:7], vcc
	v_pk_add_f32 v[64:65], v[64:65], v[206:207]
	ds_write_b64 v179, v[64:65] offset:472
	s_or_b64 exec, exec, s[6:7]
	v_ashrrev_i32_e32 v206, 8, v163
	v_ashrrev_i32_e32 v207, 31, v206
	v_lshlrev_b64 v[64:65], 13, v[206:207]
	v_lshl_add_u64 v[64:65], s[8:9], 0, v[64:65]
	v_cmp_gt_i32_e64 s[40:41], s60, v164
	v_ashrrev_i32_e32 v201, 31, v200
	s_waitcnt lgkmcnt(0)
	s_barrier
	s_and_saveexec_b64 s[6:7], s[40:41]
	s_cbranch_execz .LBB0_599
	v_lshl_add_u32 v0, v164, 3, v221
	ds_read2st64_b64 v[212:215], v0 offset1:4
	ds_read2st64_b64 v[226:229], v0 offset0:8 offset1:12
	v_ashrrev_i32_e32 v208, 8, v182
	v_ashrrev_i32_e32 v209, 31, v208
	s_waitcnt lgkmcnt(1)
	v_mov_b32_e32 v230, v212
	s_waitcnt lgkmcnt(0)
	v_mov_b32_e32 v231, v226
	v_mov_b32_e32 v232, v214
	v_mov_b32_e32 v233, v228
	v_mov_b32_e32 v226, v213
	v_mov_b32_e32 v228, v215
	v_pk_add_f32 v[230:231], v[230:231], v[232:233]
	v_pk_add_f32 v[212:213], v[226:227], v[228:229]
	v_pk_add_f32 v[230:231], v[230:231], v[230:231] op_sel:[0,1] op_sel_hi:[1,0]
	v_pk_add_f32 v[212:213], v[212:213], v[212:213] op_sel:[0,1] op_sel_hi:[1,0]
	v_lshl_add_u64 v[214:215], v[200:201], 3, v[64:65]
	v_lshl_add_u64 v[208:209], v[208:209], 3, v[214:215]
	v_mov_b32_e32 v231, v212
	global_store_dwordx2 v[208:209], v[230:231], off sc1

; DI void wait_vm0() { asm volatile("s_waitcnt vmcnt(0)" ::: "memory"); }
;   DI void pre(int grow0, int gcol0, int lane, int w, char* lds) { xpass(0, grow0, gcol0, lane, w, lds); }
; template <int BK> DI int swz(int row) { constexpr int CPR = BK / 8; return (row / (16 / CPR)) % CPR; }
; template <int ROWS, int BK>
; DI void stage_tile(const bf16_t* g, int ld, char* l, int tid) {
;   constexpr int CPR = BK / 8, TOT = ROWS * CPR, N = (TOT + NT - 1) / NT;
;   const int row0 = tid / CPR, pc = tid % CPR; const int c = pc ^ swz<BK>(row0);
;   const unsigned voff = (unsigned)(row0 * ld + c * 8) * 2u;
; #pragma unroll
;   for (int i = 0; i < N; ++i) {
;     if (TOT % NT == 0 || tid + i * NT < TOT) {
;       const char* gb = (const char*)g + (size_t)i * (NT / CPR) * ld * 2;
;       __builtin_amdgcn_global_load_lds((const unsigned*)(gb + voff), (__attribute__((address_space(3))) unsigned*)(l + i * NT * 16 + __builtin_amdgcn_readfirstlane(tid >> 6) * 1024), 16, 0, 0);
;     }
;   }
; }
;     ...
;   const bf16_t* Ag = A + (size_t)row0 * lda; const bf16_t* Bg = Bt + (size_t)col0 * ldb;
;   const int wv = __builtin_amdgcn_readfirstlane(tid >> 6);
;   __syncthreads();
;   if (!pre) { stage_tile<BM, BK>(Ag, lda, lds, tid); stage_tile<BN, BK>(Bg, ldb, lds + ABYTES, tid); }
;   wait_vm0();
;   __syncthreads();
;   const int nk = K / BK;
;   for (int kt = 0; kt < nk; ++kt) {
;     char* cur = lds + (kt & 1) * STG; char* nxt = lds + ((kt + 1) & 1) * STG;
;     const bool more = kt + 1 < nk;
;     const bf16_t* An = Ag + (kt + 1) * BK; const bf16_t* Bn = Bg + (kt + 1) * BK;
;     if (!more) epi.pre(row0 + wm * 64, col0 + wn * (32 * NTW), lane, w, lds);
;     bf16x8 fa[2][2], fb[2][NTW];
; #pragma unroll
;     for (int mt = 0; mt < 2; ++mt) { int row = wm * 64 + mt * 32 + l31; fa[0][mt] = *(const bf16x8*)(cur + row * (BK * 2) + ((hh ^ swz<BK>(row)) << 4)); }
; #pragma unroll
;     for (int nt = 0; nt < NTW; ++nt) { int row = wn * (32 * NTW) + nt * 32 + l31; fb[0][nt] = *(const bf16x8*)(cur + ABYTES + row * (BK * 2) + ((hh ^ swz<BK>(row)) << 4)); }
.LBB0_615:
	s_and_b64 vcc, exec, s[6:7]
	s_cbranch_vccz .LBB0_618
	s_waitcnt vmcnt(0)
	v_mov_b32_e32 v136, v216
	v_readlane_b32 s2, v253, 29
	v_ashrrev_i32_e32 v0, 31, v136
	v_lshrrev_b32_e32 v2, 29, v0
	v_lshrrev_b32_e32 v0, 28, v0
	v_add_u32_e32 v0, v136, v0
	v_ashrrev_i32_e32 v0, 4, v0
	v_readlane_b32 s3, v253, 30
	s_waitcnt lgkmcnt(0)
	s_add_u32 s2, s42, s2
	v_lshrrev_b32_e32 v6, 29, v0
	s_addc_u32 s3, s43, s3
	v_readlane_b32 s6, v253, 13
	v_add_u32_e32 v2, v136, v2
	v_add_u32_e32 v6, v0, v6
	v_readlane_b32 s7, v253, 14
	s_add_u32 s6, s2, s6
	v_and_b32_e32 v3, 0xffffff8, v2
	v_and_b32_e32 v6, 0xffffff8, v6
	s_addc_u32 s7, s3, s7
	v_sub_u32_e32 v3, v136, v3
	v_sub_u32_e32 v0, v0, v6
	v_lshlrev_b32_e32 v2, 8, v2
	v_readfirstlane_b32 s3, v136
	v_xor_b32_e32 v0, v0, v3
	v_and_b32_e32 v2, 0xfffff800, v2
	v_readlane_b32 s30, v253, 31
	s_lshl_b32 s3, s3, 4
	v_lshl_add_u32 v0, v0, 4, v2
	v_readlane_b32 s31, v253, 32
	s_and_b32 s3, s3, 0xfffffc00
	s_mov_b32 m0, s3
	v_lshl_add_u64 v[132:133], s[30:31], 0, v[0:1]
	s_barrier
	s_nop 0
	global_load_lds_dwordx4 v0, s[30:31]
	v_lshl_add_u64 v[2:3], v[132:133], 0, s[58:59]
	s_add_i32 m0, s3, 0x2000
	v_lshl_add_u64 v[130:131], s[6:7], 0, v[0:1]
	global_load_lds_dwordx4 v[2:3], off
	v_lshl_add_u64 v[2:3], v[132:133], 0, s[48:49]
	s_add_i32 m0, s3, 0x4000
	v_ashrrev_i32_e32 v4, 6, v136
	global_load_lds_dwordx4 v[2:3], off
	v_lshl_add_u64 v[2:3], v[132:133], 0, s[50:51]
	s_add_i32 m0, s3, 0x6000
	v_readfirstlane_b32 s2, v4
	global_load_lds_dwordx4 v[2:3], off
	s_add_i32 m0, s3, 0x8000
	v_lshl_add_u64 v[2:3], v[130:131], 0, s[58:59]
	global_load_lds_dwordx4 v0, s[6:7]
	s_add_i32 m0, s3, 0xa000
	v_lshrrev_b32_e32 v0, 30, v4
	global_load_lds_dwordx4 v[2:3], off
	v_lshl_add_u64 v[2:3], v[130:131], 0, s[48:49]
	s_add_i32 m0, s3, 0xc000
	v_lshrrev_b32_e32 v5, 5, v136
	global_load_lds_dwordx4 v[2:3], off
	v_lshl_add_u64 v[2:3], v[130:131], 0, s[50:51]
	s_add_i32 m0, s3, 0xe000
	v_bfe_u32 v20, v136, 5, 1
	global_load_lds_dwordx4 v[2:3], off
	v_add_u32_e32 v2, v4, v0
	v_ashrrev_i32_e32 v0, 2, v2
	v_mul_i32_i24_e32 v6, 4, v0
	v_sub_u32_e32 v4, v4, v6
	v_and_b32_e32 v3, 31, v136
	v_lshlrev_b32_e32 v21, 6, v4
	v_or_b32_e32 v6, v21, v3
	v_bfe_u32 v4, v4, 25, 1
	v_lshlrev_b32_e32 v137, 7, v6
	v_add_u32_e32 v7, v6, v4
	v_or_b32_e32 v6, 32, v6
	v_add_u32_e32 v4, v6, v4
	v_lshlrev_b32_e32 v164, 7, v6
	v_ashrrev_i32_e32 v6, 1, v4
	v_ashrrev_i32_e32 v4, 31, v4
	v_lshrrev_b32_e32 v4, 29, v4
	v_add_u32_e32 v4, v6, v4
	v_and_b32_e32 v4, -8, v4
	v_lshlrev_b32_e32 v0, 7, v0
	v_sub_u32_e32 v23, v6, v4
	v_or_b32_e32 v3, v0, v3
	v_bitop3_b32 v4, v23, v5, 1 bitop3:0x78
	v_lshrrev_b32_e32 v2, 31, v2
	v_lshlrev_b32_e32 v194, 4, v4
	v_add_u32_e32 v4, v3, v2
	v_ashrrev_i32_e32 v6, 1, v4
	v_ashrrev_i32_e32 v4, 31, v4
	v_lshrrev_b32_e32 v4, 29, v4
	v_add_u32_e32 v4, v6, v4
	v_and_b32_e32 v4, -8, v4
	v_sub_u32_e32 v24, v6, v4
	v_bitop3_b32 v4, v24, v5, 1 bitop3:0x78
	v_lshlrev_b32_e32 v196, 4, v4
	v_or_b32_e32 v4, 32, v3
	v_lshlrev_b32_e32 v197, 7, v4
	v_add_u32_e32 v4, v4, v2
	v_ashrrev_i32_e32 v6, 1, v4
	v_ashrrev_i32_e32 v4, 31, v4
	v_lshrrev_b32_e32 v4, 29, v4
	v_add_u32_e32 v4, v6, v4
	v_and_b32_e32 v4, -8, v4
	v_sub_u32_e32 v25, v6, v4
	v_bitop3_b32 v4, v25, v5, 1 bitop3:0x78
	v_lshlrev_b32_e32 v195, 7, v3
	v_lshlrev_b32_e32 v198, 4, v4
	v_or_b32_e32 v4, 64, v3
	v_or_b32_e32 v3, 0x60, v3
	v_lshlrev_b32_e32 v199, 7, v4
	v_add_u32_e32 v4, v4, v2
	v_add_u32_e32 v2, v3, v2
	v_lshlrev_b32_e32 v201, 7, v3
	v_ashrrev_i32_e32 v3, 1, v2
	v_ashrrev_i32_e32 v2, 31, v2
	v_ashrrev_i32_e32 v8, 1, v7
	v_ashrrev_i32_e32 v7, 31, v7
	v_lshrrev_b32_e32 v2, 29, v2
	v_lshrrev_b32_e32 v7, 29, v7
	v_add_u32_e32 v2, v3, v2
	v_add_u32_e32 v7, v8, v7
	v_and_b32_e32 v2, -8, v2
	v_and_b32_e32 v7, -8, v7
	v_sub_u32_e32 v27, v3, v2
	v_sub_u32_e32 v22, v8, v7
	v_ashrrev_i32_e32 v6, 1, v4
	v_ashrrev_i32_e32 v4, 31, v4
	v_bitop3_b32 v2, v27, v5, 1 bitop3:0x78
	v_lshrrev_b32_e32 v4, 29, v4
	v_lshlrev_b32_e32 v202, 4, v2
	v_bitop3_b32 v2, v22, v20, 2 bitop3:0x1e
	v_add_u32_e32 v4, v6, v4
	v_lshlrev_b32_e32 v203, 4, v2
	v_bitop3_b32 v2, v23, v20, 2 bitop3:0x1e
	v_and_b32_e32 v4, -8, v4
	v_lshlrev_b32_e32 v204, 4, v2
	v_bitop3_b32 v2, v24, v20, 2 bitop3:0x1e
	v_sub_u32_e32 v26, v6, v4
	v_lshlrev_b32_e32 v205, 4, v2
	v_bitop3_b32 v2, v25, v20, 2 bitop3:0x1e
	s_lshl_b32 s3, s2, 10
	v_bitop3_b32 v7, v22, v5, 1 bitop3:0x78
	v_bitop3_b32 v4, v26, v5, 1 bitop3:0x78
	v_lshlrev_b32_e32 v206, 4, v2
	v_bitop3_b32 v2, v26, v20, 2 bitop3:0x1e
	v_lshlrev_b32_e32 v163, 4, v7
	v_lshlrev_b32_e32 v200, 4, v4
	v_lshlrev_b32_e32 v207, 4, v2
	v_bitop3_b32 v2, v27, v20, 2 bitop3:0x1e
	s_add_i32 s30, s3, 0x10000
	v_lshlrev_b32_e32 v208, 4, v2
	v_add_u32_e32 v209, v137, v163
	v_add_u32_e32 v211, v195, v196
	v_add_u32_e32 v213, v199, v200
	v_lshl_add_u64 v[18:19], v[132:133], 0, s[28:29]
	v_add_u32_e32 v215, v137, v203
	v_add_u32_e32 v227, v195, v205
	v_add_u32_e32 v229, v199, v207
	s_mov_b32 m0, s30
	s_add_i32 s7, s3, 0x12000
	s_waitcnt vmcnt(0)
	s_waitcnt vmcnt(0) lgkmcnt(0)
	s_barrier
; DI f32x16 mfma(bf16x8 a, bf16x8 b, f32x16 c) { return __builtin_amdgcn_mfma_f32_32x32x16_bf16(a, b, c, 0, 0, 0); }
; template <int BK> DI int swz(int row) { constexpr int CPR = BK / 8; return (row / (16 / CPR)) % CPR; }
;   DI void pre(int grow0, int gcol0, int lane, int w, char* lds) { xpass(0, grow0, gcol0, lane, w, lds); }
;     ...
;   for (int kt = 0; kt < nk; ++kt) {
;     char* cur = lds + (kt & 1) * STG; char* nxt = lds + ((kt + 1) & 1) * STG;
;     const bool more = kt + 1 < nk;
;     const bf16_t* An = Ag + (kt + 1) * BK; const bf16_t* Bn = Bg + (kt + 1) * BK;
;     if (!more) epi.pre(row0 + wm * 64, col0 + wn * (32 * NTW), lane, w, lds);
;     bf16x8 fa[2][2], fb[2][NTW];
; #pragma unroll
;     for (int mt = 0; mt < 2; ++mt) { int row = wm * 64 + mt * 32 + l31; fa[0][mt] = *(const bf16x8*)(cur + row * (BK * 2) + ((hh ^ swz<BK>(row)) << 4)); }
; #pragma unroll
;     for (int nt = 0; nt < NTW; ++nt) { int row = wn * (32 * NTW) + nt * 32 + l31; fb[0][nt] = *(const bf16x8*)(cur + ABYTES + row * (BK * 2) + ((hh ^ swz<BK>(row)) << 4)); }
; #pragma unroll
;     for (int kk = 0; kk < NKK; ++kk) {
;       if (kk + 1 < NKK) {
;         const int ch = (kk + 1) * 2 + hh;
; #pragma unroll
;         for (int mt = 0; mt < 2; ++mt) { int row = wm * 64 + mt * 32 + l31; fa[(kk + 1) & 1][mt] = *(const bf16x8*)(cur + row * (BK * 2) + ((ch ^ swz<BK>(row)) << 4)); }
; #pragma unroll
;         for (int nt = 0; nt < NTW; ++nt) { int row = wn * (32 * NTW) + nt * 32 + l31; fb[(kk + 1) & 1][nt] = *(const bf16x8*)(cur + ABYTES + row * (BK * 2) + ((ch ^ swz<BK>(row)) << 4)); }
;       }
;       if (more) {
; #pragma unroll
;         for (int q = 0; q < PPK; ++q) {
;           const int pi = kk * PPK + q;
;           if (pi < NPA) stage_piece<BM, BK>(An, lda, nxt, tid, pi, wv);
;           else if (pi < NP) stage_piece<BN, BK>(Bn, ldb, nxt + ABYTES, tid, pi - NPA, wv);
;         }
;       }
;       __builtin_amdgcn_s_setprio(1);
; #pragma unroll
;       for (int mt = 0; mt < 2; ++mt)
; #pragma unroll
;         for (int nt = 0; nt < NTW; ++nt) acc[mt][nt] = mfma(fa[kk & 1][mt], fb[kk & 1][nt], acc[mt][nt]);
;       __builtin_amdgcn_s_setprio(0);
;       __builtin_amdgcn_sched_barrier(0);
;     }
	v_add_u32_e32 v210, v164, v194
	ds_read_b128 v[2:5], v209
	ds_read_b128 v[34:37], v210
	v_add_u32_e32 v212, v197, v198
	ds_read_b128 v[6:9], v211 offset:32768
	ds_read_b128 v[10:13], v212 offset:32768
	v_add_u32_e32 v214, v201, v202
	ds_read_b128 v[14:17], v213 offset:32768
	ds_read_b128 v[38:41], v214 offset:32768
	v_add_u32_e32 v226, v164, v204
	ds_read_b128 v[138:141], v215
	ds_read_b128 v[142:145], v226
	v_add_u32_e32 v228, v197, v206
	ds_read_b128 v[146:149], v227 offset:32768
	ds_read_b128 v[150:153], v228 offset:32768
	v_add_u32_e32 v230, v201, v208
	ds_read_b128 v[154:157], v229 offset:32768
	ds_read_b128 v[158:161], v230 offset:32768
	global_load_lds_dwordx4 v[18:19], off
	v_lshl_add_u64 v[18:19], v[132:133], 0, s[24:25]
	s_mov_b32 m0, s7
	v_readlane_b32 s6, v253, 9
	global_load_lds_dwordx4 v[18:19], off
	s_nop 0
	v_or_b32_e32 v18, s6, v20
	v_add_u32_e32 v18, v18, v21
	v_ashrrev_i32_e32 v19, 31, v18
	v_lshlrev_b64 v[134:135], 12, v[18:19]
	v_bitop3_b32 v18, v22, v20, 4 bitop3:0x1e
	v_lshlrev_b32_e32 v231, 4, v18
	v_bitop3_b32 v18, v23, v20, 4 bitop3:0x1e
	v_lshlrev_b32_e32 v232, 4, v18
	v_bitop3_b32 v18, v24, v20, 4 bitop3:0x1e
	v_lshlrev_b32_e32 v233, 4, v18
	v_bitop3_b32 v18, v25, v20, 4 bitop3:0x1e
	v_lshlrev_b32_e32 v234, 4, v18
	v_bitop3_b32 v18, v26, v20, 4 bitop3:0x1e
	v_lshlrev_b32_e32 v235, 4, v18
	v_bitop3_b32 v18, v27, v20, 4 bitop3:0x1e
	v_lshlrev_b32_e32 v236, 4, v18
	v_bitop3_b32 v18, v22, v20, 6 bitop3:0x1e
	v_lshlrev_b32_e32 v237, 4, v18
	v_bitop3_b32 v18, v23, v20, 6 bitop3:0x1e
	v_lshlrev_b32_e32 v238, 4, v18
	v_bitop3_b32 v18, v24, v20, 6 bitop3:0x1e
	v_lshlrev_b32_e32 v239, 4, v18
	v_bitop3_b32 v18, v25, v20, 6 bitop3:0x1e
	v_lshlrev_b32_e32 v240, 4, v18
	v_bitop3_b32 v18, v26, v20, 6 bitop3:0x1e
	v_lshlrev_b32_e32 v241, 4, v18
	v_bitop3_b32 v18, v27, v20, 6 bitop3:0x1e
	v_lshlrev_b32_e32 v242, 4, v18
	v_lshl_add_u64 v[190:191], v[130:131], 0, s[28:29]
	s_add_i32 s6, s3, 0x18000
	s_waitcnt lgkmcnt(0)
	v_mfma_f32_32x32x16_bf16 v[114:129], v[2:5], v[6:9], 0
	v_mfma_f32_32x32x16_bf16 v[82:97], v[2:5], v[10:13], 0
	v_mfma_f32_32x32x16_bf16 v[66:81], v[2:5], v[14:17], 0
	v_mfma_f32_32x32x16_bf16 v[98:113], v[2:5], v[38:41], 0
	v_mfma_f32_32x32x16_bf16 v[50:65], v[34:37], v[6:9], 0
	v_mfma_f32_32x32x16_bf16 v[18:33], v[34:37], v[10:13], 0
	v_mfma_f32_32x32x16_bf16 v[2:17], v[34:37], v[14:17], 0
	v_mfma_f32_32x32x16_bf16 v[34:49], v[34:37], v[38:41], 0
	s_add_i32 s34, s3, 0x14000
	v_add_u32_e32 v243, v137, v231
	v_add_u32_e32 v245, v195, v233
	v_add_u32_e32 v247, v199, v235
	v_lshl_add_u64 v[192:193], v[132:133], 0, s[26:27]
	s_mov_b32 m0, s34
	s_add_i32 s31, s3, 0x16000
	v_add_u32_e32 v244, v164, v232
	ds_read_b128 v[166:169], v243
	ds_read_b128 v[170:173], v244
	v_add_u32_e32 v246, v197, v234
	ds_read_b128 v[174:177], v245 offset:32768
	ds_read_b128 v[178:181], v246 offset:32768
	v_add_u32_e32 v248, v201, v236
	ds_read_b128 v[182:185], v247 offset:32768
	ds_read_b128 v[186:189], v248 offset:32768
	global_load_lds_dwordx4 v[192:193], off
	v_lshl_add_u64 v[192:193], v[132:133], 0, s[38:39]
	s_mov_b32 m0, s31
	s_nop 0
	global_load_lds_dwordx4 v[192:193], off
	v_mfma_f32_32x32x16_bf16 v[114:129], v[138:141], v[146:149], v[114:129]
	v_mfma_f32_32x32x16_bf16 v[82:97], v[138:141], v[150:153], v[82:97]
	v_mfma_f32_32x32x16_bf16 v[66:81], v[138:141], v[154:157], v[66:81]
	v_mfma_f32_32x32x16_bf16 v[98:113], v[138:141], v[158:161], v[98:113]
	v_mfma_f32_32x32x16_bf16 v[50:65], v[142:145], v[146:149], v[50:65]
	v_mfma_f32_32x32x16_bf16 v[18:33], v[142:145], v[150:153], v[18:33]
	v_mfma_f32_32x32x16_bf16 v[2:17], v[142:145], v[154:157], v[2:17]
	v_mfma_f32_32x32x16_bf16 v[34:49], v[142:145], v[158:161], v[34:49]
	s_mov_b32 m0, s6
	v_add_u32_e32 v249, v137, v237
	v_add_u32_e32 v251, v195, v239
	v_add_u32_e32 v217, v199, v241
	s_add_i32 s35, s3, 0x1a000
	v_add_u32_e32 v250, v164, v238
	ds_read_b128 v[138:141], v249
	ds_read_b128 v[142:145], v250
	v_add_u32_e32 v252, v197, v240
	ds_read_b128 v[146:149], v251 offset:32768
	ds_read_b128 v[150:153], v252 offset:32768
	v_add_u32_e32 v219, v201, v242
	ds_read_b128 v[154:157], v217 offset:32768
	ds_read_b128 v[158:161], v219 offset:32768
	global_load_lds_dwordx4 v[190:191], off
	v_lshl_add_u64 v[190:191], v[130:131], 0, s[24:25]
	s_mov_b32 m0, s35
	s_nop 0
	global_load_lds_dwordx4 v[190:191], off
	s_waitcnt lgkmcnt(0)
	v_mfma_f32_32x32x16_bf16 v[114:129], v[166:169], v[174:177], v[114:129]
	v_mfma_f32_32x32x16_bf16 v[82:97], v[166:169], v[178:181], v[82:97]
	v_mfma_f32_32x32x16_bf16 v[66:81], v[166:169], v[182:185], v[66:81]
	v_mfma_f32_32x32x16_bf16 v[98:113], v[166:169], v[186:189], v[98:113]
	v_mfma_f32_32x32x16_bf16 v[50:65], v[170:173], v[174:177], v[50:65]
	v_mfma_f32_32x32x16_bf16 v[18:33], v[170:173], v[178:181], v[18:33]
	v_mfma_f32_32x32x16_bf16 v[2:17], v[170:173], v[182:185], v[2:17]
	v_mfma_f32_32x32x16_bf16 v[34:49], v[170:173], v[186:189], v[34:49]
	s_add_i32 s37, s3, 0x1c000
	v_lshl_add_u64 v[166:167], v[130:131], 0, s[26:27]
	s_mov_b32 m0, s37
	s_add_i32 s36, s3, 0x1e000
	global_load_lds_dwordx4 v[166:167], off
	v_lshl_add_u64 v[166:167], v[130:131], 0, s[38:39]
	s_mov_b32 m0, s36
	s_nop 0
	global_load_lds_dwordx4 v[166:167], off
	v_mfma_f32_32x32x16_bf16 v[114:129], v[138:141], v[146:149], v[114:129]
	v_mfma_f32_32x32x16_bf16 v[82:97], v[138:141], v[150:153], v[82:97]
	v_mfma_f32_32x32x16_bf16 v[66:81], v[138:141], v[154:157], v[66:81]
	v_mfma_f32_32x32x16_bf16 v[98:113], v[138:141], v[158:161], v[98:113]
	v_mfma_f32_32x32x16_bf16 v[50:65], v[142:145], v[146:149], v[50:65]
	v_mfma_f32_32x32x16_bf16 v[18:33], v[142:145], v[150:153], v[18:33]
	v_mfma_f32_32x32x16_bf16 v[2:17], v[142:145], v[154:157], v[2:17]
	v_mfma_f32_32x32x16_bf16 v[34:49], v[142:145], v[158:161], v[34:49]
	v_add_u32_e32 v137, 0x10000, v137
	v_add_u32_e32 v195, 0x18000, v195
	v_add_u32_e32 v199, 0x18000, v199
	s_mov_b64 s[40:41], 0x100
	s_mov_b32 m0, s3
	v_add_u32_e32 v163, v137, v163
	v_add_u32_e32 v164, 0x10000, v164
	v_add_u32_e32 v196, v195, v196
	v_add_u32_e32 v197, 0x18000, v197
	v_add_u32_e32 v200, v199, v200
	v_add_u32_e32 v201, 0x18000, v201
	v_lshl_add_u64 v[190:191], v[132:133], 0, s[40:41]
	v_add_u32_e32 v203, v137, v203
	v_add_u32_e32 v205, v195, v205
	v_add_u32_e32 v207, v199, v207
	s_mov_b64 s[42:43], 0x20100
	s_waitcnt vmcnt(0)
	s_waitcnt vmcnt(0) lgkmcnt(0)
	s_barrier
; DI f32x16 mfma(bf16x8 a, bf16x8 b, f32x16 c) { return __builtin_amdgcn_mfma_f32_32x32x16_bf16(a, b, c, 0, 0, 0); }
; template <int BK> DI int swz(int row) { constexpr int CPR = BK / 8; return (row / (16 / CPR)) % CPR; }
;   DI void pre(int grow0, int gcol0, int lane, int w, char* lds) { xpass(0, grow0, gcol0, lane, w, lds); }
;     ...
;   for (int kt = 0; kt < nk; ++kt) {
;     char* cur = lds + (kt & 1) * STG; char* nxt = lds + ((kt + 1) & 1) * STG;
;     const bool more = kt + 1 < nk;
;     const bf16_t* An = Ag + (kt + 1) * BK; const bf16_t* Bn = Bg + (kt + 1) * BK;
;     if (!more) epi.pre(row0 + wm * 64, col0 + wn * (32 * NTW), lane, w, lds);
;     bf16x8 fa[2][2], fb[2][NTW];
; #pragma unroll
;     for (int mt = 0; mt < 2; ++mt) { int row = wm * 64 + mt * 32 + l31; fa[0][mt] = *(const bf16x8*)(cur + row * (BK * 2) + ((hh ^ swz<BK>(row)) << 4)); }
; #pragma unroll
;     for (int nt = 0; nt < NTW; ++nt) { int row = wn * (32 * NTW) + nt * 32 + l31; fb[0][nt] = *(const bf16x8*)(cur + ABYTES + row * (BK * 2) + ((hh ^ swz<BK>(row)) << 4)); }
; #pragma unroll
;     for (int kk = 0; kk < NKK; ++kk) {
;       if (kk + 1 < NKK) {
;         const int ch = (kk + 1) * 2 + hh;
; #pragma unroll
;         for (int mt = 0; mt < 2; ++mt) { int row = wm * 64 + mt * 32 + l31; fa[(kk + 1) & 1][mt] = *(const bf16x8*)(cur + row * (BK * 2) + ((ch ^ swz<BK>(row)) << 4)); }
; #pragma unroll
;         for (int nt = 0; nt < NTW; ++nt) { int row = wn * (32 * NTW) + nt * 32 + l31; fb[(kk + 1) & 1][nt] = *(const bf16x8*)(cur + ABYTES + row * (BK * 2) + ((ch ^ swz<BK>(row)) << 4)); }
;       }
;       if (more) {
; #pragma unroll
;         for (int q = 0; q < PPK; ++q) {
;           const int pi = kk * PPK + q;
;           if (pi < NPA) stage_piece<BM, BK>(An, lda, nxt, tid, pi, wv);
;           else if (pi < NP) stage_piece<BN, BK>(Bn, ldb, nxt + ABYTES, tid, pi - NPA, wv);
;         }
;       }
;       __builtin_amdgcn_s_setprio(1);
; #pragma unroll
;       for (int mt = 0; mt < 2; ++mt)
; #pragma unroll
;         for (int nt = 0; nt < NTW; ++nt) acc[mt][nt] = mfma(fa[kk & 1][mt], fb[kk & 1][nt], acc[mt][nt]);
;       __builtin_amdgcn_s_setprio(0);
;       __builtin_amdgcn_sched_barrier(0);
;     }
	v_add_u32_e32 v194, v164, v194
	ds_read_b128 v[138:141], v163
	ds_read_b128 v[142:145], v194
	v_add_u32_e32 v198, v197, v198
	ds_read_b128 v[146:149], v196
	ds_read_b128 v[150:153], v198
	v_add_u32_e32 v202, v201, v202
	ds_read_b128 v[154:157], v200
	ds_read_b128 v[158:161], v202
	v_add_u32_e32 v204, v164, v204
	ds_read_b128 v[166:169], v203
	ds_read_b128 v[170:173], v204
	v_add_u32_e32 v206, v197, v206
	ds_read_b128 v[174:177], v205
	ds_read_b128 v[178:181], v206
	v_add_u32_e32 v208, v201, v208
	ds_read_b128 v[182:185], v207
	ds_read_b128 v[186:189], v208
	global_load_lds_dwordx4 v[190:191], off
	v_lshl_add_u64 v[190:191], v[132:133], 0, s[42:43]
	s_add_i32 m0, s3, 0x2000
	s_nop 0
	global_load_lds_dwordx4 v[190:191], off
	v_lshl_add_u64 v[190:191], v[130:131], 0, s[40:41]
	s_add_i32 s40, s3, 0x8000
	s_waitcnt lgkmcnt(0)
	v_mfma_f32_32x32x16_bf16 v[114:129], v[138:141], v[146:149], v[114:129]
	v_mfma_f32_32x32x16_bf16 v[82:97], v[138:141], v[150:153], v[82:97]
	v_mfma_f32_32x32x16_bf16 v[66:81], v[138:141], v[154:157], v[66:81]
	v_mfma_f32_32x32x16_bf16 v[98:113], v[138:141], v[158:161], v[98:113]
	v_mfma_f32_32x32x16_bf16 v[50:65], v[142:145], v[146:149], v[50:65]
	v_mfma_f32_32x32x16_bf16 v[18:33], v[142:145], v[150:153], v[18:33]
	v_mfma_f32_32x32x16_bf16 v[2:17], v[142:145], v[154:157], v[2:17]
	v_mfma_f32_32x32x16_bf16 v[34:49], v[142:145], v[158:161], v[34:49]
	s_mov_b64 s[44:45], 0x40100
	v_add_u32_e32 v231, v137, v231
	v_add_u32_e32 v233, v195, v233
	v_add_u32_e32 v235, v199, v235
	v_lshl_add_u64 v[192:193], v[132:133], 0, s[44:45]
	s_add_i32 m0, s3, 0x4000
	s_mov_b64 s[46:47], 0x60100
	v_add_u32_e32 v232, v164, v232
	ds_read_b128 v[138:141], v231
	ds_read_b128 v[142:145], v232
	v_add_u32_e32 v234, v197, v234
	ds_read_b128 v[146:149], v233
	ds_read_b128 v[150:153], v234
	v_add_u32_e32 v236, v201, v236
	ds_read_b128 v[154:157], v235
	ds_read_b128 v[158:161], v236
	global_load_lds_dwordx4 v[192:193], off
	v_lshl_add_u64 v[192:193], v[132:133], 0, s[46:47]
	s_add_i32 m0, s3, 0x6000
	s_nop 0
	global_load_lds_dwordx4 v[192:193], off
	v_mfma_f32_32x32x16_bf16 v[114:129], v[166:169], v[174:177], v[114:129]
	v_mfma_f32_32x32x16_bf16 v[82:97], v[166:169], v[178:181], v[82:97]
	v_mfma_f32_32x32x16_bf16 v[66:81], v[166:169], v[182:185], v[66:81]
	v_mfma_f32_32x32x16_bf16 v[98:113], v[166:169], v[186:189], v[98:113]
	v_mfma_f32_32x32x16_bf16 v[50:65], v[170:173], v[174:177], v[50:65]
	v_mfma_f32_32x32x16_bf16 v[18:33], v[170:173], v[178:181], v[18:33]
	v_mfma_f32_32x32x16_bf16 v[2:17], v[170:173], v[182:185], v[2:17]
	v_mfma_f32_32x32x16_bf16 v[34:49], v[170:173], v[186:189], v[34:49]
	s_mov_b32 m0, s40
	v_add_u32_e32 v237, v137, v237
	v_add_u32_e32 v195, v195, v239
	v_add_u32_e32 v199, v199, v241
	v_add_u32_e32 v164, v164, v238
	ds_read_b128 v[166:169], v237
	ds_read_b128 v[170:173], v164
	v_add_u32_e32 v197, v197, v240
	ds_read_b128 v[174:177], v195
	ds_read_b128 v[178:181], v197
	v_add_u32_e32 v201, v201, v242
	ds_read_b128 v[182:185], v199
	ds_read_b128 v[186:189], v201
	global_load_lds_dwordx4 v[190:191], off
	v_lshl_add_u64 v[190:191], v[130:131], 0, s[42:43]
	s_add_i32 m0, s3, 0xa000
	s_nop 0
	global_load_lds_dwordx4 v[190:191], off
	s_waitcnt lgkmcnt(0)
	v_mfma_f32_32x32x16_bf16 v[114:129], v[138:141], v[146:149], v[114:129]
	v_mfma_f32_32x32x16_bf16 v[82:97], v[138:141], v[150:153], v[82:97]
	v_mfma_f32_32x32x16_bf16 v[66:81], v[138:141], v[154:157], v[66:81]
	v_mfma_f32_32x32x16_bf16 v[98:113], v[138:141], v[158:161], v[98:113]
	v_mfma_f32_32x32x16_bf16 v[50:65], v[142:145], v[146:149], v[50:65]
	v_mfma_f32_32x32x16_bf16 v[18:33], v[142:145], v[150:153], v[18:33]
	v_mfma_f32_32x32x16_bf16 v[2:17], v[142:145], v[154:157], v[2:17]
	v_mfma_f32_32x32x16_bf16 v[34:49], v[142:145], v[158:161], v[34:49]
	v_lshl_add_u64 v[138:139], v[130:131], 0, s[44:45]
	s_add_i32 m0, s3, 0xc000
	s_nop 0
	global_load_lds_dwordx4 v[138:139], off
	v_lshl_add_u64 v[138:139], v[130:131], 0, s[46:47]
	s_add_i32 m0, s3, 0xe000
	s_nop 0
	global_load_lds_dwordx4 v[138:139], off
	v_mfma_f32_32x32x16_bf16 v[114:129], v[166:169], v[174:177], v[114:129]
	v_mfma_f32_32x32x16_bf16 v[82:97], v[166:169], v[178:181], v[82:97]
	v_mfma_f32_32x32x16_bf16 v[66:81], v[166:169], v[182:185], v[66:81]
	v_mfma_f32_32x32x16_bf16 v[98:113], v[166:169], v[186:189], v[98:113]
	v_mfma_f32_32x32x16_bf16 v[50:65], v[170:173], v[174:177], v[50:65]
	v_mfma_f32_32x32x16_bf16 v[18:33], v[170:173], v[178:181], v[18:33]
	v_mfma_f32_32x32x16_bf16 v[2:17], v[170:173], v[182:185], v[2:17]
	v_mfma_f32_32x32x16_bf16 v[34:49], v[170:173], v[186:189], v[34:49]
	s_mov_b64 s[40:41], 0x180
	s_mov_b32 m0, s30
	v_lshl_add_u64 v[190:191], v[132:133], 0, s[40:41]
	s_mov_b64 s[42:43], 0x20180
	s_waitcnt vmcnt(0)
	s_waitcnt vmcnt(0) lgkmcnt(0)
	s_barrier
; DI f32x16 mfma(bf16x8 a, bf16x8 b, f32x16 c) { return __builtin_amdgcn_mfma_f32_32x32x16_bf16(a, b, c, 0, 0, 0); }
; template <int BK> DI int swz(int row) { constexpr int CPR = BK / 8; return (row / (16 / CPR)) % CPR; }
;   DI void pre(int grow0, int gcol0, int lane, int w, char* lds) { xpass(0, grow0, gcol0, lane, w, lds); }
;     ...
;   for (int kt = 0; kt < nk; ++kt) {
;     char* cur = lds + (kt & 1) * STG; char* nxt = lds + ((kt + 1) & 1) * STG;
;     const bool more = kt + 1 < nk;
;     const bf16_t* An = Ag + (kt + 1) * BK; const bf16_t* Bn = Bg + (kt + 1) * BK;
;     if (!more) epi.pre(row0 + wm * 64, col0 + wn * (32 * NTW), lane, w, lds);
;     bf16x8 fa[2][2], fb[2][NTW];
; #pragma unroll
;     for (int mt = 0; mt < 2; ++mt) { int row = wm * 64 + mt * 32 + l31; fa[0][mt] = *(const bf16x8*)(cur + row * (BK * 2) + ((hh ^ swz<BK>(row)) << 4)); }
; #pragma unroll
;     for (int nt = 0; nt < NTW; ++nt) { int row = wn * (32 * NTW) + nt * 32 + l31; fb[0][nt] = *(const bf16x8*)(cur + ABYTES + row * (BK * 2) + ((hh ^ swz<BK>(row)) << 4)); }
; #pragma unroll
;     for (int kk = 0; kk < NKK; ++kk) {
;       if (kk + 1 < NKK) {
;         const int ch = (kk + 1) * 2 + hh;
; #pragma unroll
;         for (int mt = 0; mt < 2; ++mt) { int row = wm * 64 + mt * 32 + l31; fa[(kk + 1) & 1][mt] = *(const bf16x8*)(cur + row * (BK * 2) + ((ch ^ swz<BK>(row)) << 4)); }
; #pragma unroll
;         for (int nt = 0; nt < NTW; ++nt) { int row = wn * (32 * NTW) + nt * 32 + l31; fb[(kk + 1) & 1][nt] = *(const bf16x8*)(cur + ABYTES + row * (BK * 2) + ((ch ^ swz<BK>(row)) << 4)); }
;       }
;       if (more) {
; #pragma unroll
;         for (int q = 0; q < PPK; ++q) {
;           const int pi = kk * PPK + q;
;           if (pi < NPA) stage_piece<BM, BK>(An, lda, nxt, tid, pi, wv);
;           else if (pi < NP) stage_piece<BN, BK>(Bn, ldb, nxt + ABYTES, tid, pi - NPA, wv);
;         }
;       }
;       __builtin_amdgcn_s_setprio(1);
; #pragma unroll
;       for (int mt = 0; mt < 2; ++mt)
; #pragma unroll
;         for (int nt = 0; nt < NTW; ++nt) acc[mt][nt] = mfma(fa[kk & 1][mt], fb[kk & 1][nt], acc[mt][nt]);
;       __builtin_amdgcn_s_setprio(0);
;       __builtin_amdgcn_sched_barrier(0);
;     }
	ds_read_b128 v[138:141], v209
	ds_read_b128 v[142:145], v210
	ds_read_b128 v[146:149], v211 offset:32768
	ds_read_b128 v[150:153], v212 offset:32768
	ds_read_b128 v[154:157], v213 offset:32768
	ds_read_b128 v[158:161], v214 offset:32768
	ds_read_b128 v[166:169], v215
	ds_read_b128 v[170:173], v226
	ds_read_b128 v[174:177], v227 offset:32768
	ds_read_b128 v[178:181], v228 offset:32768
	ds_read_b128 v[182:185], v229 offset:32768
	ds_read_b128 v[186:189], v230 offset:32768
	global_load_lds_dwordx4 v[190:191], off
	v_lshl_add_u64 v[190:191], v[132:133], 0, s[42:43]
	s_mov_b32 m0, s7
	s_nop 0
	global_load_lds_dwordx4 v[190:191], off
	v_lshl_add_u64 v[190:191], v[130:131], 0, s[40:41]
	s_waitcnt lgkmcnt(0)
	v_mfma_f32_32x32x16_bf16 v[114:129], v[138:141], v[146:149], v[114:129]
	v_mfma_f32_32x32x16_bf16 v[82:97], v[138:141], v[150:153], v[82:97]
	v_mfma_f32_32x32x16_bf16 v[66:81], v[138:141], v[154:157], v[66:81]
	v_mfma_f32_32x32x16_bf16 v[98:113], v[138:141], v[158:161], v[98:113]
	v_mfma_f32_32x32x16_bf16 v[50:65], v[142:145], v[146:149], v[50:65]
	v_mfma_f32_32x32x16_bf16 v[18:33], v[142:145], v[150:153], v[18:33]
	v_mfma_f32_32x32x16_bf16 v[2:17], v[142:145], v[154:157], v[2:17]
	v_mfma_f32_32x32x16_bf16 v[34:49], v[142:145], v[158:161], v[34:49]
	s_mov_b64 s[40:41], 0x40180
	s_mov_b32 m0, s34
	v_lshl_add_u64 v[192:193], v[132:133], 0, s[40:41]
	s_mov_b64 s[44:45], 0x60180
	ds_read_b128 v[138:141], v243
	ds_read_b128 v[142:145], v244
	ds_read_b128 v[146:149], v245 offset:32768
	ds_read_b128 v[150:153], v246 offset:32768
	ds_read_b128 v[154:157], v247 offset:32768
	ds_read_b128 v[158:161], v248 offset:32768
	global_load_lds_dwordx4 v[192:193], off
	v_lshl_add_u64 v[132:133], v[132:133], 0, s[44:45]
	s_mov_b32 m0, s31
	s_nop 0
	global_load_lds_dwordx4 v[132:133], off
	v_mfma_f32_32x32x16_bf16 v[114:129], v[166:169], v[174:177], v[114:129]
	v_mfma_f32_32x32x16_bf16 v[82:97], v[166:169], v[178:181], v[82:97]
	v_mfma_f32_32x32x16_bf16 v[66:81], v[166:169], v[182:185], v[66:81]
	v_mfma_f32_32x32x16_bf16 v[98:113], v[166:169], v[186:189], v[98:113]
	v_mfma_f32_32x32x16_bf16 v[50:65], v[170:173], v[174:177], v[50:65]
	v_mfma_f32_32x32x16_bf16 v[18:33], v[170:173], v[178:181], v[18:33]
	v_mfma_f32_32x32x16_bf16 v[2:17], v[170:173], v[182:185], v[2:17]
	v_mfma_f32_32x32x16_bf16 v[34:49], v[170:173], v[186:189], v[34:49]
	s_mov_b32 m0, s6
	ds_read_b128 v[166:169], v249
	ds_read_b128 v[170:173], v250
	ds_read_b128 v[174:177], v251 offset:32768
	ds_read_b128 v[178:181], v252 offset:32768
	ds_read_b128 v[182:185], v217 offset:32768
	ds_read_b128 v[186:189], v219 offset:32768
	global_load_lds_dwordx4 v[190:191], off
	v_lshl_add_u64 v[132:133], v[130:131], 0, s[42:43]
	s_mov_b32 m0, s35
	s_nop 0
	global_load_lds_dwordx4 v[132:133], off
	s_waitcnt lgkmcnt(0)
	v_mfma_f32_32x32x16_bf16 v[114:129], v[138:141], v[146:149], v[114:129]
	v_mfma_f32_32x32x16_bf16 v[82:97], v[138:141], v[150:153], v[82:97]
	v_mfma_f32_32x32x16_bf16 v[66:81], v[138:141], v[154:157], v[66:81]
	v_mfma_f32_32x32x16_bf16 v[98:113], v[138:141], v[158:161], v[98:113]
	v_mfma_f32_32x32x16_bf16 v[50:65], v[142:145], v[146:149], v[50:65]
	v_mfma_f32_32x32x16_bf16 v[18:33], v[142:145], v[150:153], v[18:33]
	v_mfma_f32_32x32x16_bf16 v[2:17], v[142:145], v[154:157], v[2:17]
	v_mfma_f32_32x32x16_bf16 v[34:49], v[142:145], v[158:161], v[34:49]
	s_mov_b32 m0, s37
	v_lshl_add_u64 v[132:133], v[130:131], 0, s[40:41]
	global_load_lds_dwordx4 v[132:133], off
	v_lshl_add_u64 v[130:131], v[130:131], 0, s[44:45]
	s_mov_b32 m0, s36
	s_nop 0
	global_load_lds_dwordx4 v[130:131], off
	v_mfma_f32_32x32x16_bf16 v[114:129], v[166:169], v[174:177], v[114:129]
	v_mfma_f32_32x32x16_bf16 v[82:97], v[166:169], v[178:181], v[82:97]
	v_mfma_f32_32x32x16_bf16 v[66:81], v[166:169], v[182:185], v[66:81]
	v_mfma_f32_32x32x16_bf16 v[98:113], v[166:169], v[186:189], v[98:113]
	v_mfma_f32_32x32x16_bf16 v[50:65], v[170:173], v[174:177], v[50:65]
	v_mfma_f32_32x32x16_bf16 v[18:33], v[170:173], v[178:181], v[18:33]
	v_mfma_f32_32x32x16_bf16 v[2:17], v[170:173], v[182:185], v[2:17]
	v_mfma_f32_32x32x16_bf16 v[34:49], v[170:173], v[186:189], v[34:49]
	v_readlane_b32 s6, v253, 27
	v_lshl_add_u64 v[132:133], s[10:11], 0, v[134:135]
	s_lshl_b32 s2, s2, 13
	v_add_u32_e32 v130, s6, v0
	v_ashrrev_i32_e32 v131, 31, v130
	v_lshlrev_b32_e32 v0, 4, v136
	v_lshl_add_u64 v[130:131], v[130:131], 2, v[132:133]
	v_and_b32_e32 v0, 0x1f0, v0
	v_lshl_add_u64 v[130:131], v[130:131], 0, v[0:1]
	s_mov_b32 m0, s2
	s_mov_b64 s[30:31], 0x2000
	s_waitcnt vmcnt(0)
	s_waitcnt vmcnt(0) lgkmcnt(0)
	s_barrier
; DI f32x16 mfma(bf16x8 a, bf16x8 b, f32x16 c) { return __builtin_amdgcn_mfma_f32_32x32x16_bf16(a, b, c, 0, 0, 0); }
; template <int BK> DI int swz(int row) { constexpr int CPR = BK / 8; return (row / (16 / CPR)) % CPR; }
; DI void wait_vm0() { asm volatile("s_waitcnt vmcnt(0)" ::: "memory"); }
;     ...
;     for (int kk = 0; kk < NKK; ++kk) {
;       if (kk + 1 < NKK) {
;         const int ch = (kk + 1) * 2 + hh;
; #pragma unroll
;         for (int mt = 0; mt < 2; ++mt) { int row = wm * 64 + mt * 32 + l31; fa[(kk + 1) & 1][mt] = *(const bf16x8*)(cur + row * (BK * 2) + ((ch ^ swz<BK>(row)) << 4)); }
; #pragma unroll
;         for (int nt = 0; nt < NTW; ++nt) { int row = wn * (32 * NTW) + nt * 32 + l31; fb[(kk + 1) & 1][nt] = *(const bf16x8*)(cur + ABYTES + row * (BK * 2) + ((ch ^ swz<BK>(row)) << 4)); }
;       }
;       if (more) {
; #pragma unroll
;         for (int q = 0; q < PPK; ++q) {
;           const int pi = kk * PPK + q;
;           if (pi < NPA) stage_piece<BM, BK>(An, lda, nxt, tid, pi, wv);
;           else if (pi < NP) stage_piece<BN, BK>(Bn, ldb, nxt + ABYTES, tid, pi - NPA, wv);
;         }
;       }
;       __builtin_amdgcn_s_setprio(1);
; #pragma unroll
;       for (int mt = 0; mt < 2; ++mt)
; #pragma unroll
;         for (int nt = 0; nt < NTW; ++nt) acc[mt][nt] = mfma(fa[kk & 1][mt], fb[kk & 1][nt], acc[mt][nt]);
;       __builtin_amdgcn_s_setprio(0);
;       __builtin_amdgcn_sched_barrier(0);
;     }
;     wait_vm0();
;     __syncthreads();
;   DI void xpass(int ps, int grow0, int gcol0, int lane, int w, char* lds) const {
;     char* xs = lds + (ps & 1) * 65536 + __builtin_amdgcn_readfirstlane(w) * 8192;
;     const float* xsrc = Xin + (size_t)(grow0 + (ps >> 1) * 32 + (ps & 1) * 16 + (lane >> 5)) * D_ + gcol0 + (lane & 31) * 4;
; #pragma unroll
;     for (int pc = 0; pc < 8; ++pc)
;       __builtin_amdgcn_global_load_lds((const unsigned*)(xsrc + (size_t)(2 * pc) * D_), (__attribute__((address_space(3))) unsigned*)(xs + pc * 1024), 16, 0, 0);
;   }
;   DI void pre(int grow0, int gcol0, int lane, int w, char* lds) { xpass(0, grow0, gcol0, lane, w, lds); }
	global_load_lds_dwordx4 v[130:131], off
	v_lshl_add_u64 v[132:133], v[130:131], 0, s[30:31]
	s_or_b32 m0, s2, 0x400
	s_mov_b64 s[30:31], 0x4000
	global_load_lds_dwordx4 v[132:133], off
	v_lshl_add_u64 v[132:133], v[130:131], 0, s[30:31]
	s_or_b32 m0, s2, 0x800
	s_mov_b64 s[30:31], 0x6000
	global_load_lds_dwordx4 v[132:133], off
	v_lshl_add_u64 v[132:133], v[130:131], 0, s[30:31]
	s_or_b32 m0, s2, 0xc00
	s_mov_b64 s[30:31], 0x8000
	global_load_lds_dwordx4 v[132:133], off
	v_lshl_add_u64 v[132:133], v[130:131], 0, s[30:31]
	s_or_b32 m0, s2, 0x1000
	s_mov_b64 s[30:31], 0xa000
	global_load_lds_dwordx4 v[132:133], off
	v_lshl_add_u64 v[132:133], v[130:131], 0, s[30:31]
	s_or_b32 m0, s2, 0x1400
	s_mov_b64 s[30:31], 0xc000
	global_load_lds_dwordx4 v[132:133], off
	v_lshl_add_u64 v[132:133], v[130:131], 0, s[30:31]
	s_or_b32 m0, s2, 0x1800
	s_mov_b64 s[30:31], 0xe000
	global_load_lds_dwordx4 v[132:133], off
	v_lshl_add_u64 v[130:131], v[130:131], 0, s[30:31]
	s_or_b32 m0, s2, 0x1c00
	v_readlane_b32 s7, v253, 28
	global_load_lds_dwordx4 v[130:131], off
	ds_read_b128 v[130:133], v163
	ds_read_b128 v[134:137], v194
	ds_read_b128 v[138:141], v196
	ds_read_b128 v[142:145], v198
	ds_read_b128 v[146:149], v200
	ds_read_b128 v[150:153], v202
	ds_read_b128 v[154:157], v203
	ds_read_b128 v[158:161], v204
	ds_read_b128 v[166:169], v205
	ds_read_b128 v[170:173], v206
	ds_read_b128 v[174:177], v207
	ds_read_b128 v[178:181], v208
	s_waitcnt lgkmcnt(0)
	v_mfma_f32_32x32x16_bf16 v[114:129], v[130:133], v[138:141], v[114:129]
	v_mfma_f32_32x32x16_bf16 v[82:97], v[130:133], v[142:145], v[82:97]
	v_mfma_f32_32x32x16_bf16 v[66:81], v[130:133], v[146:149], v[66:81]
	v_mfma_f32_32x32x16_bf16 v[98:113], v[130:133], v[150:153], v[98:113]
	v_mfma_f32_32x32x16_bf16 v[50:65], v[134:137], v[138:141], v[50:65]
	v_mfma_f32_32x32x16_bf16 v[18:33], v[134:137], v[142:145], v[18:33]
	v_mfma_f32_32x32x16_bf16 v[2:17], v[134:137], v[146:149], v[2:17]
	v_mfma_f32_32x32x16_bf16 v[34:49], v[134:137], v[150:153], v[34:49]
	ds_read_b128 v[130:133], v231
	ds_read_b128 v[134:137], v232
	ds_read_b128 v[138:141], v233
	ds_read_b128 v[142:145], v234
	ds_read_b128 v[146:149], v235
	ds_read_b128 v[150:153], v236
	v_mfma_f32_32x32x16_bf16 v[114:129], v[154:157], v[166:169], v[114:129]
	v_mfma_f32_32x32x16_bf16 v[82:97], v[154:157], v[170:173], v[82:97]
	v_mfma_f32_32x32x16_bf16 v[66:81], v[154:157], v[174:177], v[66:81]
	v_mfma_f32_32x32x16_bf16 v[98:113], v[154:157], v[178:181], v[98:113]
	v_mfma_f32_32x32x16_bf16 v[50:65], v[158:161], v[166:169], v[50:65]
	v_mfma_f32_32x32x16_bf16 v[18:33], v[158:161], v[170:173], v[18:33]
	v_mfma_f32_32x32x16_bf16 v[2:17], v[158:161], v[174:177], v[2:17]
	v_mfma_f32_32x32x16_bf16 v[34:49], v[158:161], v[178:181], v[34:49]
	ds_read_b128 v[154:157], v237
	ds_read_b128 v[158:161], v164
	ds_read_b128 v[166:169], v195
	ds_read_b128 v[170:173], v197
	ds_read_b128 v[174:177], v199
	ds_read_b128 v[178:181], v201
	s_waitcnt lgkmcnt(9)
	v_mfma_f32_32x32x16_bf16 v[114:129], v[130:133], v[138:141], v[114:129]
	s_waitcnt lgkmcnt(8)
	v_mfma_f32_32x32x16_bf16 v[82:97], v[130:133], v[142:145], v[82:97]
	s_waitcnt lgkmcnt(7)
	v_mfma_f32_32x32x16_bf16 v[66:81], v[130:133], v[146:149], v[66:81]
	s_waitcnt lgkmcnt(6)
	v_mfma_f32_32x32x16_bf16 v[98:113], v[130:133], v[150:153], v[98:113]
	v_mfma_f32_32x32x16_bf16 v[50:65], v[134:137], v[138:141], v[50:65]
	v_mfma_f32_32x32x16_bf16 v[18:33], v[134:137], v[142:145], v[18:33]
	v_mfma_f32_32x32x16_bf16 v[2:17], v[134:137], v[146:149], v[2:17]
	v_mfma_f32_32x32x16_bf16 v[34:49], v[134:137], v[150:153], v[34:49]
	s_waitcnt lgkmcnt(3)
	v_mfma_f32_32x32x16_bf16 v[114:129], v[154:157], v[166:169], v[114:129]
	s_waitcnt lgkmcnt(2)
	v_mfma_f32_32x32x16_bf16 v[82:97], v[154:157], v[170:173], v[82:97]
	s_waitcnt lgkmcnt(1)
	v_mfma_f32_32x32x16_bf16 v[66:81], v[154:157], v[174:177], v[66:81]
	s_waitcnt lgkmcnt(0)
	v_mfma_f32_32x32x16_bf16 v[98:113], v[154:157], v[178:181], v[98:113]
	v_mfma_f32_32x32x16_bf16 v[50:65], v[158:161], v[166:169], v[50:65]
	v_mfma_f32_32x32x16_bf16 v[18:33], v[158:161], v[170:173], v[18:33]
	v_mfma_f32_32x32x16_bf16 v[2:17], v[158:161], v[174:177], v[2:17]
	v_mfma_f32_32x32x16_bf16 v[34:49], v[158:161], v[178:181], v[34:49]
	v_mov_b32_e32 v163, v216
	s_waitcnt vmcnt(0)
	s_barrier
	v_readlane_b32 s2, v253, 33
	v_ashrrev_i32_e32 v176, 6, v163
	v_lshrrev_b32_e32 v0, 30, v176
	v_add_u32_e32 v0, v176, v0
	v_ashrrev_i32_e32 v0, 2, v0
	v_lshlrev_b32_e32 v133, 7, v0
	v_add_u32_e32 v142, s6, v133
	v_and_b32_e32 v132, 31, v163
	v_readlane_b32 s3, v253, 34
	v_or_b32_e32 v130, v142, v132
	s_andn2_b64 vcc, exec, s[2:3]
	v_cndmask_b32_e64 v131, 0, 1, s[2:3]
	v_cmp_ne_u32_e64 s[40:41], 1, v131
	v_ashrrev_i32_e32 v131, 31, v130
	s_cbranch_vccnz .LBB0_680
	s_load_dwordx16 s[44:59], s[0:1], 0x18
	s_waitcnt lgkmcnt(0)
	v_lshl_add_u64 v[134:135], v[130:131], 2, s[54:55]
	global_load_dword v169, v[134:135], off
	s_branch .LBB0_681

; DI bf16_t f2bf(float x) { return (bf16_t)(pack2(x, 0.f) & 0xffffu); }
; DI int crow(int i, int hh) { return (i & 3) + 8 * (i >> 2) + 4 * hh; }
; DI f32x16 mfma(bf16x8 a, bf16x8 b, f32x16 c) { return __builtin_amdgcn_mfma_f32_32x32x16_bf16(a, b, c, 0, 0, 0); }
; template <int BK> DI int swz(int row) { constexpr int CPR = BK / 8; return (row / (16 / CPR)) % CPR; }
; DI void wait_vm0() { asm volatile("s_waitcnt vmcnt(0)" ::: "memory"); }
;     ...
;     for (int kk = 0; kk < NKK; ++kk) {
;       if (kk + 1 < NKK) {
;         const int ch = (kk + 1) * 2 + hh;
; #pragma unroll
;         for (int mt = 0; mt < 2; ++mt) { int row = wm * 64 + mt * 32 + l31; fa[(kk + 1) & 1][mt] = *(const bf16x8*)(cur + row * (BK * 2) + ((ch ^ swz<BK>(row)) << 4)); }
; #pragma unroll
;         for (int nt = 0; nt < NTW; ++nt) { int row = wn * (32 * NTW) + nt * 32 + l31; fb[(kk + 1) & 1][nt] = *(const bf16x8*)(cur + ABYTES + row * (BK * 2) + ((ch ^ swz<BK>(row)) << 4)); }
;       }
;       if (more) {
; #pragma unroll
;         for (int q = 0; q < PPK; ++q) {
;           const int pi = kk * PPK + q;
;           if (pi < NPA) stage_piece<BM, BK>(An, lda, nxt, tid, pi, wv);
;           else if (pi < NP) stage_piece<BN, BK>(Bn, ldb, nxt + ABYTES, tid, pi - NPA, wv);
;         }
;       }
;       __builtin_amdgcn_s_setprio(1);
; #pragma unroll
;       for (int mt = 0; mt < 2; ++mt)
; #pragma unroll
;         for (int nt = 0; nt < NTW; ++nt) acc[mt][nt] = mfma(fa[kk & 1][mt], fb[kk & 1][nt], acc[mt][nt]);
;       __builtin_amdgcn_s_setprio(0);
;       __builtin_amdgcn_sched_barrier(0);
;     }
;     wait_vm0();
;     __syncthreads();
;   }
;   DI void operator()(f32x16 (&acc)[2][4], int grow0, int gcol0, int lane, int w, char* lds) {
;     const int l31 = lane & 31, hh = lane >> 5;
;     if (gcol0 < 1024) {
; #pragma unroll
;       for (int mt = 0; mt < 2; ++mt)
; #pragma unroll
;         for (int nt = 0; nt < 4; ++nt)
; #pragma unroll
;           for (int i = 0; i < 16; ++i) { int row = grow0 + mt * 32 + crow(i, hh); Kx[(size_t)row * D_ + gcol0 + nt * 32 + l31] = f2bf(acc[mt][nt][i]); }
;     } else {
;       const int cin = gcol0 - 1024, h = cin >> 8, b = grow0 >> 8, m0 = grow0 & 255;
;       char* stg = tr_stage(lds, w);
.Lk627_exit:
	v_mfma_f32_32x32x16_bf16 v[114:129], v[190:193], v[198:201], v[114:129]
	v_mfma_f32_32x32x16_bf16 v[98:113], v[190:193], v[202:205], v[98:113]
	v_mfma_f32_32x32x16_bf16 v[82:97], v[190:193], v[206:209], v[82:97]
	v_mfma_f32_32x32x16_bf16 v[66:81], v[190:193], v[210:213], v[66:81]
	v_mfma_f32_32x32x16_bf16 v[50:65], v[194:197], v[198:201], v[50:65]
	v_mfma_f32_32x32x16_bf16 v[34:49], v[194:197], v[202:205], v[34:49]
	v_mfma_f32_32x32x16_bf16 v[18:33], v[194:197], v[206:209], v[18:33]
	v_mfma_f32_32x32x16_bf16 v[2:17], v[194:197], v[210:213], v[2:17]
	s_waitcnt lgkmcnt(0)
	v_add_u32_e32 v0, 0x10000, v136
	v_add_u32_e32 v136, 0x10000, v142
	v_add_u32_e32 v130, v0, v141
	v_add_u32_e32 v141, v136, v144
	ds_read_b128 v[130:133], v130
	ds_read_b128 v[166:169], v141
	v_add_u32_e32 v141, 0x18000, v143
	v_add_u32_e32 v142, v141, v151
	v_add_u32_e32 v202, 0x18000, v152
	v_add_u32_e32 v203, 0x18000, v153
	v_add_u32_e32 v143, v202, v154
	ds_read_b128 v[170:173], v142
	ds_read_b128 v[174:177], v143
	v_add_u32_e32 v142, v203, v155
	v_add_u32_e32 v204, 0x18000, v156
	v_add_u32_e32 v143, v204, v164
	ds_read_b128 v[152:155], v142
	ds_read_b128 v[178:181], v143
	v_add_u32_e32 v142, v0, v161
	v_add_u32_e32 v143, v136, v163
	ds_read_b128 v[182:185], v142
	ds_read_b128 v[186:189], v143
	v_add_u32_e32 v142, v141, v159
	v_add_u32_e32 v143, v202, v160
	ds_read_b128 v[190:193], v142
	ds_read_b128 v[194:197], v143
	v_add_u32_e32 v142, v203, v157
	v_add_u32_e32 v143, v204, v158
	ds_read_b128 v[156:159], v142
	ds_read_b128 v[198:201], v143
	s_lshl_b64 s[30:31], s[6:7], 22
	s_waitcnt lgkmcnt(9)
	v_mfma_f32_32x32x16_bf16 v[114:129], v[130:133], v[170:173], v[114:129]
	s_waitcnt lgkmcnt(8)
	v_mfma_f32_32x32x16_bf16 v[98:113], v[130:133], v[174:177], v[98:113]
	s_waitcnt lgkmcnt(7)
	v_mfma_f32_32x32x16_bf16 v[82:97], v[130:133], v[152:155], v[82:97]
	s_waitcnt lgkmcnt(6)
	v_mfma_f32_32x32x16_bf16 v[66:81], v[130:133], v[178:181], v[66:81]
	v_mfma_f32_32x32x16_bf16 v[50:65], v[166:169], v[170:173], v[50:65]
	v_mfma_f32_32x32x16_bf16 v[34:49], v[166:169], v[174:177], v[34:49]
	v_mfma_f32_32x32x16_bf16 v[18:33], v[166:169], v[152:155], v[18:33]
	v_mfma_f32_32x32x16_bf16 v[2:17], v[166:169], v[178:181], v[2:17]
	v_add_u32_e32 v130, v0, v149
	v_add_u32_e32 v142, v136, v150
	ds_read_b128 v[130:133], v130
	ds_read_b128 v[150:153], v142
	v_add_u32_e32 v142, v141, v147
	v_add_u32_e32 v143, v202, v148
	ds_read_b128 v[166:169], v142
	ds_read_b128 v[170:173], v143
	v_add_u32_e32 v142, v203, v145
	v_add_u32_e32 v146, v204, v146
	ds_read_b128 v[142:145], v142
	ds_read_b128 v[146:149], v146
	s_waitcnt lgkmcnt(9)
	v_mfma_f32_32x32x16_bf16 v[114:129], v[182:185], v[190:193], v[114:129]
	s_waitcnt lgkmcnt(8)
	v_mfma_f32_32x32x16_bf16 v[98:113], v[182:185], v[194:197], v[98:113]
	s_waitcnt lgkmcnt(7)
	v_mfma_f32_32x32x16_bf16 v[82:97], v[182:185], v[156:159], v[82:97]
	s_waitcnt lgkmcnt(6)
	v_mfma_f32_32x32x16_bf16 v[66:81], v[182:185], v[198:201], v[66:81]
	v_mfma_f32_32x32x16_bf16 v[50:65], v[186:189], v[190:193], v[50:65]
	v_mfma_f32_32x32x16_bf16 v[34:49], v[186:189], v[194:197], v[34:49]
	v_mfma_f32_32x32x16_bf16 v[18:33], v[186:189], v[156:159], v[18:33]
	v_mfma_f32_32x32x16_bf16 v[2:17], v[186:189], v[198:201], v[2:17]
	v_add_u32_e32 v0, v0, v139
	v_add_u32_e32 v136, v136, v140
	ds_read_b128 v[154:157], v0
	ds_read_b128 v[158:161], v136
	v_add_u32_e32 v0, v141, v137
	v_add_u32_e32 v140, v202, v138
	ds_read_b128 v[136:139], v0
	ds_read_b128 v[174:177], v140
	v_add_u32_e32 v0, v203, v134
	v_add_u32_e32 v134, v204, v135
	ds_read_b128 v[178:181], v0
	ds_read_b128 v[182:185], v134
	s_waitcnt lgkmcnt(9)
	v_mfma_f32_32x32x16_bf16 v[114:129], v[130:133], v[166:169], v[114:129]
	s_waitcnt lgkmcnt(8)
	v_mfma_f32_32x32x16_bf16 v[98:113], v[130:133], v[170:173], v[98:113]
	s_waitcnt lgkmcnt(7)
	v_mfma_f32_32x32x16_bf16 v[82:97], v[130:133], v[142:145], v[82:97]
	s_waitcnt lgkmcnt(6)
	v_mfma_f32_32x32x16_bf16 v[66:81], v[130:133], v[146:149], v[66:81]
	v_mfma_f32_32x32x16_bf16 v[50:65], v[150:153], v[166:169], v[50:65]
	v_mfma_f32_32x32x16_bf16 v[34:49], v[150:153], v[170:173], v[34:49]
	v_mfma_f32_32x32x16_bf16 v[18:33], v[150:153], v[142:145], v[18:33]
	v_mfma_f32_32x32x16_bf16 v[2:17], v[150:153], v[146:149], v[2:17]
	s_waitcnt lgkmcnt(3)
	v_mfma_f32_32x32x16_bf16 v[114:129], v[154:157], v[136:139], v[114:129]
	s_waitcnt lgkmcnt(2)
	v_mfma_f32_32x32x16_bf16 v[98:113], v[154:157], v[174:177], v[98:113]
	s_waitcnt lgkmcnt(1)
	v_mfma_f32_32x32x16_bf16 v[82:97], v[154:157], v[178:181], v[82:97]
	s_waitcnt lgkmcnt(0)
	v_mfma_f32_32x32x16_bf16 v[66:81], v[154:157], v[182:185], v[66:81]
	v_mfma_f32_32x32x16_bf16 v[50:65], v[158:161], v[136:139], v[50:65]
	v_mfma_f32_32x32x16_bf16 v[34:49], v[158:161], v[174:177], v[34:49]
	v_mfma_f32_32x32x16_bf16 v[18:33], v[158:161], v[178:181], v[18:33]
	v_mfma_f32_32x32x16_bf16 v[2:17], v[158:161], v[182:185], v[2:17]
	v_mov_b32_e32 v135, v216
	s_waitcnt vmcnt(0)
	s_barrier
	s_nop 0
	v_ashrrev_i32_e32 v134, 6, v135
	v_lshrrev_b32_e32 v0, 30, v134
	v_add_u32_e32 v0, v134, v0
	v_ashrrev_i32_e32 v130, 2, v0
	v_mul_i32_i24_e32 v0, 4, v130
	v_sub_u32_e32 v0, v134, v0
	v_lshlrev_b32_e32 v136, 6, v0
	v_lshl_add_u32 v132, v130, 7, s3
	v_add_u32_e32 v0, s2, v136
	v_and_b32_e32 v131, 31, v135
	v_bfe_u32 v133, v135, 5, 1
	v_cmp_lt_i32_e32 vcc, s57, v132
	s_and_saveexec_b64 s[2:3], vcc
	s_xor_b64 s[6:7], exec, s[2:3]
	s_cbranch_execz .LBB0_630
; DI unsigned pack2(float lo, float hi) { f32x2 v = {lo, hi}; bf2_t r = __builtin_convertvector(v, bf2_t); return __builtin_bit_cast(unsigned, r); }
; DI void tr_put(char* stg, int erow, const f32x16& v, int hh, float mul) {
; #pragma unroll
;   for (int qd = 0; qd < 4; ++qd) {
;     u32x2 pk; pk.x = pack2(v[4 * qd] * mul, v[4 * qd + 1] * mul); pk.y = pack2(v[4 * qd + 2] * mul, v[4 * qd + 3] * mul);
;     *(u32x2*)(stg + erow * 64 + (8 * qd + 4 * hh) * 2) = pk;
;   }
; }
; template <int R>
; DI void tr_flush(const char* stg, int row0, bf16_t* g, size_t grs, int lane) {
;   const int r0 = lane >> 2, ch = lane & 3;
; #pragma unroll
;   for (int it = 0; it < R / 16; ++it) {
;     const int r = it * 16 + r0;
;     u32x4 v = *(const u32x4*)(stg + (row0 + r) * 64 + ch * 16);
;     *(u32x4*)((char*)(g + (size_t)r * grs) + ch * 16) = v;
;   }
; }
;   DI void operator()(f32x16 (&acc)[2][4], int grow0, int gcol0, int lane, int w, char* lds) {
;     ...
;       const int cin = gcol0 - 1024, h = cin >> 8, b = grow0 >> 8, m0 = grow0 & 255;
;       char* stg = tr_stage(lds, w);
; #pragma unroll
;       for (int mt = 0; mt < 2; ++mt) {
; #pragma unroll
;         for (int nt = 0; nt < 4; ++nt) tr_put(stg, nt * 32 + l31, acc[mt][nt], hh, 1.f);
;         tr_flush<128>(stg, 0, Vxt + ((size_t)(b * 4 + h) * 256 + (cin & 255)) * 256 + m0 + mt * 32, 256, lane);
;       }
	v_add_u32_e32 v132, 0xfffffc00, v132
	v_lshl_add_u32 v134, v134, 13, v224
	v_lshlrev_b32_e32 v131, 6, v131
	v_lshlrev_b32_e32 v133, 3, v133
	v_ashrrev_i32_e32 v0, 6, v0
	v_lshrrev_b32_e32 v132, 8, v132
	v_or3_b32 v131, v134, v131, v133
	v_and_b32_e32 v0, -4, v0
	v_cvt_pk_bf16_f32 v66, v66, v67
	v_cvt_pk_bf16_f32 v67, v68, v69
	v_add_u32_e32 v132, v132, v0
	ds_write_b64 v131, v[66:67] offset:6144
	v_cvt_pk_bf16_f32 v66, v70, v71
	v_cvt_pk_bf16_f32 v67, v72, v73
	v_and_b32_e32 v135, 63, v135
	s_add_u32 s34, s74, s30
	v_ashrrev_i32_e32 v133, 31, v132
	v_cvt_pk_bf16_f32 v114, v114, v115
	v_cvt_pk_bf16_f32 v115, v116, v117
	ds_write_b64 v131, v[66:67] offset:6160
	v_cvt_pk_bf16_f32 v66, v74, v75
	v_cvt_pk_bf16_f32 v67, v76, v77
	s_addc_u32 s35, s75, s31
	v_lshlrev_b64 v[132:133], 17, v[132:133]
	v_lshlrev_b32_e32 v0, 4, v135
	ds_write_b64 v131, v[114:115]
	v_cvt_pk_bf16_f32 v114, v118, v119
	v_cvt_pk_bf16_f32 v115, v120, v121
	ds_write_b64 v131, v[66:67] offset:6176
	v_cvt_pk_bf16_f32 v66, v78, v79
	v_cvt_pk_bf16_f32 v67, v80, v81
	v_lshlrev_b32_e32 v68, 16, v130
	v_and_b32_e32 v136, 0xc0, v136
	v_lshrrev_b32_e32 v137, 2, v135
	v_and_b32_e32 v0, 48, v0
	ds_write_b64 v131, v[114:115] offset:16
	v_cvt_pk_bf16_f32 v114, v122, v123
	v_cvt_pk_bf16_f32 v115, v124, v125
	ds_write_b64 v131, v[66:67] offset:6192
	v_lshl_add_u64 v[66:67], s[34:35], 0, v[132:133]
	v_and_b32_e32 v68, 0x10000, v68
	v_mov_b32_e32 v69, v1
	v_or_b32_e32 v134, v134, v0
	v_or_b32_e32 v138, 16, v137
	ds_write_b64 v131, v[114:115] offset:32
	v_cvt_pk_bf16_f32 v114, v126, v127
	v_cvt_pk_bf16_f32 v115, v128, v129
	v_lshl_add_u64 v[66:67], v[66:67], 0, v[68:69]
	v_lshlrev_b32_e32 v68, 1, v136
	v_lshl_or_b32 v139, v138, 6, v134
	ds_write_b64 v131, v[114:115] offset:48
	v_lshl_add_u64 v[70:71], v[66:67], 0, v[68:69]
	v_cvt_pk_bf16_f32 v98, v98, v99
	v_cvt_pk_bf16_f32 v99, v100, v101
	v_lshl_add_u64 v[74:75], v[70:71], 0, v[0:1]
	ds_read_b128 v[70:73], v139
	ds_write_b64 v131, v[98:99] offset:2048
	v_cvt_pk_bf16_f32 v98, v102, v103
	v_cvt_pk_bf16_f32 v99, v104, v105
	ds_write_b64 v131, v[98:99] offset:2064
	v_cvt_pk_bf16_f32 v98, v106, v107
	v_cvt_pk_bf16_f32 v99, v108, v109
	v_lshlrev_b32_e32 v0, 9, v137
	v_or_b32_e32 v142, 48, v137
	ds_write_b64 v131, v[98:99] offset:2080
	v_cvt_pk_bf16_f32 v98, v110, v111
	v_cvt_pk_bf16_f32 v99, v112, v113
	v_lshl_add_u64 v[76:77], v[74:75], 0, v[0:1]
	v_lshlrev_b32_e32 v0, 9, v138
	v_lshl_or_b32 v143, v142, 6, v134
	ds_write_b64 v131, v[98:99] offset:2096
	v_lshl_add_u64 v[78:79], v[74:75], 0, v[0:1]
	v_cvt_pk_bf16_f32 v82, v82, v83
	v_cvt_pk_bf16_f32 v83, v84, v85
	s_waitcnt lgkmcnt(4)
	global_store_dwordx4 v[78:79], v[70:73], off
	ds_read_b128 v[70:73], v143
	v_or_b32_e32 v140, 32, v137
	ds_write_b64 v131, v[82:83] offset:4096
	v_cvt_pk_bf16_f32 v82, v86, v87
	v_cvt_pk_bf16_f32 v83, v88, v89
	ds_write_b64 v131, v[82:83] offset:4112
	v_cvt_pk_bf16_f32 v82, v90, v91
	v_cvt_pk_bf16_f32 v83, v92, v93
	v_lshlrev_b32_e32 v0, 9, v140
	v_or_b32_e32 v146, 0x50, v137
	ds_write_b64 v131, v[82:83] offset:4128
	v_cvt_pk_bf16_f32 v82, v94, v95
	v_cvt_pk_bf16_f32 v83, v96, v97
	v_lshl_add_u64 v[80:81], v[74:75], 0, v[0:1]
	v_lshlrev_b32_e32 v0, 9, v142
	v_lshl_or_b32 v135, v137, 6, v134
	v_lshl_or_b32 v147, v146, 6, v134
	ds_write_b64 v131, v[82:83] offset:4144
	v_lshl_add_u64 v[82:83], v[74:75], 0, v[0:1]
	ds_read_b128 v[66:69], v135
	s_waitcnt lgkmcnt(5)
	global_store_dwordx4 v[82:83], v[70:73], off
	ds_read_b128 v[70:73], v147
	v_or_b32_e32 v144, 64, v137
	v_lshlrev_b32_e32 v0, 9, v144
	v_or_b32_e32 v148, 0x60, v137
	v_or_b32_e32 v150, 0x70, v137
	v_lshl_add_u64 v[84:85], v[74:75], 0, v[0:1]
	v_lshlrev_b32_e32 v0, 9, v146
	v_lshl_or_b32 v141, v140, 6, v134
	v_lshl_or_b32 v145, v144, 6, v134
	v_lshl_or_b32 v149, v148, 6, v134
	v_lshl_or_b32 v134, v150, 6, v134
	v_lshl_add_u64 v[86:87], v[74:75], 0, v[0:1]
	s_waitcnt lgkmcnt(0)
	global_store_dwordx4 v[86:87], v[70:73], off
	ds_read_b128 v[70:73], v134
	global_store_dwordx4 v[76:77], v[66:69], off
	ds_read_b128 v[66:69], v141
	v_cvt_pk_bf16_f32 v50, v50, v51
	v_cvt_pk_bf16_f32 v51, v52, v53
	v_cvt_pk_bf16_f32 v34, v34, v35
	v_cvt_pk_bf16_f32 v35, v36, v37
	s_waitcnt lgkmcnt(0)
	global_store_dwordx4 v[80:81], v[66:69], off
	ds_read_b128 v[66:69], v145
	v_cvt_pk_bf16_f32 v18, v18, v19
	v_cvt_pk_bf16_f32 v19, v20, v21
	v_lshlrev_b32_e32 v0, 9, v148
	ds_write_b64 v131, v[50:51]
	s_waitcnt lgkmcnt(1)
	global_store_dwordx4 v[84:85], v[66:69], off
	ds_read_b128 v[66:69], v149
	v_cvt_pk_bf16_f32 v50, v54, v55
	v_cvt_pk_bf16_f32 v51, v56, v57
	ds_write_b64 v131, v[34:35] offset:2048
	v_cvt_pk_bf16_f32 v34, v38, v39
	v_cvt_pk_bf16_f32 v35, v40, v41
	ds_write_b64 v131, v[18:19] offset:4096
	v_cvt_pk_bf16_f32 v18, v22, v23
	v_cvt_pk_bf16_f32 v19, v24, v25
	v_cvt_pk_bf16_f32 v2, v2, v3
	v_cvt_pk_bf16_f32 v3, v4, v5
	v_lshl_add_u64 v[88:89], v[74:75], 0, v[0:1]
	v_lshlrev_b32_e32 v0, 9, v150
	ds_write_b64 v131, v[50:51] offset:16
	v_cvt_pk_bf16_f32 v50, v58, v59
	v_cvt_pk_bf16_f32 v51, v60, v61
	ds_write_b64 v131, v[34:35] offset:2064
	v_cvt_pk_bf16_f32 v34, v42, v43
	v_cvt_pk_bf16_f32 v35, v44, v45
	ds_write_b64 v131, v[18:19] offset:4112
	v_cvt_pk_bf16_f32 v18, v26, v27
	v_cvt_pk_bf16_f32 v19, v28, v29
	ds_write_b64 v131, v[2:3] offset:6144
	v_cvt_pk_bf16_f32 v2, v6, v7
	v_cvt_pk_bf16_f32 v3, v8, v9
	s_waitcnt lgkmcnt(6)
	global_store_dwordx4 v[88:89], v[66:69], off
	ds_write_b64 v131, v[50:51] offset:32
	v_cvt_pk_bf16_f32 v50, v62, v63
	v_lshl_add_u64 v[66:67], v[74:75], 0, v[0:1]
	v_cvt_pk_bf16_f32 v51, v64, v65
	ds_write_b64 v131, v[34:35] offset:2080
	v_cvt_pk_bf16_f32 v34, v46, v47
	v_cvt_pk_bf16_f32 v35, v48, v49
	ds_write_b64 v131, v[18:19] offset:4128
	v_cvt_pk_bf16_f32 v18, v30, v31
	v_cvt_pk_bf16_f32 v19, v32, v33
	ds_write_b64 v131, v[2:3] offset:6160
	v_cvt_pk_bf16_f32 v2, v10, v11
	v_cvt_pk_bf16_f32 v3, v12, v13
	global_store_dwordx4 v[66:67], v[70:73], off
	ds_write_b64 v131, v[50:51] offset:48
	ds_write_b64 v131, v[34:35] offset:2096
	ds_write_b64 v131, v[18:19] offset:4144
	ds_write_b64 v131, v[2:3] offset:6176
	ds_read_b128 v[2:5], v135
	ds_read_b128 v[6:9], v139
	ds_read_b128 v[10:13], v141
	v_cvt_pk_bf16_f32 v14, v14, v15
	v_cvt_pk_bf16_f32 v15, v16, v17
	ds_write_b64 v131, v[14:15] offset:6192
	s_waitcnt lgkmcnt(3)
	global_store_dwordx4 v[76:77], v[2:5], off offset:64
	s_waitcnt lgkmcnt(2)
	global_store_dwordx4 v[78:79], v[6:9], off offset:64
	s_waitcnt lgkmcnt(1)
	global_store_dwordx4 v[80:81], v[10:13], off offset:64
	ds_read_b128 v[2:5], v143
	ds_read_b128 v[6:9], v145
	ds_read_b128 v[10:13], v147
	ds_read_b128 v[14:17], v149
	ds_read_b128 v[18:21], v134
	s_waitcnt lgkmcnt(4)
	global_store_dwordx4 v[82:83], v[2:5], off offset:64
	s_waitcnt lgkmcnt(3)
	global_store_dwordx4 v[84:85], v[6:9], off offset:64
	s_waitcnt lgkmcnt(2)
	global_store_dwordx4 v[86:87], v[10:13], off offset:64
	s_waitcnt lgkmcnt(1)
	global_store_dwordx4 v[88:89], v[14:17], off offset:64
	s_waitcnt lgkmcnt(0)
	global_store_dwordx4 v[66:67], v[18:21], off offset:64
